# GEMM K-loops: LDS-DMA loads use SGPR base + 32-bit VGPR offset (+imm, compensated in M0) instead of 16 per-iteration 64-bit VALU address adds
# speedup vs baseline: 1.0150x; 1.0150x over previous
; #define PG8_STAGE(bufoff, gbase, voff) do { _Pragma("unroll") for (int _i = 0; _i < 2; ++_i) \
;         __builtin_amdgcn_global_load_lds((const unsigned*)((const char*)(gbase) + (voff)[_i]), (PG8_LAS unsigned*)(lds + (bufoff) + ldsw + _i * 8192), 16, 0, 0); } while (0)
; #define PG8_LDA(dst, b, h) do { _Pragma("unroll") for (int m = 0; m < 4; ++m) _Pragma("unroll") for (int k = 0; k < 2; ++k) dst[m][k] = *(const PG8_LAS bf16x8*)(lds + PG8_SA(b, h) + aoff + m * 2048 + k * 1024); } while (0)
; #define PG8_LDB(dst, b, h) do { _Pragma("unroll") for (int n = 0; n < 2; ++n) _Pragma("unroll") for (int k = 0; k < 2; ++k) dst[n][k] = *(const PG8_LAS bf16x8*)(lds + PG8_SB(b, h) + boff + n * 2048 + k * 1024); } while (0)
; template <class Epi, class Sched, bool ALIGN_EPI = false, bool SP2 = false>
; __device__ __forceinline__ void gemm_phase(PG8_LAS unsigned char* lds, const Gemm g, const Sched& S, const Epi& E) {
;     ...
;         for (int t = 0; t < nt; t += 2) {
;             const bool last = (t == nt - 2);
;             const char* a1 = cA + (size_t)(t + 1) * kstep;
;             const char* a2 = last ? nA : cA + (size_t)(t + 2) * kstep; const char* b2 = last ? nB : cB + (size_t)(t + 2) * kstep;
;             const char* a3 = a2 + kstep; const char* b3 = b2 + kstep;
;             if (last && has_next) S.a_ready(nxt);
;             if constexpr (SP2) {
;             PG8_LDB(B0, 0, 0); PG8_LDB(B1, 0, 1); PG8_SCHED; PG8_LDA(At, 0, 0); PG8_STAGE(PG8_SA(1, 1), a1 + hstep, voffA);
;             PG8_WAIT_V(8); PG8_WAIT_L(0); PG8_BAR; PG8_MMA(0, 0, At, B0); PG8_MMA(0, 1, At, B1); PG8_BAR; PG8_SCHED;
;             PG8_LDA(At, 0, 1); PG8_STAGE(PG8_SB(0, 0), b2, voffB); PG8_STAGE(PG8_SB(0, 1), b2 + hstep, voffB); PG8_STAGE(PG8_SA(0, 0), a2, voffA);
;             PG8_WAIT_V(8); PG8_WAIT_L(0); PG8_BAR; PG8_MMA(1, 0, At, B0); PG8_MMA(1, 1, At, B1); PG8_BAR; PG8_SCHED;
;             PG8_LDB(B0, 1, 0); PG8_LDB(B1, 1, 1); PG8_SCHED; PG8_LDA(At, 1, 0); PG8_STAGE(PG8_SA(0, 1), a2 + hstep, voffA);
;             PG8_WAIT_V(8); PG8_WAIT_L(0); PG8_BAR; PG8_MMA(0, 0, At, B0); PG8_MMA(0, 1, At, B1); PG8_BAR; PG8_SCHED;
;             PG8_LDA(At, 1, 1); PG8_STAGE(PG8_SB(1, 0), b3, voffB); PG8_STAGE(PG8_SB(1, 1), b3 + hstep, voffB); PG8_STAGE(PG8_SA(1, 0), a3, voffA);
;             PG8_WAIT_V(8); PG8_WAIT_L(0); PG8_BAR; PG8_MMA(1, 0, At, B0); PG8_MMA(1, 1, At, B1); PG8_BAR; PG8_SCHED;
.LBB0_371:
	s_andn2_b64 vcc, exec, s[14:15]
	s_cbranch_vccnz .LBB0_374
	s_add_u32 s24, s24, 0x80
	s_addc_u32 s25, s25, 0
	s_add_u32 s62, s26, 0x100
	s_addc_u32 s63, s27, 0
	s_mov_b32 s26, 0
	ds_read_b128 v[154:157], v149
	ds_read_b128 v[158:161], v149 offset:1024
	ds_read_b128 v[162:165], v149 offset:2048
	ds_read_b128 v[166:169], v149 offset:3072
	ds_read_b128 v[170:173], v150
	ds_read_b128 v[174:177], v150 offset:1024
	ds_read_b128 v[180:183], v150 offset:2048
	ds_read_b128 v[184:187], v150 offset:3072
	s_add_i32 s64, s26, 2
	s_add_u32 s65, s24, 0x80
	s_addc_u32 s27, s25, 0
	s_cmp_eq_u32 s37, s26
	s_cselect_b32 s26, s0, s65
	s_cselect_b32 s27, s1, s27
	s_cselect_b32 s67, s23, s63
	s_cselect_b32 s66, s22, s62
	s_add_i32 m0, s28, 0xc000
	ds_read_b128 v[188:191], v151
	ds_read_b128 v[192:195], v151 offset:1024
	ds_read_b128 v[196:199], v151 offset:2048
	ds_read_b128 v[200:203], v151 offset:3072
	ds_read_b128 v[204:207], v151 offset:4096
	ds_read_b128 v[208:211], v151 offset:5120
	ds_read_b128 v[212:215], v151 offset:6144
	ds_read_b128 v[216:219], v151 offset:7168
	global_load_lds_dwordx4 v136, s[24:25]
	s_add_i32 m0, s28, 0xe000
	s_nop 0
	global_load_lds_dwordx4 v138, s[24:25]
	s_waitcnt vmcnt(8)
	s_waitcnt lgkmcnt(0)
	s_barrier
	s_setprio 1
	s_waitcnt lgkmcnt(0)
	v_mfma_f32_16x16x32_bf16 v[116:119], v[154:157], v[188:191], 0
	v_mfma_f32_16x16x32_bf16 v[112:115], v[162:165], v[188:191], 0
	v_mfma_f32_16x16x32_bf16 v[100:103], v[154:157], v[196:199], 0
	v_mfma_f32_16x16x32_bf16 v[96:99], v[162:165], v[196:199], 0
	v_mfma_f32_16x16x32_bf16 v[84:87], v[154:157], v[204:207], 0
	v_mfma_f32_16x16x32_bf16 v[80:83], v[162:165], v[204:207], 0
	v_mfma_f32_16x16x32_bf16 v[68:71], v[154:157], v[212:215], 0
	v_mfma_f32_16x16x32_bf16 v[64:67], v[162:165], v[212:215], 0
	v_mfma_f32_16x16x32_bf16 v[116:119], v[158:161], v[192:195], v[116:119]
	v_mfma_f32_16x16x32_bf16 v[112:115], v[166:169], v[192:195], v[112:115]
	v_mfma_f32_16x16x32_bf16 v[100:103], v[158:161], v[200:203], v[100:103]
	v_mfma_f32_16x16x32_bf16 v[96:99], v[166:169], v[200:203], v[96:99]
	v_mfma_f32_16x16x32_bf16 v[84:87], v[158:161], v[208:211], v[84:87]
	v_mfma_f32_16x16x32_bf16 v[80:83], v[166:169], v[208:211], v[80:83]
	v_mfma_f32_16x16x32_bf16 v[68:71], v[158:161], v[216:219], v[68:71]
	v_mfma_f32_16x16x32_bf16 v[64:67], v[166:169], v[216:219], v[64:67]
	s_setprio 0
	s_setprio 1
	v_mfma_f32_16x16x32_bf16 v[124:127], v[170:173], v[188:191], 0
	v_mfma_f32_16x16x32_bf16 v[120:123], v[180:183], v[188:191], 0
	v_mfma_f32_16x16x32_bf16 v[108:111], v[170:173], v[196:199], 0
	v_mfma_f32_16x16x32_bf16 v[104:107], v[180:183], v[196:199], 0
	v_mfma_f32_16x16x32_bf16 v[92:95], v[170:173], v[204:207], 0
	v_mfma_f32_16x16x32_bf16 v[88:91], v[180:183], v[204:207], 0
	v_mfma_f32_16x16x32_bf16 v[76:79], v[170:173], v[212:215], 0
	v_mfma_f32_16x16x32_bf16 v[72:75], v[180:183], v[212:215], 0
	v_mfma_f32_16x16x32_bf16 v[124:127], v[174:177], v[192:195], v[124:127]
	v_mfma_f32_16x16x32_bf16 v[120:123], v[184:187], v[192:195], v[120:123]
	v_mfma_f32_16x16x32_bf16 v[108:111], v[174:177], v[200:203], v[108:111]
	v_mfma_f32_16x16x32_bf16 v[104:107], v[184:187], v[200:203], v[104:107]
	v_mfma_f32_16x16x32_bf16 v[92:95], v[174:177], v[208:211], v[92:95]
	v_mfma_f32_16x16x32_bf16 v[88:91], v[184:187], v[208:211], v[88:91]
	v_mfma_f32_16x16x32_bf16 v[76:79], v[174:177], v[216:219], v[76:79]
	v_mfma_f32_16x16x32_bf16 v[72:75], v[184:187], v[216:219], v[72:75]
	s_setprio 0
	s_barrier
	s_add_i32 s65, s40, s16
	s_mov_b64 s[98:99], s[66:67]
	s_mov_b32 m0, s65
	ds_read_b128 v[188:191], v151 offset:16384
	ds_read_b128 v[192:195], v151 offset:17408
	ds_read_b128 v[196:199], v151 offset:18432
	ds_read_b128 v[200:203], v151 offset:19456
	ds_read_b128 v[204:207], v151 offset:20480
	ds_read_b128 v[208:211], v151 offset:21504
	ds_read_b128 v[212:215], v151 offset:22528
	ds_read_b128 v[216:219], v151 offset:23552
	global_load_lds_dwordx4 v132, s[66:67]
	s_add_i32 m0, s65, 0x2000
	s_add_u32 s66, s66, s6
	s_addc_u32 s67, s67, s7
	s_add_i32 s65, s41, s16
	global_load_lds_dwordx4 v128, s[98:99]
	s_mov_b64 s[100:101], s[66:67]
	s_mov_b32 m0, s65
	s_nop 0
	global_load_lds_dwordx4 v132, s[66:67]
	s_add_i32 m0, s65, 0x2000
	s_mov_b64 s[12:13], s[26:27]
	global_load_lds_dwordx4 v128, s[66:67]
	s_mov_b32 m0, s28
	s_nop 0
	global_load_lds_dwordx4 v134, s[26:27]
	s_mov_b32 m0, s29
	s_nop 0
	global_load_lds_dwordx4 v130, s[26:27]
	s_waitcnt vmcnt(8)
	s_waitcnt lgkmcnt(0)
	s_barrier
	s_setprio 1
	s_waitcnt lgkmcnt(0)
	v_mfma_f32_16x16x32_bf16 v[52:55], v[154:157], v[188:191], 0
	v_mfma_f32_16x16x32_bf16 v[48:51], v[162:165], v[188:191], 0
	v_mfma_f32_16x16x32_bf16 v[36:39], v[154:157], v[196:199], 0
	v_mfma_f32_16x16x32_bf16 v[32:35], v[162:165], v[196:199], 0
	v_mfma_f32_16x16x32_bf16 v[20:23], v[154:157], v[204:207], 0
	v_mfma_f32_16x16x32_bf16 v[16:19], v[162:165], v[204:207], 0
	v_mfma_f32_16x16x32_bf16 v[4:7], v[154:157], v[212:215], 0
	v_mfma_f32_16x16x32_bf16 v[0:3], v[162:165], v[212:215], 0
	v_mfma_f32_16x16x32_bf16 v[52:55], v[158:161], v[192:195], v[52:55]
	v_mfma_f32_16x16x32_bf16 v[48:51], v[166:169], v[192:195], v[48:51]
	v_mfma_f32_16x16x32_bf16 v[36:39], v[158:161], v[200:203], v[36:39]
	v_mfma_f32_16x16x32_bf16 v[32:35], v[166:169], v[200:203], v[32:35]
	v_mfma_f32_16x16x32_bf16 v[20:23], v[158:161], v[208:211], v[20:23]
	v_mfma_f32_16x16x32_bf16 v[16:19], v[166:169], v[208:211], v[16:19]
	v_mfma_f32_16x16x32_bf16 v[4:7], v[158:161], v[216:219], v[4:7]
	v_mfma_f32_16x16x32_bf16 v[0:3], v[166:169], v[216:219], v[0:3]
	s_setprio 0
	s_setprio 1
	v_mfma_f32_16x16x32_bf16 v[60:63], v[170:173], v[188:191], 0
	v_mfma_f32_16x16x32_bf16 v[56:59], v[180:183], v[188:191], 0
	v_mfma_f32_16x16x32_bf16 v[44:47], v[170:173], v[196:199], 0
	v_mfma_f32_16x16x32_bf16 v[40:43], v[180:183], v[196:199], 0
	v_mfma_f32_16x16x32_bf16 v[28:31], v[170:173], v[204:207], 0
	v_mfma_f32_16x16x32_bf16 v[24:27], v[180:183], v[204:207], 0
	v_mfma_f32_16x16x32_bf16 v[12:15], v[170:173], v[212:215], 0
	v_mfma_f32_16x16x32_bf16 v[8:11], v[180:183], v[212:215], 0
	v_mfma_f32_16x16x32_bf16 v[60:63], v[174:177], v[192:195], v[60:63]
	v_mfma_f32_16x16x32_bf16 v[56:59], v[184:187], v[192:195], v[56:59]
	v_mfma_f32_16x16x32_bf16 v[44:47], v[174:177], v[200:203], v[44:47]
	v_mfma_f32_16x16x32_bf16 v[40:43], v[184:187], v[200:203], v[40:43]
	v_mfma_f32_16x16x32_bf16 v[28:31], v[174:177], v[208:211], v[28:31]
	v_mfma_f32_16x16x32_bf16 v[24:27], v[184:187], v[208:211], v[24:27]
	v_mfma_f32_16x16x32_bf16 v[12:15], v[174:177], v[216:219], v[12:15]
	v_mfma_f32_16x16x32_bf16 v[8:11], v[184:187], v[216:219], v[8:11]
	s_setprio 0
	s_barrier
; #define PG8_STAGE(bufoff, gbase, voff) do { _Pragma("unroll") for (int _i = 0; _i < 2; ++_i) \
;         __builtin_amdgcn_global_load_lds((const unsigned*)((const char*)(gbase) + (voff)[_i]), (PG8_LAS unsigned*)(lds + (bufoff) + ldsw + _i * 8192), 16, 0, 0); } while (0)
; #define PG8_LDA(dst, b, h) do { _Pragma("unroll") for (int m = 0; m < 4; ++m) _Pragma("unroll") for (int k = 0; k < 2; ++k) dst[m][k] = *(const PG8_LAS bf16x8*)(lds + PG8_SA(b, h) + aoff + m * 2048 + k * 1024); } while (0)
; #define PG8_LDB(dst, b, h) do { _Pragma("unroll") for (int n = 0; n < 2; ++n) _Pragma("unroll") for (int k = 0; k < 2; ++k) dst[n][k] = *(const PG8_LAS bf16x8*)(lds + PG8_SB(b, h) + boff + n * 2048 + k * 1024); } while (0)
; #define PG8_MMA(ai, bj, At, Bt) do { __builtin_amdgcn_s_setprio(1); _Pragma("unroll") for (int m = 0; m < 4; ++m) _Pragma("unroll") for (int n = 0; n < 2; ++n) _Pragma("unroll") for (int k = 0; k < 2; ++k) \
;         acc[ai][bj][m][n] = __builtin_amdgcn_mfma_f32_16x16x32_bf16(Bt[n][k], At[m][k], acc[ai][bj][m][n], 0, 0, 0); __builtin_amdgcn_s_setprio(0); } while (0)
; #define PG8_WAIT_V(n) asm volatile("s_waitcnt vmcnt(" #n ")" ::: "memory")
; template <class Epi, class Sched, bool ALIGN_EPI = false, bool SP2 = false>
; __device__ __forceinline__ void gemm_phase(PG8_LAS unsigned char* lds, const Gemm g, const Sched& S, const Epi& E) {
;     ...
;             PG8_LDB(B0, 0, 0); PG8_LDB(B1, 0, 1); PG8_SCHED; PG8_LDA(At, 0, 0); PG8_STAGE(PG8_SA(1, 1), a1 + hstep, voffA);
;             PG8_WAIT_V(8); PG8_WAIT_L(0); PG8_BAR; PG8_MMA(0, 0, At, B0); PG8_MMA(0, 1, At, B1); PG8_BAR; PG8_SCHED;
;             PG8_LDA(At, 0, 1); PG8_STAGE(PG8_SB(0, 0), b2, voffB); PG8_STAGE(PG8_SB(0, 1), b2 + hstep, voffB); PG8_STAGE(PG8_SA(0, 0), a2, voffA);
;             PG8_WAIT_V(8); PG8_WAIT_L(0); PG8_BAR; PG8_MMA(1, 0, At, B0); PG8_MMA(1, 1, At, B1); PG8_BAR; PG8_SCHED;
;             PG8_LDB(B0, 1, 0); PG8_LDB(B1, 1, 1); PG8_SCHED; PG8_LDA(At, 1, 0); PG8_STAGE(PG8_SA(0, 1), a2 + hstep, voffA);
;             PG8_WAIT_V(8); PG8_WAIT_L(0); PG8_BAR; PG8_MMA(0, 0, At, B0); PG8_MMA(0, 1, At, B1); PG8_BAR; PG8_SCHED;
;             PG8_LDA(At, 1, 1); PG8_STAGE(PG8_SB(1, 0), b3, voffB); PG8_STAGE(PG8_SB(1, 1), b3 + hstep, voffB); PG8_STAGE(PG8_SA(1, 0), a3, voffA);
;             PG8_WAIT_V(8); PG8_WAIT_L(0); PG8_BAR; PG8_MMA(1, 0, At, B0); PG8_MMA(1, 1, At, B1); PG8_BAR; PG8_SCHED;
	s_add_i32 s65, 0, 0x18000
	v_add_u32_e32 v153, s65, v147
	s_add_i32 s66, 0, 0x1c000
	ds_read_b128 v[154:157], v153
	ds_read_b128 v[158:161], v153 offset:1024
	ds_read_b128 v[162:165], v153 offset:2048
	ds_read_b128 v[166:169], v153 offset:3072
	v_add_u32_e32 v153, s66, v147
	ds_read_b128 v[170:173], v153
	ds_read_b128 v[174:177], v153 offset:1024
	ds_read_b128 v[180:183], v153 offset:2048
	ds_read_b128 v[184:187], v153 offset:3072
	s_add_u32 s26, s26, s6
	s_addc_u32 s27, s27, s7
	s_mov_b32 m0, s30
	ds_read_b128 v[188:191], v151 offset:32768
	ds_read_b128 v[192:195], v151 offset:33792
	ds_read_b128 v[196:199], v151 offset:34816
	ds_read_b128 v[200:203], v151 offset:35840
	ds_read_b128 v[204:207], v151 offset:36864
	ds_read_b128 v[208:211], v151 offset:37888
	ds_read_b128 v[212:215], v151 offset:38912
	ds_read_b128 v[216:219], v151 offset:39936
	global_load_lds_dwordx4 v134, s[26:27]
	s_mov_b32 m0, s31
	s_nop 0
	global_load_lds_dwordx4 v130, s[26:27]
	s_waitcnt vmcnt(8)
	s_waitcnt lgkmcnt(0)
	s_barrier
	s_setprio 1
	s_waitcnt lgkmcnt(0)
	v_mfma_f32_16x16x32_bf16 v[116:119], v[154:157], v[188:191], v[116:119]
	v_mfma_f32_16x16x32_bf16 v[112:115], v[162:165], v[188:191], v[112:115]
	v_mfma_f32_16x16x32_bf16 v[100:103], v[154:157], v[196:199], v[100:103]
	v_mfma_f32_16x16x32_bf16 v[96:99], v[162:165], v[196:199], v[96:99]
	v_mfma_f32_16x16x32_bf16 v[84:87], v[154:157], v[204:207], v[84:87]
	v_mfma_f32_16x16x32_bf16 v[80:83], v[162:165], v[204:207], v[80:83]
	v_mfma_f32_16x16x32_bf16 v[68:71], v[154:157], v[212:215], v[68:71]
	v_mfma_f32_16x16x32_bf16 v[64:67], v[162:165], v[212:215], v[64:67]
	v_mfma_f32_16x16x32_bf16 v[116:119], v[158:161], v[192:195], v[116:119]
	v_mfma_f32_16x16x32_bf16 v[112:115], v[166:169], v[192:195], v[112:115]
	v_mfma_f32_16x16x32_bf16 v[100:103], v[158:161], v[200:203], v[100:103]
	v_mfma_f32_16x16x32_bf16 v[96:99], v[166:169], v[200:203], v[96:99]
	v_mfma_f32_16x16x32_bf16 v[84:87], v[158:161], v[208:211], v[84:87]
	v_mfma_f32_16x16x32_bf16 v[80:83], v[166:169], v[208:211], v[80:83]
	v_mfma_f32_16x16x32_bf16 v[68:71], v[158:161], v[216:219], v[68:71]
	v_mfma_f32_16x16x32_bf16 v[64:67], v[166:169], v[216:219], v[64:67]
	s_setprio 0
	s_setprio 1
	v_mfma_f32_16x16x32_bf16 v[124:127], v[170:173], v[188:191], v[124:127]
	v_mfma_f32_16x16x32_bf16 v[120:123], v[180:183], v[188:191], v[120:123]
	v_mfma_f32_16x16x32_bf16 v[108:111], v[170:173], v[196:199], v[108:111]
	v_mfma_f32_16x16x32_bf16 v[104:107], v[180:183], v[196:199], v[104:107]
	v_mfma_f32_16x16x32_bf16 v[92:95], v[170:173], v[204:207], v[92:95]
	v_mfma_f32_16x16x32_bf16 v[88:91], v[180:183], v[204:207], v[88:91]
	v_mfma_f32_16x16x32_bf16 v[76:79], v[170:173], v[212:215], v[76:79]
	v_mfma_f32_16x16x32_bf16 v[72:75], v[180:183], v[212:215], v[72:75]
	v_mfma_f32_16x16x32_bf16 v[124:127], v[174:177], v[192:195], v[124:127]
	v_mfma_f32_16x16x32_bf16 v[120:123], v[184:187], v[192:195], v[120:123]
	v_mfma_f32_16x16x32_bf16 v[108:111], v[174:177], v[200:203], v[108:111]
	v_mfma_f32_16x16x32_bf16 v[104:107], v[184:187], v[200:203], v[104:107]
	v_mfma_f32_16x16x32_bf16 v[92:95], v[174:177], v[208:211], v[92:95]
	v_mfma_f32_16x16x32_bf16 v[88:91], v[184:187], v[208:211], v[88:91]
	v_mfma_f32_16x16x32_bf16 v[76:79], v[174:177], v[216:219], v[76:79]
	v_mfma_f32_16x16x32_bf16 v[72:75], v[184:187], v[216:219], v[72:75]
	s_setprio 0
	s_barrier
	s_add_i32 s26, s65, s16
	s_add_i32 m0, s26, 0xffffff80
	ds_read_b128 v[188:191], v151 offset:49152
	ds_read_b128 v[192:195], v151 offset:50176
	ds_read_b128 v[196:199], v151 offset:51200
	ds_read_b128 v[200:203], v151 offset:52224
	ds_read_b128 v[204:207], v151 offset:53248
	ds_read_b128 v[208:211], v151 offset:54272
	ds_read_b128 v[212:215], v151 offset:55296
	ds_read_b128 v[216:219], v151 offset:56320
	global_load_lds_dwordx4 v132, s[98:99] offset:128
	s_add_i32 m0, s26, 0x1f80
	s_add_i32 s26, s66, s16
	global_load_lds_dwordx4 v128, s[98:99] offset:128
	s_add_i32 m0, s26, 0xffffff80
	s_nop 0
	global_load_lds_dwordx4 v132, s[100:101] offset:128
	s_add_i32 m0, s26, 0x1f80
	s_nop 0
	global_load_lds_dwordx4 v128, s[100:101] offset:128
	s_add_i32 m0, s34, 0xffffff80
	s_nop 0
	global_load_lds_dwordx4 v134, s[12:13] offset:128
	s_add_i32 m0, s35, 0xffffff80
	s_nop 0
	global_load_lds_dwordx4 v130, s[12:13] offset:128
	s_waitcnt vmcnt(8)
	s_waitcnt lgkmcnt(0)
	s_barrier
	s_setprio 1
	s_waitcnt lgkmcnt(0)
	v_mfma_f32_16x16x32_bf16 v[52:55], v[154:157], v[188:191], v[52:55]
	v_mfma_f32_16x16x32_bf16 v[48:51], v[162:165], v[188:191], v[48:51]
	v_mfma_f32_16x16x32_bf16 v[36:39], v[154:157], v[196:199], v[36:39]
	v_mfma_f32_16x16x32_bf16 v[32:35], v[162:165], v[196:199], v[32:35]
	v_mfma_f32_16x16x32_bf16 v[20:23], v[154:157], v[204:207], v[20:23]
	v_mfma_f32_16x16x32_bf16 v[16:19], v[162:165], v[204:207], v[16:19]
	v_mfma_f32_16x16x32_bf16 v[4:7], v[154:157], v[212:215], v[4:7]
	v_mfma_f32_16x16x32_bf16 v[0:3], v[162:165], v[212:215], v[0:3]
	v_mfma_f32_16x16x32_bf16 v[52:55], v[158:161], v[192:195], v[52:55]
	v_mfma_f32_16x16x32_bf16 v[48:51], v[166:169], v[192:195], v[48:51]
	v_mfma_f32_16x16x32_bf16 v[36:39], v[158:161], v[200:203], v[36:39]
	v_mfma_f32_16x16x32_bf16 v[32:35], v[166:169], v[200:203], v[32:35]
	v_mfma_f32_16x16x32_bf16 v[20:23], v[158:161], v[208:211], v[20:23]
	v_mfma_f32_16x16x32_bf16 v[16:19], v[166:169], v[208:211], v[16:19]
	v_mfma_f32_16x16x32_bf16 v[4:7], v[158:161], v[216:219], v[4:7]
	v_mfma_f32_16x16x32_bf16 v[0:3], v[166:169], v[216:219], v[0:3]
	s_setprio 0
	s_setprio 1
	v_mfma_f32_16x16x32_bf16 v[60:63], v[170:173], v[188:191], v[60:63]
	v_mfma_f32_16x16x32_bf16 v[56:59], v[180:183], v[188:191], v[56:59]
	v_mfma_f32_16x16x32_bf16 v[44:47], v[170:173], v[196:199], v[44:47]
	v_mfma_f32_16x16x32_bf16 v[40:43], v[180:183], v[196:199], v[40:43]
	v_mfma_f32_16x16x32_bf16 v[28:31], v[170:173], v[204:207], v[28:31]
	v_mfma_f32_16x16x32_bf16 v[24:27], v[180:183], v[204:207], v[24:27]
	v_mfma_f32_16x16x32_bf16 v[12:15], v[170:173], v[212:215], v[12:15]
	v_mfma_f32_16x16x32_bf16 v[8:11], v[180:183], v[212:215], v[8:11]
	v_mfma_f32_16x16x32_bf16 v[60:63], v[174:177], v[192:195], v[60:63]
	v_mfma_f32_16x16x32_bf16 v[56:59], v[184:187], v[192:195], v[56:59]
	v_mfma_f32_16x16x32_bf16 v[44:47], v[174:177], v[200:203], v[44:47]
	v_mfma_f32_16x16x32_bf16 v[40:43], v[184:187], v[200:203], v[40:43]
	v_mfma_f32_16x16x32_bf16 v[28:31], v[174:177], v[208:211], v[28:31]
	v_mfma_f32_16x16x32_bf16 v[24:27], v[184:187], v[208:211], v[24:27]
	v_mfma_f32_16x16x32_bf16 v[12:15], v[174:177], v[216:219], v[12:15]
	v_mfma_f32_16x16x32_bf16 v[8:11], v[184:187], v[216:219], v[8:11]
	s_setprio 0
	s_barrier
	s_add_u32 s24, s24, 0x100
	s_addc_u32 s25, s25, 0
	s_add_u32 s62, s62, 0x100
	s_addc_u32 s63, s63, 0
	s_cmp_ge_i32 s64, s36
	s_mov_b32 s26, s64
	s_cbranch_scc0 .LBB0_373
	s_branch .Lpeel_x0
; #define PG8_STAGE(bufoff, gbase, voff) do { _Pragma("unroll") for (int _i = 0; _i < 2; ++_i) \
;         __builtin_amdgcn_global_load_lds((const unsigned*)((const char*)(gbase) + (voff)[_i]), (PG8_LAS unsigned*)(lds + (bufoff) + ldsw + _i * 8192), 16, 0, 0); } while (0)
; #define PG8_LDA(dst, b, h) do { _Pragma("unroll") for (int m = 0; m < 4; ++m) _Pragma("unroll") for (int k = 0; k < 2; ++k) dst[m][k] = *(const PG8_LAS bf16x8*)(lds + PG8_SA(b, h) + aoff + m * 2048 + k * 1024); } while (0)
; #define PG8_LDB(dst, b, h) do { _Pragma("unroll") for (int n = 0; n < 2; ++n) _Pragma("unroll") for (int k = 0; k < 2; ++k) dst[n][k] = *(const PG8_LAS bf16x8*)(lds + PG8_SB(b, h) + boff + n * 2048 + k * 1024); } while (0)
; #define PG8_MMA(ai, bj, At, Bt) do { __builtin_amdgcn_s_setprio(1); _Pragma("unroll") for (int m = 0; m < 4; ++m) _Pragma("unroll") for (int n = 0; n < 2; ++n) _Pragma("unroll") for (int k = 0; k < 2; ++k) \
;         acc[ai][bj][m][n] = __builtin_amdgcn_mfma_f32_16x16x32_bf16(Bt[n][k], At[m][k], acc[ai][bj][m][n], 0, 0, 0); __builtin_amdgcn_s_setprio(0); } while (0)
; #define PG8_WAIT_V(n) asm volatile("s_waitcnt vmcnt(" #n ")" ::: "memory")
; #define PG8_WAIT_L(n) asm volatile("s_waitcnt lgkmcnt(" #n ")" ::: "memory")
; #define PG8_BAR __builtin_amdgcn_s_barrier()
; #define PG8_SCHED __builtin_amdgcn_sched_barrier(0)
; template <class Epi, class Sched, bool ALIGN_EPI = false, bool SP2 = false>
; __device__ __forceinline__ void gemm_phase(PG8_LAS unsigned char* lds, const Gemm g, const Sched& S, const Epi& E) {
;     ...
;             PG8_LDB(B0, 0, 0); PG8_LDB(B1, 0, 1); PG8_SCHED; PG8_LDA(At, 0, 0); PG8_STAGE(PG8_SA(1, 1), a1 + hstep, voffA);
;             PG8_WAIT_V(8); PG8_WAIT_L(0); PG8_BAR; PG8_MMA(0, 0, At, B0); PG8_MMA(0, 1, At, B1); PG8_BAR; PG8_SCHED;
;             PG8_LDA(At, 0, 1); PG8_STAGE(PG8_SB(0, 0), b2, voffB); PG8_STAGE(PG8_SB(0, 1), b2 + hstep, voffB); PG8_STAGE(PG8_SA(0, 0), a2, voffA);
;             PG8_WAIT_V(8); PG8_WAIT_L(0); PG8_BAR; PG8_MMA(1, 0, At, B0); PG8_MMA(1, 1, At, B1); PG8_BAR; PG8_SCHED;
.LBB0_373:
	ds_read_b128 v[154:157], v149
	ds_read_b128 v[158:161], v149 offset:1024
	ds_read_b128 v[162:165], v149 offset:2048
	ds_read_b128 v[166:169], v149 offset:3072
	ds_read_b128 v[170:173], v150
	ds_read_b128 v[174:177], v150 offset:1024
	ds_read_b128 v[180:183], v150 offset:2048
	ds_read_b128 v[184:187], v150 offset:3072
	s_add_i32 s64, s26, 2
	s_add_u32 s65, s24, 0x80
	s_addc_u32 s27, s25, 0
	s_cmp_eq_u32 s37, s26
	s_cselect_b32 s26, s0, s65
	s_cselect_b32 s27, s1, s27
	s_cselect_b32 s67, s23, s63
	s_cselect_b32 s66, s22, s62
	s_add_i32 m0, s28, 0xc000
	ds_read_b128 v[188:191], v151
	ds_read_b128 v[192:195], v151 offset:1024
	ds_read_b128 v[196:199], v151 offset:2048
	ds_read_b128 v[200:203], v151 offset:3072
	ds_read_b128 v[204:207], v151 offset:4096
	ds_read_b128 v[208:211], v151 offset:5120
	ds_read_b128 v[212:215], v151 offset:6144
	ds_read_b128 v[216:219], v151 offset:7168
	global_load_lds_dwordx4 v136, s[24:25]
	s_add_i32 m0, s28, 0xe000
	s_nop 0
	global_load_lds_dwordx4 v138, s[24:25]
	s_waitcnt vmcnt(8)
	s_waitcnt lgkmcnt(0)
	s_barrier
	s_setprio 1
	s_waitcnt lgkmcnt(0)
	v_mfma_f32_16x16x32_bf16 v[116:119], v[154:157], v[188:191], v[116:119]
	v_mfma_f32_16x16x32_bf16 v[112:115], v[162:165], v[188:191], v[112:115]
	v_mfma_f32_16x16x32_bf16 v[100:103], v[154:157], v[196:199], v[100:103]
	v_mfma_f32_16x16x32_bf16 v[96:99], v[162:165], v[196:199], v[96:99]
	v_mfma_f32_16x16x32_bf16 v[84:87], v[154:157], v[204:207], v[84:87]
	v_mfma_f32_16x16x32_bf16 v[80:83], v[162:165], v[204:207], v[80:83]
	v_mfma_f32_16x16x32_bf16 v[68:71], v[154:157], v[212:215], v[68:71]
	v_mfma_f32_16x16x32_bf16 v[64:67], v[162:165], v[212:215], v[64:67]
	v_mfma_f32_16x16x32_bf16 v[116:119], v[158:161], v[192:195], v[116:119]
	v_mfma_f32_16x16x32_bf16 v[112:115], v[166:169], v[192:195], v[112:115]
	v_mfma_f32_16x16x32_bf16 v[100:103], v[158:161], v[200:203], v[100:103]
	v_mfma_f32_16x16x32_bf16 v[96:99], v[166:169], v[200:203], v[96:99]
	v_mfma_f32_16x16x32_bf16 v[84:87], v[158:161], v[208:211], v[84:87]
	v_mfma_f32_16x16x32_bf16 v[80:83], v[166:169], v[208:211], v[80:83]
	v_mfma_f32_16x16x32_bf16 v[68:71], v[158:161], v[216:219], v[68:71]
	v_mfma_f32_16x16x32_bf16 v[64:67], v[166:169], v[216:219], v[64:67]
	s_setprio 0
	s_setprio 1
	v_mfma_f32_16x16x32_bf16 v[124:127], v[170:173], v[188:191], v[124:127]
	v_mfma_f32_16x16x32_bf16 v[120:123], v[180:183], v[188:191], v[120:123]
	v_mfma_f32_16x16x32_bf16 v[108:111], v[170:173], v[196:199], v[108:111]
	v_mfma_f32_16x16x32_bf16 v[104:107], v[180:183], v[196:199], v[104:107]
	v_mfma_f32_16x16x32_bf16 v[92:95], v[170:173], v[204:207], v[92:95]
	v_mfma_f32_16x16x32_bf16 v[88:91], v[180:183], v[204:207], v[88:91]
	v_mfma_f32_16x16x32_bf16 v[76:79], v[170:173], v[212:215], v[76:79]
	v_mfma_f32_16x16x32_bf16 v[72:75], v[180:183], v[212:215], v[72:75]
	v_mfma_f32_16x16x32_bf16 v[124:127], v[174:177], v[192:195], v[124:127]
	v_mfma_f32_16x16x32_bf16 v[120:123], v[184:187], v[192:195], v[120:123]
	v_mfma_f32_16x16x32_bf16 v[108:111], v[174:177], v[200:203], v[108:111]
	v_mfma_f32_16x16x32_bf16 v[104:107], v[184:187], v[200:203], v[104:107]
	v_mfma_f32_16x16x32_bf16 v[92:95], v[174:177], v[208:211], v[92:95]
	v_mfma_f32_16x16x32_bf16 v[88:91], v[184:187], v[208:211], v[88:91]
	v_mfma_f32_16x16x32_bf16 v[76:79], v[174:177], v[216:219], v[76:79]
	v_mfma_f32_16x16x32_bf16 v[72:75], v[184:187], v[216:219], v[72:75]
	s_setprio 0
	s_barrier
	s_add_i32 s65, s40, s16
	s_mov_b64 s[98:99], s[66:67]
	s_mov_b32 m0, s65
	ds_read_b128 v[188:191], v151 offset:16384
	ds_read_b128 v[192:195], v151 offset:17408
	ds_read_b128 v[196:199], v151 offset:18432
	ds_read_b128 v[200:203], v151 offset:19456
	ds_read_b128 v[204:207], v151 offset:20480
	ds_read_b128 v[208:211], v151 offset:21504
	ds_read_b128 v[212:215], v151 offset:22528
	ds_read_b128 v[216:219], v151 offset:23552
	global_load_lds_dwordx4 v132, s[66:67]
	s_add_i32 m0, s65, 0x2000
	s_add_u32 s66, s66, s6
	s_addc_u32 s67, s67, s7
	s_add_i32 s65, s41, s16
	global_load_lds_dwordx4 v128, s[98:99]
	s_mov_b64 s[100:101], s[66:67]
	s_mov_b32 m0, s65
	s_nop 0
	global_load_lds_dwordx4 v132, s[66:67]
	s_add_i32 m0, s65, 0x2000
	s_mov_b64 s[12:13], s[26:27]
	global_load_lds_dwordx4 v128, s[66:67]
	s_mov_b32 m0, s28
	s_nop 0
	global_load_lds_dwordx4 v134, s[26:27]
	s_mov_b32 m0, s29
	s_nop 0
	global_load_lds_dwordx4 v130, s[26:27]
	s_waitcnt vmcnt(8)
	s_waitcnt lgkmcnt(0)
	s_barrier
	s_setprio 1
	s_waitcnt lgkmcnt(0)
	v_mfma_f32_16x16x32_bf16 v[52:55], v[154:157], v[188:191], v[52:55]
	v_mfma_f32_16x16x32_bf16 v[48:51], v[162:165], v[188:191], v[48:51]
	v_mfma_f32_16x16x32_bf16 v[36:39], v[154:157], v[196:199], v[36:39]
	v_mfma_f32_16x16x32_bf16 v[32:35], v[162:165], v[196:199], v[32:35]
	v_mfma_f32_16x16x32_bf16 v[20:23], v[154:157], v[204:207], v[20:23]
	v_mfma_f32_16x16x32_bf16 v[16:19], v[162:165], v[204:207], v[16:19]
	v_mfma_f32_16x16x32_bf16 v[4:7], v[154:157], v[212:215], v[4:7]
	v_mfma_f32_16x16x32_bf16 v[0:3], v[162:165], v[212:215], v[0:3]
	v_mfma_f32_16x16x32_bf16 v[52:55], v[158:161], v[192:195], v[52:55]
	v_mfma_f32_16x16x32_bf16 v[48:51], v[166:169], v[192:195], v[48:51]
	v_mfma_f32_16x16x32_bf16 v[36:39], v[158:161], v[200:203], v[36:39]
	v_mfma_f32_16x16x32_bf16 v[32:35], v[166:169], v[200:203], v[32:35]
	v_mfma_f32_16x16x32_bf16 v[20:23], v[158:161], v[208:211], v[20:23]
	v_mfma_f32_16x16x32_bf16 v[16:19], v[166:169], v[208:211], v[16:19]
	v_mfma_f32_16x16x32_bf16 v[4:7], v[158:161], v[216:219], v[4:7]
	v_mfma_f32_16x16x32_bf16 v[0:3], v[166:169], v[216:219], v[0:3]
	s_setprio 0
	s_setprio 1
	v_mfma_f32_16x16x32_bf16 v[60:63], v[170:173], v[188:191], v[60:63]
	v_mfma_f32_16x16x32_bf16 v[56:59], v[180:183], v[188:191], v[56:59]
	v_mfma_f32_16x16x32_bf16 v[44:47], v[170:173], v[196:199], v[44:47]
	v_mfma_f32_16x16x32_bf16 v[40:43], v[180:183], v[196:199], v[40:43]
	v_mfma_f32_16x16x32_bf16 v[28:31], v[170:173], v[204:207], v[28:31]
	v_mfma_f32_16x16x32_bf16 v[24:27], v[180:183], v[204:207], v[24:27]
	v_mfma_f32_16x16x32_bf16 v[12:15], v[170:173], v[212:215], v[12:15]
	v_mfma_f32_16x16x32_bf16 v[8:11], v[180:183], v[212:215], v[8:11]
	v_mfma_f32_16x16x32_bf16 v[60:63], v[174:177], v[192:195], v[60:63]
	v_mfma_f32_16x16x32_bf16 v[56:59], v[184:187], v[192:195], v[56:59]
	v_mfma_f32_16x16x32_bf16 v[44:47], v[174:177], v[200:203], v[44:47]
	v_mfma_f32_16x16x32_bf16 v[40:43], v[184:187], v[200:203], v[40:43]
	v_mfma_f32_16x16x32_bf16 v[28:31], v[174:177], v[208:211], v[28:31]
	v_mfma_f32_16x16x32_bf16 v[24:27], v[184:187], v[208:211], v[24:27]
	v_mfma_f32_16x16x32_bf16 v[12:15], v[174:177], v[216:219], v[12:15]
	v_mfma_f32_16x16x32_bf16 v[8:11], v[184:187], v[216:219], v[8:11]
	s_setprio 0
	s_barrier
; #define PG8_STAGE(bufoff, gbase, voff) do { _Pragma("unroll") for (int _i = 0; _i < 2; ++_i) \
;         __builtin_amdgcn_global_load_lds((const unsigned*)((const char*)(gbase) + (voff)[_i]), (PG8_LAS unsigned*)(lds + (bufoff) + ldsw + _i * 8192), 16, 0, 0); } while (0)
; #define PG8_LDA(dst, b, h) do { _Pragma("unroll") for (int m = 0; m < 4; ++m) _Pragma("unroll") for (int k = 0; k < 2; ++k) dst[m][k] = *(const PG8_LAS bf16x8*)(lds + PG8_SA(b, h) + aoff + m * 2048 + k * 1024); } while (0)
; #define PG8_LDB(dst, b, h) do { _Pragma("unroll") for (int n = 0; n < 2; ++n) _Pragma("unroll") for (int k = 0; k < 2; ++k) dst[n][k] = *(const PG8_LAS bf16x8*)(lds + PG8_SB(b, h) + boff + n * 2048 + k * 1024); } while (0)
; #define PG8_MMA(ai, bj, At, Bt) do { __builtin_amdgcn_s_setprio(1); _Pragma("unroll") for (int m = 0; m < 4; ++m) _Pragma("unroll") for (int n = 0; n < 2; ++n) _Pragma("unroll") for (int k = 0; k < 2; ++k) \
;         acc[ai][bj][m][n] = __builtin_amdgcn_mfma_f32_16x16x32_bf16(Bt[n][k], At[m][k], acc[ai][bj][m][n], 0, 0, 0); __builtin_amdgcn_s_setprio(0); } while (0)
; #define PG8_WAIT_V(n) asm volatile("s_waitcnt vmcnt(" #n ")" ::: "memory")
; #define PG8_WAIT_L(n) asm volatile("s_waitcnt lgkmcnt(" #n ")" ::: "memory")
; #define PG8_BAR __builtin_amdgcn_s_barrier()
; #define PG8_SCHED __builtin_amdgcn_sched_barrier(0)
; template <class Epi, class Sched, bool ALIGN_EPI = false, bool SP2 = false>
; __device__ __forceinline__ void gemm_phase(PG8_LAS unsigned char* lds, const Gemm g, const Sched& S, const Epi& E) {
;     ...
;             PG8_LDB(B0, 1, 0); PG8_LDB(B1, 1, 1); PG8_SCHED; PG8_LDA(At, 1, 0); PG8_STAGE(PG8_SA(0, 1), a2 + hstep, voffA);
;             PG8_WAIT_V(8); PG8_WAIT_L(0); PG8_BAR; PG8_MMA(0, 0, At, B0); PG8_MMA(0, 1, At, B1); PG8_BAR; PG8_SCHED;
;             PG8_LDA(At, 1, 1); PG8_STAGE(PG8_SB(1, 0), b3, voffB); PG8_STAGE(PG8_SB(1, 1), b3 + hstep, voffB); PG8_STAGE(PG8_SA(1, 0), a3, voffA);
;             PG8_WAIT_V(8); PG8_WAIT_L(0); PG8_BAR; PG8_MMA(1, 0, At, B0); PG8_MMA(1, 1, At, B1); PG8_BAR; PG8_SCHED;
	s_add_i32 s65, 0, 0x18000
	v_add_u32_e32 v153, s65, v147
	s_add_i32 s66, 0, 0x1c000
	ds_read_b128 v[154:157], v153
	ds_read_b128 v[158:161], v153 offset:1024
	ds_read_b128 v[162:165], v153 offset:2048
	ds_read_b128 v[166:169], v153 offset:3072
	v_add_u32_e32 v153, s66, v147
	ds_read_b128 v[170:173], v153
	ds_read_b128 v[174:177], v153 offset:1024
	ds_read_b128 v[180:183], v153 offset:2048
	ds_read_b128 v[184:187], v153 offset:3072
	s_add_u32 s26, s26, s6
	s_addc_u32 s27, s27, s7
	s_mov_b32 m0, s30
	ds_read_b128 v[188:191], v151 offset:32768
	ds_read_b128 v[192:195], v151 offset:33792
	ds_read_b128 v[196:199], v151 offset:34816
	ds_read_b128 v[200:203], v151 offset:35840
	ds_read_b128 v[204:207], v151 offset:36864
	ds_read_b128 v[208:211], v151 offset:37888
	ds_read_b128 v[212:215], v151 offset:38912
	ds_read_b128 v[216:219], v151 offset:39936
	global_load_lds_dwordx4 v134, s[26:27]
	s_mov_b32 m0, s31
	s_nop 0
	global_load_lds_dwordx4 v130, s[26:27]
	s_waitcnt vmcnt(8)
	s_waitcnt lgkmcnt(0)
	s_barrier
	s_setprio 1
	s_waitcnt lgkmcnt(0)
	v_mfma_f32_16x16x32_bf16 v[116:119], v[154:157], v[188:191], v[116:119]
	v_mfma_f32_16x16x32_bf16 v[112:115], v[162:165], v[188:191], v[112:115]
	v_mfma_f32_16x16x32_bf16 v[100:103], v[154:157], v[196:199], v[100:103]
	v_mfma_f32_16x16x32_bf16 v[96:99], v[162:165], v[196:199], v[96:99]
	v_mfma_f32_16x16x32_bf16 v[84:87], v[154:157], v[204:207], v[84:87]
	v_mfma_f32_16x16x32_bf16 v[80:83], v[162:165], v[204:207], v[80:83]
	v_mfma_f32_16x16x32_bf16 v[68:71], v[154:157], v[212:215], v[68:71]
	v_mfma_f32_16x16x32_bf16 v[64:67], v[162:165], v[212:215], v[64:67]
	v_mfma_f32_16x16x32_bf16 v[116:119], v[158:161], v[192:195], v[116:119]
	v_mfma_f32_16x16x32_bf16 v[112:115], v[166:169], v[192:195], v[112:115]
	v_mfma_f32_16x16x32_bf16 v[100:103], v[158:161], v[200:203], v[100:103]
	v_mfma_f32_16x16x32_bf16 v[96:99], v[166:169], v[200:203], v[96:99]
	v_mfma_f32_16x16x32_bf16 v[84:87], v[158:161], v[208:211], v[84:87]
	v_mfma_f32_16x16x32_bf16 v[80:83], v[166:169], v[208:211], v[80:83]
	v_mfma_f32_16x16x32_bf16 v[68:71], v[158:161], v[216:219], v[68:71]
	v_mfma_f32_16x16x32_bf16 v[64:67], v[166:169], v[216:219], v[64:67]
	s_setprio 0
	s_setprio 1
	v_mfma_f32_16x16x32_bf16 v[124:127], v[170:173], v[188:191], v[124:127]
	v_mfma_f32_16x16x32_bf16 v[120:123], v[180:183], v[188:191], v[120:123]
	v_mfma_f32_16x16x32_bf16 v[108:111], v[170:173], v[196:199], v[108:111]
	v_mfma_f32_16x16x32_bf16 v[104:107], v[180:183], v[196:199], v[104:107]
	v_mfma_f32_16x16x32_bf16 v[92:95], v[170:173], v[204:207], v[92:95]
	v_mfma_f32_16x16x32_bf16 v[88:91], v[180:183], v[204:207], v[88:91]
	v_mfma_f32_16x16x32_bf16 v[76:79], v[170:173], v[212:215], v[76:79]
	v_mfma_f32_16x16x32_bf16 v[72:75], v[180:183], v[212:215], v[72:75]
	v_mfma_f32_16x16x32_bf16 v[124:127], v[174:177], v[192:195], v[124:127]
	v_mfma_f32_16x16x32_bf16 v[120:123], v[184:187], v[192:195], v[120:123]
	v_mfma_f32_16x16x32_bf16 v[108:111], v[174:177], v[200:203], v[108:111]
	v_mfma_f32_16x16x32_bf16 v[104:107], v[184:187], v[200:203], v[104:107]
	v_mfma_f32_16x16x32_bf16 v[92:95], v[174:177], v[208:211], v[92:95]
	v_mfma_f32_16x16x32_bf16 v[88:91], v[184:187], v[208:211], v[88:91]
	v_mfma_f32_16x16x32_bf16 v[76:79], v[174:177], v[216:219], v[76:79]
	v_mfma_f32_16x16x32_bf16 v[72:75], v[184:187], v[216:219], v[72:75]
	s_setprio 0
	s_barrier
	s_add_i32 s26, s65, s16
	s_add_i32 m0, s26, 0xffffff80
	ds_read_b128 v[188:191], v151 offset:49152
	ds_read_b128 v[192:195], v151 offset:50176
	ds_read_b128 v[196:199], v151 offset:51200
	ds_read_b128 v[200:203], v151 offset:52224
	ds_read_b128 v[204:207], v151 offset:53248
	ds_read_b128 v[208:211], v151 offset:54272
	ds_read_b128 v[212:215], v151 offset:55296
	ds_read_b128 v[216:219], v151 offset:56320
	global_load_lds_dwordx4 v132, s[98:99] offset:128
	s_add_i32 m0, s26, 0x1f80
	s_add_i32 s26, s66, s16
	global_load_lds_dwordx4 v128, s[98:99] offset:128
	s_add_i32 m0, s26, 0xffffff80
	s_nop 0
	global_load_lds_dwordx4 v132, s[100:101] offset:128
	s_add_i32 m0, s26, 0x1f80
	s_nop 0
	global_load_lds_dwordx4 v128, s[100:101] offset:128
	s_add_i32 m0, s34, 0xffffff80
	s_nop 0
	global_load_lds_dwordx4 v134, s[12:13] offset:128
	s_add_i32 m0, s35, 0xffffff80
	s_nop 0
	global_load_lds_dwordx4 v130, s[12:13] offset:128
	s_waitcnt vmcnt(8)
	s_waitcnt lgkmcnt(0)
	s_barrier
	s_setprio 1
	s_waitcnt lgkmcnt(0)
	v_mfma_f32_16x16x32_bf16 v[52:55], v[154:157], v[188:191], v[52:55]
	v_mfma_f32_16x16x32_bf16 v[48:51], v[162:165], v[188:191], v[48:51]
	v_mfma_f32_16x16x32_bf16 v[36:39], v[154:157], v[196:199], v[36:39]
	v_mfma_f32_16x16x32_bf16 v[32:35], v[162:165], v[196:199], v[32:35]
	v_mfma_f32_16x16x32_bf16 v[20:23], v[154:157], v[204:207], v[20:23]
	v_mfma_f32_16x16x32_bf16 v[16:19], v[162:165], v[204:207], v[16:19]
	v_mfma_f32_16x16x32_bf16 v[4:7], v[154:157], v[212:215], v[4:7]
	v_mfma_f32_16x16x32_bf16 v[0:3], v[162:165], v[212:215], v[0:3]
	v_mfma_f32_16x16x32_bf16 v[52:55], v[158:161], v[192:195], v[52:55]
	v_mfma_f32_16x16x32_bf16 v[48:51], v[166:169], v[192:195], v[48:51]
	v_mfma_f32_16x16x32_bf16 v[36:39], v[158:161], v[200:203], v[36:39]
	v_mfma_f32_16x16x32_bf16 v[32:35], v[166:169], v[200:203], v[32:35]
	v_mfma_f32_16x16x32_bf16 v[20:23], v[158:161], v[208:211], v[20:23]
	v_mfma_f32_16x16x32_bf16 v[16:19], v[166:169], v[208:211], v[16:19]
	v_mfma_f32_16x16x32_bf16 v[4:7], v[158:161], v[216:219], v[4:7]
	v_mfma_f32_16x16x32_bf16 v[0:3], v[166:169], v[216:219], v[0:3]
	s_setprio 0
	s_setprio 1
	v_mfma_f32_16x16x32_bf16 v[60:63], v[170:173], v[188:191], v[60:63]
	v_mfma_f32_16x16x32_bf16 v[56:59], v[180:183], v[188:191], v[56:59]
	v_mfma_f32_16x16x32_bf16 v[44:47], v[170:173], v[196:199], v[44:47]
	v_mfma_f32_16x16x32_bf16 v[40:43], v[180:183], v[196:199], v[40:43]
	v_mfma_f32_16x16x32_bf16 v[28:31], v[170:173], v[204:207], v[28:31]
	v_mfma_f32_16x16x32_bf16 v[24:27], v[180:183], v[204:207], v[24:27]
	v_mfma_f32_16x16x32_bf16 v[12:15], v[170:173], v[212:215], v[12:15]
	v_mfma_f32_16x16x32_bf16 v[8:11], v[180:183], v[212:215], v[8:11]
	v_mfma_f32_16x16x32_bf16 v[60:63], v[174:177], v[192:195], v[60:63]
	v_mfma_f32_16x16x32_bf16 v[56:59], v[184:187], v[192:195], v[56:59]
	v_mfma_f32_16x16x32_bf16 v[44:47], v[174:177], v[200:203], v[44:47]
	v_mfma_f32_16x16x32_bf16 v[40:43], v[184:187], v[200:203], v[40:43]
	v_mfma_f32_16x16x32_bf16 v[28:31], v[174:177], v[208:211], v[28:31]
	v_mfma_f32_16x16x32_bf16 v[24:27], v[184:187], v[208:211], v[24:27]
	v_mfma_f32_16x16x32_bf16 v[12:15], v[174:177], v[216:219], v[12:15]
	v_mfma_f32_16x16x32_bf16 v[8:11], v[184:187], v[216:219], v[8:11]
	s_setprio 0
	s_barrier
	s_add_u32 s24, s24, 0x100
	s_addc_u32 s25, s25, 0
	s_add_u32 s62, s62, 0x100
	s_addc_u32 s63, s63, 0
	s_cmp_ge_i32 s64, s36
	s_mov_b32 s26, s64
	s_cbranch_scc0 .LBB0_373

; #define PG8_STAGE(bufoff, gbase, voff) do { _Pragma("unroll") for (int _i = 0; _i < 2; ++_i) \
;         __builtin_amdgcn_global_load_lds((const unsigned*)((const char*)(gbase) + (voff)[_i]), (PG8_LAS unsigned*)(lds + (bufoff) + ldsw + _i * 8192), 16, 0, 0); } while (0)
; #define PG8_LDA(dst, b, h) do { _Pragma("unroll") for (int m = 0; m < 4; ++m) _Pragma("unroll") for (int k = 0; k < 2; ++k) dst[m][k] = *(const PG8_LAS bf16x8*)(lds + PG8_SA(b, h) + aoff + m * 2048 + k * 1024); } while (0)
; #define PG8_LDB(dst, b, h) do { _Pragma("unroll") for (int n = 0; n < 2; ++n) _Pragma("unroll") for (int k = 0; k < 2; ++k) dst[n][k] = *(const PG8_LAS bf16x8*)(lds + PG8_SB(b, h) + boff + n * 2048 + k * 1024); } while (0)
; #define PG8_MMA(ai, bj, At, Bt) do { __builtin_amdgcn_s_setprio(1); _Pragma("unroll") for (int m = 0; m < 4; ++m) _Pragma("unroll") for (int n = 0; n < 2; ++n) _Pragma("unroll") for (int k = 0; k < 2; ++k) \
;         acc[ai][bj][m][n] = __builtin_amdgcn_mfma_f32_16x16x32_bf16(Bt[n][k], At[m][k], acc[ai][bj][m][n], 0, 0, 0); __builtin_amdgcn_s_setprio(0); } while (0)
; #define PG8_WAIT_V(n) asm volatile("s_waitcnt vmcnt(" #n ")" ::: "memory")
; #define PG8_BAR __builtin_amdgcn_s_barrier()
; template <class Epi, class Sched, bool ALIGN_EPI = false, bool SP2 = false>
; __device__ __forceinline__ void gemm_phase(PG8_LAS unsigned char* lds, const Gemm g, const Sched& S, const Epi& E) {
;     ...
;         for (int t = 0; t < nt; t += 2) {
;             const bool last = (t == nt - 2);
;             const char* a1 = cA + (size_t)(t + 1) * kstep;
;             const char* a2 = last ? nA : cA + (size_t)(t + 2) * kstep; const char* b2 = last ? nB : cB + (size_t)(t + 2) * kstep;
;             const char* a3 = a2 + kstep; const char* b3 = b2 + kstep;
;             if (last && has_next) S.a_ready(nxt);
;             if constexpr (SP2) {
;             PG8_LDB(B0, 0, 0); PG8_LDB(B1, 0, 1); PG8_SCHED; PG8_LDA(At, 0, 0); PG8_STAGE(PG8_SA(1, 1), a1 + hstep, voffA);
;             PG8_WAIT_V(8); PG8_WAIT_L(0); PG8_BAR; PG8_MMA(0, 0, At, B0); PG8_MMA(0, 1, At, B1); PG8_BAR; PG8_SCHED;
;             PG8_LDA(At, 0, 1); PG8_STAGE(PG8_SB(0, 0), b2, voffB); PG8_STAGE(PG8_SB(0, 1), b2 + hstep, voffB); PG8_STAGE(PG8_SA(0, 0), a2, voffA);
;             PG8_WAIT_V(8); PG8_WAIT_L(0); PG8_BAR; PG8_MMA(1, 0, At, B0); PG8_MMA(1, 1, At, B1); PG8_BAR; PG8_SCHED;
.LBB0_465:
	v_mov_b32_e32 v151, 0
	s_andn2_b64 vcc, exec, s[24:25]
	v_mov_b32_e32 v150, 0
	v_mov_b32_e32 v155, 0
	v_mov_b32_e32 v154, 0
	v_mov_b32_e32 v153, 0
	v_mov_b32_e32 v152, 0
	v_mov_b32_e32 v149, 0
	v_mov_b32_e32 v148, 0
	v_mov_b32_e32 v145, 0
	v_mov_b32_e32 v144, 0
	v_mov_b32_e32 v147, 0
	v_mov_b32_e32 v146, 0
	s_waitcnt lgkmcnt(0)
	s_cbranch_vccnz .LBB0_469
	s_add_u32 s30, s30, 0x80
	s_addc_u32 s31, s31, 0
	s_add_u32 s65, s34, 0x100
	s_addc_u32 s66, s35, 0
	s_mov_b32 s34, 0
	ds_read_b128 v[144:147], v159
	ds_read_b128 v[148:151], v159 offset:1024
	ds_read_b128 v[152:155], v159 offset:2048
	ds_read_b128 v[164:167], v159 offset:3072
	ds_read_b128 v[168:171], v160
	ds_read_b128 v[172:175], v160 offset:1024
	ds_read_b128 v[180:183], v160 offset:2048
	ds_read_b128 v[184:187], v160 offset:3072
	s_add_i32 s67, s34, 2
	s_add_u32 s68, s30, 0x80
	s_addc_u32 s35, s31, 0
	s_cmp_eq_u32 s41, s34
	s_cselect_b32 s34, s0, s68
	s_cselect_b32 s35, s1, s35
	s_cselect_b32 s69, s29, s66
	s_cselect_b32 s68, s28, s65
	s_add_i32 m0, s17, 0xc000
	ds_read_b128 v[188:191], v161
	ds_read_b128 v[192:195], v161 offset:1024
	ds_read_b128 v[196:199], v161 offset:2048
	ds_read_b128 v[200:203], v161 offset:3072
	ds_read_b128 v[204:207], v161 offset:4096
	ds_read_b128 v[208:211], v161 offset:5120
	ds_read_b128 v[212:215], v161 offset:6144
	ds_read_b128 v[216:219], v161 offset:7168
	global_load_lds_dwordx4 v136, s[30:31]
	s_add_i32 m0, s17, 0xe000
	s_nop 0
	global_load_lds_dwordx4 v138, s[30:31]
	s_waitcnt vmcnt(8)
	s_waitcnt lgkmcnt(0)
	s_barrier
	s_setprio 1
	s_waitcnt lgkmcnt(0)
	v_mfma_f32_16x16x32_bf16 v[124:127], v[144:147], v[188:191], 0
	v_mfma_f32_16x16x32_bf16 v[120:123], v[152:155], v[188:191], 0
	v_mfma_f32_16x16x32_bf16 v[116:119], v[144:147], v[196:199], 0
	v_mfma_f32_16x16x32_bf16 v[112:115], v[152:155], v[196:199], 0
	v_mfma_f32_16x16x32_bf16 v[104:107], v[144:147], v[204:207], 0
	v_mfma_f32_16x16x32_bf16 v[96:99], v[152:155], v[204:207], 0
	v_mfma_f32_16x16x32_bf16 v[88:91], v[144:147], v[212:215], 0
	v_mfma_f32_16x16x32_bf16 v[80:83], v[152:155], v[212:215], 0
	v_mfma_f32_16x16x32_bf16 v[124:127], v[148:151], v[192:195], v[124:127]
	v_mfma_f32_16x16x32_bf16 v[120:123], v[164:167], v[192:195], v[120:123]
	v_mfma_f32_16x16x32_bf16 v[116:119], v[148:151], v[200:203], v[116:119]
	v_mfma_f32_16x16x32_bf16 v[112:115], v[164:167], v[200:203], v[112:115]
	v_mfma_f32_16x16x32_bf16 v[104:107], v[148:151], v[208:211], v[104:107]
	v_mfma_f32_16x16x32_bf16 v[96:99], v[164:167], v[208:211], v[96:99]
	v_mfma_f32_16x16x32_bf16 v[88:91], v[148:151], v[216:219], v[88:91]
	v_mfma_f32_16x16x32_bf16 v[80:83], v[164:167], v[216:219], v[80:83]
	s_setprio 0
	s_setprio 1
	v_mfma_f32_16x16x32_bf16 v[108:111], v[168:171], v[188:191], 0
	v_mfma_f32_16x16x32_bf16 v[100:103], v[180:183], v[188:191], 0
	v_mfma_f32_16x16x32_bf16 v[92:95], v[168:171], v[196:199], 0
	v_mfma_f32_16x16x32_bf16 v[84:87], v[180:183], v[196:199], 0
	v_mfma_f32_16x16x32_bf16 v[76:79], v[168:171], v[204:207], 0
	v_mfma_f32_16x16x32_bf16 v[72:75], v[180:183], v[204:207], 0
	v_mfma_f32_16x16x32_bf16 v[68:71], v[168:171], v[212:215], 0
	v_mfma_f32_16x16x32_bf16 v[64:67], v[180:183], v[212:215], 0
	v_mfma_f32_16x16x32_bf16 v[108:111], v[172:175], v[192:195], v[108:111]
	v_mfma_f32_16x16x32_bf16 v[100:103], v[184:187], v[192:195], v[100:103]
	v_mfma_f32_16x16x32_bf16 v[92:95], v[172:175], v[200:203], v[92:95]
	v_mfma_f32_16x16x32_bf16 v[84:87], v[184:187], v[200:203], v[84:87]
	v_mfma_f32_16x16x32_bf16 v[76:79], v[172:175], v[208:211], v[76:79]
	v_mfma_f32_16x16x32_bf16 v[72:75], v[184:187], v[208:211], v[72:75]
	v_mfma_f32_16x16x32_bf16 v[68:71], v[172:175], v[216:219], v[68:71]
	v_mfma_f32_16x16x32_bf16 v[64:67], v[184:187], v[216:219], v[64:67]
	s_setprio 0
	s_barrier
	s_add_i32 s70, s59, s16
	s_mov_b64 s[98:99], s[68:69]
	s_mov_b32 m0, s70
	ds_read_b128 v[188:191], v161 offset:16384
	ds_read_b128 v[192:195], v161 offset:17408
	ds_read_b128 v[196:199], v161 offset:18432
	ds_read_b128 v[200:203], v161 offset:19456
	ds_read_b128 v[204:207], v161 offset:20480
	ds_read_b128 v[208:211], v161 offset:21504
	ds_read_b128 v[212:215], v161 offset:22528
	ds_read_b128 v[216:219], v161 offset:23552
	global_load_lds_dwordx4 v130, s[68:69]
	s_add_i32 m0, s70, 0x2000
	s_add_u32 s68, s68, s6
	s_addc_u32 s69, s69, s7
	s_add_i32 s70, s60, s16
	global_load_lds_dwordx4 v134, s[98:99]
	s_mov_b64 s[100:101], s[68:69]
	s_mov_b32 m0, s70
	s_nop 0
	global_load_lds_dwordx4 v130, s[68:69]
	s_add_i32 m0, s70, 0x2000
	s_mov_b64 s[22:23], s[34:35]
	global_load_lds_dwordx4 v134, s[68:69]
	s_mov_b32 m0, s17
	s_nop 0
	global_load_lds_dwordx4 v128, s[34:35]
	s_mov_b32 m0, s19
	s_nop 0
	global_load_lds_dwordx4 v132, s[34:35]
	s_waitcnt vmcnt(8)
	s_waitcnt lgkmcnt(0)
	s_barrier
; #define PG8_STAGE(bufoff, gbase, voff) do { _Pragma("unroll") for (int _i = 0; _i < 2; ++_i) \
;         __builtin_amdgcn_global_load_lds((const unsigned*)((const char*)(gbase) + (voff)[_i]), (PG8_LAS unsigned*)(lds + (bufoff) + ldsw + _i * 8192), 16, 0, 0); } while (0)
; #define PG8_LDA(dst, b, h) do { _Pragma("unroll") for (int m = 0; m < 4; ++m) _Pragma("unroll") for (int k = 0; k < 2; ++k) dst[m][k] = *(const PG8_LAS bf16x8*)(lds + PG8_SA(b, h) + aoff + m * 2048 + k * 1024); } while (0)
; #define PG8_LDB(dst, b, h) do { _Pragma("unroll") for (int n = 0; n < 2; ++n) _Pragma("unroll") for (int k = 0; k < 2; ++k) dst[n][k] = *(const PG8_LAS bf16x8*)(lds + PG8_SB(b, h) + boff + n * 2048 + k * 1024); } while (0)
; #define PG8_MMA(ai, bj, At, Bt) do { __builtin_amdgcn_s_setprio(1); _Pragma("unroll") for (int m = 0; m < 4; ++m) _Pragma("unroll") for (int n = 0; n < 2; ++n) _Pragma("unroll") for (int k = 0; k < 2; ++k) \
;         acc[ai][bj][m][n] = __builtin_amdgcn_mfma_f32_16x16x32_bf16(Bt[n][k], At[m][k], acc[ai][bj][m][n], 0, 0, 0); __builtin_amdgcn_s_setprio(0); } while (0)
; #define PG8_WAIT_V(n) asm volatile("s_waitcnt vmcnt(" #n ")" ::: "memory")
; #define PG8_WAIT_L(n) asm volatile("s_waitcnt lgkmcnt(" #n ")" ::: "memory")
; #define PG8_BAR __builtin_amdgcn_s_barrier()
; #define PG8_SCHED __builtin_amdgcn_sched_barrier(0)
; template <class Epi, class Sched, bool ALIGN_EPI = false, bool SP2 = false>
; __device__ __forceinline__ void gemm_phase(PG8_LAS unsigned char* lds, const Gemm g, const Sched& S, const Epi& E) {
;     ...
;             PG8_WAIT_V(8); PG8_WAIT_L(0); PG8_BAR; PG8_MMA(0, 0, At, B0); PG8_MMA(0, 1, At, B1); PG8_BAR; PG8_SCHED;
;             PG8_LDA(At, 0, 1); PG8_STAGE(PG8_SB(0, 0), b2, voffB); PG8_STAGE(PG8_SB(0, 1), b2 + hstep, voffB); PG8_STAGE(PG8_SA(0, 0), a2, voffA);
;             PG8_WAIT_V(8); PG8_WAIT_L(0); PG8_BAR; PG8_MMA(1, 0, At, B0); PG8_MMA(1, 1, At, B1); PG8_BAR; PG8_SCHED;
;             PG8_LDB(B0, 1, 0); PG8_LDB(B1, 1, 1); PG8_SCHED; PG8_LDA(At, 1, 0); PG8_STAGE(PG8_SA(0, 1), a2 + hstep, voffA);
;             PG8_WAIT_V(8); PG8_WAIT_L(0); PG8_BAR; PG8_MMA(0, 0, At, B0); PG8_MMA(0, 1, At, B1); PG8_BAR; PG8_SCHED;
	s_setprio 1
	s_waitcnt lgkmcnt(0)
	v_mfma_f32_16x16x32_bf16 v[60:63], v[144:147], v[188:191], 0
	v_mfma_f32_16x16x32_bf16 v[56:59], v[152:155], v[188:191], 0
	v_mfma_f32_16x16x32_bf16 v[52:55], v[144:147], v[196:199], 0
	v_mfma_f32_16x16x32_bf16 v[48:51], v[152:155], v[196:199], 0
	v_mfma_f32_16x16x32_bf16 v[40:43], v[144:147], v[204:207], 0
	v_mfma_f32_16x16x32_bf16 v[32:35], v[152:155], v[204:207], 0
	v_mfma_f32_16x16x32_bf16 v[24:27], v[144:147], v[212:215], 0
	v_mfma_f32_16x16x32_bf16 v[16:19], v[152:155], v[212:215], 0
	v_mfma_f32_16x16x32_bf16 v[60:63], v[148:151], v[192:195], v[60:63]
	v_mfma_f32_16x16x32_bf16 v[56:59], v[164:167], v[192:195], v[56:59]
	v_mfma_f32_16x16x32_bf16 v[52:55], v[148:151], v[200:203], v[52:55]
	v_mfma_f32_16x16x32_bf16 v[48:51], v[164:167], v[200:203], v[48:51]
	v_mfma_f32_16x16x32_bf16 v[40:43], v[148:151], v[208:211], v[40:43]
	v_mfma_f32_16x16x32_bf16 v[32:35], v[164:167], v[208:211], v[32:35]
	v_mfma_f32_16x16x32_bf16 v[24:27], v[148:151], v[216:219], v[24:27]
	v_mfma_f32_16x16x32_bf16 v[16:19], v[164:167], v[216:219], v[16:19]
	s_setprio 0
	s_setprio 1
	v_mfma_f32_16x16x32_bf16 v[44:47], v[168:171], v[188:191], 0
	v_mfma_f32_16x16x32_bf16 v[36:39], v[180:183], v[188:191], 0
	v_mfma_f32_16x16x32_bf16 v[28:31], v[168:171], v[196:199], 0
	v_mfma_f32_16x16x32_bf16 v[20:23], v[180:183], v[196:199], 0
	v_mfma_f32_16x16x32_bf16 v[12:15], v[168:171], v[204:207], 0
	v_mfma_f32_16x16x32_bf16 v[8:11], v[180:183], v[204:207], 0
	v_mfma_f32_16x16x32_bf16 v[4:7], v[168:171], v[212:215], 0
	v_mfma_f32_16x16x32_bf16 v[0:3], v[180:183], v[212:215], 0
	v_mfma_f32_16x16x32_bf16 v[44:47], v[172:175], v[192:195], v[44:47]
	v_mfma_f32_16x16x32_bf16 v[36:39], v[184:187], v[192:195], v[36:39]
	v_mfma_f32_16x16x32_bf16 v[28:31], v[172:175], v[200:203], v[28:31]
	v_mfma_f32_16x16x32_bf16 v[20:23], v[184:187], v[200:203], v[20:23]
	v_mfma_f32_16x16x32_bf16 v[12:15], v[172:175], v[208:211], v[12:15]
	v_mfma_f32_16x16x32_bf16 v[8:11], v[184:187], v[208:211], v[8:11]
	v_mfma_f32_16x16x32_bf16 v[4:7], v[172:175], v[216:219], v[4:7]
	v_mfma_f32_16x16x32_bf16 v[0:3], v[184:187], v[216:219], v[0:3]
	s_setprio 0
	s_barrier
	s_add_i32 s68, 0, 0x18000
	v_add_u32_e32 v163, s68, v157
	s_add_i32 s69, 0, 0x1c000
	ds_read_b128 v[144:147], v163
	ds_read_b128 v[148:151], v163 offset:1024
	ds_read_b128 v[152:155], v163 offset:2048
	ds_read_b128 v[164:167], v163 offset:3072
	v_add_u32_e32 v163, s69, v157
	ds_read_b128 v[168:171], v163
	ds_read_b128 v[172:175], v163 offset:1024
	ds_read_b128 v[180:183], v163 offset:2048
	ds_read_b128 v[184:187], v163 offset:3072
	s_add_u32 s34, s34, s6
	s_addc_u32 s35, s35, s7
	s_mov_b32 m0, s33
	ds_read_b128 v[188:191], v161 offset:32768
	ds_read_b128 v[192:195], v161 offset:33792
	ds_read_b128 v[196:199], v161 offset:34816
	ds_read_b128 v[200:203], v161 offset:35840
	ds_read_b128 v[204:207], v161 offset:36864
	ds_read_b128 v[208:211], v161 offset:37888
	ds_read_b128 v[212:215], v161 offset:38912
	ds_read_b128 v[216:219], v161 offset:39936
	global_load_lds_dwordx4 v128, s[34:35]
	s_mov_b32 m0, s36
	s_nop 0
	global_load_lds_dwordx4 v132, s[34:35]
	s_waitcnt vmcnt(8)
	s_waitcnt lgkmcnt(0)
	s_barrier
	s_setprio 1
	s_waitcnt lgkmcnt(0)
	v_mfma_f32_16x16x32_bf16 v[124:127], v[144:147], v[188:191], v[124:127]
	v_mfma_f32_16x16x32_bf16 v[120:123], v[152:155], v[188:191], v[120:123]
	v_mfma_f32_16x16x32_bf16 v[116:119], v[144:147], v[196:199], v[116:119]
	v_mfma_f32_16x16x32_bf16 v[112:115], v[152:155], v[196:199], v[112:115]
	v_mfma_f32_16x16x32_bf16 v[104:107], v[144:147], v[204:207], v[104:107]
	v_mfma_f32_16x16x32_bf16 v[96:99], v[152:155], v[204:207], v[96:99]
	v_mfma_f32_16x16x32_bf16 v[88:91], v[144:147], v[212:215], v[88:91]
	v_mfma_f32_16x16x32_bf16 v[80:83], v[152:155], v[212:215], v[80:83]
	v_mfma_f32_16x16x32_bf16 v[124:127], v[148:151], v[192:195], v[124:127]
	v_mfma_f32_16x16x32_bf16 v[120:123], v[164:167], v[192:195], v[120:123]
	v_mfma_f32_16x16x32_bf16 v[116:119], v[148:151], v[200:203], v[116:119]
	v_mfma_f32_16x16x32_bf16 v[112:115], v[164:167], v[200:203], v[112:115]
	v_mfma_f32_16x16x32_bf16 v[104:107], v[148:151], v[208:211], v[104:107]
	v_mfma_f32_16x16x32_bf16 v[96:99], v[164:167], v[208:211], v[96:99]
	v_mfma_f32_16x16x32_bf16 v[88:91], v[148:151], v[216:219], v[88:91]
	v_mfma_f32_16x16x32_bf16 v[80:83], v[164:167], v[216:219], v[80:83]
	s_setprio 0
	s_setprio 1
	v_mfma_f32_16x16x32_bf16 v[108:111], v[168:171], v[188:191], v[108:111]
	v_mfma_f32_16x16x32_bf16 v[100:103], v[180:183], v[188:191], v[100:103]
	v_mfma_f32_16x16x32_bf16 v[92:95], v[168:171], v[196:199], v[92:95]
	v_mfma_f32_16x16x32_bf16 v[84:87], v[180:183], v[196:199], v[84:87]
	v_mfma_f32_16x16x32_bf16 v[76:79], v[168:171], v[204:207], v[76:79]
	v_mfma_f32_16x16x32_bf16 v[72:75], v[180:183], v[204:207], v[72:75]
	v_mfma_f32_16x16x32_bf16 v[68:71], v[168:171], v[212:215], v[68:71]
	v_mfma_f32_16x16x32_bf16 v[64:67], v[180:183], v[212:215], v[64:67]
	v_mfma_f32_16x16x32_bf16 v[108:111], v[172:175], v[192:195], v[108:111]
	v_mfma_f32_16x16x32_bf16 v[100:103], v[184:187], v[192:195], v[100:103]
	v_mfma_f32_16x16x32_bf16 v[92:95], v[172:175], v[200:203], v[92:95]
	v_mfma_f32_16x16x32_bf16 v[84:87], v[184:187], v[200:203], v[84:87]
	v_mfma_f32_16x16x32_bf16 v[76:79], v[172:175], v[208:211], v[76:79]
	v_mfma_f32_16x16x32_bf16 v[72:75], v[184:187], v[208:211], v[72:75]
	v_mfma_f32_16x16x32_bf16 v[68:71], v[172:175], v[216:219], v[68:71]
	v_mfma_f32_16x16x32_bf16 v[64:67], v[184:187], v[216:219], v[64:67]
	s_setprio 0
	s_barrier
; #define PG8_STAGE(bufoff, gbase, voff) do { _Pragma("unroll") for (int _i = 0; _i < 2; ++_i) \
;         __builtin_amdgcn_global_load_lds((const unsigned*)((const char*)(gbase) + (voff)[_i]), (PG8_LAS unsigned*)(lds + (bufoff) + ldsw + _i * 8192), 16, 0, 0); } while (0)
; #define PG8_LDA(dst, b, h) do { _Pragma("unroll") for (int m = 0; m < 4; ++m) _Pragma("unroll") for (int k = 0; k < 2; ++k) dst[m][k] = *(const PG8_LAS bf16x8*)(lds + PG8_SA(b, h) + aoff + m * 2048 + k * 1024); } while (0)
; #define PG8_LDB(dst, b, h) do { _Pragma("unroll") for (int n = 0; n < 2; ++n) _Pragma("unroll") for (int k = 0; k < 2; ++k) dst[n][k] = *(const PG8_LAS bf16x8*)(lds + PG8_SB(b, h) + boff + n * 2048 + k * 1024); } while (0)
; #define PG8_MMA(ai, bj, At, Bt) do { __builtin_amdgcn_s_setprio(1); _Pragma("unroll") for (int m = 0; m < 4; ++m) _Pragma("unroll") for (int n = 0; n < 2; ++n) _Pragma("unroll") for (int k = 0; k < 2; ++k) \
;         acc[ai][bj][m][n] = __builtin_amdgcn_mfma_f32_16x16x32_bf16(Bt[n][k], At[m][k], acc[ai][bj][m][n], 0, 0, 0); __builtin_amdgcn_s_setprio(0); } while (0)
; #define PG8_WAIT_V(n) asm volatile("s_waitcnt vmcnt(" #n ")" ::: "memory")
; #define PG8_WAIT_L(n) asm volatile("s_waitcnt lgkmcnt(" #n ")" ::: "memory")
; #define PG8_BAR __builtin_amdgcn_s_barrier()
; #define PG8_SCHED __builtin_amdgcn_sched_barrier(0)
; template <class Epi, class Sched, bool ALIGN_EPI = false, bool SP2 = false>
; __device__ __forceinline__ void gemm_phase(PG8_LAS unsigned char* lds, const Gemm g, const Sched& S, const Epi& E) {
;     ...
;             PG8_LDB(B0, 0, 0); PG8_LDB(B1, 0, 1); PG8_SCHED; PG8_LDA(At, 0, 0); PG8_STAGE(PG8_SA(1, 1), a1 + hstep, voffA);
;             PG8_WAIT_V(8); PG8_WAIT_L(0); PG8_BAR; PG8_MMA(0, 0, At, B0); PG8_MMA(0, 1, At, B1); PG8_BAR; PG8_SCHED;
;     ...
;             PG8_LDA(At, 1, 1); PG8_STAGE(PG8_SB(1, 0), b3, voffB); PG8_STAGE(PG8_SB(1, 1), b3 + hstep, voffB); PG8_STAGE(PG8_SA(1, 0), a3, voffA);
;             PG8_WAIT_V(8); PG8_WAIT_L(0); PG8_BAR; PG8_MMA(1, 0, At, B0); PG8_MMA(1, 1, At, B1); PG8_BAR; PG8_SCHED;
	s_add_i32 s34, s68, s16
	s_add_i32 m0, s34, 0xffffff80
	ds_read_b128 v[188:191], v161 offset:49152
	ds_read_b128 v[192:195], v161 offset:50176
	ds_read_b128 v[196:199], v161 offset:51200
	ds_read_b128 v[200:203], v161 offset:52224
	ds_read_b128 v[204:207], v161 offset:53248
	ds_read_b128 v[208:211], v161 offset:54272
	ds_read_b128 v[212:215], v161 offset:55296
	ds_read_b128 v[216:219], v161 offset:56320
	global_load_lds_dwordx4 v130, s[98:99] offset:128
	s_add_i32 m0, s34, 0x1f80
	s_add_i32 s34, s69, s16
	global_load_lds_dwordx4 v134, s[98:99] offset:128
	s_add_i32 m0, s34, 0xffffff80
	s_nop 0
	global_load_lds_dwordx4 v130, s[100:101] offset:128
	s_add_i32 m0, s34, 0x1f80
	s_nop 0
	global_load_lds_dwordx4 v134, s[100:101] offset:128
	s_add_i32 m0, s37, 0xffffff80
	s_nop 0
	global_load_lds_dwordx4 v128, s[22:23] offset:128
	s_add_i32 m0, s38, 0xffffff80
	s_nop 0
	global_load_lds_dwordx4 v132, s[22:23] offset:128
	s_waitcnt vmcnt(8)
	s_waitcnt lgkmcnt(0)
	s_barrier
	s_setprio 1
	s_waitcnt lgkmcnt(0)
	v_mfma_f32_16x16x32_bf16 v[60:63], v[144:147], v[188:191], v[60:63]
	v_mfma_f32_16x16x32_bf16 v[56:59], v[152:155], v[188:191], v[56:59]
	v_mfma_f32_16x16x32_bf16 v[52:55], v[144:147], v[196:199], v[52:55]
	v_mfma_f32_16x16x32_bf16 v[48:51], v[152:155], v[196:199], v[48:51]
	v_mfma_f32_16x16x32_bf16 v[40:43], v[144:147], v[204:207], v[40:43]
	v_mfma_f32_16x16x32_bf16 v[32:35], v[152:155], v[204:207], v[32:35]
	v_mfma_f32_16x16x32_bf16 v[24:27], v[144:147], v[212:215], v[24:27]
	v_mfma_f32_16x16x32_bf16 v[16:19], v[152:155], v[212:215], v[16:19]
	v_mfma_f32_16x16x32_bf16 v[60:63], v[148:151], v[192:195], v[60:63]
	v_mfma_f32_16x16x32_bf16 v[56:59], v[164:167], v[192:195], v[56:59]
	v_mfma_f32_16x16x32_bf16 v[52:55], v[148:151], v[200:203], v[52:55]
	v_mfma_f32_16x16x32_bf16 v[48:51], v[164:167], v[200:203], v[48:51]
	v_mfma_f32_16x16x32_bf16 v[40:43], v[148:151], v[208:211], v[40:43]
	v_mfma_f32_16x16x32_bf16 v[32:35], v[164:167], v[208:211], v[32:35]
	v_mfma_f32_16x16x32_bf16 v[24:27], v[148:151], v[216:219], v[24:27]
	v_mfma_f32_16x16x32_bf16 v[16:19], v[164:167], v[216:219], v[16:19]
	s_setprio 0
	s_setprio 1
	v_mfma_f32_16x16x32_bf16 v[44:47], v[168:171], v[188:191], v[44:47]
	v_mfma_f32_16x16x32_bf16 v[36:39], v[180:183], v[188:191], v[36:39]
	v_mfma_f32_16x16x32_bf16 v[28:31], v[168:171], v[196:199], v[28:31]
	v_mfma_f32_16x16x32_bf16 v[20:23], v[180:183], v[196:199], v[20:23]
	v_mfma_f32_16x16x32_bf16 v[12:15], v[168:171], v[204:207], v[12:15]
	v_mfma_f32_16x16x32_bf16 v[8:11], v[180:183], v[204:207], v[8:11]
	v_mfma_f32_16x16x32_bf16 v[4:7], v[168:171], v[212:215], v[4:7]
	v_mfma_f32_16x16x32_bf16 v[0:3], v[180:183], v[212:215], v[0:3]
	v_mfma_f32_16x16x32_bf16 v[44:47], v[172:175], v[192:195], v[44:47]
	v_mfma_f32_16x16x32_bf16 v[36:39], v[184:187], v[192:195], v[36:39]
	v_mfma_f32_16x16x32_bf16 v[28:31], v[172:175], v[200:203], v[28:31]
	v_mfma_f32_16x16x32_bf16 v[20:23], v[184:187], v[200:203], v[20:23]
	v_mfma_f32_16x16x32_bf16 v[12:15], v[172:175], v[208:211], v[12:15]
	v_mfma_f32_16x16x32_bf16 v[8:11], v[184:187], v[208:211], v[8:11]
	v_mfma_f32_16x16x32_bf16 v[4:7], v[172:175], v[216:219], v[4:7]
	v_mfma_f32_16x16x32_bf16 v[0:3], v[184:187], v[216:219], v[0:3]
	s_setprio 0
	s_barrier
	s_add_u32 s30, s30, 0x100
	s_addc_u32 s31, s31, 0
	s_add_u32 s65, s65, 0x100
	s_addc_u32 s66, s66, 0
	s_cmp_ge_i32 s67, s40
	s_mov_b32 s34, s67
	s_cbranch_scc0 .LBB0_467
	s_branch .Lpeel_x1
.LBB0_467:
	ds_read_b128 v[144:147], v159
	ds_read_b128 v[148:151], v159 offset:1024
	ds_read_b128 v[152:155], v159 offset:2048
	ds_read_b128 v[164:167], v159 offset:3072
	ds_read_b128 v[168:171], v160
	ds_read_b128 v[172:175], v160 offset:1024
	ds_read_b128 v[180:183], v160 offset:2048
	ds_read_b128 v[184:187], v160 offset:3072
	s_add_i32 s67, s34, 2
	s_add_u32 s68, s30, 0x80
	s_addc_u32 s35, s31, 0
	s_cmp_eq_u32 s41, s34
	s_cselect_b32 s34, s0, s68
	s_cselect_b32 s35, s1, s35
	s_cselect_b32 s69, s29, s66
	s_cselect_b32 s68, s28, s65
	s_add_i32 m0, s17, 0xc000
	ds_read_b128 v[188:191], v161
	ds_read_b128 v[192:195], v161 offset:1024
	ds_read_b128 v[196:199], v161 offset:2048
	ds_read_b128 v[200:203], v161 offset:3072
	ds_read_b128 v[204:207], v161 offset:4096
	ds_read_b128 v[208:211], v161 offset:5120
	ds_read_b128 v[212:215], v161 offset:6144
	ds_read_b128 v[216:219], v161 offset:7168
	global_load_lds_dwordx4 v136, s[30:31]
	s_add_i32 m0, s17, 0xe000
	s_nop 0
	global_load_lds_dwordx4 v138, s[30:31]
	s_waitcnt vmcnt(8)
	s_waitcnt lgkmcnt(0)
	s_barrier
; #define PG8_STAGE(bufoff, gbase, voff) do { _Pragma("unroll") for (int _i = 0; _i < 2; ++_i) \
;         __builtin_amdgcn_global_load_lds((const unsigned*)((const char*)(gbase) + (voff)[_i]), (PG8_LAS unsigned*)(lds + (bufoff) + ldsw + _i * 8192), 16, 0, 0); } while (0)
; #define PG8_LDA(dst, b, h) do { _Pragma("unroll") for (int m = 0; m < 4; ++m) _Pragma("unroll") for (int k = 0; k < 2; ++k) dst[m][k] = *(const PG8_LAS bf16x8*)(lds + PG8_SA(b, h) + aoff + m * 2048 + k * 1024); } while (0)
; #define PG8_LDB(dst, b, h) do { _Pragma("unroll") for (int n = 0; n < 2; ++n) _Pragma("unroll") for (int k = 0; k < 2; ++k) dst[n][k] = *(const PG8_LAS bf16x8*)(lds + PG8_SB(b, h) + boff + n * 2048 + k * 1024); } while (0)
; #define PG8_MMA(ai, bj, At, Bt) do { __builtin_amdgcn_s_setprio(1); _Pragma("unroll") for (int m = 0; m < 4; ++m) _Pragma("unroll") for (int n = 0; n < 2; ++n) _Pragma("unroll") for (int k = 0; k < 2; ++k) \
;         acc[ai][bj][m][n] = __builtin_amdgcn_mfma_f32_16x16x32_bf16(Bt[n][k], At[m][k], acc[ai][bj][m][n], 0, 0, 0); __builtin_amdgcn_s_setprio(0); } while (0)
; #define PG8_WAIT_V(n) asm volatile("s_waitcnt vmcnt(" #n ")" ::: "memory")
; #define PG8_WAIT_L(n) asm volatile("s_waitcnt lgkmcnt(" #n ")" ::: "memory")
; #define PG8_BAR __builtin_amdgcn_s_barrier()
; #define PG8_SCHED __builtin_amdgcn_sched_barrier(0)
; template <class Epi, class Sched, bool ALIGN_EPI = false, bool SP2 = false>
; __device__ __forceinline__ void gemm_phase(PG8_LAS unsigned char* lds, const Gemm g, const Sched& S, const Epi& E) {
;     ...
;             PG8_LDB(B0, 0, 0); PG8_LDB(B1, 0, 1); PG8_SCHED; PG8_LDA(At, 0, 0); PG8_STAGE(PG8_SA(1, 1), a1 + hstep, voffA);
;             PG8_WAIT_V(8); PG8_WAIT_L(0); PG8_BAR; PG8_MMA(0, 0, At, B0); PG8_MMA(0, 1, At, B1); PG8_BAR; PG8_SCHED;
;             PG8_LDA(At, 0, 1); PG8_STAGE(PG8_SB(0, 0), b2, voffB); PG8_STAGE(PG8_SB(0, 1), b2 + hstep, voffB); PG8_STAGE(PG8_SA(0, 0), a2, voffA);
;             PG8_WAIT_V(8); PG8_WAIT_L(0); PG8_BAR; PG8_MMA(1, 0, At, B0); PG8_MMA(1, 1, At, B1); PG8_BAR; PG8_SCHED;
	s_setprio 1
	s_waitcnt lgkmcnt(0)
	v_mfma_f32_16x16x32_bf16 v[124:127], v[144:147], v[188:191], v[124:127]
	v_mfma_f32_16x16x32_bf16 v[120:123], v[152:155], v[188:191], v[120:123]
	v_mfma_f32_16x16x32_bf16 v[116:119], v[144:147], v[196:199], v[116:119]
	v_mfma_f32_16x16x32_bf16 v[112:115], v[152:155], v[196:199], v[112:115]
	v_mfma_f32_16x16x32_bf16 v[104:107], v[144:147], v[204:207], v[104:107]
	v_mfma_f32_16x16x32_bf16 v[96:99], v[152:155], v[204:207], v[96:99]
	v_mfma_f32_16x16x32_bf16 v[88:91], v[144:147], v[212:215], v[88:91]
	v_mfma_f32_16x16x32_bf16 v[80:83], v[152:155], v[212:215], v[80:83]
	v_mfma_f32_16x16x32_bf16 v[124:127], v[148:151], v[192:195], v[124:127]
	v_mfma_f32_16x16x32_bf16 v[120:123], v[164:167], v[192:195], v[120:123]
	v_mfma_f32_16x16x32_bf16 v[116:119], v[148:151], v[200:203], v[116:119]
	v_mfma_f32_16x16x32_bf16 v[112:115], v[164:167], v[200:203], v[112:115]
	v_mfma_f32_16x16x32_bf16 v[104:107], v[148:151], v[208:211], v[104:107]
	v_mfma_f32_16x16x32_bf16 v[96:99], v[164:167], v[208:211], v[96:99]
	v_mfma_f32_16x16x32_bf16 v[88:91], v[148:151], v[216:219], v[88:91]
	v_mfma_f32_16x16x32_bf16 v[80:83], v[164:167], v[216:219], v[80:83]
	s_setprio 0
	s_setprio 1
	v_mfma_f32_16x16x32_bf16 v[108:111], v[168:171], v[188:191], v[108:111]
	v_mfma_f32_16x16x32_bf16 v[100:103], v[180:183], v[188:191], v[100:103]
	v_mfma_f32_16x16x32_bf16 v[92:95], v[168:171], v[196:199], v[92:95]
	v_mfma_f32_16x16x32_bf16 v[84:87], v[180:183], v[196:199], v[84:87]
	v_mfma_f32_16x16x32_bf16 v[76:79], v[168:171], v[204:207], v[76:79]
	v_mfma_f32_16x16x32_bf16 v[72:75], v[180:183], v[204:207], v[72:75]
	v_mfma_f32_16x16x32_bf16 v[68:71], v[168:171], v[212:215], v[68:71]
	v_mfma_f32_16x16x32_bf16 v[64:67], v[180:183], v[212:215], v[64:67]
	v_mfma_f32_16x16x32_bf16 v[108:111], v[172:175], v[192:195], v[108:111]
	v_mfma_f32_16x16x32_bf16 v[100:103], v[184:187], v[192:195], v[100:103]
	v_mfma_f32_16x16x32_bf16 v[92:95], v[172:175], v[200:203], v[92:95]
	v_mfma_f32_16x16x32_bf16 v[84:87], v[184:187], v[200:203], v[84:87]
	v_mfma_f32_16x16x32_bf16 v[76:79], v[172:175], v[208:211], v[76:79]
	v_mfma_f32_16x16x32_bf16 v[72:75], v[184:187], v[208:211], v[72:75]
	v_mfma_f32_16x16x32_bf16 v[68:71], v[172:175], v[216:219], v[68:71]
	v_mfma_f32_16x16x32_bf16 v[64:67], v[184:187], v[216:219], v[64:67]
	s_setprio 0
	s_barrier
	s_add_i32 s70, s59, s16
	s_mov_b64 s[98:99], s[68:69]
	s_mov_b32 m0, s70
	ds_read_b128 v[188:191], v161 offset:16384
	ds_read_b128 v[192:195], v161 offset:17408
	ds_read_b128 v[196:199], v161 offset:18432
	ds_read_b128 v[200:203], v161 offset:19456
	ds_read_b128 v[204:207], v161 offset:20480
	ds_read_b128 v[208:211], v161 offset:21504
	ds_read_b128 v[212:215], v161 offset:22528
	ds_read_b128 v[216:219], v161 offset:23552
	global_load_lds_dwordx4 v130, s[68:69]
	s_add_i32 m0, s70, 0x2000
	s_add_u32 s68, s68, s6
	s_addc_u32 s69, s69, s7
	s_add_i32 s70, s60, s16
	global_load_lds_dwordx4 v134, s[98:99]
	s_mov_b64 s[100:101], s[68:69]
	s_mov_b32 m0, s70
	s_nop 0
	global_load_lds_dwordx4 v130, s[68:69]
	s_add_i32 m0, s70, 0x2000
	s_mov_b64 s[22:23], s[34:35]
	global_load_lds_dwordx4 v134, s[68:69]
	s_mov_b32 m0, s17
	s_nop 0
	global_load_lds_dwordx4 v128, s[34:35]
	s_mov_b32 m0, s19
	s_nop 0
	global_load_lds_dwordx4 v132, s[34:35]
	s_waitcnt vmcnt(8)
	s_waitcnt lgkmcnt(0)
	s_barrier
	s_setprio 1
	s_waitcnt lgkmcnt(0)
	v_mfma_f32_16x16x32_bf16 v[60:63], v[144:147], v[188:191], v[60:63]
	v_mfma_f32_16x16x32_bf16 v[56:59], v[152:155], v[188:191], v[56:59]
	v_mfma_f32_16x16x32_bf16 v[52:55], v[144:147], v[196:199], v[52:55]
	v_mfma_f32_16x16x32_bf16 v[48:51], v[152:155], v[196:199], v[48:51]
	v_mfma_f32_16x16x32_bf16 v[40:43], v[144:147], v[204:207], v[40:43]
	v_mfma_f32_16x16x32_bf16 v[32:35], v[152:155], v[204:207], v[32:35]
	v_mfma_f32_16x16x32_bf16 v[24:27], v[144:147], v[212:215], v[24:27]
	v_mfma_f32_16x16x32_bf16 v[16:19], v[152:155], v[212:215], v[16:19]
	v_mfma_f32_16x16x32_bf16 v[60:63], v[148:151], v[192:195], v[60:63]
	v_mfma_f32_16x16x32_bf16 v[56:59], v[164:167], v[192:195], v[56:59]
	v_mfma_f32_16x16x32_bf16 v[52:55], v[148:151], v[200:203], v[52:55]
	v_mfma_f32_16x16x32_bf16 v[48:51], v[164:167], v[200:203], v[48:51]
	v_mfma_f32_16x16x32_bf16 v[40:43], v[148:151], v[208:211], v[40:43]
	v_mfma_f32_16x16x32_bf16 v[32:35], v[164:167], v[208:211], v[32:35]
	v_mfma_f32_16x16x32_bf16 v[24:27], v[148:151], v[216:219], v[24:27]
	v_mfma_f32_16x16x32_bf16 v[16:19], v[164:167], v[216:219], v[16:19]
	s_setprio 0
	s_setprio 1
	v_mfma_f32_16x16x32_bf16 v[44:47], v[168:171], v[188:191], v[44:47]
	v_mfma_f32_16x16x32_bf16 v[36:39], v[180:183], v[188:191], v[36:39]
	v_mfma_f32_16x16x32_bf16 v[28:31], v[168:171], v[196:199], v[28:31]
	v_mfma_f32_16x16x32_bf16 v[20:23], v[180:183], v[196:199], v[20:23]
	v_mfma_f32_16x16x32_bf16 v[12:15], v[168:171], v[204:207], v[12:15]
	v_mfma_f32_16x16x32_bf16 v[8:11], v[180:183], v[204:207], v[8:11]
	v_mfma_f32_16x16x32_bf16 v[4:7], v[168:171], v[212:215], v[4:7]
	v_mfma_f32_16x16x32_bf16 v[0:3], v[180:183], v[212:215], v[0:3]
	v_mfma_f32_16x16x32_bf16 v[44:47], v[172:175], v[192:195], v[44:47]
	v_mfma_f32_16x16x32_bf16 v[36:39], v[184:187], v[192:195], v[36:39]
	v_mfma_f32_16x16x32_bf16 v[28:31], v[172:175], v[200:203], v[28:31]
	v_mfma_f32_16x16x32_bf16 v[20:23], v[184:187], v[200:203], v[20:23]
	v_mfma_f32_16x16x32_bf16 v[12:15], v[172:175], v[208:211], v[12:15]
	v_mfma_f32_16x16x32_bf16 v[8:11], v[184:187], v[208:211], v[8:11]
	v_mfma_f32_16x16x32_bf16 v[4:7], v[172:175], v[216:219], v[4:7]
	v_mfma_f32_16x16x32_bf16 v[0:3], v[184:187], v[216:219], v[0:3]
	s_setprio 0
	s_barrier
; #define PG8_STAGE(bufoff, gbase, voff) do { _Pragma("unroll") for (int _i = 0; _i < 2; ++_i) \
;         __builtin_amdgcn_global_load_lds((const unsigned*)((const char*)(gbase) + (voff)[_i]), (PG8_LAS unsigned*)(lds + (bufoff) + ldsw + _i * 8192), 16, 0, 0); } while (0)
; #define PG8_LDA(dst, b, h) do { _Pragma("unroll") for (int m = 0; m < 4; ++m) _Pragma("unroll") for (int k = 0; k < 2; ++k) dst[m][k] = *(const PG8_LAS bf16x8*)(lds + PG8_SA(b, h) + aoff + m * 2048 + k * 1024); } while (0)
; #define PG8_LDB(dst, b, h) do { _Pragma("unroll") for (int n = 0; n < 2; ++n) _Pragma("unroll") for (int k = 0; k < 2; ++k) dst[n][k] = *(const PG8_LAS bf16x8*)(lds + PG8_SB(b, h) + boff + n * 2048 + k * 1024); } while (0)
; #define PG8_MMA(ai, bj, At, Bt) do { __builtin_amdgcn_s_setprio(1); _Pragma("unroll") for (int m = 0; m < 4; ++m) _Pragma("unroll") for (int n = 0; n < 2; ++n) _Pragma("unroll") for (int k = 0; k < 2; ++k) \
;         acc[ai][bj][m][n] = __builtin_amdgcn_mfma_f32_16x16x32_bf16(Bt[n][k], At[m][k], acc[ai][bj][m][n], 0, 0, 0); __builtin_amdgcn_s_setprio(0); } while (0)
; #define PG8_WAIT_V(n) asm volatile("s_waitcnt vmcnt(" #n ")" ::: "memory")
; #define PG8_WAIT_L(n) asm volatile("s_waitcnt lgkmcnt(" #n ")" ::: "memory")
; #define PG8_BAR __builtin_amdgcn_s_barrier()
; #define PG8_SCHED __builtin_amdgcn_sched_barrier(0)
; template <class Epi, class Sched, bool ALIGN_EPI = false, bool SP2 = false>
; __device__ __forceinline__ void gemm_phase(PG8_LAS unsigned char* lds, const Gemm g, const Sched& S, const Epi& E) {
;     ...
;             PG8_LDB(B0, 1, 0); PG8_LDB(B1, 1, 1); PG8_SCHED; PG8_LDA(At, 1, 0); PG8_STAGE(PG8_SA(0, 1), a2 + hstep, voffA);
;             PG8_WAIT_V(8); PG8_WAIT_L(0); PG8_BAR; PG8_MMA(0, 0, At, B0); PG8_MMA(0, 1, At, B1); PG8_BAR; PG8_SCHED;
;             PG8_LDA(At, 1, 1); PG8_STAGE(PG8_SB(1, 0), b3, voffB); PG8_STAGE(PG8_SB(1, 1), b3 + hstep, voffB); PG8_STAGE(PG8_SA(1, 0), a3, voffA);
;             PG8_WAIT_V(8); PG8_WAIT_L(0); PG8_BAR; PG8_MMA(1, 0, At, B0); PG8_MMA(1, 1, At, B1); PG8_BAR; PG8_SCHED;
	s_add_i32 s68, 0, 0x18000
	v_add_u32_e32 v163, s68, v157
	s_add_i32 s69, 0, 0x1c000
	ds_read_b128 v[144:147], v163
	ds_read_b128 v[148:151], v163 offset:1024
	ds_read_b128 v[152:155], v163 offset:2048
	ds_read_b128 v[164:167], v163 offset:3072
	v_add_u32_e32 v163, s69, v157
	ds_read_b128 v[168:171], v163
	ds_read_b128 v[172:175], v163 offset:1024
	ds_read_b128 v[180:183], v163 offset:2048
	ds_read_b128 v[184:187], v163 offset:3072
	s_add_u32 s34, s34, s6
	s_addc_u32 s35, s35, s7
	s_mov_b32 m0, s33
	ds_read_b128 v[188:191], v161 offset:32768
	ds_read_b128 v[192:195], v161 offset:33792
	ds_read_b128 v[196:199], v161 offset:34816
	ds_read_b128 v[200:203], v161 offset:35840
	ds_read_b128 v[204:207], v161 offset:36864
	ds_read_b128 v[208:211], v161 offset:37888
	ds_read_b128 v[212:215], v161 offset:38912
	ds_read_b128 v[216:219], v161 offset:39936
	global_load_lds_dwordx4 v128, s[34:35]
	s_mov_b32 m0, s36
	s_nop 0
	global_load_lds_dwordx4 v132, s[34:35]
	s_waitcnt vmcnt(8)
	s_waitcnt lgkmcnt(0)
	s_barrier
	s_setprio 1
	s_waitcnt lgkmcnt(0)
	v_mfma_f32_16x16x32_bf16 v[124:127], v[144:147], v[188:191], v[124:127]
	v_mfma_f32_16x16x32_bf16 v[120:123], v[152:155], v[188:191], v[120:123]
	v_mfma_f32_16x16x32_bf16 v[116:119], v[144:147], v[196:199], v[116:119]
	v_mfma_f32_16x16x32_bf16 v[112:115], v[152:155], v[196:199], v[112:115]
	v_mfma_f32_16x16x32_bf16 v[104:107], v[144:147], v[204:207], v[104:107]
	v_mfma_f32_16x16x32_bf16 v[96:99], v[152:155], v[204:207], v[96:99]
	v_mfma_f32_16x16x32_bf16 v[88:91], v[144:147], v[212:215], v[88:91]
	v_mfma_f32_16x16x32_bf16 v[80:83], v[152:155], v[212:215], v[80:83]
	v_mfma_f32_16x16x32_bf16 v[124:127], v[148:151], v[192:195], v[124:127]
	v_mfma_f32_16x16x32_bf16 v[120:123], v[164:167], v[192:195], v[120:123]
	v_mfma_f32_16x16x32_bf16 v[116:119], v[148:151], v[200:203], v[116:119]
	v_mfma_f32_16x16x32_bf16 v[112:115], v[164:167], v[200:203], v[112:115]
	v_mfma_f32_16x16x32_bf16 v[104:107], v[148:151], v[208:211], v[104:107]
	v_mfma_f32_16x16x32_bf16 v[96:99], v[164:167], v[208:211], v[96:99]
	v_mfma_f32_16x16x32_bf16 v[88:91], v[148:151], v[216:219], v[88:91]
	v_mfma_f32_16x16x32_bf16 v[80:83], v[164:167], v[216:219], v[80:83]
	s_setprio 0
	s_setprio 1
	v_mfma_f32_16x16x32_bf16 v[108:111], v[168:171], v[188:191], v[108:111]
	v_mfma_f32_16x16x32_bf16 v[100:103], v[180:183], v[188:191], v[100:103]
	v_mfma_f32_16x16x32_bf16 v[92:95], v[168:171], v[196:199], v[92:95]
	v_mfma_f32_16x16x32_bf16 v[84:87], v[180:183], v[196:199], v[84:87]
	v_mfma_f32_16x16x32_bf16 v[76:79], v[168:171], v[204:207], v[76:79]
	v_mfma_f32_16x16x32_bf16 v[72:75], v[180:183], v[204:207], v[72:75]
	v_mfma_f32_16x16x32_bf16 v[68:71], v[168:171], v[212:215], v[68:71]
	v_mfma_f32_16x16x32_bf16 v[64:67], v[180:183], v[212:215], v[64:67]
	v_mfma_f32_16x16x32_bf16 v[108:111], v[172:175], v[192:195], v[108:111]
	v_mfma_f32_16x16x32_bf16 v[100:103], v[184:187], v[192:195], v[100:103]
	v_mfma_f32_16x16x32_bf16 v[92:95], v[172:175], v[200:203], v[92:95]
	v_mfma_f32_16x16x32_bf16 v[84:87], v[184:187], v[200:203], v[84:87]
	v_mfma_f32_16x16x32_bf16 v[76:79], v[172:175], v[208:211], v[76:79]
	v_mfma_f32_16x16x32_bf16 v[72:75], v[184:187], v[208:211], v[72:75]
	v_mfma_f32_16x16x32_bf16 v[68:71], v[172:175], v[216:219], v[68:71]
	v_mfma_f32_16x16x32_bf16 v[64:67], v[184:187], v[216:219], v[64:67]
	s_setprio 0
	s_barrier
	s_add_i32 s34, s68, s16
	s_add_i32 m0, s34, 0xffffff80
	ds_read_b128 v[188:191], v161 offset:49152
	ds_read_b128 v[192:195], v161 offset:50176
	ds_read_b128 v[196:199], v161 offset:51200
	ds_read_b128 v[200:203], v161 offset:52224
	ds_read_b128 v[204:207], v161 offset:53248
	ds_read_b128 v[208:211], v161 offset:54272
	ds_read_b128 v[212:215], v161 offset:55296
	ds_read_b128 v[216:219], v161 offset:56320
	global_load_lds_dwordx4 v130, s[98:99] offset:128
	s_add_i32 m0, s34, 0x1f80
	s_add_i32 s34, s69, s16
	global_load_lds_dwordx4 v134, s[98:99] offset:128
	s_add_i32 m0, s34, 0xffffff80
	s_nop 0
	global_load_lds_dwordx4 v130, s[100:101] offset:128
	s_add_i32 m0, s34, 0x1f80
	s_nop 0
	global_load_lds_dwordx4 v134, s[100:101] offset:128
	s_add_i32 m0, s37, 0xffffff80
	s_nop 0
	global_load_lds_dwordx4 v128, s[22:23] offset:128
	s_add_i32 m0, s38, 0xffffff80
	s_nop 0
	global_load_lds_dwordx4 v132, s[22:23] offset:128
	s_waitcnt vmcnt(8)
	s_waitcnt lgkmcnt(0)
	s_barrier
	s_setprio 1
	s_waitcnt lgkmcnt(0)
	v_mfma_f32_16x16x32_bf16 v[60:63], v[144:147], v[188:191], v[60:63]
	v_mfma_f32_16x16x32_bf16 v[56:59], v[152:155], v[188:191], v[56:59]
	v_mfma_f32_16x16x32_bf16 v[52:55], v[144:147], v[196:199], v[52:55]
	v_mfma_f32_16x16x32_bf16 v[48:51], v[152:155], v[196:199], v[48:51]
	v_mfma_f32_16x16x32_bf16 v[40:43], v[144:147], v[204:207], v[40:43]
	v_mfma_f32_16x16x32_bf16 v[32:35], v[152:155], v[204:207], v[32:35]
	v_mfma_f32_16x16x32_bf16 v[24:27], v[144:147], v[212:215], v[24:27]
	v_mfma_f32_16x16x32_bf16 v[16:19], v[152:155], v[212:215], v[16:19]
	v_mfma_f32_16x16x32_bf16 v[60:63], v[148:151], v[192:195], v[60:63]
	v_mfma_f32_16x16x32_bf16 v[56:59], v[164:167], v[192:195], v[56:59]
	v_mfma_f32_16x16x32_bf16 v[52:55], v[148:151], v[200:203], v[52:55]
	v_mfma_f32_16x16x32_bf16 v[48:51], v[164:167], v[200:203], v[48:51]
	v_mfma_f32_16x16x32_bf16 v[40:43], v[148:151], v[208:211], v[40:43]
	v_mfma_f32_16x16x32_bf16 v[32:35], v[164:167], v[208:211], v[32:35]
	v_mfma_f32_16x16x32_bf16 v[24:27], v[148:151], v[216:219], v[24:27]
	v_mfma_f32_16x16x32_bf16 v[16:19], v[164:167], v[216:219], v[16:19]
	s_setprio 0
	s_setprio 1
	v_mfma_f32_16x16x32_bf16 v[44:47], v[168:171], v[188:191], v[44:47]
	v_mfma_f32_16x16x32_bf16 v[36:39], v[180:183], v[188:191], v[36:39]
	v_mfma_f32_16x16x32_bf16 v[28:31], v[168:171], v[196:199], v[28:31]
	v_mfma_f32_16x16x32_bf16 v[20:23], v[180:183], v[196:199], v[20:23]
	v_mfma_f32_16x16x32_bf16 v[12:15], v[168:171], v[204:207], v[12:15]
	v_mfma_f32_16x16x32_bf16 v[8:11], v[180:183], v[204:207], v[8:11]
	v_mfma_f32_16x16x32_bf16 v[4:7], v[168:171], v[212:215], v[4:7]
	v_mfma_f32_16x16x32_bf16 v[0:3], v[180:183], v[212:215], v[0:3]
	v_mfma_f32_16x16x32_bf16 v[44:47], v[172:175], v[192:195], v[44:47]
	v_mfma_f32_16x16x32_bf16 v[36:39], v[184:187], v[192:195], v[36:39]
	v_mfma_f32_16x16x32_bf16 v[28:31], v[172:175], v[200:203], v[28:31]
	v_mfma_f32_16x16x32_bf16 v[20:23], v[184:187], v[200:203], v[20:23]
	v_mfma_f32_16x16x32_bf16 v[12:15], v[172:175], v[208:211], v[12:15]
	v_mfma_f32_16x16x32_bf16 v[8:11], v[184:187], v[208:211], v[8:11]
	v_mfma_f32_16x16x32_bf16 v[4:7], v[172:175], v[216:219], v[4:7]
	v_mfma_f32_16x16x32_bf16 v[0:3], v[184:187], v[216:219], v[0:3]
	s_setprio 0
	s_barrier
	s_add_u32 s30, s30, 0x100
	s_addc_u32 s31, s31, 0
	s_add_u32 s65, s65, 0x100
	s_addc_u32 s66, s66, 0
	s_cmp_ge_i32 s67, s40
	s_mov_b32 s34, s67
	s_cbranch_scc0 .LBB0_467

; #define PG8_STAGE(bufoff, gbase, voff) do { _Pragma("unroll") for (int _i = 0; _i < 2; ++_i) \
;         __builtin_amdgcn_global_load_lds((const unsigned*)((const char*)(gbase) + (voff)[_i]), (PG8_LAS unsigned*)(lds + (bufoff) + ldsw + _i * 8192), 16, 0, 0); } while (0)
; #define PG8_LDA(dst, b, h) do { _Pragma("unroll") for (int m = 0; m < 4; ++m) _Pragma("unroll") for (int k = 0; k < 2; ++k) dst[m][k] = *(const PG8_LAS bf16x8*)(lds + PG8_SA(b, h) + aoff + m * 2048 + k * 1024); } while (0)
; #define PG8_LDB(dst, b, h) do { _Pragma("unroll") for (int n = 0; n < 2; ++n) _Pragma("unroll") for (int k = 0; k < 2; ++k) dst[n][k] = *(const PG8_LAS bf16x8*)(lds + PG8_SB(b, h) + boff + n * 2048 + k * 1024); } while (0)
; #define PG8_MMA(ai, bj, At, Bt) do { __builtin_amdgcn_s_setprio(1); _Pragma("unroll") for (int m = 0; m < 4; ++m) _Pragma("unroll") for (int n = 0; n < 2; ++n) _Pragma("unroll") for (int k = 0; k < 2; ++k) \
;         acc[ai][bj][m][n] = __builtin_amdgcn_mfma_f32_16x16x32_bf16(Bt[n][k], At[m][k], acc[ai][bj][m][n], 0, 0, 0); __builtin_amdgcn_s_setprio(0); } while (0)
; #define PG8_WAIT_V(n) asm volatile("s_waitcnt vmcnt(" #n ")" ::: "memory")
; #define PG8_BAR __builtin_amdgcn_s_barrier()
; template <class Epi, class Sched, bool ALIGN_EPI = false, bool SP2 = false>
; __device__ __forceinline__ void gemm_phase(PG8_LAS unsigned char* lds, const Gemm g, const Sched& S, const Epi& E) {
;     ...
;         for (int t = 0; t < nt; t += 2) {
;             const bool last = (t == nt - 2);
;             const char* a1 = cA + (size_t)(t + 1) * kstep;
;             const char* a2 = last ? nA : cA + (size_t)(t + 2) * kstep; const char* b2 = last ? nB : cB + (size_t)(t + 2) * kstep;
;             const char* a3 = a2 + kstep; const char* b3 = b2 + kstep;
;             if (last && has_next) S.a_ready(nxt);
;             if constexpr (SP2) {
;             PG8_LDB(B0, 0, 0); PG8_LDB(B1, 0, 1); PG8_SCHED; PG8_LDA(At, 0, 0); PG8_STAGE(PG8_SA(1, 1), a1 + hstep, voffA);
;             PG8_WAIT_V(8); PG8_WAIT_L(0); PG8_BAR; PG8_MMA(0, 0, At, B0); PG8_MMA(0, 1, At, B1); PG8_BAR; PG8_SCHED;
;             PG8_LDA(At, 0, 1); PG8_STAGE(PG8_SB(0, 0), b2, voffB); PG8_STAGE(PG8_SB(0, 1), b2 + hstep, voffB); PG8_STAGE(PG8_SA(0, 0), a2, voffA);
;             PG8_WAIT_V(8); PG8_WAIT_L(0); PG8_BAR; PG8_MMA(1, 0, At, B0); PG8_MMA(1, 1, At, B1); PG8_BAR; PG8_SCHED;
.LBB0_595:
	s_andn2_b64 vcc, exec, s[78:79]
	s_cbranch_vccnz .LBB0_598
	s_add_u32 s4, s4, 0x80
	s_addc_u32 s5, s5, 0
	s_add_u32 s9, s6, 0x100
	s_addc_u32 s27, s7, 0
	s_mov_b32 s6, 0
	ds_read_b128 v[128:131], v177
	ds_read_b128 v[154:157], v177 offset:1024
	ds_read_b128 v[158:161], v177 offset:2048
	ds_read_b128 v[162:165], v177 offset:3072
	ds_read_b128 v[166:169], v179
	ds_read_b128 v[170:173], v179 offset:1024
	ds_read_b128 v[184:187], v179 offset:2048
	ds_read_b128 v[188:191], v179 offset:3072
	s_add_i32 s28, s6, 2
	s_add_u32 s29, s4, 0x80
	s_addc_u32 s7, s5, 0
	s_cmp_eq_u32 s86, s6
	s_cselect_b32 s6, s0, s29
	s_cselect_b32 s7, s1, s7
	s_cselect_b32 s39, s37, s27
	s_cselect_b32 s38, s36, s9
	s_add_i32 m0, s67, 0xc000
	ds_read_b128 v[192:195], v180
	ds_read_b128 v[196:199], v180 offset:1024
	ds_read_b128 v[200:203], v180 offset:2048
	ds_read_b128 v[204:207], v180 offset:3072
	ds_read_b128 v[208:211], v180 offset:4096
	ds_read_b128 v[212:215], v180 offset:5120
	ds_read_b128 v[216:219], v180 offset:6144
	ds_read_b128 v[220:223], v180 offset:7168
	global_load_lds_dwordx4 v146, s[4:5]
	s_add_i32 m0, s67, 0xe000
	s_nop 0
	global_load_lds_dwordx4 v148, s[4:5]
	s_waitcnt vmcnt(8)
	s_waitcnt lgkmcnt(0)
	s_barrier
	s_setprio 1
	s_waitcnt lgkmcnt(0)
	v_mfma_f32_16x16x32_bf16 v[120:123], v[128:131], v[192:195], 0
	v_mfma_f32_16x16x32_bf16 v[124:127], v[158:161], v[192:195], 0
	v_mfma_f32_16x16x32_bf16 v[108:111], v[128:131], v[200:203], 0
	v_mfma_f32_16x16x32_bf16 v[104:107], v[158:161], v[200:203], 0
	v_mfma_f32_16x16x32_bf16 v[92:95], v[128:131], v[208:211], 0
	v_mfma_f32_16x16x32_bf16 v[88:91], v[158:161], v[208:211], 0
	v_mfma_f32_16x16x32_bf16 v[76:79], v[128:131], v[216:219], 0
	v_mfma_f32_16x16x32_bf16 v[72:75], v[158:161], v[216:219], 0
	v_mfma_f32_16x16x32_bf16 v[120:123], v[154:157], v[196:199], v[120:123]
	v_mfma_f32_16x16x32_bf16 v[124:127], v[162:165], v[196:199], v[124:127]
	v_mfma_f32_16x16x32_bf16 v[108:111], v[154:157], v[204:207], v[108:111]
	v_mfma_f32_16x16x32_bf16 v[104:107], v[162:165], v[204:207], v[104:107]
	v_mfma_f32_16x16x32_bf16 v[92:95], v[154:157], v[212:215], v[92:95]
	v_mfma_f32_16x16x32_bf16 v[88:91], v[162:165], v[212:215], v[88:91]
	v_mfma_f32_16x16x32_bf16 v[76:79], v[154:157], v[220:223], v[76:79]
	v_mfma_f32_16x16x32_bf16 v[72:75], v[162:165], v[220:223], v[72:75]
	s_setprio 0
	s_setprio 1
	v_mfma_f32_16x16x32_bf16 v[116:119], v[166:169], v[192:195], 0
	v_mfma_f32_16x16x32_bf16 v[112:115], v[184:187], v[192:195], 0
	v_mfma_f32_16x16x32_bf16 v[100:103], v[166:169], v[200:203], 0
	v_mfma_f32_16x16x32_bf16 v[96:99], v[184:187], v[200:203], 0
	v_mfma_f32_16x16x32_bf16 v[84:87], v[166:169], v[208:211], 0
	v_mfma_f32_16x16x32_bf16 v[80:83], v[184:187], v[208:211], 0
	v_mfma_f32_16x16x32_bf16 v[68:71], v[166:169], v[216:219], 0
	v_mfma_f32_16x16x32_bf16 v[64:67], v[184:187], v[216:219], 0
	v_mfma_f32_16x16x32_bf16 v[116:119], v[170:173], v[196:199], v[116:119]
	v_mfma_f32_16x16x32_bf16 v[112:115], v[188:191], v[196:199], v[112:115]
	v_mfma_f32_16x16x32_bf16 v[100:103], v[170:173], v[204:207], v[100:103]
	v_mfma_f32_16x16x32_bf16 v[96:99], v[188:191], v[204:207], v[96:99]
	v_mfma_f32_16x16x32_bf16 v[84:87], v[170:173], v[212:215], v[84:87]
	v_mfma_f32_16x16x32_bf16 v[80:83], v[188:191], v[212:215], v[80:83]
	v_mfma_f32_16x16x32_bf16 v[68:71], v[170:173], v[220:223], v[68:71]
	v_mfma_f32_16x16x32_bf16 v[64:67], v[188:191], v[220:223], v[64:67]
	s_setprio 0
	s_barrier
	s_add_i32 s29, s11, s66
	s_mov_b64 s[98:99], s[38:39]
	s_mov_b32 m0, s29
	ds_read_b128 v[192:195], v180 offset:16384
	ds_read_b128 v[196:199], v180 offset:17408
	ds_read_b128 v[200:203], v180 offset:18432
	ds_read_b128 v[204:207], v180 offset:19456
	ds_read_b128 v[208:211], v180 offset:20480
	ds_read_b128 v[212:215], v180 offset:21504
	ds_read_b128 v[216:219], v180 offset:22528
	ds_read_b128 v[220:223], v180 offset:23552
	global_load_lds_dwordx4 v134, s[38:39]
	s_add_i32 m0, s29, 0x2000
	s_add_u32 s38, s38, s14
	s_addc_u32 s39, s39, s15
	s_add_i32 s29, s19, s66
	global_load_lds_dwordx4 v138, s[98:99]
	s_mov_b64 s[100:101], s[38:39]
	s_mov_b32 m0, s29
	s_nop 0
	global_load_lds_dwordx4 v134, s[38:39]
	s_add_i32 m0, s29, 0x2000
	s_mov_b64 s[24:25], s[6:7]
	global_load_lds_dwordx4 v138, s[38:39]
	s_mov_b32 m0, s67
	s_nop 0
	global_load_lds_dwordx4 v132, s[6:7]
	s_mov_b32 m0, s68
	s_nop 0
	global_load_lds_dwordx4 v136, s[6:7]
	s_waitcnt vmcnt(8)
	s_waitcnt lgkmcnt(0)
	s_barrier
	s_setprio 1
	s_waitcnt lgkmcnt(0)
	v_mfma_f32_16x16x32_bf16 v[60:63], v[128:131], v[192:195], 0
	v_mfma_f32_16x16x32_bf16 v[56:59], v[158:161], v[192:195], 0
	v_mfma_f32_16x16x32_bf16 v[44:47], v[128:131], v[200:203], 0
	v_mfma_f32_16x16x32_bf16 v[40:43], v[158:161], v[200:203], 0
	v_mfma_f32_16x16x32_bf16 v[28:31], v[128:131], v[208:211], 0
	v_mfma_f32_16x16x32_bf16 v[24:27], v[158:161], v[208:211], 0
	v_mfma_f32_16x16x32_bf16 v[12:15], v[128:131], v[216:219], 0
	v_mfma_f32_16x16x32_bf16 v[8:11], v[158:161], v[216:219], 0
	v_mfma_f32_16x16x32_bf16 v[60:63], v[154:157], v[196:199], v[60:63]
	v_mfma_f32_16x16x32_bf16 v[56:59], v[162:165], v[196:199], v[56:59]
	v_mfma_f32_16x16x32_bf16 v[44:47], v[154:157], v[204:207], v[44:47]
	v_mfma_f32_16x16x32_bf16 v[40:43], v[162:165], v[204:207], v[40:43]
	v_mfma_f32_16x16x32_bf16 v[28:31], v[154:157], v[212:215], v[28:31]
	v_mfma_f32_16x16x32_bf16 v[24:27], v[162:165], v[212:215], v[24:27]
	v_mfma_f32_16x16x32_bf16 v[12:15], v[154:157], v[220:223], v[12:15]
	v_mfma_f32_16x16x32_bf16 v[8:11], v[162:165], v[220:223], v[8:11]
	s_setprio 0
	s_setprio 1
	v_mfma_f32_16x16x32_bf16 v[52:55], v[166:169], v[192:195], 0
	v_mfma_f32_16x16x32_bf16 v[48:51], v[184:187], v[192:195], 0
	v_mfma_f32_16x16x32_bf16 v[36:39], v[166:169], v[200:203], 0
	v_mfma_f32_16x16x32_bf16 v[32:35], v[184:187], v[200:203], 0
	v_mfma_f32_16x16x32_bf16 v[20:23], v[166:169], v[208:211], 0
	v_mfma_f32_16x16x32_bf16 v[16:19], v[184:187], v[208:211], 0
	v_mfma_f32_16x16x32_bf16 v[4:7], v[166:169], v[216:219], 0
	v_mfma_f32_16x16x32_bf16 v[0:3], v[184:187], v[216:219], 0
	v_mfma_f32_16x16x32_bf16 v[52:55], v[170:173], v[196:199], v[52:55]
	v_mfma_f32_16x16x32_bf16 v[48:51], v[188:191], v[196:199], v[48:51]
	v_mfma_f32_16x16x32_bf16 v[36:39], v[170:173], v[204:207], v[36:39]
	v_mfma_f32_16x16x32_bf16 v[32:35], v[188:191], v[204:207], v[32:35]
	v_mfma_f32_16x16x32_bf16 v[20:23], v[170:173], v[212:215], v[20:23]
	v_mfma_f32_16x16x32_bf16 v[16:19], v[188:191], v[212:215], v[16:19]
	v_mfma_f32_16x16x32_bf16 v[4:7], v[170:173], v[220:223], v[4:7]
	v_mfma_f32_16x16x32_bf16 v[0:3], v[188:191], v[220:223], v[0:3]
	s_setprio 0
	s_barrier
; #define PG8_STAGE(bufoff, gbase, voff) do { _Pragma("unroll") for (int _i = 0; _i < 2; ++_i) \
;         __builtin_amdgcn_global_load_lds((const unsigned*)((const char*)(gbase) + (voff)[_i]), (PG8_LAS unsigned*)(lds + (bufoff) + ldsw + _i * 8192), 16, 0, 0); } while (0)
; #define PG8_LDA(dst, b, h) do { _Pragma("unroll") for (int m = 0; m < 4; ++m) _Pragma("unroll") for (int k = 0; k < 2; ++k) dst[m][k] = *(const PG8_LAS bf16x8*)(lds + PG8_SA(b, h) + aoff + m * 2048 + k * 1024); } while (0)
; #define PG8_LDB(dst, b, h) do { _Pragma("unroll") for (int n = 0; n < 2; ++n) _Pragma("unroll") for (int k = 0; k < 2; ++k) dst[n][k] = *(const PG8_LAS bf16x8*)(lds + PG8_SB(b, h) + boff + n * 2048 + k * 1024); } while (0)
; #define PG8_MMA(ai, bj, At, Bt) do { __builtin_amdgcn_s_setprio(1); _Pragma("unroll") for (int m = 0; m < 4; ++m) _Pragma("unroll") for (int n = 0; n < 2; ++n) _Pragma("unroll") for (int k = 0; k < 2; ++k) \
;         acc[ai][bj][m][n] = __builtin_amdgcn_mfma_f32_16x16x32_bf16(Bt[n][k], At[m][k], acc[ai][bj][m][n], 0, 0, 0); __builtin_amdgcn_s_setprio(0); } while (0)
; #define PG8_WAIT_V(n) asm volatile("s_waitcnt vmcnt(" #n ")" ::: "memory")
; #define PG8_WAIT_L(n) asm volatile("s_waitcnt lgkmcnt(" #n ")" ::: "memory")
; #define PG8_BAR __builtin_amdgcn_s_barrier()
; #define PG8_SCHED __builtin_amdgcn_sched_barrier(0)
; template <class Epi, class Sched, bool ALIGN_EPI = false, bool SP2 = false>
; __device__ __forceinline__ void gemm_phase(PG8_LAS unsigned char* lds, const Gemm g, const Sched& S, const Epi& E) {
;     ...
;             PG8_LDB(B0, 1, 0); PG8_LDB(B1, 1, 1); PG8_SCHED; PG8_LDA(At, 1, 0); PG8_STAGE(PG8_SA(0, 1), a2 + hstep, voffA);
;             PG8_WAIT_V(8); PG8_WAIT_L(0); PG8_BAR; PG8_MMA(0, 0, At, B0); PG8_MMA(0, 1, At, B1); PG8_BAR; PG8_SCHED;
;             PG8_LDA(At, 1, 1); PG8_STAGE(PG8_SB(1, 0), b3, voffB); PG8_STAGE(PG8_SB(1, 1), b3 + hstep, voffB); PG8_STAGE(PG8_SA(1, 0), a3, voffA);
;             PG8_WAIT_V(8); PG8_WAIT_L(0); PG8_BAR; PG8_MMA(1, 0, At, B0); PG8_MMA(1, 1, At, B1); PG8_BAR; PG8_SCHED;
	s_add_i32 s29, 0, 0x18000
	v_add_u32_e32 v140, s29, v175
	s_add_i32 s38, 0, 0x1c000
	ds_read_b128 v[128:131], v140
	ds_read_b128 v[154:157], v140 offset:1024
	ds_read_b128 v[158:161], v140 offset:2048
	ds_read_b128 v[162:165], v140 offset:3072
	v_add_u32_e32 v140, s38, v175
	ds_read_b128 v[166:169], v140
	ds_read_b128 v[170:173], v140 offset:1024
	ds_read_b128 v[184:187], v140 offset:2048
	ds_read_b128 v[188:191], v140 offset:3072
	s_add_u32 s6, s6, s14
	s_addc_u32 s7, s7, s15
	s_mov_b32 m0, s69
	ds_read_b128 v[192:195], v180 offset:32768
	ds_read_b128 v[196:199], v180 offset:33792
	ds_read_b128 v[200:203], v180 offset:34816
	ds_read_b128 v[204:207], v180 offset:35840
	ds_read_b128 v[208:211], v180 offset:36864
	ds_read_b128 v[212:215], v180 offset:37888
	ds_read_b128 v[216:219], v180 offset:38912
	ds_read_b128 v[220:223], v180 offset:39936
	global_load_lds_dwordx4 v132, s[6:7]
	s_mov_b32 m0, s70
	s_nop 0
	global_load_lds_dwordx4 v136, s[6:7]
	s_waitcnt vmcnt(8)
	s_waitcnt lgkmcnt(0)
	s_barrier
	s_setprio 1
	s_waitcnt lgkmcnt(0)
	v_mfma_f32_16x16x32_bf16 v[120:123], v[128:131], v[192:195], v[120:123]
	v_mfma_f32_16x16x32_bf16 v[124:127], v[158:161], v[192:195], v[124:127]
	v_mfma_f32_16x16x32_bf16 v[108:111], v[128:131], v[200:203], v[108:111]
	v_mfma_f32_16x16x32_bf16 v[104:107], v[158:161], v[200:203], v[104:107]
	v_mfma_f32_16x16x32_bf16 v[92:95], v[128:131], v[208:211], v[92:95]
	v_mfma_f32_16x16x32_bf16 v[88:91], v[158:161], v[208:211], v[88:91]
	v_mfma_f32_16x16x32_bf16 v[76:79], v[128:131], v[216:219], v[76:79]
	v_mfma_f32_16x16x32_bf16 v[72:75], v[158:161], v[216:219], v[72:75]
	v_mfma_f32_16x16x32_bf16 v[120:123], v[154:157], v[196:199], v[120:123]
	v_mfma_f32_16x16x32_bf16 v[124:127], v[162:165], v[196:199], v[124:127]
	v_mfma_f32_16x16x32_bf16 v[108:111], v[154:157], v[204:207], v[108:111]
	v_mfma_f32_16x16x32_bf16 v[104:107], v[162:165], v[204:207], v[104:107]
	v_mfma_f32_16x16x32_bf16 v[92:95], v[154:157], v[212:215], v[92:95]
	v_mfma_f32_16x16x32_bf16 v[88:91], v[162:165], v[212:215], v[88:91]
	v_mfma_f32_16x16x32_bf16 v[76:79], v[154:157], v[220:223], v[76:79]
	v_mfma_f32_16x16x32_bf16 v[72:75], v[162:165], v[220:223], v[72:75]
	s_setprio 0
	s_setprio 1
	v_mfma_f32_16x16x32_bf16 v[116:119], v[166:169], v[192:195], v[116:119]
	v_mfma_f32_16x16x32_bf16 v[112:115], v[184:187], v[192:195], v[112:115]
	v_mfma_f32_16x16x32_bf16 v[100:103], v[166:169], v[200:203], v[100:103]
	v_mfma_f32_16x16x32_bf16 v[96:99], v[184:187], v[200:203], v[96:99]
	v_mfma_f32_16x16x32_bf16 v[84:87], v[166:169], v[208:211], v[84:87]
	v_mfma_f32_16x16x32_bf16 v[80:83], v[184:187], v[208:211], v[80:83]
	v_mfma_f32_16x16x32_bf16 v[68:71], v[166:169], v[216:219], v[68:71]
	v_mfma_f32_16x16x32_bf16 v[64:67], v[184:187], v[216:219], v[64:67]
	v_mfma_f32_16x16x32_bf16 v[116:119], v[170:173], v[196:199], v[116:119]
	v_mfma_f32_16x16x32_bf16 v[112:115], v[188:191], v[196:199], v[112:115]
	v_mfma_f32_16x16x32_bf16 v[100:103], v[170:173], v[204:207], v[100:103]
	v_mfma_f32_16x16x32_bf16 v[96:99], v[188:191], v[204:207], v[96:99]
	v_mfma_f32_16x16x32_bf16 v[84:87], v[170:173], v[212:215], v[84:87]
	v_mfma_f32_16x16x32_bf16 v[80:83], v[188:191], v[212:215], v[80:83]
	v_mfma_f32_16x16x32_bf16 v[68:71], v[170:173], v[220:223], v[68:71]
	v_mfma_f32_16x16x32_bf16 v[64:67], v[188:191], v[220:223], v[64:67]
	s_setprio 0
	s_barrier
	s_add_i32 s6, s29, s66
	s_add_i32 m0, s6, 0xffffff80
	ds_read_b128 v[192:195], v180 offset:49152
	ds_read_b128 v[196:199], v180 offset:50176
	ds_read_b128 v[200:203], v180 offset:51200
	ds_read_b128 v[204:207], v180 offset:52224
	ds_read_b128 v[208:211], v180 offset:53248
	ds_read_b128 v[212:215], v180 offset:54272
	ds_read_b128 v[216:219], v180 offset:55296
	ds_read_b128 v[220:223], v180 offset:56320
	global_load_lds_dwordx4 v134, s[98:99] offset:128
	s_add_i32 m0, s6, 0x1f80
	s_add_i32 s6, s38, s66
	global_load_lds_dwordx4 v138, s[98:99] offset:128
	s_add_i32 m0, s6, 0xffffff80
	s_nop 0
	global_load_lds_dwordx4 v134, s[100:101] offset:128
	s_add_i32 m0, s6, 0x1f80
	s_nop 0
	global_load_lds_dwordx4 v138, s[100:101] offset:128
	s_add_i32 m0, s72, 0xffffff80
	s_nop 0
	global_load_lds_dwordx4 v132, s[24:25] offset:128
	s_add_i32 m0, s73, 0xffffff80
	s_nop 0
	global_load_lds_dwordx4 v136, s[24:25] offset:128
	s_waitcnt vmcnt(8)
	s_waitcnt lgkmcnt(0)
	s_barrier
	s_setprio 1
	s_waitcnt lgkmcnt(0)
	v_mfma_f32_16x16x32_bf16 v[60:63], v[128:131], v[192:195], v[60:63]
	v_mfma_f32_16x16x32_bf16 v[56:59], v[158:161], v[192:195], v[56:59]
	v_mfma_f32_16x16x32_bf16 v[44:47], v[128:131], v[200:203], v[44:47]
	v_mfma_f32_16x16x32_bf16 v[40:43], v[158:161], v[200:203], v[40:43]
	v_mfma_f32_16x16x32_bf16 v[28:31], v[128:131], v[208:211], v[28:31]
	v_mfma_f32_16x16x32_bf16 v[24:27], v[158:161], v[208:211], v[24:27]
	v_mfma_f32_16x16x32_bf16 v[12:15], v[128:131], v[216:219], v[12:15]
	v_mfma_f32_16x16x32_bf16 v[8:11], v[158:161], v[216:219], v[8:11]
	v_mfma_f32_16x16x32_bf16 v[60:63], v[154:157], v[196:199], v[60:63]
	v_mfma_f32_16x16x32_bf16 v[56:59], v[162:165], v[196:199], v[56:59]
	v_mfma_f32_16x16x32_bf16 v[44:47], v[154:157], v[204:207], v[44:47]
	v_mfma_f32_16x16x32_bf16 v[40:43], v[162:165], v[204:207], v[40:43]
	v_mfma_f32_16x16x32_bf16 v[28:31], v[154:157], v[212:215], v[28:31]
	v_mfma_f32_16x16x32_bf16 v[24:27], v[162:165], v[212:215], v[24:27]
	v_mfma_f32_16x16x32_bf16 v[12:15], v[154:157], v[220:223], v[12:15]
	v_mfma_f32_16x16x32_bf16 v[8:11], v[162:165], v[220:223], v[8:11]
	s_setprio 0
	s_setprio 1
	v_mfma_f32_16x16x32_bf16 v[52:55], v[166:169], v[192:195], v[52:55]
	v_mfma_f32_16x16x32_bf16 v[48:51], v[184:187], v[192:195], v[48:51]
	v_mfma_f32_16x16x32_bf16 v[36:39], v[166:169], v[200:203], v[36:39]
	v_mfma_f32_16x16x32_bf16 v[32:35], v[184:187], v[200:203], v[32:35]
	v_mfma_f32_16x16x32_bf16 v[20:23], v[166:169], v[208:211], v[20:23]
	v_mfma_f32_16x16x32_bf16 v[16:19], v[184:187], v[208:211], v[16:19]
	v_mfma_f32_16x16x32_bf16 v[4:7], v[166:169], v[216:219], v[4:7]
	v_mfma_f32_16x16x32_bf16 v[0:3], v[184:187], v[216:219], v[0:3]
	v_mfma_f32_16x16x32_bf16 v[52:55], v[170:173], v[196:199], v[52:55]
	v_mfma_f32_16x16x32_bf16 v[48:51], v[188:191], v[196:199], v[48:51]
	v_mfma_f32_16x16x32_bf16 v[36:39], v[170:173], v[204:207], v[36:39]
	v_mfma_f32_16x16x32_bf16 v[32:35], v[188:191], v[204:207], v[32:35]
	v_mfma_f32_16x16x32_bf16 v[20:23], v[170:173], v[212:215], v[20:23]
	v_mfma_f32_16x16x32_bf16 v[16:19], v[188:191], v[212:215], v[16:19]
	v_mfma_f32_16x16x32_bf16 v[4:7], v[170:173], v[220:223], v[4:7]
	v_mfma_f32_16x16x32_bf16 v[0:3], v[188:191], v[220:223], v[0:3]
	s_setprio 0
	s_barrier
	s_add_u32 s4, s4, 0x100
	s_addc_u32 s5, s5, 0
	s_add_u32 s9, s9, 0x100
	s_addc_u32 s27, s27, 0
	s_cmp_ge_i32 s28, s33
	s_mov_b32 s6, s28
	s_cbranch_scc0 .LBB0_597
	s_branch .Lpeel_x2
; #define PG8_STAGE(bufoff, gbase, voff) do { _Pragma("unroll") for (int _i = 0; _i < 2; ++_i) \
;         __builtin_amdgcn_global_load_lds((const unsigned*)((const char*)(gbase) + (voff)[_i]), (PG8_LAS unsigned*)(lds + (bufoff) + ldsw + _i * 8192), 16, 0, 0); } while (0)
; #define PG8_LDA(dst, b, h) do { _Pragma("unroll") for (int m = 0; m < 4; ++m) _Pragma("unroll") for (int k = 0; k < 2; ++k) dst[m][k] = *(const PG8_LAS bf16x8*)(lds + PG8_SA(b, h) + aoff + m * 2048 + k * 1024); } while (0)
; #define PG8_LDB(dst, b, h) do { _Pragma("unroll") for (int n = 0; n < 2; ++n) _Pragma("unroll") for (int k = 0; k < 2; ++k) dst[n][k] = *(const PG8_LAS bf16x8*)(lds + PG8_SB(b, h) + boff + n * 2048 + k * 1024); } while (0)
; #define PG8_MMA(ai, bj, At, Bt) do { __builtin_amdgcn_s_setprio(1); _Pragma("unroll") for (int m = 0; m < 4; ++m) _Pragma("unroll") for (int n = 0; n < 2; ++n) _Pragma("unroll") for (int k = 0; k < 2; ++k) \
;         acc[ai][bj][m][n] = __builtin_amdgcn_mfma_f32_16x16x32_bf16(Bt[n][k], At[m][k], acc[ai][bj][m][n], 0, 0, 0); __builtin_amdgcn_s_setprio(0); } while (0)
; #define PG8_WAIT_V(n) asm volatile("s_waitcnt vmcnt(" #n ")" ::: "memory")
; #define PG8_BAR __builtin_amdgcn_s_barrier()
; template <class Epi, class Sched, bool ALIGN_EPI = false, bool SP2 = false>
; __device__ __forceinline__ void gemm_phase(PG8_LAS unsigned char* lds, const Gemm g, const Sched& S, const Epi& E) {
;     ...
;         for (int t = 0; t < nt; t += 2) {
;             const bool last = (t == nt - 2);
;             const char* a1 = cA + (size_t)(t + 1) * kstep;
;             const char* a2 = last ? nA : cA + (size_t)(t + 2) * kstep; const char* b2 = last ? nB : cB + (size_t)(t + 2) * kstep;
;             const char* a3 = a2 + kstep; const char* b3 = b2 + kstep;
;             if (last && has_next) S.a_ready(nxt);
;             if constexpr (SP2) {
;             PG8_LDB(B0, 0, 0); PG8_LDB(B1, 0, 1); PG8_SCHED; PG8_LDA(At, 0, 0); PG8_STAGE(PG8_SA(1, 1), a1 + hstep, voffA);
;             PG8_WAIT_V(8); PG8_WAIT_L(0); PG8_BAR; PG8_MMA(0, 0, At, B0); PG8_MMA(0, 1, At, B1); PG8_BAR; PG8_SCHED;
;             PG8_LDA(At, 0, 1); PG8_STAGE(PG8_SB(0, 0), b2, voffB); PG8_STAGE(PG8_SB(0, 1), b2 + hstep, voffB); PG8_STAGE(PG8_SA(0, 0), a2, voffA);
;             PG8_WAIT_V(8); PG8_WAIT_L(0); PG8_BAR; PG8_MMA(1, 0, At, B0); PG8_MMA(1, 1, At, B1); PG8_BAR; PG8_SCHED;
.LBB0_597:
	ds_read_b128 v[128:131], v177
	ds_read_b128 v[154:157], v177 offset:1024
	ds_read_b128 v[158:161], v177 offset:2048
	ds_read_b128 v[162:165], v177 offset:3072
	ds_read_b128 v[166:169], v179
	ds_read_b128 v[170:173], v179 offset:1024
	ds_read_b128 v[184:187], v179 offset:2048
	ds_read_b128 v[188:191], v179 offset:3072
	s_add_i32 s28, s6, 2
	s_add_u32 s29, s4, 0x80
	s_addc_u32 s7, s5, 0
	s_cmp_eq_u32 s86, s6
	s_cselect_b32 s6, s0, s29
	s_cselect_b32 s7, s1, s7
	s_cselect_b32 s39, s37, s27
	s_cselect_b32 s38, s36, s9
	s_add_i32 m0, s67, 0xc000
	ds_read_b128 v[192:195], v180
	ds_read_b128 v[196:199], v180 offset:1024
	ds_read_b128 v[200:203], v180 offset:2048
	ds_read_b128 v[204:207], v180 offset:3072
	ds_read_b128 v[208:211], v180 offset:4096
	ds_read_b128 v[212:215], v180 offset:5120
	ds_read_b128 v[216:219], v180 offset:6144
	ds_read_b128 v[220:223], v180 offset:7168
	global_load_lds_dwordx4 v146, s[4:5]
	s_add_i32 m0, s67, 0xe000
	s_nop 0
	global_load_lds_dwordx4 v148, s[4:5]
	s_waitcnt vmcnt(8)
	s_waitcnt lgkmcnt(0)
	s_barrier
	s_setprio 1
	s_waitcnt lgkmcnt(0)
	v_mfma_f32_16x16x32_bf16 v[120:123], v[128:131], v[192:195], v[120:123]
	v_mfma_f32_16x16x32_bf16 v[124:127], v[158:161], v[192:195], v[124:127]
	v_mfma_f32_16x16x32_bf16 v[108:111], v[128:131], v[200:203], v[108:111]
	v_mfma_f32_16x16x32_bf16 v[104:107], v[158:161], v[200:203], v[104:107]
	v_mfma_f32_16x16x32_bf16 v[92:95], v[128:131], v[208:211], v[92:95]
	v_mfma_f32_16x16x32_bf16 v[88:91], v[158:161], v[208:211], v[88:91]
	v_mfma_f32_16x16x32_bf16 v[76:79], v[128:131], v[216:219], v[76:79]
	v_mfma_f32_16x16x32_bf16 v[72:75], v[158:161], v[216:219], v[72:75]
	v_mfma_f32_16x16x32_bf16 v[120:123], v[154:157], v[196:199], v[120:123]
	v_mfma_f32_16x16x32_bf16 v[124:127], v[162:165], v[196:199], v[124:127]
	v_mfma_f32_16x16x32_bf16 v[108:111], v[154:157], v[204:207], v[108:111]
	v_mfma_f32_16x16x32_bf16 v[104:107], v[162:165], v[204:207], v[104:107]
	v_mfma_f32_16x16x32_bf16 v[92:95], v[154:157], v[212:215], v[92:95]
	v_mfma_f32_16x16x32_bf16 v[88:91], v[162:165], v[212:215], v[88:91]
	v_mfma_f32_16x16x32_bf16 v[76:79], v[154:157], v[220:223], v[76:79]
	v_mfma_f32_16x16x32_bf16 v[72:75], v[162:165], v[220:223], v[72:75]
	s_setprio 0
	s_setprio 1
	v_mfma_f32_16x16x32_bf16 v[116:119], v[166:169], v[192:195], v[116:119]
	v_mfma_f32_16x16x32_bf16 v[112:115], v[184:187], v[192:195], v[112:115]
	v_mfma_f32_16x16x32_bf16 v[100:103], v[166:169], v[200:203], v[100:103]
	v_mfma_f32_16x16x32_bf16 v[96:99], v[184:187], v[200:203], v[96:99]
	v_mfma_f32_16x16x32_bf16 v[84:87], v[166:169], v[208:211], v[84:87]
	v_mfma_f32_16x16x32_bf16 v[80:83], v[184:187], v[208:211], v[80:83]
	v_mfma_f32_16x16x32_bf16 v[68:71], v[166:169], v[216:219], v[68:71]
	v_mfma_f32_16x16x32_bf16 v[64:67], v[184:187], v[216:219], v[64:67]
	v_mfma_f32_16x16x32_bf16 v[116:119], v[170:173], v[196:199], v[116:119]
	v_mfma_f32_16x16x32_bf16 v[112:115], v[188:191], v[196:199], v[112:115]
	v_mfma_f32_16x16x32_bf16 v[100:103], v[170:173], v[204:207], v[100:103]
	v_mfma_f32_16x16x32_bf16 v[96:99], v[188:191], v[204:207], v[96:99]
	v_mfma_f32_16x16x32_bf16 v[84:87], v[170:173], v[212:215], v[84:87]
	v_mfma_f32_16x16x32_bf16 v[80:83], v[188:191], v[212:215], v[80:83]
	v_mfma_f32_16x16x32_bf16 v[68:71], v[170:173], v[220:223], v[68:71]
	v_mfma_f32_16x16x32_bf16 v[64:67], v[188:191], v[220:223], v[64:67]
	s_setprio 0
	s_barrier
	s_add_i32 s29, s11, s66
	s_mov_b64 s[98:99], s[38:39]
	s_mov_b32 m0, s29
	ds_read_b128 v[192:195], v180 offset:16384
	ds_read_b128 v[196:199], v180 offset:17408
	ds_read_b128 v[200:203], v180 offset:18432
	ds_read_b128 v[204:207], v180 offset:19456
	ds_read_b128 v[208:211], v180 offset:20480
	ds_read_b128 v[212:215], v180 offset:21504
	ds_read_b128 v[216:219], v180 offset:22528
	ds_read_b128 v[220:223], v180 offset:23552
	global_load_lds_dwordx4 v134, s[38:39]
	s_add_i32 m0, s29, 0x2000
	s_add_u32 s38, s38, s14
	s_addc_u32 s39, s39, s15
	s_add_i32 s29, s19, s66
	global_load_lds_dwordx4 v138, s[98:99]
	s_mov_b64 s[100:101], s[38:39]
	s_mov_b32 m0, s29
	s_nop 0
	global_load_lds_dwordx4 v134, s[38:39]
	s_add_i32 m0, s29, 0x2000
	s_mov_b64 s[24:25], s[6:7]
	global_load_lds_dwordx4 v138, s[38:39]
	s_mov_b32 m0, s67
	s_nop 0
	global_load_lds_dwordx4 v132, s[6:7]
	s_mov_b32 m0, s68
	s_nop 0
	global_load_lds_dwordx4 v136, s[6:7]
	s_waitcnt vmcnt(8)
	s_waitcnt lgkmcnt(0)
	s_barrier
	s_setprio 1
	s_waitcnt lgkmcnt(0)
	v_mfma_f32_16x16x32_bf16 v[60:63], v[128:131], v[192:195], v[60:63]
	v_mfma_f32_16x16x32_bf16 v[56:59], v[158:161], v[192:195], v[56:59]
	v_mfma_f32_16x16x32_bf16 v[44:47], v[128:131], v[200:203], v[44:47]
	v_mfma_f32_16x16x32_bf16 v[40:43], v[158:161], v[200:203], v[40:43]
	v_mfma_f32_16x16x32_bf16 v[28:31], v[128:131], v[208:211], v[28:31]
	v_mfma_f32_16x16x32_bf16 v[24:27], v[158:161], v[208:211], v[24:27]
	v_mfma_f32_16x16x32_bf16 v[12:15], v[128:131], v[216:219], v[12:15]
	v_mfma_f32_16x16x32_bf16 v[8:11], v[158:161], v[216:219], v[8:11]
	v_mfma_f32_16x16x32_bf16 v[60:63], v[154:157], v[196:199], v[60:63]
	v_mfma_f32_16x16x32_bf16 v[56:59], v[162:165], v[196:199], v[56:59]
	v_mfma_f32_16x16x32_bf16 v[44:47], v[154:157], v[204:207], v[44:47]
	v_mfma_f32_16x16x32_bf16 v[40:43], v[162:165], v[204:207], v[40:43]
	v_mfma_f32_16x16x32_bf16 v[28:31], v[154:157], v[212:215], v[28:31]
	v_mfma_f32_16x16x32_bf16 v[24:27], v[162:165], v[212:215], v[24:27]
	v_mfma_f32_16x16x32_bf16 v[12:15], v[154:157], v[220:223], v[12:15]
	v_mfma_f32_16x16x32_bf16 v[8:11], v[162:165], v[220:223], v[8:11]
	s_setprio 0
	s_setprio 1
	v_mfma_f32_16x16x32_bf16 v[52:55], v[166:169], v[192:195], v[52:55]
	v_mfma_f32_16x16x32_bf16 v[48:51], v[184:187], v[192:195], v[48:51]
	v_mfma_f32_16x16x32_bf16 v[36:39], v[166:169], v[200:203], v[36:39]
	v_mfma_f32_16x16x32_bf16 v[32:35], v[184:187], v[200:203], v[32:35]
	v_mfma_f32_16x16x32_bf16 v[20:23], v[166:169], v[208:211], v[20:23]
	v_mfma_f32_16x16x32_bf16 v[16:19], v[184:187], v[208:211], v[16:19]
	v_mfma_f32_16x16x32_bf16 v[4:7], v[166:169], v[216:219], v[4:7]
	v_mfma_f32_16x16x32_bf16 v[0:3], v[184:187], v[216:219], v[0:3]
	v_mfma_f32_16x16x32_bf16 v[52:55], v[170:173], v[196:199], v[52:55]
	v_mfma_f32_16x16x32_bf16 v[48:51], v[188:191], v[196:199], v[48:51]
	v_mfma_f32_16x16x32_bf16 v[36:39], v[170:173], v[204:207], v[36:39]
	v_mfma_f32_16x16x32_bf16 v[32:35], v[188:191], v[204:207], v[32:35]
	v_mfma_f32_16x16x32_bf16 v[20:23], v[170:173], v[212:215], v[20:23]
	v_mfma_f32_16x16x32_bf16 v[16:19], v[188:191], v[212:215], v[16:19]
	v_mfma_f32_16x16x32_bf16 v[4:7], v[170:173], v[220:223], v[4:7]
	v_mfma_f32_16x16x32_bf16 v[0:3], v[188:191], v[220:223], v[0:3]
	s_setprio 0
	s_barrier
; #define PG8_STAGE(bufoff, gbase, voff) do { _Pragma("unroll") for (int _i = 0; _i < 2; ++_i) \
;         __builtin_amdgcn_global_load_lds((const unsigned*)((const char*)(gbase) + (voff)[_i]), (PG8_LAS unsigned*)(lds + (bufoff) + ldsw + _i * 8192), 16, 0, 0); } while (0)
; #define PG8_LDA(dst, b, h) do { _Pragma("unroll") for (int m = 0; m < 4; ++m) _Pragma("unroll") for (int k = 0; k < 2; ++k) dst[m][k] = *(const PG8_LAS bf16x8*)(lds + PG8_SA(b, h) + aoff + m * 2048 + k * 1024); } while (0)
; #define PG8_LDB(dst, b, h) do { _Pragma("unroll") for (int n = 0; n < 2; ++n) _Pragma("unroll") for (int k = 0; k < 2; ++k) dst[n][k] = *(const PG8_LAS bf16x8*)(lds + PG8_SB(b, h) + boff + n * 2048 + k * 1024); } while (0)
; #define PG8_MMA(ai, bj, At, Bt) do { __builtin_amdgcn_s_setprio(1); _Pragma("unroll") for (int m = 0; m < 4; ++m) _Pragma("unroll") for (int n = 0; n < 2; ++n) _Pragma("unroll") for (int k = 0; k < 2; ++k) \
;         acc[ai][bj][m][n] = __builtin_amdgcn_mfma_f32_16x16x32_bf16(Bt[n][k], At[m][k], acc[ai][bj][m][n], 0, 0, 0); __builtin_amdgcn_s_setprio(0); } while (0)
; #define PG8_WAIT_V(n) asm volatile("s_waitcnt vmcnt(" #n ")" ::: "memory")
; #define PG8_WAIT_L(n) asm volatile("s_waitcnt lgkmcnt(" #n ")" ::: "memory")
; #define PG8_BAR __builtin_amdgcn_s_barrier()
; #define PG8_SCHED __builtin_amdgcn_sched_barrier(0)
; template <class Epi, class Sched, bool ALIGN_EPI = false, bool SP2 = false>
; __device__ __forceinline__ void gemm_phase(PG8_LAS unsigned char* lds, const Gemm g, const Sched& S, const Epi& E) {
;     ...
;             PG8_LDB(B0, 1, 0); PG8_LDB(B1, 1, 1); PG8_SCHED; PG8_LDA(At, 1, 0); PG8_STAGE(PG8_SA(0, 1), a2 + hstep, voffA);
;             PG8_WAIT_V(8); PG8_WAIT_L(0); PG8_BAR; PG8_MMA(0, 0, At, B0); PG8_MMA(0, 1, At, B1); PG8_BAR; PG8_SCHED;
;             PG8_LDA(At, 1, 1); PG8_STAGE(PG8_SB(1, 0), b3, voffB); PG8_STAGE(PG8_SB(1, 1), b3 + hstep, voffB); PG8_STAGE(PG8_SA(1, 0), a3, voffA);
;             PG8_WAIT_V(8); PG8_WAIT_L(0); PG8_BAR; PG8_MMA(1, 0, At, B0); PG8_MMA(1, 1, At, B1); PG8_BAR; PG8_SCHED;
	s_add_i32 s29, 0, 0x18000
	v_add_u32_e32 v140, s29, v175
	s_add_i32 s38, 0, 0x1c000
	ds_read_b128 v[128:131], v140
	ds_read_b128 v[154:157], v140 offset:1024
	ds_read_b128 v[158:161], v140 offset:2048
	ds_read_b128 v[162:165], v140 offset:3072
	v_add_u32_e32 v140, s38, v175
	ds_read_b128 v[166:169], v140
	ds_read_b128 v[170:173], v140 offset:1024
	ds_read_b128 v[184:187], v140 offset:2048
	ds_read_b128 v[188:191], v140 offset:3072
	s_add_u32 s6, s6, s14
	s_addc_u32 s7, s7, s15
	s_mov_b32 m0, s69
	ds_read_b128 v[192:195], v180 offset:32768
	ds_read_b128 v[196:199], v180 offset:33792
	ds_read_b128 v[200:203], v180 offset:34816
	ds_read_b128 v[204:207], v180 offset:35840
	ds_read_b128 v[208:211], v180 offset:36864
	ds_read_b128 v[212:215], v180 offset:37888
	ds_read_b128 v[216:219], v180 offset:38912
	ds_read_b128 v[220:223], v180 offset:39936
	global_load_lds_dwordx4 v132, s[6:7]
	s_mov_b32 m0, s70
	s_nop 0
	global_load_lds_dwordx4 v136, s[6:7]
	s_waitcnt vmcnt(8)
	s_waitcnt lgkmcnt(0)
	s_barrier
	s_setprio 1
	s_waitcnt lgkmcnt(0)
	v_mfma_f32_16x16x32_bf16 v[120:123], v[128:131], v[192:195], v[120:123]
	v_mfma_f32_16x16x32_bf16 v[124:127], v[158:161], v[192:195], v[124:127]
	v_mfma_f32_16x16x32_bf16 v[108:111], v[128:131], v[200:203], v[108:111]
	v_mfma_f32_16x16x32_bf16 v[104:107], v[158:161], v[200:203], v[104:107]
	v_mfma_f32_16x16x32_bf16 v[92:95], v[128:131], v[208:211], v[92:95]
	v_mfma_f32_16x16x32_bf16 v[88:91], v[158:161], v[208:211], v[88:91]
	v_mfma_f32_16x16x32_bf16 v[76:79], v[128:131], v[216:219], v[76:79]
	v_mfma_f32_16x16x32_bf16 v[72:75], v[158:161], v[216:219], v[72:75]
	v_mfma_f32_16x16x32_bf16 v[120:123], v[154:157], v[196:199], v[120:123]
	v_mfma_f32_16x16x32_bf16 v[124:127], v[162:165], v[196:199], v[124:127]
	v_mfma_f32_16x16x32_bf16 v[108:111], v[154:157], v[204:207], v[108:111]
	v_mfma_f32_16x16x32_bf16 v[104:107], v[162:165], v[204:207], v[104:107]
	v_mfma_f32_16x16x32_bf16 v[92:95], v[154:157], v[212:215], v[92:95]
	v_mfma_f32_16x16x32_bf16 v[88:91], v[162:165], v[212:215], v[88:91]
	v_mfma_f32_16x16x32_bf16 v[76:79], v[154:157], v[220:223], v[76:79]
	v_mfma_f32_16x16x32_bf16 v[72:75], v[162:165], v[220:223], v[72:75]
	s_setprio 0
	s_setprio 1
	v_mfma_f32_16x16x32_bf16 v[116:119], v[166:169], v[192:195], v[116:119]
	v_mfma_f32_16x16x32_bf16 v[112:115], v[184:187], v[192:195], v[112:115]
	v_mfma_f32_16x16x32_bf16 v[100:103], v[166:169], v[200:203], v[100:103]
	v_mfma_f32_16x16x32_bf16 v[96:99], v[184:187], v[200:203], v[96:99]
	v_mfma_f32_16x16x32_bf16 v[84:87], v[166:169], v[208:211], v[84:87]
	v_mfma_f32_16x16x32_bf16 v[80:83], v[184:187], v[208:211], v[80:83]
	v_mfma_f32_16x16x32_bf16 v[68:71], v[166:169], v[216:219], v[68:71]
	v_mfma_f32_16x16x32_bf16 v[64:67], v[184:187], v[216:219], v[64:67]
	v_mfma_f32_16x16x32_bf16 v[116:119], v[170:173], v[196:199], v[116:119]
	v_mfma_f32_16x16x32_bf16 v[112:115], v[188:191], v[196:199], v[112:115]
	v_mfma_f32_16x16x32_bf16 v[100:103], v[170:173], v[204:207], v[100:103]
	v_mfma_f32_16x16x32_bf16 v[96:99], v[188:191], v[204:207], v[96:99]
	v_mfma_f32_16x16x32_bf16 v[84:87], v[170:173], v[212:215], v[84:87]
	v_mfma_f32_16x16x32_bf16 v[80:83], v[188:191], v[212:215], v[80:83]
	v_mfma_f32_16x16x32_bf16 v[68:71], v[170:173], v[220:223], v[68:71]
	v_mfma_f32_16x16x32_bf16 v[64:67], v[188:191], v[220:223], v[64:67]
	s_setprio 0
	s_barrier
	s_add_i32 s6, s29, s66
	s_add_i32 m0, s6, 0xffffff80
	ds_read_b128 v[192:195], v180 offset:49152
	ds_read_b128 v[196:199], v180 offset:50176
	ds_read_b128 v[200:203], v180 offset:51200
	ds_read_b128 v[204:207], v180 offset:52224
	ds_read_b128 v[208:211], v180 offset:53248
	ds_read_b128 v[212:215], v180 offset:54272
	ds_read_b128 v[216:219], v180 offset:55296
	ds_read_b128 v[220:223], v180 offset:56320
	global_load_lds_dwordx4 v134, s[98:99] offset:128
	s_add_i32 m0, s6, 0x1f80
	s_add_i32 s6, s38, s66
	global_load_lds_dwordx4 v138, s[98:99] offset:128
	s_add_i32 m0, s6, 0xffffff80
	s_nop 0
	global_load_lds_dwordx4 v134, s[100:101] offset:128
	s_add_i32 m0, s6, 0x1f80
	s_nop 0
	global_load_lds_dwordx4 v138, s[100:101] offset:128
	s_add_i32 m0, s72, 0xffffff80
	s_nop 0
	global_load_lds_dwordx4 v132, s[24:25] offset:128
	s_add_i32 m0, s73, 0xffffff80
	s_nop 0
	global_load_lds_dwordx4 v136, s[24:25] offset:128
	s_waitcnt vmcnt(8)
	s_waitcnt lgkmcnt(0)
	s_barrier
	s_setprio 1
	s_waitcnt lgkmcnt(0)
	v_mfma_f32_16x16x32_bf16 v[60:63], v[128:131], v[192:195], v[60:63]
	v_mfma_f32_16x16x32_bf16 v[56:59], v[158:161], v[192:195], v[56:59]
	v_mfma_f32_16x16x32_bf16 v[44:47], v[128:131], v[200:203], v[44:47]
	v_mfma_f32_16x16x32_bf16 v[40:43], v[158:161], v[200:203], v[40:43]
	v_mfma_f32_16x16x32_bf16 v[28:31], v[128:131], v[208:211], v[28:31]
	v_mfma_f32_16x16x32_bf16 v[24:27], v[158:161], v[208:211], v[24:27]
	v_mfma_f32_16x16x32_bf16 v[12:15], v[128:131], v[216:219], v[12:15]
	v_mfma_f32_16x16x32_bf16 v[8:11], v[158:161], v[216:219], v[8:11]
	v_mfma_f32_16x16x32_bf16 v[60:63], v[154:157], v[196:199], v[60:63]
	v_mfma_f32_16x16x32_bf16 v[56:59], v[162:165], v[196:199], v[56:59]
	v_mfma_f32_16x16x32_bf16 v[44:47], v[154:157], v[204:207], v[44:47]
	v_mfma_f32_16x16x32_bf16 v[40:43], v[162:165], v[204:207], v[40:43]
	v_mfma_f32_16x16x32_bf16 v[28:31], v[154:157], v[212:215], v[28:31]
	v_mfma_f32_16x16x32_bf16 v[24:27], v[162:165], v[212:215], v[24:27]
	v_mfma_f32_16x16x32_bf16 v[12:15], v[154:157], v[220:223], v[12:15]
	v_mfma_f32_16x16x32_bf16 v[8:11], v[162:165], v[220:223], v[8:11]
	s_setprio 0
	s_setprio 1
	v_mfma_f32_16x16x32_bf16 v[52:55], v[166:169], v[192:195], v[52:55]
	v_mfma_f32_16x16x32_bf16 v[48:51], v[184:187], v[192:195], v[48:51]
	v_mfma_f32_16x16x32_bf16 v[36:39], v[166:169], v[200:203], v[36:39]
	v_mfma_f32_16x16x32_bf16 v[32:35], v[184:187], v[200:203], v[32:35]
	v_mfma_f32_16x16x32_bf16 v[20:23], v[166:169], v[208:211], v[20:23]
	v_mfma_f32_16x16x32_bf16 v[16:19], v[184:187], v[208:211], v[16:19]
	v_mfma_f32_16x16x32_bf16 v[4:7], v[166:169], v[216:219], v[4:7]
	v_mfma_f32_16x16x32_bf16 v[0:3], v[184:187], v[216:219], v[0:3]
	v_mfma_f32_16x16x32_bf16 v[52:55], v[170:173], v[196:199], v[52:55]
	v_mfma_f32_16x16x32_bf16 v[48:51], v[188:191], v[196:199], v[48:51]
	v_mfma_f32_16x16x32_bf16 v[36:39], v[170:173], v[204:207], v[36:39]
	v_mfma_f32_16x16x32_bf16 v[32:35], v[188:191], v[204:207], v[32:35]
	v_mfma_f32_16x16x32_bf16 v[20:23], v[170:173], v[212:215], v[20:23]
	v_mfma_f32_16x16x32_bf16 v[16:19], v[188:191], v[212:215], v[16:19]
	v_mfma_f32_16x16x32_bf16 v[4:7], v[170:173], v[220:223], v[4:7]
	v_mfma_f32_16x16x32_bf16 v[0:3], v[188:191], v[220:223], v[0:3]
	s_setprio 0
	s_barrier
	s_add_u32 s4, s4, 0x100
	s_addc_u32 s5, s5, 0
	s_add_u32 s9, s9, 0x100
	s_addc_u32 s27, s27, 0
	s_cmp_ge_i32 s28, s33
	s_mov_b32 s6, s28
	s_cbranch_scc0 .LBB0_597

; #define PG8_STAGE(bufoff, gbase, voff) do { _Pragma("unroll") for (int _i = 0; _i < 2; ++_i) \
;         __builtin_amdgcn_global_load_lds((const unsigned*)((const char*)(gbase) + (voff)[_i]), (PG8_LAS unsigned*)(lds + (bufoff) + ldsw + _i * 8192), 16, 0, 0); } while (0)
; #define PG8_LDA(dst, b, h) do { _Pragma("unroll") for (int m = 0; m < 4; ++m) _Pragma("unroll") for (int k = 0; k < 2; ++k) dst[m][k] = *(const PG8_LAS bf16x8*)(lds + PG8_SA(b, h) + aoff + m * 2048 + k * 1024); } while (0)
; #define PG8_LDB(dst, b, h) do { _Pragma("unroll") for (int n = 0; n < 2; ++n) _Pragma("unroll") for (int k = 0; k < 2; ++k) dst[n][k] = *(const PG8_LAS bf16x8*)(lds + PG8_SB(b, h) + boff + n * 2048 + k * 1024); } while (0)
; #define PG8_MMA(ai, bj, At, Bt) do { __builtin_amdgcn_s_setprio(1); _Pragma("unroll") for (int m = 0; m < 4; ++m) _Pragma("unroll") for (int n = 0; n < 2; ++n) _Pragma("unroll") for (int k = 0; k < 2; ++k) \
;         acc[ai][bj][m][n] = __builtin_amdgcn_mfma_f32_16x16x32_bf16(Bt[n][k], At[m][k], acc[ai][bj][m][n], 0, 0, 0); __builtin_amdgcn_s_setprio(0); } while (0)
; #define PG8_WAIT_V(n) asm volatile("s_waitcnt vmcnt(" #n ")" ::: "memory")
; #define PG8_BAR __builtin_amdgcn_s_barrier()
; template <class Epi, class Sched, bool ALIGN_EPI = false, bool SP2 = false>
; __device__ __forceinline__ void gemm_phase(PG8_LAS unsigned char* lds, const Gemm g, const Sched& S, const Epi& E) {
;     ...
;         for (int t = 0; t < nt; t += 2) {
;             const bool last = (t == nt - 2);
;             const char* a1 = cA + (size_t)(t + 1) * kstep;
;             const char* a2 = last ? nA : cA + (size_t)(t + 2) * kstep; const char* b2 = last ? nB : cB + (size_t)(t + 2) * kstep;
;             const char* a3 = a2 + kstep; const char* b3 = b2 + kstep;
;             if (last && has_next) S.a_ready(nxt);
;             if constexpr (SP2) {
;             PG8_LDB(B0, 0, 0); PG8_LDB(B1, 0, 1); PG8_SCHED; PG8_LDA(At, 0, 0); PG8_STAGE(PG8_SA(1, 1), a1 + hstep, voffA);
;             PG8_WAIT_V(8); PG8_WAIT_L(0); PG8_BAR; PG8_MMA(0, 0, At, B0); PG8_MMA(0, 1, At, B1); PG8_BAR; PG8_SCHED;
;             PG8_LDA(At, 0, 1); PG8_STAGE(PG8_SB(0, 0), b2, voffB); PG8_STAGE(PG8_SB(0, 1), b2 + hstep, voffB); PG8_STAGE(PG8_SA(0, 0), a2, voffA);
;             PG8_WAIT_V(8); PG8_WAIT_L(0); PG8_BAR; PG8_MMA(1, 0, At, B0); PG8_MMA(1, 1, At, B1); PG8_BAR; PG8_SCHED;
.LBB0_1220:
	s_andn2_b64 vcc, exec, s[24:25]
	s_waitcnt vmcnt(0)
	s_waitcnt lgkmcnt(0)
	s_cbranch_vccnz .LBB0_1223
	s_add_u32 s30, s30, 0x80
	s_addc_u32 s31, s31, 0
	s_add_u32 s63, s34, 0x100
	s_addc_u32 s64, s35, 0
	s_mov_b32 s34, 0
	ds_read_b128 v[144:147], v151
	ds_read_b128 v[156:159], v151 offset:1024
	ds_read_b128 v[160:163], v151 offset:2048
	ds_read_b128 v[164:167], v151 offset:3072
	ds_read_b128 v[168:171], v152
	ds_read_b128 v[172:175], v152 offset:1024
	ds_read_b128 v[180:183], v152 offset:2048
	ds_read_b128 v[184:187], v152 offset:3072
	s_add_i32 s65, s34, 2
	s_add_u32 s66, s30, 0x80
	s_addc_u32 s35, s31, 0
	s_cmp_eq_u32 s41, s34
	s_cselect_b32 s34, s0, s66
	s_cselect_b32 s35, s1, s35
	s_cselect_b32 s67, s29, s64
	s_cselect_b32 s66, s28, s63
	s_add_i32 m0, s17, 0xc000
	ds_read_b128 v[188:191], v153
	ds_read_b128 v[192:195], v153 offset:1024
	ds_read_b128 v[196:199], v153 offset:2048
	ds_read_b128 v[200:203], v153 offset:3072
	ds_read_b128 v[204:207], v153 offset:4096
	ds_read_b128 v[208:211], v153 offset:5120
	ds_read_b128 v[212:215], v153 offset:6144
	ds_read_b128 v[216:219], v153 offset:7168
	global_load_lds_dwordx4 v136, s[30:31]
	s_add_i32 m0, s17, 0xe000
	s_nop 0
	global_load_lds_dwordx4 v138, s[30:31]
	s_waitcnt vmcnt(8)
	s_waitcnt lgkmcnt(0)
	s_barrier
	s_setprio 1
	s_waitcnt lgkmcnt(0)
	v_mfma_f32_16x16x32_bf16 v[124:127], v[144:147], v[188:191], 0
	v_mfma_f32_16x16x32_bf16 v[120:123], v[160:163], v[188:191], 0
	v_mfma_f32_16x16x32_bf16 v[108:111], v[144:147], v[196:199], 0
	v_mfma_f32_16x16x32_bf16 v[104:107], v[160:163], v[196:199], 0
	v_mfma_f32_16x16x32_bf16 v[92:95], v[144:147], v[204:207], 0
	v_mfma_f32_16x16x32_bf16 v[88:91], v[160:163], v[204:207], 0
	v_mfma_f32_16x16x32_bf16 v[76:79], v[144:147], v[212:215], 0
	v_mfma_f32_16x16x32_bf16 v[72:75], v[160:163], v[212:215], 0
	v_mfma_f32_16x16x32_bf16 v[124:127], v[156:159], v[192:195], v[124:127]
	v_mfma_f32_16x16x32_bf16 v[120:123], v[164:167], v[192:195], v[120:123]
	v_mfma_f32_16x16x32_bf16 v[108:111], v[156:159], v[200:203], v[108:111]
	v_mfma_f32_16x16x32_bf16 v[104:107], v[164:167], v[200:203], v[104:107]
	v_mfma_f32_16x16x32_bf16 v[92:95], v[156:159], v[208:211], v[92:95]
	v_mfma_f32_16x16x32_bf16 v[88:91], v[164:167], v[208:211], v[88:91]
	v_mfma_f32_16x16x32_bf16 v[76:79], v[156:159], v[216:219], v[76:79]
	v_mfma_f32_16x16x32_bf16 v[72:75], v[164:167], v[216:219], v[72:75]
	s_setprio 0
	s_setprio 1
	v_mfma_f32_16x16x32_bf16 v[116:119], v[168:171], v[188:191], 0
	v_mfma_f32_16x16x32_bf16 v[112:115], v[180:183], v[188:191], 0
	v_mfma_f32_16x16x32_bf16 v[100:103], v[168:171], v[196:199], 0
	v_mfma_f32_16x16x32_bf16 v[96:99], v[180:183], v[196:199], 0
	v_mfma_f32_16x16x32_bf16 v[84:87], v[168:171], v[204:207], 0
	v_mfma_f32_16x16x32_bf16 v[80:83], v[180:183], v[204:207], 0
	v_mfma_f32_16x16x32_bf16 v[68:71], v[168:171], v[212:215], 0
	v_mfma_f32_16x16x32_bf16 v[64:67], v[180:183], v[212:215], 0
	v_mfma_f32_16x16x32_bf16 v[116:119], v[172:175], v[192:195], v[116:119]
	v_mfma_f32_16x16x32_bf16 v[112:115], v[184:187], v[192:195], v[112:115]
	v_mfma_f32_16x16x32_bf16 v[100:103], v[172:175], v[200:203], v[100:103]
	v_mfma_f32_16x16x32_bf16 v[96:99], v[184:187], v[200:203], v[96:99]
	v_mfma_f32_16x16x32_bf16 v[84:87], v[172:175], v[208:211], v[84:87]
	v_mfma_f32_16x16x32_bf16 v[80:83], v[184:187], v[208:211], v[80:83]
	v_mfma_f32_16x16x32_bf16 v[68:71], v[172:175], v[216:219], v[68:71]
	v_mfma_f32_16x16x32_bf16 v[64:67], v[184:187], v[216:219], v[64:67]
	s_setprio 0
	s_barrier
	s_add_i32 s68, s57, s16
	s_mov_b64 s[98:99], s[66:67]
	s_mov_b32 m0, s68
	ds_read_b128 v[188:191], v153 offset:16384
	ds_read_b128 v[192:195], v153 offset:17408
	ds_read_b128 v[196:199], v153 offset:18432
	ds_read_b128 v[200:203], v153 offset:19456
	ds_read_b128 v[204:207], v153 offset:20480
	ds_read_b128 v[208:211], v153 offset:21504
	ds_read_b128 v[212:215], v153 offset:22528
	ds_read_b128 v[216:219], v153 offset:23552
	global_load_lds_dwordx4 v130, s[66:67]
	s_add_i32 m0, s68, 0x2000
	s_add_u32 s66, s66, s6
	s_addc_u32 s67, s67, s7
	s_add_i32 s68, s58, s16
	global_load_lds_dwordx4 v134, s[98:99]
	s_mov_b64 s[100:101], s[66:67]
	s_mov_b32 m0, s68
	s_nop 0
	global_load_lds_dwordx4 v130, s[66:67]
	s_add_i32 m0, s68, 0x2000
	s_mov_b64 s[22:23], s[34:35]
	global_load_lds_dwordx4 v134, s[66:67]
	s_mov_b32 m0, s17
	s_nop 0
	global_load_lds_dwordx4 v128, s[34:35]
	s_mov_b32 m0, s19
	s_nop 0
	global_load_lds_dwordx4 v132, s[34:35]
	s_waitcnt vmcnt(8)
	s_waitcnt lgkmcnt(0)
	s_barrier
	s_setprio 1
	s_waitcnt lgkmcnt(0)
	v_mfma_f32_16x16x32_bf16 v[60:63], v[144:147], v[188:191], 0
	v_mfma_f32_16x16x32_bf16 v[56:59], v[160:163], v[188:191], 0
	v_mfma_f32_16x16x32_bf16 v[44:47], v[144:147], v[196:199], 0
	v_mfma_f32_16x16x32_bf16 v[40:43], v[160:163], v[196:199], 0
	v_mfma_f32_16x16x32_bf16 v[28:31], v[144:147], v[204:207], 0
	v_mfma_f32_16x16x32_bf16 v[24:27], v[160:163], v[204:207], 0
	v_mfma_f32_16x16x32_bf16 v[12:15], v[144:147], v[212:215], 0
	v_mfma_f32_16x16x32_bf16 v[8:11], v[160:163], v[212:215], 0
	v_mfma_f32_16x16x32_bf16 v[60:63], v[156:159], v[192:195], v[60:63]
	v_mfma_f32_16x16x32_bf16 v[56:59], v[164:167], v[192:195], v[56:59]
	v_mfma_f32_16x16x32_bf16 v[44:47], v[156:159], v[200:203], v[44:47]
	v_mfma_f32_16x16x32_bf16 v[40:43], v[164:167], v[200:203], v[40:43]
	v_mfma_f32_16x16x32_bf16 v[28:31], v[156:159], v[208:211], v[28:31]
	v_mfma_f32_16x16x32_bf16 v[24:27], v[164:167], v[208:211], v[24:27]
	v_mfma_f32_16x16x32_bf16 v[12:15], v[156:159], v[216:219], v[12:15]
	v_mfma_f32_16x16x32_bf16 v[8:11], v[164:167], v[216:219], v[8:11]
	s_setprio 0
	s_setprio 1
	v_mfma_f32_16x16x32_bf16 v[52:55], v[168:171], v[188:191], 0
	v_mfma_f32_16x16x32_bf16 v[48:51], v[180:183], v[188:191], 0
	v_mfma_f32_16x16x32_bf16 v[36:39], v[168:171], v[196:199], 0
	v_mfma_f32_16x16x32_bf16 v[32:35], v[180:183], v[196:199], 0
	v_mfma_f32_16x16x32_bf16 v[20:23], v[168:171], v[204:207], 0
	v_mfma_f32_16x16x32_bf16 v[16:19], v[180:183], v[204:207], 0
	v_mfma_f32_16x16x32_bf16 v[4:7], v[168:171], v[212:215], 0
	v_mfma_f32_16x16x32_bf16 v[0:3], v[180:183], v[212:215], 0
	v_mfma_f32_16x16x32_bf16 v[52:55], v[172:175], v[192:195], v[52:55]
	v_mfma_f32_16x16x32_bf16 v[48:51], v[184:187], v[192:195], v[48:51]
	v_mfma_f32_16x16x32_bf16 v[36:39], v[172:175], v[200:203], v[36:39]
	v_mfma_f32_16x16x32_bf16 v[32:35], v[184:187], v[200:203], v[32:35]
	v_mfma_f32_16x16x32_bf16 v[20:23], v[172:175], v[208:211], v[20:23]
	v_mfma_f32_16x16x32_bf16 v[16:19], v[184:187], v[208:211], v[16:19]
	v_mfma_f32_16x16x32_bf16 v[4:7], v[172:175], v[216:219], v[4:7]
	v_mfma_f32_16x16x32_bf16 v[0:3], v[184:187], v[216:219], v[0:3]
	s_setprio 0
	s_barrier
; #define PG8_STAGE(bufoff, gbase, voff) do { _Pragma("unroll") for (int _i = 0; _i < 2; ++_i) \
;         __builtin_amdgcn_global_load_lds((const unsigned*)((const char*)(gbase) + (voff)[_i]), (PG8_LAS unsigned*)(lds + (bufoff) + ldsw + _i * 8192), 16, 0, 0); } while (0)
; #define PG8_LDA(dst, b, h) do { _Pragma("unroll") for (int m = 0; m < 4; ++m) _Pragma("unroll") for (int k = 0; k < 2; ++k) dst[m][k] = *(const PG8_LAS bf16x8*)(lds + PG8_SA(b, h) + aoff + m * 2048 + k * 1024); } while (0)
; #define PG8_LDB(dst, b, h) do { _Pragma("unroll") for (int n = 0; n < 2; ++n) _Pragma("unroll") for (int k = 0; k < 2; ++k) dst[n][k] = *(const PG8_LAS bf16x8*)(lds + PG8_SB(b, h) + boff + n * 2048 + k * 1024); } while (0)
; #define PG8_MMA(ai, bj, At, Bt) do { __builtin_amdgcn_s_setprio(1); _Pragma("unroll") for (int m = 0; m < 4; ++m) _Pragma("unroll") for (int n = 0; n < 2; ++n) _Pragma("unroll") for (int k = 0; k < 2; ++k) \
;         acc[ai][bj][m][n] = __builtin_amdgcn_mfma_f32_16x16x32_bf16(Bt[n][k], At[m][k], acc[ai][bj][m][n], 0, 0, 0); __builtin_amdgcn_s_setprio(0); } while (0)
; #define PG8_WAIT_V(n) asm volatile("s_waitcnt vmcnt(" #n ")" ::: "memory")
; #define PG8_WAIT_L(n) asm volatile("s_waitcnt lgkmcnt(" #n ")" ::: "memory")
; #define PG8_BAR __builtin_amdgcn_s_barrier()
; #define PG8_SCHED __builtin_amdgcn_sched_barrier(0)
; template <class Epi, class Sched, bool ALIGN_EPI = false, bool SP2 = false>
; __device__ __forceinline__ void gemm_phase(PG8_LAS unsigned char* lds, const Gemm g, const Sched& S, const Epi& E) {
;     ...
;             PG8_LDB(B0, 1, 0); PG8_LDB(B1, 1, 1); PG8_SCHED; PG8_LDA(At, 1, 0); PG8_STAGE(PG8_SA(0, 1), a2 + hstep, voffA);
;             PG8_WAIT_V(8); PG8_WAIT_L(0); PG8_BAR; PG8_MMA(0, 0, At, B0); PG8_MMA(0, 1, At, B1); PG8_BAR; PG8_SCHED;
;             PG8_LDA(At, 1, 1); PG8_STAGE(PG8_SB(1, 0), b3, voffB); PG8_STAGE(PG8_SB(1, 1), b3 + hstep, voffB); PG8_STAGE(PG8_SA(1, 0), a3, voffA);
;             PG8_WAIT_V(8); PG8_WAIT_L(0); PG8_BAR; PG8_MMA(1, 0, At, B0); PG8_MMA(1, 1, At, B1); PG8_BAR; PG8_SCHED;
	s_add_i32 s66, 0, 0x18000
	v_add_u32_e32 v155, s66, v149
	s_add_i32 s67, 0, 0x1c000
	ds_read_b128 v[144:147], v155
	ds_read_b128 v[156:159], v155 offset:1024
	ds_read_b128 v[160:163], v155 offset:2048
	ds_read_b128 v[164:167], v155 offset:3072
	v_add_u32_e32 v155, s67, v149
	ds_read_b128 v[168:171], v155
	ds_read_b128 v[172:175], v155 offset:1024
	ds_read_b128 v[180:183], v155 offset:2048
	ds_read_b128 v[184:187], v155 offset:3072
	s_add_u32 s34, s34, s6
	s_addc_u32 s35, s35, s7
	s_mov_b32 m0, s33
	ds_read_b128 v[188:191], v153 offset:32768
	ds_read_b128 v[192:195], v153 offset:33792
	ds_read_b128 v[196:199], v153 offset:34816
	ds_read_b128 v[200:203], v153 offset:35840
	ds_read_b128 v[204:207], v153 offset:36864
	ds_read_b128 v[208:211], v153 offset:37888
	ds_read_b128 v[212:215], v153 offset:38912
	ds_read_b128 v[216:219], v153 offset:39936
	global_load_lds_dwordx4 v128, s[34:35]
	s_mov_b32 m0, s36
	s_nop 0
	global_load_lds_dwordx4 v132, s[34:35]
	s_waitcnt vmcnt(8)
	s_waitcnt lgkmcnt(0)
	s_barrier
	s_setprio 1
	s_waitcnt lgkmcnt(0)
	v_mfma_f32_16x16x32_bf16 v[124:127], v[144:147], v[188:191], v[124:127]
	v_mfma_f32_16x16x32_bf16 v[120:123], v[160:163], v[188:191], v[120:123]
	v_mfma_f32_16x16x32_bf16 v[108:111], v[144:147], v[196:199], v[108:111]
	v_mfma_f32_16x16x32_bf16 v[104:107], v[160:163], v[196:199], v[104:107]
	v_mfma_f32_16x16x32_bf16 v[92:95], v[144:147], v[204:207], v[92:95]
	v_mfma_f32_16x16x32_bf16 v[88:91], v[160:163], v[204:207], v[88:91]
	v_mfma_f32_16x16x32_bf16 v[76:79], v[144:147], v[212:215], v[76:79]
	v_mfma_f32_16x16x32_bf16 v[72:75], v[160:163], v[212:215], v[72:75]
	v_mfma_f32_16x16x32_bf16 v[124:127], v[156:159], v[192:195], v[124:127]
	v_mfma_f32_16x16x32_bf16 v[120:123], v[164:167], v[192:195], v[120:123]
	v_mfma_f32_16x16x32_bf16 v[108:111], v[156:159], v[200:203], v[108:111]
	v_mfma_f32_16x16x32_bf16 v[104:107], v[164:167], v[200:203], v[104:107]
	v_mfma_f32_16x16x32_bf16 v[92:95], v[156:159], v[208:211], v[92:95]
	v_mfma_f32_16x16x32_bf16 v[88:91], v[164:167], v[208:211], v[88:91]
	v_mfma_f32_16x16x32_bf16 v[76:79], v[156:159], v[216:219], v[76:79]
	v_mfma_f32_16x16x32_bf16 v[72:75], v[164:167], v[216:219], v[72:75]
	s_setprio 0
	s_setprio 1
	v_mfma_f32_16x16x32_bf16 v[116:119], v[168:171], v[188:191], v[116:119]
	v_mfma_f32_16x16x32_bf16 v[112:115], v[180:183], v[188:191], v[112:115]
	v_mfma_f32_16x16x32_bf16 v[100:103], v[168:171], v[196:199], v[100:103]
	v_mfma_f32_16x16x32_bf16 v[96:99], v[180:183], v[196:199], v[96:99]
	v_mfma_f32_16x16x32_bf16 v[84:87], v[168:171], v[204:207], v[84:87]
	v_mfma_f32_16x16x32_bf16 v[80:83], v[180:183], v[204:207], v[80:83]
	v_mfma_f32_16x16x32_bf16 v[68:71], v[168:171], v[212:215], v[68:71]
	v_mfma_f32_16x16x32_bf16 v[64:67], v[180:183], v[212:215], v[64:67]
	v_mfma_f32_16x16x32_bf16 v[116:119], v[172:175], v[192:195], v[116:119]
	v_mfma_f32_16x16x32_bf16 v[112:115], v[184:187], v[192:195], v[112:115]
	v_mfma_f32_16x16x32_bf16 v[100:103], v[172:175], v[200:203], v[100:103]
	v_mfma_f32_16x16x32_bf16 v[96:99], v[184:187], v[200:203], v[96:99]
	v_mfma_f32_16x16x32_bf16 v[84:87], v[172:175], v[208:211], v[84:87]
	v_mfma_f32_16x16x32_bf16 v[80:83], v[184:187], v[208:211], v[80:83]
	v_mfma_f32_16x16x32_bf16 v[68:71], v[172:175], v[216:219], v[68:71]
	v_mfma_f32_16x16x32_bf16 v[64:67], v[184:187], v[216:219], v[64:67]
	s_setprio 0
	s_barrier
	s_add_i32 s34, s66, s16
	s_add_i32 m0, s34, 0xffffff80
	ds_read_b128 v[188:191], v153 offset:49152
	ds_read_b128 v[192:195], v153 offset:50176
	ds_read_b128 v[196:199], v153 offset:51200
	ds_read_b128 v[200:203], v153 offset:52224
	ds_read_b128 v[204:207], v153 offset:53248
	ds_read_b128 v[208:211], v153 offset:54272
	ds_read_b128 v[212:215], v153 offset:55296
	ds_read_b128 v[216:219], v153 offset:56320
	global_load_lds_dwordx4 v130, s[98:99] offset:128
	s_add_i32 m0, s34, 0x1f80
	s_add_i32 s34, s67, s16
	global_load_lds_dwordx4 v134, s[98:99] offset:128
	s_add_i32 m0, s34, 0xffffff80
	s_nop 0
	global_load_lds_dwordx4 v130, s[100:101] offset:128
	s_add_i32 m0, s34, 0x1f80
	s_nop 0
	global_load_lds_dwordx4 v134, s[100:101] offset:128
	s_add_i32 m0, s37, 0xffffff80
	s_nop 0
	global_load_lds_dwordx4 v128, s[22:23] offset:128
	s_add_i32 m0, s38, 0xffffff80
	s_nop 0
	global_load_lds_dwordx4 v132, s[22:23] offset:128
	s_waitcnt vmcnt(8)
	s_waitcnt lgkmcnt(0)
	s_barrier
	s_setprio 1
	s_waitcnt lgkmcnt(0)
	v_mfma_f32_16x16x32_bf16 v[60:63], v[144:147], v[188:191], v[60:63]
	v_mfma_f32_16x16x32_bf16 v[56:59], v[160:163], v[188:191], v[56:59]
	v_mfma_f32_16x16x32_bf16 v[44:47], v[144:147], v[196:199], v[44:47]
	v_mfma_f32_16x16x32_bf16 v[40:43], v[160:163], v[196:199], v[40:43]
	v_mfma_f32_16x16x32_bf16 v[28:31], v[144:147], v[204:207], v[28:31]
	v_mfma_f32_16x16x32_bf16 v[24:27], v[160:163], v[204:207], v[24:27]
	v_mfma_f32_16x16x32_bf16 v[12:15], v[144:147], v[212:215], v[12:15]
	v_mfma_f32_16x16x32_bf16 v[8:11], v[160:163], v[212:215], v[8:11]
	v_mfma_f32_16x16x32_bf16 v[60:63], v[156:159], v[192:195], v[60:63]
	v_mfma_f32_16x16x32_bf16 v[56:59], v[164:167], v[192:195], v[56:59]
	v_mfma_f32_16x16x32_bf16 v[44:47], v[156:159], v[200:203], v[44:47]
	v_mfma_f32_16x16x32_bf16 v[40:43], v[164:167], v[200:203], v[40:43]
	v_mfma_f32_16x16x32_bf16 v[28:31], v[156:159], v[208:211], v[28:31]
	v_mfma_f32_16x16x32_bf16 v[24:27], v[164:167], v[208:211], v[24:27]
	v_mfma_f32_16x16x32_bf16 v[12:15], v[156:159], v[216:219], v[12:15]
	v_mfma_f32_16x16x32_bf16 v[8:11], v[164:167], v[216:219], v[8:11]
	s_setprio 0
	s_setprio 1
	v_mfma_f32_16x16x32_bf16 v[52:55], v[168:171], v[188:191], v[52:55]
	v_mfma_f32_16x16x32_bf16 v[48:51], v[180:183], v[188:191], v[48:51]
	v_mfma_f32_16x16x32_bf16 v[36:39], v[168:171], v[196:199], v[36:39]
	v_mfma_f32_16x16x32_bf16 v[32:35], v[180:183], v[196:199], v[32:35]
	v_mfma_f32_16x16x32_bf16 v[20:23], v[168:171], v[204:207], v[20:23]
	v_mfma_f32_16x16x32_bf16 v[16:19], v[180:183], v[204:207], v[16:19]
	v_mfma_f32_16x16x32_bf16 v[4:7], v[168:171], v[212:215], v[4:7]
	v_mfma_f32_16x16x32_bf16 v[0:3], v[180:183], v[212:215], v[0:3]
	v_mfma_f32_16x16x32_bf16 v[52:55], v[172:175], v[192:195], v[52:55]
	v_mfma_f32_16x16x32_bf16 v[48:51], v[184:187], v[192:195], v[48:51]
	v_mfma_f32_16x16x32_bf16 v[36:39], v[172:175], v[200:203], v[36:39]
	v_mfma_f32_16x16x32_bf16 v[32:35], v[184:187], v[200:203], v[32:35]
	v_mfma_f32_16x16x32_bf16 v[20:23], v[172:175], v[208:211], v[20:23]
	v_mfma_f32_16x16x32_bf16 v[16:19], v[184:187], v[208:211], v[16:19]
	v_mfma_f32_16x16x32_bf16 v[4:7], v[172:175], v[216:219], v[4:7]
	v_mfma_f32_16x16x32_bf16 v[0:3], v[184:187], v[216:219], v[0:3]
	s_setprio 0
	s_barrier
	s_add_u32 s30, s30, 0x100
	s_addc_u32 s31, s31, 0
	s_add_u32 s63, s63, 0x100
	s_addc_u32 s64, s64, 0
	s_cmp_ge_i32 s65, s40
	s_mov_b32 s34, s65
	s_cbranch_scc0 .LBB0_1222
	s_branch .Lpeel_x3
; #define PG8_STAGE(bufoff, gbase, voff) do { _Pragma("unroll") for (int _i = 0; _i < 2; ++_i) \
;         __builtin_amdgcn_global_load_lds((const unsigned*)((const char*)(gbase) + (voff)[_i]), (PG8_LAS unsigned*)(lds + (bufoff) + ldsw + _i * 8192), 16, 0, 0); } while (0)
; #define PG8_LDA(dst, b, h) do { _Pragma("unroll") for (int m = 0; m < 4; ++m) _Pragma("unroll") for (int k = 0; k < 2; ++k) dst[m][k] = *(const PG8_LAS bf16x8*)(lds + PG8_SA(b, h) + aoff + m * 2048 + k * 1024); } while (0)
; #define PG8_LDB(dst, b, h) do { _Pragma("unroll") for (int n = 0; n < 2; ++n) _Pragma("unroll") for (int k = 0; k < 2; ++k) dst[n][k] = *(const PG8_LAS bf16x8*)(lds + PG8_SB(b, h) + boff + n * 2048 + k * 1024); } while (0)
; #define PG8_MMA(ai, bj, At, Bt) do { __builtin_amdgcn_s_setprio(1); _Pragma("unroll") for (int m = 0; m < 4; ++m) _Pragma("unroll") for (int n = 0; n < 2; ++n) _Pragma("unroll") for (int k = 0; k < 2; ++k) \
;         acc[ai][bj][m][n] = __builtin_amdgcn_mfma_f32_16x16x32_bf16(Bt[n][k], At[m][k], acc[ai][bj][m][n], 0, 0, 0); __builtin_amdgcn_s_setprio(0); } while (0)
; #define PG8_WAIT_V(n) asm volatile("s_waitcnt vmcnt(" #n ")" ::: "memory")
; #define PG8_BAR __builtin_amdgcn_s_barrier()
; template <class Epi, class Sched, bool ALIGN_EPI = false, bool SP2 = false>
; __device__ __forceinline__ void gemm_phase(PG8_LAS unsigned char* lds, const Gemm g, const Sched& S, const Epi& E) {
;     ...
;         for (int t = 0; t < nt; t += 2) {
;             const bool last = (t == nt - 2);
;             const char* a1 = cA + (size_t)(t + 1) * kstep;
;             const char* a2 = last ? nA : cA + (size_t)(t + 2) * kstep; const char* b2 = last ? nB : cB + (size_t)(t + 2) * kstep;
;             const char* a3 = a2 + kstep; const char* b3 = b2 + kstep;
;             if (last && has_next) S.a_ready(nxt);
;             if constexpr (SP2) {
;             PG8_LDB(B0, 0, 0); PG8_LDB(B1, 0, 1); PG8_SCHED; PG8_LDA(At, 0, 0); PG8_STAGE(PG8_SA(1, 1), a1 + hstep, voffA);
;             PG8_WAIT_V(8); PG8_WAIT_L(0); PG8_BAR; PG8_MMA(0, 0, At, B0); PG8_MMA(0, 1, At, B1); PG8_BAR; PG8_SCHED;
;             PG8_LDA(At, 0, 1); PG8_STAGE(PG8_SB(0, 0), b2, voffB); PG8_STAGE(PG8_SB(0, 1), b2 + hstep, voffB); PG8_STAGE(PG8_SA(0, 0), a2, voffA);
;             PG8_WAIT_V(8); PG8_WAIT_L(0); PG8_BAR; PG8_MMA(1, 0, At, B0); PG8_MMA(1, 1, At, B1); PG8_BAR; PG8_SCHED;
.LBB0_1222:
	ds_read_b128 v[144:147], v151
	ds_read_b128 v[156:159], v151 offset:1024
	ds_read_b128 v[160:163], v151 offset:2048
	ds_read_b128 v[164:167], v151 offset:3072
	ds_read_b128 v[168:171], v152
	ds_read_b128 v[172:175], v152 offset:1024
	ds_read_b128 v[180:183], v152 offset:2048
	ds_read_b128 v[184:187], v152 offset:3072
	s_add_i32 s65, s34, 2
	s_add_u32 s66, s30, 0x80
	s_addc_u32 s35, s31, 0
	s_cmp_eq_u32 s41, s34
	s_cselect_b32 s34, s0, s66
	s_cselect_b32 s35, s1, s35
	s_cselect_b32 s67, s29, s64
	s_cselect_b32 s66, s28, s63
	s_add_i32 m0, s17, 0xc000
	ds_read_b128 v[188:191], v153
	ds_read_b128 v[192:195], v153 offset:1024
	ds_read_b128 v[196:199], v153 offset:2048
	ds_read_b128 v[200:203], v153 offset:3072
	ds_read_b128 v[204:207], v153 offset:4096
	ds_read_b128 v[208:211], v153 offset:5120
	ds_read_b128 v[212:215], v153 offset:6144
	ds_read_b128 v[216:219], v153 offset:7168
	global_load_lds_dwordx4 v136, s[30:31]
	s_add_i32 m0, s17, 0xe000
	s_nop 0
	global_load_lds_dwordx4 v138, s[30:31]
	s_waitcnt vmcnt(8)
	s_waitcnt lgkmcnt(0)
	s_barrier
	s_setprio 1
	s_waitcnt lgkmcnt(0)
	v_mfma_f32_16x16x32_bf16 v[124:127], v[144:147], v[188:191], v[124:127]
	v_mfma_f32_16x16x32_bf16 v[120:123], v[160:163], v[188:191], v[120:123]
	v_mfma_f32_16x16x32_bf16 v[108:111], v[144:147], v[196:199], v[108:111]
	v_mfma_f32_16x16x32_bf16 v[104:107], v[160:163], v[196:199], v[104:107]
	v_mfma_f32_16x16x32_bf16 v[92:95], v[144:147], v[204:207], v[92:95]
	v_mfma_f32_16x16x32_bf16 v[88:91], v[160:163], v[204:207], v[88:91]
	v_mfma_f32_16x16x32_bf16 v[76:79], v[144:147], v[212:215], v[76:79]
	v_mfma_f32_16x16x32_bf16 v[72:75], v[160:163], v[212:215], v[72:75]
	v_mfma_f32_16x16x32_bf16 v[124:127], v[156:159], v[192:195], v[124:127]
	v_mfma_f32_16x16x32_bf16 v[120:123], v[164:167], v[192:195], v[120:123]
	v_mfma_f32_16x16x32_bf16 v[108:111], v[156:159], v[200:203], v[108:111]
	v_mfma_f32_16x16x32_bf16 v[104:107], v[164:167], v[200:203], v[104:107]
	v_mfma_f32_16x16x32_bf16 v[92:95], v[156:159], v[208:211], v[92:95]
	v_mfma_f32_16x16x32_bf16 v[88:91], v[164:167], v[208:211], v[88:91]
	v_mfma_f32_16x16x32_bf16 v[76:79], v[156:159], v[216:219], v[76:79]
	v_mfma_f32_16x16x32_bf16 v[72:75], v[164:167], v[216:219], v[72:75]
	s_setprio 0
	s_setprio 1
	v_mfma_f32_16x16x32_bf16 v[116:119], v[168:171], v[188:191], v[116:119]
	v_mfma_f32_16x16x32_bf16 v[112:115], v[180:183], v[188:191], v[112:115]
	v_mfma_f32_16x16x32_bf16 v[100:103], v[168:171], v[196:199], v[100:103]
	v_mfma_f32_16x16x32_bf16 v[96:99], v[180:183], v[196:199], v[96:99]
	v_mfma_f32_16x16x32_bf16 v[84:87], v[168:171], v[204:207], v[84:87]
	v_mfma_f32_16x16x32_bf16 v[80:83], v[180:183], v[204:207], v[80:83]
	v_mfma_f32_16x16x32_bf16 v[68:71], v[168:171], v[212:215], v[68:71]
	v_mfma_f32_16x16x32_bf16 v[64:67], v[180:183], v[212:215], v[64:67]
	v_mfma_f32_16x16x32_bf16 v[116:119], v[172:175], v[192:195], v[116:119]
	v_mfma_f32_16x16x32_bf16 v[112:115], v[184:187], v[192:195], v[112:115]
	v_mfma_f32_16x16x32_bf16 v[100:103], v[172:175], v[200:203], v[100:103]
	v_mfma_f32_16x16x32_bf16 v[96:99], v[184:187], v[200:203], v[96:99]
	v_mfma_f32_16x16x32_bf16 v[84:87], v[172:175], v[208:211], v[84:87]
	v_mfma_f32_16x16x32_bf16 v[80:83], v[184:187], v[208:211], v[80:83]
	v_mfma_f32_16x16x32_bf16 v[68:71], v[172:175], v[216:219], v[68:71]
	v_mfma_f32_16x16x32_bf16 v[64:67], v[184:187], v[216:219], v[64:67]
	s_setprio 0
	s_barrier
	s_add_i32 s68, s57, s16
	s_mov_b64 s[98:99], s[66:67]
	s_mov_b32 m0, s68
	ds_read_b128 v[188:191], v153 offset:16384
	ds_read_b128 v[192:195], v153 offset:17408
	ds_read_b128 v[196:199], v153 offset:18432
	ds_read_b128 v[200:203], v153 offset:19456
	ds_read_b128 v[204:207], v153 offset:20480
	ds_read_b128 v[208:211], v153 offset:21504
	ds_read_b128 v[212:215], v153 offset:22528
	ds_read_b128 v[216:219], v153 offset:23552
	global_load_lds_dwordx4 v130, s[66:67]
	s_add_i32 m0, s68, 0x2000
	s_add_u32 s66, s66, s6
	s_addc_u32 s67, s67, s7
	s_add_i32 s68, s58, s16
	global_load_lds_dwordx4 v134, s[98:99]
	s_mov_b64 s[100:101], s[66:67]
	s_mov_b32 m0, s68
	s_nop 0
	global_load_lds_dwordx4 v130, s[66:67]
	s_add_i32 m0, s68, 0x2000
	s_mov_b64 s[22:23], s[34:35]
	global_load_lds_dwordx4 v134, s[66:67]
	s_mov_b32 m0, s17
	s_nop 0
	global_load_lds_dwordx4 v128, s[34:35]
	s_mov_b32 m0, s19
	s_nop 0
	global_load_lds_dwordx4 v132, s[34:35]
	s_waitcnt vmcnt(8)
	s_waitcnt lgkmcnt(0)
	s_barrier
	s_setprio 1
	s_waitcnt lgkmcnt(0)
	v_mfma_f32_16x16x32_bf16 v[60:63], v[144:147], v[188:191], v[60:63]
	v_mfma_f32_16x16x32_bf16 v[56:59], v[160:163], v[188:191], v[56:59]
	v_mfma_f32_16x16x32_bf16 v[44:47], v[144:147], v[196:199], v[44:47]
	v_mfma_f32_16x16x32_bf16 v[40:43], v[160:163], v[196:199], v[40:43]
	v_mfma_f32_16x16x32_bf16 v[28:31], v[144:147], v[204:207], v[28:31]
	v_mfma_f32_16x16x32_bf16 v[24:27], v[160:163], v[204:207], v[24:27]
	v_mfma_f32_16x16x32_bf16 v[12:15], v[144:147], v[212:215], v[12:15]
	v_mfma_f32_16x16x32_bf16 v[8:11], v[160:163], v[212:215], v[8:11]
	v_mfma_f32_16x16x32_bf16 v[60:63], v[156:159], v[192:195], v[60:63]
	v_mfma_f32_16x16x32_bf16 v[56:59], v[164:167], v[192:195], v[56:59]
	v_mfma_f32_16x16x32_bf16 v[44:47], v[156:159], v[200:203], v[44:47]
	v_mfma_f32_16x16x32_bf16 v[40:43], v[164:167], v[200:203], v[40:43]
	v_mfma_f32_16x16x32_bf16 v[28:31], v[156:159], v[208:211], v[28:31]
	v_mfma_f32_16x16x32_bf16 v[24:27], v[164:167], v[208:211], v[24:27]
	v_mfma_f32_16x16x32_bf16 v[12:15], v[156:159], v[216:219], v[12:15]
	v_mfma_f32_16x16x32_bf16 v[8:11], v[164:167], v[216:219], v[8:11]
	s_setprio 0
	s_setprio 1
	v_mfma_f32_16x16x32_bf16 v[52:55], v[168:171], v[188:191], v[52:55]
	v_mfma_f32_16x16x32_bf16 v[48:51], v[180:183], v[188:191], v[48:51]
	v_mfma_f32_16x16x32_bf16 v[36:39], v[168:171], v[196:199], v[36:39]
	v_mfma_f32_16x16x32_bf16 v[32:35], v[180:183], v[196:199], v[32:35]
	v_mfma_f32_16x16x32_bf16 v[20:23], v[168:171], v[204:207], v[20:23]
	v_mfma_f32_16x16x32_bf16 v[16:19], v[180:183], v[204:207], v[16:19]
	v_mfma_f32_16x16x32_bf16 v[4:7], v[168:171], v[212:215], v[4:7]
	v_mfma_f32_16x16x32_bf16 v[0:3], v[180:183], v[212:215], v[0:3]
	v_mfma_f32_16x16x32_bf16 v[52:55], v[172:175], v[192:195], v[52:55]
	v_mfma_f32_16x16x32_bf16 v[48:51], v[184:187], v[192:195], v[48:51]
	v_mfma_f32_16x16x32_bf16 v[36:39], v[172:175], v[200:203], v[36:39]
	v_mfma_f32_16x16x32_bf16 v[32:35], v[184:187], v[200:203], v[32:35]
	v_mfma_f32_16x16x32_bf16 v[20:23], v[172:175], v[208:211], v[20:23]
	v_mfma_f32_16x16x32_bf16 v[16:19], v[184:187], v[208:211], v[16:19]
	v_mfma_f32_16x16x32_bf16 v[4:7], v[172:175], v[216:219], v[4:7]
	v_mfma_f32_16x16x32_bf16 v[0:3], v[184:187], v[216:219], v[0:3]
	s_setprio 0
	s_barrier
; #define PG8_STAGE(bufoff, gbase, voff) do { _Pragma("unroll") for (int _i = 0; _i < 2; ++_i) \
;         __builtin_amdgcn_global_load_lds((const unsigned*)((const char*)(gbase) + (voff)[_i]), (PG8_LAS unsigned*)(lds + (bufoff) + ldsw + _i * 8192), 16, 0, 0); } while (0)
; #define PG8_LDA(dst, b, h) do { _Pragma("unroll") for (int m = 0; m < 4; ++m) _Pragma("unroll") for (int k = 0; k < 2; ++k) dst[m][k] = *(const PG8_LAS bf16x8*)(lds + PG8_SA(b, h) + aoff + m * 2048 + k * 1024); } while (0)
; #define PG8_LDB(dst, b, h) do { _Pragma("unroll") for (int n = 0; n < 2; ++n) _Pragma("unroll") for (int k = 0; k < 2; ++k) dst[n][k] = *(const PG8_LAS bf16x8*)(lds + PG8_SB(b, h) + boff + n * 2048 + k * 1024); } while (0)
; #define PG8_MMA(ai, bj, At, Bt) do { __builtin_amdgcn_s_setprio(1); _Pragma("unroll") for (int m = 0; m < 4; ++m) _Pragma("unroll") for (int n = 0; n < 2; ++n) _Pragma("unroll") for (int k = 0; k < 2; ++k) \
;         acc[ai][bj][m][n] = __builtin_amdgcn_mfma_f32_16x16x32_bf16(Bt[n][k], At[m][k], acc[ai][bj][m][n], 0, 0, 0); __builtin_amdgcn_s_setprio(0); } while (0)
; #define PG8_WAIT_V(n) asm volatile("s_waitcnt vmcnt(" #n ")" ::: "memory")
; #define PG8_WAIT_L(n) asm volatile("s_waitcnt lgkmcnt(" #n ")" ::: "memory")
; #define PG8_BAR __builtin_amdgcn_s_barrier()
; #define PG8_SCHED __builtin_amdgcn_sched_barrier(0)
; template <class Epi, class Sched, bool ALIGN_EPI = false, bool SP2 = false>
; __device__ __forceinline__ void gemm_phase(PG8_LAS unsigned char* lds, const Gemm g, const Sched& S, const Epi& E) {
;     ...
;             PG8_LDB(B0, 1, 0); PG8_LDB(B1, 1, 1); PG8_SCHED; PG8_LDA(At, 1, 0); PG8_STAGE(PG8_SA(0, 1), a2 + hstep, voffA);
;             PG8_WAIT_V(8); PG8_WAIT_L(0); PG8_BAR; PG8_MMA(0, 0, At, B0); PG8_MMA(0, 1, At, B1); PG8_BAR; PG8_SCHED;
;             PG8_LDA(At, 1, 1); PG8_STAGE(PG8_SB(1, 0), b3, voffB); PG8_STAGE(PG8_SB(1, 1), b3 + hstep, voffB); PG8_STAGE(PG8_SA(1, 0), a3, voffA);
;             PG8_WAIT_V(8); PG8_WAIT_L(0); PG8_BAR; PG8_MMA(1, 0, At, B0); PG8_MMA(1, 1, At, B1); PG8_BAR; PG8_SCHED;
	s_add_i32 s66, 0, 0x18000
	v_add_u32_e32 v155, s66, v149
	s_add_i32 s67, 0, 0x1c000
	ds_read_b128 v[144:147], v155
	ds_read_b128 v[156:159], v155 offset:1024
	ds_read_b128 v[160:163], v155 offset:2048
	ds_read_b128 v[164:167], v155 offset:3072
	v_add_u32_e32 v155, s67, v149
	ds_read_b128 v[168:171], v155
	ds_read_b128 v[172:175], v155 offset:1024
	ds_read_b128 v[180:183], v155 offset:2048
	ds_read_b128 v[184:187], v155 offset:3072
	s_add_u32 s34, s34, s6
	s_addc_u32 s35, s35, s7
	s_mov_b32 m0, s33
	ds_read_b128 v[188:191], v153 offset:32768
	ds_read_b128 v[192:195], v153 offset:33792
	ds_read_b128 v[196:199], v153 offset:34816
	ds_read_b128 v[200:203], v153 offset:35840
	ds_read_b128 v[204:207], v153 offset:36864
	ds_read_b128 v[208:211], v153 offset:37888
	ds_read_b128 v[212:215], v153 offset:38912
	ds_read_b128 v[216:219], v153 offset:39936
	global_load_lds_dwordx4 v128, s[34:35]
	s_mov_b32 m0, s36
	s_nop 0
	global_load_lds_dwordx4 v132, s[34:35]
	s_waitcnt vmcnt(8)
	s_waitcnt lgkmcnt(0)
	s_barrier
	s_setprio 1
	s_waitcnt lgkmcnt(0)
	v_mfma_f32_16x16x32_bf16 v[124:127], v[144:147], v[188:191], v[124:127]
	v_mfma_f32_16x16x32_bf16 v[120:123], v[160:163], v[188:191], v[120:123]
	v_mfma_f32_16x16x32_bf16 v[108:111], v[144:147], v[196:199], v[108:111]
	v_mfma_f32_16x16x32_bf16 v[104:107], v[160:163], v[196:199], v[104:107]
	v_mfma_f32_16x16x32_bf16 v[92:95], v[144:147], v[204:207], v[92:95]
	v_mfma_f32_16x16x32_bf16 v[88:91], v[160:163], v[204:207], v[88:91]
	v_mfma_f32_16x16x32_bf16 v[76:79], v[144:147], v[212:215], v[76:79]
	v_mfma_f32_16x16x32_bf16 v[72:75], v[160:163], v[212:215], v[72:75]
	v_mfma_f32_16x16x32_bf16 v[124:127], v[156:159], v[192:195], v[124:127]
	v_mfma_f32_16x16x32_bf16 v[120:123], v[164:167], v[192:195], v[120:123]
	v_mfma_f32_16x16x32_bf16 v[108:111], v[156:159], v[200:203], v[108:111]
	v_mfma_f32_16x16x32_bf16 v[104:107], v[164:167], v[200:203], v[104:107]
	v_mfma_f32_16x16x32_bf16 v[92:95], v[156:159], v[208:211], v[92:95]
	v_mfma_f32_16x16x32_bf16 v[88:91], v[164:167], v[208:211], v[88:91]
	v_mfma_f32_16x16x32_bf16 v[76:79], v[156:159], v[216:219], v[76:79]
	v_mfma_f32_16x16x32_bf16 v[72:75], v[164:167], v[216:219], v[72:75]
	s_setprio 0
	s_setprio 1
	v_mfma_f32_16x16x32_bf16 v[116:119], v[168:171], v[188:191], v[116:119]
	v_mfma_f32_16x16x32_bf16 v[112:115], v[180:183], v[188:191], v[112:115]
	v_mfma_f32_16x16x32_bf16 v[100:103], v[168:171], v[196:199], v[100:103]
	v_mfma_f32_16x16x32_bf16 v[96:99], v[180:183], v[196:199], v[96:99]
	v_mfma_f32_16x16x32_bf16 v[84:87], v[168:171], v[204:207], v[84:87]
	v_mfma_f32_16x16x32_bf16 v[80:83], v[180:183], v[204:207], v[80:83]
	v_mfma_f32_16x16x32_bf16 v[68:71], v[168:171], v[212:215], v[68:71]
	v_mfma_f32_16x16x32_bf16 v[64:67], v[180:183], v[212:215], v[64:67]
	v_mfma_f32_16x16x32_bf16 v[116:119], v[172:175], v[192:195], v[116:119]
	v_mfma_f32_16x16x32_bf16 v[112:115], v[184:187], v[192:195], v[112:115]
	v_mfma_f32_16x16x32_bf16 v[100:103], v[172:175], v[200:203], v[100:103]
	v_mfma_f32_16x16x32_bf16 v[96:99], v[184:187], v[200:203], v[96:99]
	v_mfma_f32_16x16x32_bf16 v[84:87], v[172:175], v[208:211], v[84:87]
	v_mfma_f32_16x16x32_bf16 v[80:83], v[184:187], v[208:211], v[80:83]
	v_mfma_f32_16x16x32_bf16 v[68:71], v[172:175], v[216:219], v[68:71]
	v_mfma_f32_16x16x32_bf16 v[64:67], v[184:187], v[216:219], v[64:67]
	s_setprio 0
	s_barrier
	s_add_i32 s34, s66, s16
	s_add_i32 m0, s34, 0xffffff80
	ds_read_b128 v[188:191], v153 offset:49152
	ds_read_b128 v[192:195], v153 offset:50176
	ds_read_b128 v[196:199], v153 offset:51200
	ds_read_b128 v[200:203], v153 offset:52224
	ds_read_b128 v[204:207], v153 offset:53248
	ds_read_b128 v[208:211], v153 offset:54272
	ds_read_b128 v[212:215], v153 offset:55296
	ds_read_b128 v[216:219], v153 offset:56320
	global_load_lds_dwordx4 v130, s[98:99] offset:128
	s_add_i32 m0, s34, 0x1f80
	s_add_i32 s34, s67, s16
	global_load_lds_dwordx4 v134, s[98:99] offset:128
	s_add_i32 m0, s34, 0xffffff80
	s_nop 0
	global_load_lds_dwordx4 v130, s[100:101] offset:128
	s_add_i32 m0, s34, 0x1f80
	s_nop 0
	global_load_lds_dwordx4 v134, s[100:101] offset:128
	s_add_i32 m0, s37, 0xffffff80
	s_nop 0
	global_load_lds_dwordx4 v128, s[22:23] offset:128
	s_add_i32 m0, s38, 0xffffff80
	s_nop 0
	global_load_lds_dwordx4 v132, s[22:23] offset:128
	s_waitcnt vmcnt(8)
	s_waitcnt lgkmcnt(0)
	s_barrier
	s_setprio 1
	s_waitcnt lgkmcnt(0)
	v_mfma_f32_16x16x32_bf16 v[60:63], v[144:147], v[188:191], v[60:63]
	v_mfma_f32_16x16x32_bf16 v[56:59], v[160:163], v[188:191], v[56:59]
	v_mfma_f32_16x16x32_bf16 v[44:47], v[144:147], v[196:199], v[44:47]
	v_mfma_f32_16x16x32_bf16 v[40:43], v[160:163], v[196:199], v[40:43]
	v_mfma_f32_16x16x32_bf16 v[28:31], v[144:147], v[204:207], v[28:31]
	v_mfma_f32_16x16x32_bf16 v[24:27], v[160:163], v[204:207], v[24:27]
	v_mfma_f32_16x16x32_bf16 v[12:15], v[144:147], v[212:215], v[12:15]
	v_mfma_f32_16x16x32_bf16 v[8:11], v[160:163], v[212:215], v[8:11]
	v_mfma_f32_16x16x32_bf16 v[60:63], v[156:159], v[192:195], v[60:63]
	v_mfma_f32_16x16x32_bf16 v[56:59], v[164:167], v[192:195], v[56:59]
	v_mfma_f32_16x16x32_bf16 v[44:47], v[156:159], v[200:203], v[44:47]
	v_mfma_f32_16x16x32_bf16 v[40:43], v[164:167], v[200:203], v[40:43]
	v_mfma_f32_16x16x32_bf16 v[28:31], v[156:159], v[208:211], v[28:31]
	v_mfma_f32_16x16x32_bf16 v[24:27], v[164:167], v[208:211], v[24:27]
	v_mfma_f32_16x16x32_bf16 v[12:15], v[156:159], v[216:219], v[12:15]
	v_mfma_f32_16x16x32_bf16 v[8:11], v[164:167], v[216:219], v[8:11]
	s_setprio 0
	s_setprio 1
	v_mfma_f32_16x16x32_bf16 v[52:55], v[168:171], v[188:191], v[52:55]
	v_mfma_f32_16x16x32_bf16 v[48:51], v[180:183], v[188:191], v[48:51]
	v_mfma_f32_16x16x32_bf16 v[36:39], v[168:171], v[196:199], v[36:39]
	v_mfma_f32_16x16x32_bf16 v[32:35], v[180:183], v[196:199], v[32:35]
	v_mfma_f32_16x16x32_bf16 v[20:23], v[168:171], v[204:207], v[20:23]
	v_mfma_f32_16x16x32_bf16 v[16:19], v[180:183], v[204:207], v[16:19]
	v_mfma_f32_16x16x32_bf16 v[4:7], v[168:171], v[212:215], v[4:7]
	v_mfma_f32_16x16x32_bf16 v[0:3], v[180:183], v[212:215], v[0:3]
	v_mfma_f32_16x16x32_bf16 v[52:55], v[172:175], v[192:195], v[52:55]
	v_mfma_f32_16x16x32_bf16 v[48:51], v[184:187], v[192:195], v[48:51]
	v_mfma_f32_16x16x32_bf16 v[36:39], v[172:175], v[200:203], v[36:39]
	v_mfma_f32_16x16x32_bf16 v[32:35], v[184:187], v[200:203], v[32:35]
	v_mfma_f32_16x16x32_bf16 v[20:23], v[172:175], v[208:211], v[20:23]
	v_mfma_f32_16x16x32_bf16 v[16:19], v[184:187], v[208:211], v[16:19]
	v_mfma_f32_16x16x32_bf16 v[4:7], v[172:175], v[216:219], v[4:7]
	v_mfma_f32_16x16x32_bf16 v[0:3], v[184:187], v[216:219], v[0:3]
	s_setprio 0
	s_barrier
	s_add_u32 s30, s30, 0x100
	s_addc_u32 s31, s31, 0
	s_add_u32 s63, s63, 0x100
	s_addc_u32 s64, s64, 0
	s_cmp_ge_i32 s65, s40
	s_mov_b32 s34, s65
	s_cbranch_scc0 .LBB0_1222

; #define PG8_STAGE(bufoff, gbase, voff) do { _Pragma("unroll") for (int _i = 0; _i < 2; ++_i) \
;         __builtin_amdgcn_global_load_lds((const unsigned*)((const char*)(gbase) + (voff)[_i]), (PG8_LAS unsigned*)(lds + (bufoff) + ldsw + _i * 8192), 16, 0, 0); } while (0)
; #define PG8_LDA(dst, b, h) do { _Pragma("unroll") for (int m = 0; m < 4; ++m) _Pragma("unroll") for (int k = 0; k < 2; ++k) dst[m][k] = *(const PG8_LAS bf16x8*)(lds + PG8_SA(b, h) + aoff + m * 2048 + k * 1024); } while (0)
; #define PG8_LDB(dst, b, h) do { _Pragma("unroll") for (int n = 0; n < 2; ++n) _Pragma("unroll") for (int k = 0; k < 2; ++k) dst[n][k] = *(const PG8_LAS bf16x8*)(lds + PG8_SB(b, h) + boff + n * 2048 + k * 1024); } while (0)
; #define PG8_MMA(ai, bj, At, Bt) do { __builtin_amdgcn_s_setprio(1); _Pragma("unroll") for (int m = 0; m < 4; ++m) _Pragma("unroll") for (int n = 0; n < 2; ++n) _Pragma("unroll") for (int k = 0; k < 2; ++k) \
;         acc[ai][bj][m][n] = __builtin_amdgcn_mfma_f32_16x16x32_bf16(Bt[n][k], At[m][k], acc[ai][bj][m][n], 0, 0, 0); __builtin_amdgcn_s_setprio(0); } while (0)
; #define PG8_WAIT_V(n) asm volatile("s_waitcnt vmcnt(" #n ")" ::: "memory")
; #define PG8_BAR __builtin_amdgcn_s_barrier()
; template <class Epi, class Sched, bool ALIGN_EPI = false, bool SP2 = false>
; __device__ __forceinline__ void gemm_phase(PG8_LAS unsigned char* lds, const Gemm g, const Sched& S, const Epi& E) {
;     ...
;         for (int t = 0; t < nt; t += 2) {
;             const bool last = (t == nt - 2);
;             const char* a1 = cA + (size_t)(t + 1) * kstep;
;             const char* a2 = last ? nA : cA + (size_t)(t + 2) * kstep; const char* b2 = last ? nB : cB + (size_t)(t + 2) * kstep;
;             const char* a3 = a2 + kstep; const char* b3 = b2 + kstep;
;             if (last && has_next) S.a_ready(nxt);
;             if constexpr (SP2) {
;             PG8_LDB(B0, 0, 0); PG8_LDB(B1, 0, 1); PG8_SCHED; PG8_LDA(At, 0, 0); PG8_STAGE(PG8_SA(1, 1), a1 + hstep, voffA);
;             PG8_WAIT_V(8); PG8_WAIT_L(0); PG8_BAR; PG8_MMA(0, 0, At, B0); PG8_MMA(0, 1, At, B1); PG8_BAR; PG8_SCHED;
;             PG8_LDA(At, 0, 1); PG8_STAGE(PG8_SB(0, 0), b2, voffB); PG8_STAGE(PG8_SB(0, 1), b2 + hstep, voffB); PG8_STAGE(PG8_SA(0, 0), a2, voffA);
;             PG8_WAIT_V(8); PG8_WAIT_L(0); PG8_BAR; PG8_MMA(1, 0, At, B0); PG8_MMA(1, 1, At, B1); PG8_BAR; PG8_SCHED;
.LBB0_1315:
	s_andn2_b64 vcc, exec, s[20:21]
	s_waitcnt vmcnt(0)
	s_cbranch_vccnz .LBB0_1318
	s_add_u32 s26, s26, 0x80
	s_addc_u32 s27, s27, 0
	s_add_u32 s62, s28, 0x100
	s_addc_u32 s63, s29, 0
	s_mov_b32 s28, 0
	ds_read_b128 v[154:157], v149
	ds_read_b128 v[158:161], v149 offset:1024
	ds_read_b128 v[162:165], v149 offset:2048
	ds_read_b128 v[166:169], v149 offset:3072
	ds_read_b128 v[170:173], v150
	ds_read_b128 v[174:177], v150 offset:1024
	ds_read_b128 v[180:183], v150 offset:2048
	ds_read_b128 v[184:187], v150 offset:3072
	s_add_i32 s64, s28, 2
	s_add_u32 s65, s26, 0x80
	s_addc_u32 s29, s27, 0
	s_cmp_eq_u32 s39, s28
	s_cselect_b32 s28, s0, s65
	s_cselect_b32 s29, s1, s29
	s_cselect_b32 s67, s25, s63
	s_cselect_b32 s66, s24, s62
	s_add_i32 m0, s30, 0xc000
	ds_read_b128 v[188:191], v151
	ds_read_b128 v[192:195], v151 offset:1024
	ds_read_b128 v[196:199], v151 offset:2048
	ds_read_b128 v[200:203], v151 offset:3072
	ds_read_b128 v[204:207], v151 offset:4096
	ds_read_b128 v[208:211], v151 offset:5120
	ds_read_b128 v[212:215], v151 offset:6144
	ds_read_b128 v[216:219], v151 offset:7168
	global_load_lds_dwordx4 v136, s[26:27]
	s_add_i32 m0, s30, 0xe000
	s_nop 0
	global_load_lds_dwordx4 v138, s[26:27]
	s_waitcnt vmcnt(8)
	s_waitcnt lgkmcnt(0)
	s_barrier
	s_setprio 1
	s_waitcnt lgkmcnt(0)
	v_mfma_f32_16x16x32_bf16 v[116:119], v[154:157], v[188:191], 0
	v_mfma_f32_16x16x32_bf16 v[112:115], v[162:165], v[188:191], 0
	v_mfma_f32_16x16x32_bf16 v[100:103], v[154:157], v[196:199], 0
	v_mfma_f32_16x16x32_bf16 v[96:99], v[162:165], v[196:199], 0
	v_mfma_f32_16x16x32_bf16 v[84:87], v[154:157], v[204:207], 0
	v_mfma_f32_16x16x32_bf16 v[80:83], v[162:165], v[204:207], 0
	v_mfma_f32_16x16x32_bf16 v[68:71], v[154:157], v[212:215], 0
	v_mfma_f32_16x16x32_bf16 v[64:67], v[162:165], v[212:215], 0
	v_mfma_f32_16x16x32_bf16 v[116:119], v[158:161], v[192:195], v[116:119]
	v_mfma_f32_16x16x32_bf16 v[112:115], v[166:169], v[192:195], v[112:115]
	v_mfma_f32_16x16x32_bf16 v[100:103], v[158:161], v[200:203], v[100:103]
	v_mfma_f32_16x16x32_bf16 v[96:99], v[166:169], v[200:203], v[96:99]
	v_mfma_f32_16x16x32_bf16 v[84:87], v[158:161], v[208:211], v[84:87]
	v_mfma_f32_16x16x32_bf16 v[80:83], v[166:169], v[208:211], v[80:83]
	v_mfma_f32_16x16x32_bf16 v[68:71], v[158:161], v[216:219], v[68:71]
	v_mfma_f32_16x16x32_bf16 v[64:67], v[166:169], v[216:219], v[64:67]
	s_setprio 0
	s_setprio 1
	v_mfma_f32_16x16x32_bf16 v[124:127], v[170:173], v[188:191], 0
	v_mfma_f32_16x16x32_bf16 v[120:123], v[180:183], v[188:191], 0
	v_mfma_f32_16x16x32_bf16 v[108:111], v[170:173], v[196:199], 0
	v_mfma_f32_16x16x32_bf16 v[104:107], v[180:183], v[196:199], 0
	v_mfma_f32_16x16x32_bf16 v[92:95], v[170:173], v[204:207], 0
	v_mfma_f32_16x16x32_bf16 v[88:91], v[180:183], v[204:207], 0
	v_mfma_f32_16x16x32_bf16 v[76:79], v[170:173], v[212:215], 0
	v_mfma_f32_16x16x32_bf16 v[72:75], v[180:183], v[212:215], 0
	v_mfma_f32_16x16x32_bf16 v[124:127], v[174:177], v[192:195], v[124:127]
	v_mfma_f32_16x16x32_bf16 v[120:123], v[184:187], v[192:195], v[120:123]
	v_mfma_f32_16x16x32_bf16 v[108:111], v[174:177], v[200:203], v[108:111]
	v_mfma_f32_16x16x32_bf16 v[104:107], v[184:187], v[200:203], v[104:107]
	v_mfma_f32_16x16x32_bf16 v[92:95], v[174:177], v[208:211], v[92:95]
	v_mfma_f32_16x16x32_bf16 v[88:91], v[184:187], v[208:211], v[88:91]
	v_mfma_f32_16x16x32_bf16 v[76:79], v[174:177], v[216:219], v[76:79]
	v_mfma_f32_16x16x32_bf16 v[72:75], v[184:187], v[216:219], v[72:75]
	s_setprio 0
	s_barrier
	s_add_i32 s65, s50, s16
	s_mov_b64 s[98:99], s[66:67]
	s_mov_b32 m0, s65
	ds_read_b128 v[188:191], v151 offset:16384
	ds_read_b128 v[192:195], v151 offset:17408
	ds_read_b128 v[196:199], v151 offset:18432
	ds_read_b128 v[200:203], v151 offset:19456
	ds_read_b128 v[204:207], v151 offset:20480
	ds_read_b128 v[208:211], v151 offset:21504
	ds_read_b128 v[212:215], v151 offset:22528
	ds_read_b128 v[216:219], v151 offset:23552
	global_load_lds_dwordx4 v132, s[66:67]
	s_add_i32 m0, s65, 0x2000
	s_add_u32 s66, s66, s8
	s_addc_u32 s67, s67, s9
	s_add_i32 s65, s51, s16
	global_load_lds_dwordx4 v128, s[98:99]
	s_mov_b64 s[100:101], s[66:67]
	s_mov_b32 m0, s65
	s_nop 0
	global_load_lds_dwordx4 v132, s[66:67]
	s_add_i32 m0, s65, 0x2000
	s_mov_b64 s[14:15], s[28:29]
	global_load_lds_dwordx4 v128, s[66:67]
	s_mov_b32 m0, s30
	s_nop 0
	global_load_lds_dwordx4 v134, s[28:29]
	s_mov_b32 m0, s31
	s_nop 0
	global_load_lds_dwordx4 v130, s[28:29]
	s_waitcnt vmcnt(8)
	s_waitcnt lgkmcnt(0)
	s_barrier
	s_setprio 1
	s_waitcnt lgkmcnt(0)
	v_mfma_f32_16x16x32_bf16 v[52:55], v[154:157], v[188:191], 0
	v_mfma_f32_16x16x32_bf16 v[48:51], v[162:165], v[188:191], 0
	v_mfma_f32_16x16x32_bf16 v[36:39], v[154:157], v[196:199], 0
	v_mfma_f32_16x16x32_bf16 v[32:35], v[162:165], v[196:199], 0
	v_mfma_f32_16x16x32_bf16 v[20:23], v[154:157], v[204:207], 0
	v_mfma_f32_16x16x32_bf16 v[16:19], v[162:165], v[204:207], 0
	v_mfma_f32_16x16x32_bf16 v[4:7], v[154:157], v[212:215], 0
	v_mfma_f32_16x16x32_bf16 v[0:3], v[162:165], v[212:215], 0
	v_mfma_f32_16x16x32_bf16 v[52:55], v[158:161], v[192:195], v[52:55]
	v_mfma_f32_16x16x32_bf16 v[48:51], v[166:169], v[192:195], v[48:51]
	v_mfma_f32_16x16x32_bf16 v[36:39], v[158:161], v[200:203], v[36:39]
	v_mfma_f32_16x16x32_bf16 v[32:35], v[166:169], v[200:203], v[32:35]
	v_mfma_f32_16x16x32_bf16 v[20:23], v[158:161], v[208:211], v[20:23]
	v_mfma_f32_16x16x32_bf16 v[16:19], v[166:169], v[208:211], v[16:19]
	v_mfma_f32_16x16x32_bf16 v[4:7], v[158:161], v[216:219], v[4:7]
	v_mfma_f32_16x16x32_bf16 v[0:3], v[166:169], v[216:219], v[0:3]
	s_setprio 0
	s_setprio 1
	v_mfma_f32_16x16x32_bf16 v[60:63], v[170:173], v[188:191], 0
	v_mfma_f32_16x16x32_bf16 v[56:59], v[180:183], v[188:191], 0
	v_mfma_f32_16x16x32_bf16 v[44:47], v[170:173], v[196:199], 0
	v_mfma_f32_16x16x32_bf16 v[40:43], v[180:183], v[196:199], 0
	v_mfma_f32_16x16x32_bf16 v[28:31], v[170:173], v[204:207], 0
	v_mfma_f32_16x16x32_bf16 v[24:27], v[180:183], v[204:207], 0
	v_mfma_f32_16x16x32_bf16 v[12:15], v[170:173], v[212:215], 0
	v_mfma_f32_16x16x32_bf16 v[8:11], v[180:183], v[212:215], 0
	v_mfma_f32_16x16x32_bf16 v[60:63], v[174:177], v[192:195], v[60:63]
	v_mfma_f32_16x16x32_bf16 v[56:59], v[184:187], v[192:195], v[56:59]
	v_mfma_f32_16x16x32_bf16 v[44:47], v[174:177], v[200:203], v[44:47]
	v_mfma_f32_16x16x32_bf16 v[40:43], v[184:187], v[200:203], v[40:43]
	v_mfma_f32_16x16x32_bf16 v[28:31], v[174:177], v[208:211], v[28:31]
	v_mfma_f32_16x16x32_bf16 v[24:27], v[184:187], v[208:211], v[24:27]
	v_mfma_f32_16x16x32_bf16 v[12:15], v[174:177], v[216:219], v[12:15]
	v_mfma_f32_16x16x32_bf16 v[8:11], v[184:187], v[216:219], v[8:11]
	s_setprio 0
	s_barrier
; #define PG8_STAGE(bufoff, gbase, voff) do { _Pragma("unroll") for (int _i = 0; _i < 2; ++_i) \
;         __builtin_amdgcn_global_load_lds((const unsigned*)((const char*)(gbase) + (voff)[_i]), (PG8_LAS unsigned*)(lds + (bufoff) + ldsw + _i * 8192), 16, 0, 0); } while (0)
; #define PG8_LDA(dst, b, h) do { _Pragma("unroll") for (int m = 0; m < 4; ++m) _Pragma("unroll") for (int k = 0; k < 2; ++k) dst[m][k] = *(const PG8_LAS bf16x8*)(lds + PG8_SA(b, h) + aoff + m * 2048 + k * 1024); } while (0)
; #define PG8_LDB(dst, b, h) do { _Pragma("unroll") for (int n = 0; n < 2; ++n) _Pragma("unroll") for (int k = 0; k < 2; ++k) dst[n][k] = *(const PG8_LAS bf16x8*)(lds + PG8_SB(b, h) + boff + n * 2048 + k * 1024); } while (0)
; #define PG8_MMA(ai, bj, At, Bt) do { __builtin_amdgcn_s_setprio(1); _Pragma("unroll") for (int m = 0; m < 4; ++m) _Pragma("unroll") for (int n = 0; n < 2; ++n) _Pragma("unroll") for (int k = 0; k < 2; ++k) \
;         acc[ai][bj][m][n] = __builtin_amdgcn_mfma_f32_16x16x32_bf16(Bt[n][k], At[m][k], acc[ai][bj][m][n], 0, 0, 0); __builtin_amdgcn_s_setprio(0); } while (0)
; #define PG8_WAIT_V(n) asm volatile("s_waitcnt vmcnt(" #n ")" ::: "memory")
; #define PG8_WAIT_L(n) asm volatile("s_waitcnt lgkmcnt(" #n ")" ::: "memory")
; #define PG8_BAR __builtin_amdgcn_s_barrier()
; #define PG8_SCHED __builtin_amdgcn_sched_barrier(0)
; template <class Epi, class Sched, bool ALIGN_EPI = false, bool SP2 = false>
; __device__ __forceinline__ void gemm_phase(PG8_LAS unsigned char* lds, const Gemm g, const Sched& S, const Epi& E) {
;     ...
;             PG8_LDB(B0, 1, 0); PG8_LDB(B1, 1, 1); PG8_SCHED; PG8_LDA(At, 1, 0); PG8_STAGE(PG8_SA(0, 1), a2 + hstep, voffA);
;             PG8_WAIT_V(8); PG8_WAIT_L(0); PG8_BAR; PG8_MMA(0, 0, At, B0); PG8_MMA(0, 1, At, B1); PG8_BAR; PG8_SCHED;
;             PG8_LDA(At, 1, 1); PG8_STAGE(PG8_SB(1, 0), b3, voffB); PG8_STAGE(PG8_SB(1, 1), b3 + hstep, voffB); PG8_STAGE(PG8_SA(1, 0), a3, voffA);
;             PG8_WAIT_V(8); PG8_WAIT_L(0); PG8_BAR; PG8_MMA(1, 0, At, B0); PG8_MMA(1, 1, At, B1); PG8_BAR; PG8_SCHED;
	s_add_i32 s65, 0, 0x18000
	v_add_u32_e32 v153, s65, v147
	s_add_i32 s66, 0, 0x1c000
	ds_read_b128 v[154:157], v153
	ds_read_b128 v[158:161], v153 offset:1024
	ds_read_b128 v[162:165], v153 offset:2048
	ds_read_b128 v[166:169], v153 offset:3072
	v_add_u32_e32 v153, s66, v147
	ds_read_b128 v[170:173], v153
	ds_read_b128 v[174:177], v153 offset:1024
	ds_read_b128 v[180:183], v153 offset:2048
	ds_read_b128 v[184:187], v153 offset:3072
	s_add_u32 s28, s28, s8
	s_addc_u32 s29, s29, s9
	s_mov_b32 m0, s33
	ds_read_b128 v[188:191], v151 offset:32768
	ds_read_b128 v[192:195], v151 offset:33792
	ds_read_b128 v[196:199], v151 offset:34816
	ds_read_b128 v[200:203], v151 offset:35840
	ds_read_b128 v[204:207], v151 offset:36864
	ds_read_b128 v[208:211], v151 offset:37888
	ds_read_b128 v[212:215], v151 offset:38912
	ds_read_b128 v[216:219], v151 offset:39936
	global_load_lds_dwordx4 v134, s[28:29]
	s_mov_b32 m0, s34
	s_nop 0
	global_load_lds_dwordx4 v130, s[28:29]
	s_waitcnt vmcnt(8)
	s_waitcnt lgkmcnt(0)
	s_barrier
	s_setprio 1
	s_waitcnt lgkmcnt(0)
	v_mfma_f32_16x16x32_bf16 v[116:119], v[154:157], v[188:191], v[116:119]
	v_mfma_f32_16x16x32_bf16 v[112:115], v[162:165], v[188:191], v[112:115]
	v_mfma_f32_16x16x32_bf16 v[100:103], v[154:157], v[196:199], v[100:103]
	v_mfma_f32_16x16x32_bf16 v[96:99], v[162:165], v[196:199], v[96:99]
	v_mfma_f32_16x16x32_bf16 v[84:87], v[154:157], v[204:207], v[84:87]
	v_mfma_f32_16x16x32_bf16 v[80:83], v[162:165], v[204:207], v[80:83]
	v_mfma_f32_16x16x32_bf16 v[68:71], v[154:157], v[212:215], v[68:71]
	v_mfma_f32_16x16x32_bf16 v[64:67], v[162:165], v[212:215], v[64:67]
	v_mfma_f32_16x16x32_bf16 v[116:119], v[158:161], v[192:195], v[116:119]
	v_mfma_f32_16x16x32_bf16 v[112:115], v[166:169], v[192:195], v[112:115]
	v_mfma_f32_16x16x32_bf16 v[100:103], v[158:161], v[200:203], v[100:103]
	v_mfma_f32_16x16x32_bf16 v[96:99], v[166:169], v[200:203], v[96:99]
	v_mfma_f32_16x16x32_bf16 v[84:87], v[158:161], v[208:211], v[84:87]
	v_mfma_f32_16x16x32_bf16 v[80:83], v[166:169], v[208:211], v[80:83]
	v_mfma_f32_16x16x32_bf16 v[68:71], v[158:161], v[216:219], v[68:71]
	v_mfma_f32_16x16x32_bf16 v[64:67], v[166:169], v[216:219], v[64:67]
	s_setprio 0
	s_setprio 1
	v_mfma_f32_16x16x32_bf16 v[124:127], v[170:173], v[188:191], v[124:127]
	v_mfma_f32_16x16x32_bf16 v[120:123], v[180:183], v[188:191], v[120:123]
	v_mfma_f32_16x16x32_bf16 v[108:111], v[170:173], v[196:199], v[108:111]
	v_mfma_f32_16x16x32_bf16 v[104:107], v[180:183], v[196:199], v[104:107]
	v_mfma_f32_16x16x32_bf16 v[92:95], v[170:173], v[204:207], v[92:95]
	v_mfma_f32_16x16x32_bf16 v[88:91], v[180:183], v[204:207], v[88:91]
	v_mfma_f32_16x16x32_bf16 v[76:79], v[170:173], v[212:215], v[76:79]
	v_mfma_f32_16x16x32_bf16 v[72:75], v[180:183], v[212:215], v[72:75]
	v_mfma_f32_16x16x32_bf16 v[124:127], v[174:177], v[192:195], v[124:127]
	v_mfma_f32_16x16x32_bf16 v[120:123], v[184:187], v[192:195], v[120:123]
	v_mfma_f32_16x16x32_bf16 v[108:111], v[174:177], v[200:203], v[108:111]
	v_mfma_f32_16x16x32_bf16 v[104:107], v[184:187], v[200:203], v[104:107]
	v_mfma_f32_16x16x32_bf16 v[92:95], v[174:177], v[208:211], v[92:95]
	v_mfma_f32_16x16x32_bf16 v[88:91], v[184:187], v[208:211], v[88:91]
	v_mfma_f32_16x16x32_bf16 v[76:79], v[174:177], v[216:219], v[76:79]
	v_mfma_f32_16x16x32_bf16 v[72:75], v[184:187], v[216:219], v[72:75]
	s_setprio 0
	s_barrier
	s_add_i32 s28, s65, s16
	s_add_i32 m0, s28, 0xffffff80
	ds_read_b128 v[188:191], v151 offset:49152
	ds_read_b128 v[192:195], v151 offset:50176
	ds_read_b128 v[196:199], v151 offset:51200
	ds_read_b128 v[200:203], v151 offset:52224
	ds_read_b128 v[204:207], v151 offset:53248
	ds_read_b128 v[208:211], v151 offset:54272
	ds_read_b128 v[212:215], v151 offset:55296
	ds_read_b128 v[216:219], v151 offset:56320
	global_load_lds_dwordx4 v132, s[98:99] offset:128
	s_add_i32 m0, s28, 0x1f80
	s_add_i32 s28, s66, s16
	global_load_lds_dwordx4 v128, s[98:99] offset:128
	s_add_i32 m0, s28, 0xffffff80
	s_nop 0
	global_load_lds_dwordx4 v132, s[100:101] offset:128
	s_add_i32 m0, s28, 0x1f80
	s_nop 0
	global_load_lds_dwordx4 v128, s[100:101] offset:128
	s_add_i32 m0, s36, 0xffffff80
	s_nop 0
	global_load_lds_dwordx4 v134, s[14:15] offset:128
	s_add_i32 m0, s37, 0xffffff80
	s_nop 0
	global_load_lds_dwordx4 v130, s[14:15] offset:128
	s_waitcnt vmcnt(8)
	s_waitcnt lgkmcnt(0)
	s_barrier
	s_setprio 1
	s_waitcnt lgkmcnt(0)
	v_mfma_f32_16x16x32_bf16 v[52:55], v[154:157], v[188:191], v[52:55]
	v_mfma_f32_16x16x32_bf16 v[48:51], v[162:165], v[188:191], v[48:51]
	v_mfma_f32_16x16x32_bf16 v[36:39], v[154:157], v[196:199], v[36:39]
	v_mfma_f32_16x16x32_bf16 v[32:35], v[162:165], v[196:199], v[32:35]
	v_mfma_f32_16x16x32_bf16 v[20:23], v[154:157], v[204:207], v[20:23]
	v_mfma_f32_16x16x32_bf16 v[16:19], v[162:165], v[204:207], v[16:19]
	v_mfma_f32_16x16x32_bf16 v[4:7], v[154:157], v[212:215], v[4:7]
	v_mfma_f32_16x16x32_bf16 v[0:3], v[162:165], v[212:215], v[0:3]
	v_mfma_f32_16x16x32_bf16 v[52:55], v[158:161], v[192:195], v[52:55]
	v_mfma_f32_16x16x32_bf16 v[48:51], v[166:169], v[192:195], v[48:51]
	v_mfma_f32_16x16x32_bf16 v[36:39], v[158:161], v[200:203], v[36:39]
	v_mfma_f32_16x16x32_bf16 v[32:35], v[166:169], v[200:203], v[32:35]
	v_mfma_f32_16x16x32_bf16 v[20:23], v[158:161], v[208:211], v[20:23]
	v_mfma_f32_16x16x32_bf16 v[16:19], v[166:169], v[208:211], v[16:19]
	v_mfma_f32_16x16x32_bf16 v[4:7], v[158:161], v[216:219], v[4:7]
	v_mfma_f32_16x16x32_bf16 v[0:3], v[166:169], v[216:219], v[0:3]
	s_setprio 0
	s_setprio 1
	v_mfma_f32_16x16x32_bf16 v[60:63], v[170:173], v[188:191], v[60:63]
	v_mfma_f32_16x16x32_bf16 v[56:59], v[180:183], v[188:191], v[56:59]
	v_mfma_f32_16x16x32_bf16 v[44:47], v[170:173], v[196:199], v[44:47]
	v_mfma_f32_16x16x32_bf16 v[40:43], v[180:183], v[196:199], v[40:43]
	v_mfma_f32_16x16x32_bf16 v[28:31], v[170:173], v[204:207], v[28:31]
	v_mfma_f32_16x16x32_bf16 v[24:27], v[180:183], v[204:207], v[24:27]
	v_mfma_f32_16x16x32_bf16 v[12:15], v[170:173], v[212:215], v[12:15]
	v_mfma_f32_16x16x32_bf16 v[8:11], v[180:183], v[212:215], v[8:11]
	v_mfma_f32_16x16x32_bf16 v[60:63], v[174:177], v[192:195], v[60:63]
	v_mfma_f32_16x16x32_bf16 v[56:59], v[184:187], v[192:195], v[56:59]
	v_mfma_f32_16x16x32_bf16 v[44:47], v[174:177], v[200:203], v[44:47]
	v_mfma_f32_16x16x32_bf16 v[40:43], v[184:187], v[200:203], v[40:43]
	v_mfma_f32_16x16x32_bf16 v[28:31], v[174:177], v[208:211], v[28:31]
	v_mfma_f32_16x16x32_bf16 v[24:27], v[184:187], v[208:211], v[24:27]
	v_mfma_f32_16x16x32_bf16 v[12:15], v[174:177], v[216:219], v[12:15]
	v_mfma_f32_16x16x32_bf16 v[8:11], v[184:187], v[216:219], v[8:11]
	s_setprio 0
	s_barrier
	s_add_u32 s26, s26, 0x100
	s_addc_u32 s27, s27, 0
	s_add_u32 s62, s62, 0x100
	s_addc_u32 s63, s63, 0
	s_cmp_ge_i32 s64, s38
	s_mov_b32 s28, s64
	s_cbranch_scc0 .LBB0_1317
	s_branch .Lpeel_x4
; #define PG8_STAGE(bufoff, gbase, voff) do { _Pragma("unroll") for (int _i = 0; _i < 2; ++_i) \
;         __builtin_amdgcn_global_load_lds((const unsigned*)((const char*)(gbase) + (voff)[_i]), (PG8_LAS unsigned*)(lds + (bufoff) + ldsw + _i * 8192), 16, 0, 0); } while (0)
; #define PG8_LDA(dst, b, h) do { _Pragma("unroll") for (int m = 0; m < 4; ++m) _Pragma("unroll") for (int k = 0; k < 2; ++k) dst[m][k] = *(const PG8_LAS bf16x8*)(lds + PG8_SA(b, h) + aoff + m * 2048 + k * 1024); } while (0)
; #define PG8_LDB(dst, b, h) do { _Pragma("unroll") for (int n = 0; n < 2; ++n) _Pragma("unroll") for (int k = 0; k < 2; ++k) dst[n][k] = *(const PG8_LAS bf16x8*)(lds + PG8_SB(b, h) + boff + n * 2048 + k * 1024); } while (0)
; #define PG8_MMA(ai, bj, At, Bt) do { __builtin_amdgcn_s_setprio(1); _Pragma("unroll") for (int m = 0; m < 4; ++m) _Pragma("unroll") for (int n = 0; n < 2; ++n) _Pragma("unroll") for (int k = 0; k < 2; ++k) \
;         acc[ai][bj][m][n] = __builtin_amdgcn_mfma_f32_16x16x32_bf16(Bt[n][k], At[m][k], acc[ai][bj][m][n], 0, 0, 0); __builtin_amdgcn_s_setprio(0); } while (0)
; #define PG8_WAIT_V(n) asm volatile("s_waitcnt vmcnt(" #n ")" ::: "memory")
; #define PG8_BAR __builtin_amdgcn_s_barrier()
; template <class Epi, class Sched, bool ALIGN_EPI = false, bool SP2 = false>
; __device__ __forceinline__ void gemm_phase(PG8_LAS unsigned char* lds, const Gemm g, const Sched& S, const Epi& E) {
;     ...
;         for (int t = 0; t < nt; t += 2) {
;             const bool last = (t == nt - 2);
;             const char* a1 = cA + (size_t)(t + 1) * kstep;
;             const char* a2 = last ? nA : cA + (size_t)(t + 2) * kstep; const char* b2 = last ? nB : cB + (size_t)(t + 2) * kstep;
;             const char* a3 = a2 + kstep; const char* b3 = b2 + kstep;
;             if (last && has_next) S.a_ready(nxt);
;             if constexpr (SP2) {
;             PG8_LDB(B0, 0, 0); PG8_LDB(B1, 0, 1); PG8_SCHED; PG8_LDA(At, 0, 0); PG8_STAGE(PG8_SA(1, 1), a1 + hstep, voffA);
;             PG8_WAIT_V(8); PG8_WAIT_L(0); PG8_BAR; PG8_MMA(0, 0, At, B0); PG8_MMA(0, 1, At, B1); PG8_BAR; PG8_SCHED;
;             PG8_LDA(At, 0, 1); PG8_STAGE(PG8_SB(0, 0), b2, voffB); PG8_STAGE(PG8_SB(0, 1), b2 + hstep, voffB); PG8_STAGE(PG8_SA(0, 0), a2, voffA);
;             PG8_WAIT_V(8); PG8_WAIT_L(0); PG8_BAR; PG8_MMA(1, 0, At, B0); PG8_MMA(1, 1, At, B1); PG8_BAR; PG8_SCHED;
.LBB0_1317:
	ds_read_b128 v[154:157], v149
	ds_read_b128 v[158:161], v149 offset:1024
	ds_read_b128 v[162:165], v149 offset:2048
	ds_read_b128 v[166:169], v149 offset:3072
	ds_read_b128 v[170:173], v150
	ds_read_b128 v[174:177], v150 offset:1024
	ds_read_b128 v[180:183], v150 offset:2048
	ds_read_b128 v[184:187], v150 offset:3072
	s_add_i32 s64, s28, 2
	s_add_u32 s65, s26, 0x80
	s_addc_u32 s29, s27, 0
	s_cmp_eq_u32 s39, s28
	s_cselect_b32 s28, s0, s65
	s_cselect_b32 s29, s1, s29
	s_cselect_b32 s67, s25, s63
	s_cselect_b32 s66, s24, s62
	s_add_i32 m0, s30, 0xc000
	ds_read_b128 v[188:191], v151
	ds_read_b128 v[192:195], v151 offset:1024
	ds_read_b128 v[196:199], v151 offset:2048
	ds_read_b128 v[200:203], v151 offset:3072
	ds_read_b128 v[204:207], v151 offset:4096
	ds_read_b128 v[208:211], v151 offset:5120
	ds_read_b128 v[212:215], v151 offset:6144
	ds_read_b128 v[216:219], v151 offset:7168
	global_load_lds_dwordx4 v136, s[26:27]
	s_add_i32 m0, s30, 0xe000
	s_nop 0
	global_load_lds_dwordx4 v138, s[26:27]
	s_waitcnt vmcnt(8)
	s_waitcnt lgkmcnt(0)
	s_barrier
	s_setprio 1
	s_waitcnt lgkmcnt(0)
	v_mfma_f32_16x16x32_bf16 v[116:119], v[154:157], v[188:191], v[116:119]
	v_mfma_f32_16x16x32_bf16 v[112:115], v[162:165], v[188:191], v[112:115]
	v_mfma_f32_16x16x32_bf16 v[100:103], v[154:157], v[196:199], v[100:103]
	v_mfma_f32_16x16x32_bf16 v[96:99], v[162:165], v[196:199], v[96:99]
	v_mfma_f32_16x16x32_bf16 v[84:87], v[154:157], v[204:207], v[84:87]
	v_mfma_f32_16x16x32_bf16 v[80:83], v[162:165], v[204:207], v[80:83]
	v_mfma_f32_16x16x32_bf16 v[68:71], v[154:157], v[212:215], v[68:71]
	v_mfma_f32_16x16x32_bf16 v[64:67], v[162:165], v[212:215], v[64:67]
	v_mfma_f32_16x16x32_bf16 v[116:119], v[158:161], v[192:195], v[116:119]
	v_mfma_f32_16x16x32_bf16 v[112:115], v[166:169], v[192:195], v[112:115]
	v_mfma_f32_16x16x32_bf16 v[100:103], v[158:161], v[200:203], v[100:103]
	v_mfma_f32_16x16x32_bf16 v[96:99], v[166:169], v[200:203], v[96:99]
	v_mfma_f32_16x16x32_bf16 v[84:87], v[158:161], v[208:211], v[84:87]
	v_mfma_f32_16x16x32_bf16 v[80:83], v[166:169], v[208:211], v[80:83]
	v_mfma_f32_16x16x32_bf16 v[68:71], v[158:161], v[216:219], v[68:71]
	v_mfma_f32_16x16x32_bf16 v[64:67], v[166:169], v[216:219], v[64:67]
	s_setprio 0
	s_setprio 1
	v_mfma_f32_16x16x32_bf16 v[124:127], v[170:173], v[188:191], v[124:127]
	v_mfma_f32_16x16x32_bf16 v[120:123], v[180:183], v[188:191], v[120:123]
	v_mfma_f32_16x16x32_bf16 v[108:111], v[170:173], v[196:199], v[108:111]
	v_mfma_f32_16x16x32_bf16 v[104:107], v[180:183], v[196:199], v[104:107]
	v_mfma_f32_16x16x32_bf16 v[92:95], v[170:173], v[204:207], v[92:95]
	v_mfma_f32_16x16x32_bf16 v[88:91], v[180:183], v[204:207], v[88:91]
	v_mfma_f32_16x16x32_bf16 v[76:79], v[170:173], v[212:215], v[76:79]
	v_mfma_f32_16x16x32_bf16 v[72:75], v[180:183], v[212:215], v[72:75]
	v_mfma_f32_16x16x32_bf16 v[124:127], v[174:177], v[192:195], v[124:127]
	v_mfma_f32_16x16x32_bf16 v[120:123], v[184:187], v[192:195], v[120:123]
	v_mfma_f32_16x16x32_bf16 v[108:111], v[174:177], v[200:203], v[108:111]
	v_mfma_f32_16x16x32_bf16 v[104:107], v[184:187], v[200:203], v[104:107]
	v_mfma_f32_16x16x32_bf16 v[92:95], v[174:177], v[208:211], v[92:95]
	v_mfma_f32_16x16x32_bf16 v[88:91], v[184:187], v[208:211], v[88:91]
	v_mfma_f32_16x16x32_bf16 v[76:79], v[174:177], v[216:219], v[76:79]
	v_mfma_f32_16x16x32_bf16 v[72:75], v[184:187], v[216:219], v[72:75]
	s_setprio 0
	s_barrier
	s_add_i32 s65, s50, s16
	s_mov_b64 s[98:99], s[66:67]
	s_mov_b32 m0, s65
	ds_read_b128 v[188:191], v151 offset:16384
	ds_read_b128 v[192:195], v151 offset:17408
	ds_read_b128 v[196:199], v151 offset:18432
	ds_read_b128 v[200:203], v151 offset:19456
	ds_read_b128 v[204:207], v151 offset:20480
	ds_read_b128 v[208:211], v151 offset:21504
	ds_read_b128 v[212:215], v151 offset:22528
	ds_read_b128 v[216:219], v151 offset:23552
	global_load_lds_dwordx4 v132, s[66:67]
	s_add_i32 m0, s65, 0x2000
	s_add_u32 s66, s66, s8
	s_addc_u32 s67, s67, s9
	s_add_i32 s65, s51, s16
	global_load_lds_dwordx4 v128, s[98:99]
	s_mov_b64 s[100:101], s[66:67]
	s_mov_b32 m0, s65
	s_nop 0
	global_load_lds_dwordx4 v132, s[66:67]
	s_add_i32 m0, s65, 0x2000
	s_mov_b64 s[14:15], s[28:29]
	global_load_lds_dwordx4 v128, s[66:67]
	s_mov_b32 m0, s30
	s_nop 0
	global_load_lds_dwordx4 v134, s[28:29]
	s_mov_b32 m0, s31
	s_nop 0
	global_load_lds_dwordx4 v130, s[28:29]
	s_waitcnt vmcnt(8)
	s_waitcnt lgkmcnt(0)
	s_barrier
	s_setprio 1
	s_waitcnt lgkmcnt(0)
	v_mfma_f32_16x16x32_bf16 v[52:55], v[154:157], v[188:191], v[52:55]
	v_mfma_f32_16x16x32_bf16 v[48:51], v[162:165], v[188:191], v[48:51]
	v_mfma_f32_16x16x32_bf16 v[36:39], v[154:157], v[196:199], v[36:39]
	v_mfma_f32_16x16x32_bf16 v[32:35], v[162:165], v[196:199], v[32:35]
	v_mfma_f32_16x16x32_bf16 v[20:23], v[154:157], v[204:207], v[20:23]
	v_mfma_f32_16x16x32_bf16 v[16:19], v[162:165], v[204:207], v[16:19]
	v_mfma_f32_16x16x32_bf16 v[4:7], v[154:157], v[212:215], v[4:7]
	v_mfma_f32_16x16x32_bf16 v[0:3], v[162:165], v[212:215], v[0:3]
	v_mfma_f32_16x16x32_bf16 v[52:55], v[158:161], v[192:195], v[52:55]
	v_mfma_f32_16x16x32_bf16 v[48:51], v[166:169], v[192:195], v[48:51]
	v_mfma_f32_16x16x32_bf16 v[36:39], v[158:161], v[200:203], v[36:39]
	v_mfma_f32_16x16x32_bf16 v[32:35], v[166:169], v[200:203], v[32:35]
	v_mfma_f32_16x16x32_bf16 v[20:23], v[158:161], v[208:211], v[20:23]
	v_mfma_f32_16x16x32_bf16 v[16:19], v[166:169], v[208:211], v[16:19]
	v_mfma_f32_16x16x32_bf16 v[4:7], v[158:161], v[216:219], v[4:7]
	v_mfma_f32_16x16x32_bf16 v[0:3], v[166:169], v[216:219], v[0:3]
	s_setprio 0
	s_setprio 1
	v_mfma_f32_16x16x32_bf16 v[60:63], v[170:173], v[188:191], v[60:63]
	v_mfma_f32_16x16x32_bf16 v[56:59], v[180:183], v[188:191], v[56:59]
	v_mfma_f32_16x16x32_bf16 v[44:47], v[170:173], v[196:199], v[44:47]
	v_mfma_f32_16x16x32_bf16 v[40:43], v[180:183], v[196:199], v[40:43]
	v_mfma_f32_16x16x32_bf16 v[28:31], v[170:173], v[204:207], v[28:31]
	v_mfma_f32_16x16x32_bf16 v[24:27], v[180:183], v[204:207], v[24:27]
	v_mfma_f32_16x16x32_bf16 v[12:15], v[170:173], v[212:215], v[12:15]
	v_mfma_f32_16x16x32_bf16 v[8:11], v[180:183], v[212:215], v[8:11]
	v_mfma_f32_16x16x32_bf16 v[60:63], v[174:177], v[192:195], v[60:63]
	v_mfma_f32_16x16x32_bf16 v[56:59], v[184:187], v[192:195], v[56:59]
	v_mfma_f32_16x16x32_bf16 v[44:47], v[174:177], v[200:203], v[44:47]
	v_mfma_f32_16x16x32_bf16 v[40:43], v[184:187], v[200:203], v[40:43]
	v_mfma_f32_16x16x32_bf16 v[28:31], v[174:177], v[208:211], v[28:31]
	v_mfma_f32_16x16x32_bf16 v[24:27], v[184:187], v[208:211], v[24:27]
	v_mfma_f32_16x16x32_bf16 v[12:15], v[174:177], v[216:219], v[12:15]
	v_mfma_f32_16x16x32_bf16 v[8:11], v[184:187], v[216:219], v[8:11]
	s_setprio 0
	s_barrier
; #define PG8_STAGE(bufoff, gbase, voff) do { _Pragma("unroll") for (int _i = 0; _i < 2; ++_i) \
;         __builtin_amdgcn_global_load_lds((const unsigned*)((const char*)(gbase) + (voff)[_i]), (PG8_LAS unsigned*)(lds + (bufoff) + ldsw + _i * 8192), 16, 0, 0); } while (0)
; #define PG8_LDA(dst, b, h) do { _Pragma("unroll") for (int m = 0; m < 4; ++m) _Pragma("unroll") for (int k = 0; k < 2; ++k) dst[m][k] = *(const PG8_LAS bf16x8*)(lds + PG8_SA(b, h) + aoff + m * 2048 + k * 1024); } while (0)
; #define PG8_LDB(dst, b, h) do { _Pragma("unroll") for (int n = 0; n < 2; ++n) _Pragma("unroll") for (int k = 0; k < 2; ++k) dst[n][k] = *(const PG8_LAS bf16x8*)(lds + PG8_SB(b, h) + boff + n * 2048 + k * 1024); } while (0)
; #define PG8_MMA(ai, bj, At, Bt) do { __builtin_amdgcn_s_setprio(1); _Pragma("unroll") for (int m = 0; m < 4; ++m) _Pragma("unroll") for (int n = 0; n < 2; ++n) _Pragma("unroll") for (int k = 0; k < 2; ++k) \
;         acc[ai][bj][m][n] = __builtin_amdgcn_mfma_f32_16x16x32_bf16(Bt[n][k], At[m][k], acc[ai][bj][m][n], 0, 0, 0); __builtin_amdgcn_s_setprio(0); } while (0)
; #define PG8_WAIT_V(n) asm volatile("s_waitcnt vmcnt(" #n ")" ::: "memory")
; #define PG8_WAIT_L(n) asm volatile("s_waitcnt lgkmcnt(" #n ")" ::: "memory")
; #define PG8_BAR __builtin_amdgcn_s_barrier()
; #define PG8_SCHED __builtin_amdgcn_sched_barrier(0)
; template <class Epi, class Sched, bool ALIGN_EPI = false, bool SP2 = false>
; __device__ __forceinline__ void gemm_phase(PG8_LAS unsigned char* lds, const Gemm g, const Sched& S, const Epi& E) {
;     ...
;             PG8_LDB(B0, 1, 0); PG8_LDB(B1, 1, 1); PG8_SCHED; PG8_LDA(At, 1, 0); PG8_STAGE(PG8_SA(0, 1), a2 + hstep, voffA);
;             PG8_WAIT_V(8); PG8_WAIT_L(0); PG8_BAR; PG8_MMA(0, 0, At, B0); PG8_MMA(0, 1, At, B1); PG8_BAR; PG8_SCHED;
;             PG8_LDA(At, 1, 1); PG8_STAGE(PG8_SB(1, 0), b3, voffB); PG8_STAGE(PG8_SB(1, 1), b3 + hstep, voffB); PG8_STAGE(PG8_SA(1, 0), a3, voffA);
;             PG8_WAIT_V(8); PG8_WAIT_L(0); PG8_BAR; PG8_MMA(1, 0, At, B0); PG8_MMA(1, 1, At, B1); PG8_BAR; PG8_SCHED;
	s_add_i32 s65, 0, 0x18000
	v_add_u32_e32 v153, s65, v147
	s_add_i32 s66, 0, 0x1c000
	ds_read_b128 v[154:157], v153
	ds_read_b128 v[158:161], v153 offset:1024
	ds_read_b128 v[162:165], v153 offset:2048
	ds_read_b128 v[166:169], v153 offset:3072
	v_add_u32_e32 v153, s66, v147
	ds_read_b128 v[170:173], v153
	ds_read_b128 v[174:177], v153 offset:1024
	ds_read_b128 v[180:183], v153 offset:2048
	ds_read_b128 v[184:187], v153 offset:3072
	s_add_u32 s28, s28, s8
	s_addc_u32 s29, s29, s9
	s_mov_b32 m0, s33
	ds_read_b128 v[188:191], v151 offset:32768
	ds_read_b128 v[192:195], v151 offset:33792
	ds_read_b128 v[196:199], v151 offset:34816
	ds_read_b128 v[200:203], v151 offset:35840
	ds_read_b128 v[204:207], v151 offset:36864
	ds_read_b128 v[208:211], v151 offset:37888
	ds_read_b128 v[212:215], v151 offset:38912
	ds_read_b128 v[216:219], v151 offset:39936
	global_load_lds_dwordx4 v134, s[28:29]
	s_mov_b32 m0, s34
	s_nop 0
	global_load_lds_dwordx4 v130, s[28:29]
	s_waitcnt vmcnt(8)
	s_waitcnt lgkmcnt(0)
	s_barrier
	s_setprio 1
	s_waitcnt lgkmcnt(0)
	v_mfma_f32_16x16x32_bf16 v[116:119], v[154:157], v[188:191], v[116:119]
	v_mfma_f32_16x16x32_bf16 v[112:115], v[162:165], v[188:191], v[112:115]
	v_mfma_f32_16x16x32_bf16 v[100:103], v[154:157], v[196:199], v[100:103]
	v_mfma_f32_16x16x32_bf16 v[96:99], v[162:165], v[196:199], v[96:99]
	v_mfma_f32_16x16x32_bf16 v[84:87], v[154:157], v[204:207], v[84:87]
	v_mfma_f32_16x16x32_bf16 v[80:83], v[162:165], v[204:207], v[80:83]
	v_mfma_f32_16x16x32_bf16 v[68:71], v[154:157], v[212:215], v[68:71]
	v_mfma_f32_16x16x32_bf16 v[64:67], v[162:165], v[212:215], v[64:67]
	v_mfma_f32_16x16x32_bf16 v[116:119], v[158:161], v[192:195], v[116:119]
	v_mfma_f32_16x16x32_bf16 v[112:115], v[166:169], v[192:195], v[112:115]
	v_mfma_f32_16x16x32_bf16 v[100:103], v[158:161], v[200:203], v[100:103]
	v_mfma_f32_16x16x32_bf16 v[96:99], v[166:169], v[200:203], v[96:99]
	v_mfma_f32_16x16x32_bf16 v[84:87], v[158:161], v[208:211], v[84:87]
	v_mfma_f32_16x16x32_bf16 v[80:83], v[166:169], v[208:211], v[80:83]
	v_mfma_f32_16x16x32_bf16 v[68:71], v[158:161], v[216:219], v[68:71]
	v_mfma_f32_16x16x32_bf16 v[64:67], v[166:169], v[216:219], v[64:67]
	s_setprio 0
	s_setprio 1
	v_mfma_f32_16x16x32_bf16 v[124:127], v[170:173], v[188:191], v[124:127]
	v_mfma_f32_16x16x32_bf16 v[120:123], v[180:183], v[188:191], v[120:123]
	v_mfma_f32_16x16x32_bf16 v[108:111], v[170:173], v[196:199], v[108:111]
	v_mfma_f32_16x16x32_bf16 v[104:107], v[180:183], v[196:199], v[104:107]
	v_mfma_f32_16x16x32_bf16 v[92:95], v[170:173], v[204:207], v[92:95]
	v_mfma_f32_16x16x32_bf16 v[88:91], v[180:183], v[204:207], v[88:91]
	v_mfma_f32_16x16x32_bf16 v[76:79], v[170:173], v[212:215], v[76:79]
	v_mfma_f32_16x16x32_bf16 v[72:75], v[180:183], v[212:215], v[72:75]
	v_mfma_f32_16x16x32_bf16 v[124:127], v[174:177], v[192:195], v[124:127]
	v_mfma_f32_16x16x32_bf16 v[120:123], v[184:187], v[192:195], v[120:123]
	v_mfma_f32_16x16x32_bf16 v[108:111], v[174:177], v[200:203], v[108:111]
	v_mfma_f32_16x16x32_bf16 v[104:107], v[184:187], v[200:203], v[104:107]
	v_mfma_f32_16x16x32_bf16 v[92:95], v[174:177], v[208:211], v[92:95]
	v_mfma_f32_16x16x32_bf16 v[88:91], v[184:187], v[208:211], v[88:91]
	v_mfma_f32_16x16x32_bf16 v[76:79], v[174:177], v[216:219], v[76:79]
	v_mfma_f32_16x16x32_bf16 v[72:75], v[184:187], v[216:219], v[72:75]
	s_setprio 0
	s_barrier
	s_add_i32 s28, s65, s16
	s_add_i32 m0, s28, 0xffffff80
	ds_read_b128 v[188:191], v151 offset:49152
	ds_read_b128 v[192:195], v151 offset:50176
	ds_read_b128 v[196:199], v151 offset:51200
	ds_read_b128 v[200:203], v151 offset:52224
	ds_read_b128 v[204:207], v151 offset:53248
	ds_read_b128 v[208:211], v151 offset:54272
	ds_read_b128 v[212:215], v151 offset:55296
	ds_read_b128 v[216:219], v151 offset:56320
	global_load_lds_dwordx4 v132, s[98:99] offset:128
	s_add_i32 m0, s28, 0x1f80
	s_add_i32 s28, s66, s16
	global_load_lds_dwordx4 v128, s[98:99] offset:128
	s_add_i32 m0, s28, 0xffffff80
	s_nop 0
	global_load_lds_dwordx4 v132, s[100:101] offset:128
	s_add_i32 m0, s28, 0x1f80
	s_nop 0
	global_load_lds_dwordx4 v128, s[100:101] offset:128
	s_add_i32 m0, s36, 0xffffff80
	s_nop 0
	global_load_lds_dwordx4 v134, s[14:15] offset:128
	s_add_i32 m0, s37, 0xffffff80
	s_nop 0
	global_load_lds_dwordx4 v130, s[14:15] offset:128
	s_waitcnt vmcnt(8)
	s_waitcnt lgkmcnt(0)
	s_barrier
	s_setprio 1
	s_waitcnt lgkmcnt(0)
	v_mfma_f32_16x16x32_bf16 v[52:55], v[154:157], v[188:191], v[52:55]
	v_mfma_f32_16x16x32_bf16 v[48:51], v[162:165], v[188:191], v[48:51]
	v_mfma_f32_16x16x32_bf16 v[36:39], v[154:157], v[196:199], v[36:39]
	v_mfma_f32_16x16x32_bf16 v[32:35], v[162:165], v[196:199], v[32:35]
	v_mfma_f32_16x16x32_bf16 v[20:23], v[154:157], v[204:207], v[20:23]
	v_mfma_f32_16x16x32_bf16 v[16:19], v[162:165], v[204:207], v[16:19]
	v_mfma_f32_16x16x32_bf16 v[4:7], v[154:157], v[212:215], v[4:7]
	v_mfma_f32_16x16x32_bf16 v[0:3], v[162:165], v[212:215], v[0:3]
	v_mfma_f32_16x16x32_bf16 v[52:55], v[158:161], v[192:195], v[52:55]
	v_mfma_f32_16x16x32_bf16 v[48:51], v[166:169], v[192:195], v[48:51]
	v_mfma_f32_16x16x32_bf16 v[36:39], v[158:161], v[200:203], v[36:39]
	v_mfma_f32_16x16x32_bf16 v[32:35], v[166:169], v[200:203], v[32:35]
	v_mfma_f32_16x16x32_bf16 v[20:23], v[158:161], v[208:211], v[20:23]
	v_mfma_f32_16x16x32_bf16 v[16:19], v[166:169], v[208:211], v[16:19]
	v_mfma_f32_16x16x32_bf16 v[4:7], v[158:161], v[216:219], v[4:7]
	v_mfma_f32_16x16x32_bf16 v[0:3], v[166:169], v[216:219], v[0:3]
	s_setprio 0
	s_setprio 1
	v_mfma_f32_16x16x32_bf16 v[60:63], v[170:173], v[188:191], v[60:63]
	v_mfma_f32_16x16x32_bf16 v[56:59], v[180:183], v[188:191], v[56:59]
	v_mfma_f32_16x16x32_bf16 v[44:47], v[170:173], v[196:199], v[44:47]
	v_mfma_f32_16x16x32_bf16 v[40:43], v[180:183], v[196:199], v[40:43]
	v_mfma_f32_16x16x32_bf16 v[28:31], v[170:173], v[204:207], v[28:31]
	v_mfma_f32_16x16x32_bf16 v[24:27], v[180:183], v[204:207], v[24:27]
	v_mfma_f32_16x16x32_bf16 v[12:15], v[170:173], v[212:215], v[12:15]
	v_mfma_f32_16x16x32_bf16 v[8:11], v[180:183], v[212:215], v[8:11]
	v_mfma_f32_16x16x32_bf16 v[60:63], v[174:177], v[192:195], v[60:63]
	v_mfma_f32_16x16x32_bf16 v[56:59], v[184:187], v[192:195], v[56:59]
	v_mfma_f32_16x16x32_bf16 v[44:47], v[174:177], v[200:203], v[44:47]
	v_mfma_f32_16x16x32_bf16 v[40:43], v[184:187], v[200:203], v[40:43]
	v_mfma_f32_16x16x32_bf16 v[28:31], v[174:177], v[208:211], v[28:31]
	v_mfma_f32_16x16x32_bf16 v[24:27], v[184:187], v[208:211], v[24:27]
	v_mfma_f32_16x16x32_bf16 v[12:15], v[174:177], v[216:219], v[12:15]
	v_mfma_f32_16x16x32_bf16 v[8:11], v[184:187], v[216:219], v[8:11]
	s_setprio 0
	s_barrier
	s_add_u32 s26, s26, 0x100
	s_addc_u32 s27, s27, 0
	s_add_u32 s62, s62, 0x100
	s_addc_u32 s63, s63, 0
	s_cmp_ge_i32 s64, s38
	s_mov_b32 s28, s64
	s_cbranch_scc0 .LBB0_1317

; #define PG8_STAGE(bufoff, gbase, voff) do { _Pragma("unroll") for (int _i = 0; _i < 2; ++_i) \
;         __builtin_amdgcn_global_load_lds((const unsigned*)((const char*)(gbase) + (voff)[_i]), (PG8_LAS unsigned*)(lds + (bufoff) + ldsw + _i * 8192), 16, 0, 0); } while (0)
; #define PG8_LDA(dst, b, h) do { _Pragma("unroll") for (int m = 0; m < 4; ++m) _Pragma("unroll") for (int k = 0; k < 2; ++k) dst[m][k] = *(const PG8_LAS bf16x8*)(lds + PG8_SA(b, h) + aoff + m * 2048 + k * 1024); } while (0)
; #define PG8_LDB(dst, b, h) do { _Pragma("unroll") for (int n = 0; n < 2; ++n) _Pragma("unroll") for (int k = 0; k < 2; ++k) dst[n][k] = *(const PG8_LAS bf16x8*)(lds + PG8_SB(b, h) + boff + n * 2048 + k * 1024); } while (0)
; #define PG8_MMA(ai, bj, At, Bt) do { __builtin_amdgcn_s_setprio(1); _Pragma("unroll") for (int m = 0; m < 4; ++m) _Pragma("unroll") for (int n = 0; n < 2; ++n) _Pragma("unroll") for (int k = 0; k < 2; ++k) \
;         acc[ai][bj][m][n] = __builtin_amdgcn_mfma_f32_16x16x32_bf16(Bt[n][k], At[m][k], acc[ai][bj][m][n], 0, 0, 0); __builtin_amdgcn_s_setprio(0); } while (0)
; #define PG8_WAIT_V(n) asm volatile("s_waitcnt vmcnt(" #n ")" ::: "memory")
; #define PG8_BAR __builtin_amdgcn_s_barrier()
; template <class Epi, class Sched, bool ALIGN_EPI = false, bool SP2 = false>
; __device__ __forceinline__ void gemm_phase(PG8_LAS unsigned char* lds, const Gemm g, const Sched& S, const Epi& E) {
;     ...
;         for (int t = 0; t < nt; t += 2) {
;             const bool last = (t == nt - 2);
;             const char* a1 = cA + (size_t)(t + 1) * kstep;
;             const char* a2 = last ? nA : cA + (size_t)(t + 2) * kstep; const char* b2 = last ? nB : cB + (size_t)(t + 2) * kstep;
;             const char* a3 = a2 + kstep; const char* b3 = b2 + kstep;
;             if (last && has_next) S.a_ready(nxt);
;             if constexpr (SP2) {
;             PG8_LDB(B0, 0, 0); PG8_LDB(B1, 0, 1); PG8_SCHED; PG8_LDA(At, 0, 0); PG8_STAGE(PG8_SA(1, 1), a1 + hstep, voffA);
;             PG8_WAIT_V(8); PG8_WAIT_L(0); PG8_BAR; PG8_MMA(0, 0, At, B0); PG8_MMA(0, 1, At, B1); PG8_BAR; PG8_SCHED;
;             PG8_LDA(At, 0, 1); PG8_STAGE(PG8_SB(0, 0), b2, voffB); PG8_STAGE(PG8_SB(0, 1), b2 + hstep, voffB); PG8_STAGE(PG8_SA(0, 0), a2, voffA);
;             PG8_WAIT_V(8); PG8_WAIT_L(0); PG8_BAR; PG8_MMA(1, 0, At, B0); PG8_MMA(1, 1, At, B1); PG8_BAR; PG8_SCHED;
.LBB0_1409:
	v_mov_b32_e32 v151, 0
	s_andn2_b64 vcc, exec, s[24:25]
	v_mov_b32_e32 v150, 0
	v_mov_b32_e32 v155, 0
	v_mov_b32_e32 v154, 0
	v_mov_b32_e32 v153, 0
	v_mov_b32_e32 v152, 0
	v_mov_b32_e32 v149, 0
	v_mov_b32_e32 v148, 0
	s_waitcnt vmcnt(0)
	v_mov_b32_e32 v145, 0
	v_mov_b32_e32 v144, 0
	v_mov_b32_e32 v147, 0
	v_mov_b32_e32 v146, 0
	s_waitcnt lgkmcnt(0)
	s_cbranch_vccnz .LBB0_1413
	s_add_u32 s30, s30, 0x80
	s_addc_u32 s31, s31, 0
	s_add_u32 s63, s34, 0x100
	s_addc_u32 s64, s35, 0
	s_mov_b32 s34, 0
	ds_read_b128 v[144:147], v159
	ds_read_b128 v[148:151], v159 offset:1024
	ds_read_b128 v[152:155], v159 offset:2048
	ds_read_b128 v[164:167], v159 offset:3072
	ds_read_b128 v[168:171], v160
	ds_read_b128 v[172:175], v160 offset:1024
	ds_read_b128 v[180:183], v160 offset:2048
	ds_read_b128 v[184:187], v160 offset:3072
	s_add_i32 s65, s34, 2
	s_add_u32 s66, s30, 0x80
	s_addc_u32 s35, s31, 0
	s_cmp_eq_u32 s41, s34
	s_cselect_b32 s34, s0, s66
	s_cselect_b32 s35, s1, s35
	s_cselect_b32 s67, s29, s64
	s_cselect_b32 s66, s28, s63
	s_add_i32 m0, s17, 0xc000
	ds_read_b128 v[188:191], v161
	ds_read_b128 v[192:195], v161 offset:1024
	ds_read_b128 v[196:199], v161 offset:2048
	ds_read_b128 v[200:203], v161 offset:3072
	ds_read_b128 v[204:207], v161 offset:4096
	ds_read_b128 v[208:211], v161 offset:5120
	ds_read_b128 v[212:215], v161 offset:6144
	ds_read_b128 v[216:219], v161 offset:7168
	global_load_lds_dwordx4 v136, s[30:31]
	s_add_i32 m0, s17, 0xe000
	s_nop 0
	global_load_lds_dwordx4 v138, s[30:31]
	s_waitcnt vmcnt(8)
	s_waitcnt lgkmcnt(0)
	s_barrier
	s_setprio 1
	s_waitcnt lgkmcnt(0)
	v_mfma_f32_16x16x32_bf16 v[124:127], v[144:147], v[188:191], 0
	v_mfma_f32_16x16x32_bf16 v[120:123], v[152:155], v[188:191], 0
	v_mfma_f32_16x16x32_bf16 v[116:119], v[144:147], v[196:199], 0
	v_mfma_f32_16x16x32_bf16 v[112:115], v[152:155], v[196:199], 0
	v_mfma_f32_16x16x32_bf16 v[104:107], v[144:147], v[204:207], 0
	v_mfma_f32_16x16x32_bf16 v[96:99], v[152:155], v[204:207], 0
	v_mfma_f32_16x16x32_bf16 v[88:91], v[144:147], v[212:215], 0
	v_mfma_f32_16x16x32_bf16 v[80:83], v[152:155], v[212:215], 0
	v_mfma_f32_16x16x32_bf16 v[124:127], v[148:151], v[192:195], v[124:127]
	v_mfma_f32_16x16x32_bf16 v[120:123], v[164:167], v[192:195], v[120:123]
	v_mfma_f32_16x16x32_bf16 v[116:119], v[148:151], v[200:203], v[116:119]
	v_mfma_f32_16x16x32_bf16 v[112:115], v[164:167], v[200:203], v[112:115]
	v_mfma_f32_16x16x32_bf16 v[104:107], v[148:151], v[208:211], v[104:107]
	v_mfma_f32_16x16x32_bf16 v[96:99], v[164:167], v[208:211], v[96:99]
	v_mfma_f32_16x16x32_bf16 v[88:91], v[148:151], v[216:219], v[88:91]
	v_mfma_f32_16x16x32_bf16 v[80:83], v[164:167], v[216:219], v[80:83]
	s_setprio 0
	s_setprio 1
	v_mfma_f32_16x16x32_bf16 v[108:111], v[168:171], v[188:191], 0
	v_mfma_f32_16x16x32_bf16 v[100:103], v[180:183], v[188:191], 0
	v_mfma_f32_16x16x32_bf16 v[92:95], v[168:171], v[196:199], 0
	v_mfma_f32_16x16x32_bf16 v[84:87], v[180:183], v[196:199], 0
	v_mfma_f32_16x16x32_bf16 v[76:79], v[168:171], v[204:207], 0
	v_mfma_f32_16x16x32_bf16 v[72:75], v[180:183], v[204:207], 0
	v_mfma_f32_16x16x32_bf16 v[68:71], v[168:171], v[212:215], 0
	v_mfma_f32_16x16x32_bf16 v[64:67], v[180:183], v[212:215], 0
	v_mfma_f32_16x16x32_bf16 v[108:111], v[172:175], v[192:195], v[108:111]
	v_mfma_f32_16x16x32_bf16 v[100:103], v[184:187], v[192:195], v[100:103]
	v_mfma_f32_16x16x32_bf16 v[92:95], v[172:175], v[200:203], v[92:95]
	v_mfma_f32_16x16x32_bf16 v[84:87], v[184:187], v[200:203], v[84:87]
	v_mfma_f32_16x16x32_bf16 v[76:79], v[172:175], v[208:211], v[76:79]
	v_mfma_f32_16x16x32_bf16 v[72:75], v[184:187], v[208:211], v[72:75]
	v_mfma_f32_16x16x32_bf16 v[68:71], v[172:175], v[216:219], v[68:71]
	v_mfma_f32_16x16x32_bf16 v[64:67], v[184:187], v[216:219], v[64:67]
	s_setprio 0
	s_barrier
	s_add_i32 s68, s57, s16
	s_mov_b64 s[98:99], s[66:67]
	s_mov_b32 m0, s68
	ds_read_b128 v[188:191], v161 offset:16384
	ds_read_b128 v[192:195], v161 offset:17408
	ds_read_b128 v[196:199], v161 offset:18432
	ds_read_b128 v[200:203], v161 offset:19456
	ds_read_b128 v[204:207], v161 offset:20480
	ds_read_b128 v[208:211], v161 offset:21504
	ds_read_b128 v[212:215], v161 offset:22528
	ds_read_b128 v[216:219], v161 offset:23552
	global_load_lds_dwordx4 v130, s[66:67]
	s_add_i32 m0, s68, 0x2000
	s_add_u32 s66, s66, s6
	s_addc_u32 s67, s67, s7
	s_add_i32 s68, s58, s16
	global_load_lds_dwordx4 v134, s[98:99]
	s_mov_b64 s[100:101], s[66:67]
	s_mov_b32 m0, s68
	s_nop 0
	global_load_lds_dwordx4 v130, s[66:67]
	s_add_i32 m0, s68, 0x2000
	s_mov_b64 s[22:23], s[34:35]
	global_load_lds_dwordx4 v134, s[66:67]
	s_mov_b32 m0, s17
	s_nop 0
	global_load_lds_dwordx4 v128, s[34:35]
	s_mov_b32 m0, s19
	s_nop 0
	global_load_lds_dwordx4 v132, s[34:35]
	s_waitcnt vmcnt(8)
	s_waitcnt lgkmcnt(0)
	s_barrier
; #define PG8_STAGE(bufoff, gbase, voff) do { _Pragma("unroll") for (int _i = 0; _i < 2; ++_i) \
;         __builtin_amdgcn_global_load_lds((const unsigned*)((const char*)(gbase) + (voff)[_i]), (PG8_LAS unsigned*)(lds + (bufoff) + ldsw + _i * 8192), 16, 0, 0); } while (0)
; #define PG8_LDA(dst, b, h) do { _Pragma("unroll") for (int m = 0; m < 4; ++m) _Pragma("unroll") for (int k = 0; k < 2; ++k) dst[m][k] = *(const PG8_LAS bf16x8*)(lds + PG8_SA(b, h) + aoff + m * 2048 + k * 1024); } while (0)
; #define PG8_LDB(dst, b, h) do { _Pragma("unroll") for (int n = 0; n < 2; ++n) _Pragma("unroll") for (int k = 0; k < 2; ++k) dst[n][k] = *(const PG8_LAS bf16x8*)(lds + PG8_SB(b, h) + boff + n * 2048 + k * 1024); } while (0)
; #define PG8_MMA(ai, bj, At, Bt) do { __builtin_amdgcn_s_setprio(1); _Pragma("unroll") for (int m = 0; m < 4; ++m) _Pragma("unroll") for (int n = 0; n < 2; ++n) _Pragma("unroll") for (int k = 0; k < 2; ++k) \
;         acc[ai][bj][m][n] = __builtin_amdgcn_mfma_f32_16x16x32_bf16(Bt[n][k], At[m][k], acc[ai][bj][m][n], 0, 0, 0); __builtin_amdgcn_s_setprio(0); } while (0)
; #define PG8_WAIT_V(n) asm volatile("s_waitcnt vmcnt(" #n ")" ::: "memory")
; #define PG8_WAIT_L(n) asm volatile("s_waitcnt lgkmcnt(" #n ")" ::: "memory")
; #define PG8_BAR __builtin_amdgcn_s_barrier()
; #define PG8_SCHED __builtin_amdgcn_sched_barrier(0)
; template <class Epi, class Sched, bool ALIGN_EPI = false, bool SP2 = false>
; __device__ __forceinline__ void gemm_phase(PG8_LAS unsigned char* lds, const Gemm g, const Sched& S, const Epi& E) {
;     ...
;             PG8_WAIT_V(8); PG8_WAIT_L(0); PG8_BAR; PG8_MMA(1, 0, At, B0); PG8_MMA(1, 1, At, B1); PG8_BAR; PG8_SCHED;
;             PG8_LDB(B0, 1, 0); PG8_LDB(B1, 1, 1); PG8_SCHED; PG8_LDA(At, 1, 0); PG8_STAGE(PG8_SA(0, 1), a2 + hstep, voffA);
;             PG8_WAIT_V(8); PG8_WAIT_L(0); PG8_BAR; PG8_MMA(0, 0, At, B0); PG8_MMA(0, 1, At, B1); PG8_BAR; PG8_SCHED;
	s_setprio 1
	s_waitcnt lgkmcnt(0)
	v_mfma_f32_16x16x32_bf16 v[60:63], v[144:147], v[188:191], 0
	v_mfma_f32_16x16x32_bf16 v[56:59], v[152:155], v[188:191], 0
	v_mfma_f32_16x16x32_bf16 v[52:55], v[144:147], v[196:199], 0
	v_mfma_f32_16x16x32_bf16 v[48:51], v[152:155], v[196:199], 0
	v_mfma_f32_16x16x32_bf16 v[40:43], v[144:147], v[204:207], 0
	v_mfma_f32_16x16x32_bf16 v[32:35], v[152:155], v[204:207], 0
	v_mfma_f32_16x16x32_bf16 v[24:27], v[144:147], v[212:215], 0
	v_mfma_f32_16x16x32_bf16 v[16:19], v[152:155], v[212:215], 0
	v_mfma_f32_16x16x32_bf16 v[60:63], v[148:151], v[192:195], v[60:63]
	v_mfma_f32_16x16x32_bf16 v[56:59], v[164:167], v[192:195], v[56:59]
	v_mfma_f32_16x16x32_bf16 v[52:55], v[148:151], v[200:203], v[52:55]
	v_mfma_f32_16x16x32_bf16 v[48:51], v[164:167], v[200:203], v[48:51]
	v_mfma_f32_16x16x32_bf16 v[40:43], v[148:151], v[208:211], v[40:43]
	v_mfma_f32_16x16x32_bf16 v[32:35], v[164:167], v[208:211], v[32:35]
	v_mfma_f32_16x16x32_bf16 v[24:27], v[148:151], v[216:219], v[24:27]
	v_mfma_f32_16x16x32_bf16 v[16:19], v[164:167], v[216:219], v[16:19]
	s_setprio 0
	s_setprio 1
	v_mfma_f32_16x16x32_bf16 v[44:47], v[168:171], v[188:191], 0
	v_mfma_f32_16x16x32_bf16 v[36:39], v[180:183], v[188:191], 0
	v_mfma_f32_16x16x32_bf16 v[28:31], v[168:171], v[196:199], 0
	v_mfma_f32_16x16x32_bf16 v[20:23], v[180:183], v[196:199], 0
	v_mfma_f32_16x16x32_bf16 v[12:15], v[168:171], v[204:207], 0
	v_mfma_f32_16x16x32_bf16 v[8:11], v[180:183], v[204:207], 0
	v_mfma_f32_16x16x32_bf16 v[4:7], v[168:171], v[212:215], 0
	v_mfma_f32_16x16x32_bf16 v[0:3], v[180:183], v[212:215], 0
	v_mfma_f32_16x16x32_bf16 v[44:47], v[172:175], v[192:195], v[44:47]
	v_mfma_f32_16x16x32_bf16 v[36:39], v[184:187], v[192:195], v[36:39]
	v_mfma_f32_16x16x32_bf16 v[28:31], v[172:175], v[200:203], v[28:31]
	v_mfma_f32_16x16x32_bf16 v[20:23], v[184:187], v[200:203], v[20:23]
	v_mfma_f32_16x16x32_bf16 v[12:15], v[172:175], v[208:211], v[12:15]
	v_mfma_f32_16x16x32_bf16 v[8:11], v[184:187], v[208:211], v[8:11]
	v_mfma_f32_16x16x32_bf16 v[4:7], v[172:175], v[216:219], v[4:7]
	v_mfma_f32_16x16x32_bf16 v[0:3], v[184:187], v[216:219], v[0:3]
	s_setprio 0
	s_barrier
	s_add_i32 s66, 0, 0x18000
	v_add_u32_e32 v163, s66, v157
	s_add_i32 s67, 0, 0x1c000
	ds_read_b128 v[144:147], v163
	ds_read_b128 v[148:151], v163 offset:1024
	ds_read_b128 v[152:155], v163 offset:2048
	ds_read_b128 v[164:167], v163 offset:3072
	v_add_u32_e32 v163, s67, v157
	ds_read_b128 v[168:171], v163
	ds_read_b128 v[172:175], v163 offset:1024
	ds_read_b128 v[180:183], v163 offset:2048
	ds_read_b128 v[184:187], v163 offset:3072
	s_add_u32 s34, s34, s6
	s_addc_u32 s35, s35, s7
	s_mov_b32 m0, s33
	ds_read_b128 v[188:191], v161 offset:32768
	ds_read_b128 v[192:195], v161 offset:33792
	ds_read_b128 v[196:199], v161 offset:34816
	ds_read_b128 v[200:203], v161 offset:35840
	ds_read_b128 v[204:207], v161 offset:36864
	ds_read_b128 v[208:211], v161 offset:37888
	ds_read_b128 v[212:215], v161 offset:38912
	ds_read_b128 v[216:219], v161 offset:39936
	global_load_lds_dwordx4 v128, s[34:35]
	s_mov_b32 m0, s36
	s_nop 0
	global_load_lds_dwordx4 v132, s[34:35]
	s_waitcnt vmcnt(8)
	s_waitcnt lgkmcnt(0)
	s_barrier
	s_setprio 1
	s_waitcnt lgkmcnt(0)
	v_mfma_f32_16x16x32_bf16 v[124:127], v[144:147], v[188:191], v[124:127]
	v_mfma_f32_16x16x32_bf16 v[120:123], v[152:155], v[188:191], v[120:123]
	v_mfma_f32_16x16x32_bf16 v[116:119], v[144:147], v[196:199], v[116:119]
	v_mfma_f32_16x16x32_bf16 v[112:115], v[152:155], v[196:199], v[112:115]
	v_mfma_f32_16x16x32_bf16 v[104:107], v[144:147], v[204:207], v[104:107]
	v_mfma_f32_16x16x32_bf16 v[96:99], v[152:155], v[204:207], v[96:99]
	v_mfma_f32_16x16x32_bf16 v[88:91], v[144:147], v[212:215], v[88:91]
	v_mfma_f32_16x16x32_bf16 v[80:83], v[152:155], v[212:215], v[80:83]
	v_mfma_f32_16x16x32_bf16 v[124:127], v[148:151], v[192:195], v[124:127]
	v_mfma_f32_16x16x32_bf16 v[120:123], v[164:167], v[192:195], v[120:123]
	v_mfma_f32_16x16x32_bf16 v[116:119], v[148:151], v[200:203], v[116:119]
	v_mfma_f32_16x16x32_bf16 v[112:115], v[164:167], v[200:203], v[112:115]
	v_mfma_f32_16x16x32_bf16 v[104:107], v[148:151], v[208:211], v[104:107]
	v_mfma_f32_16x16x32_bf16 v[96:99], v[164:167], v[208:211], v[96:99]
	v_mfma_f32_16x16x32_bf16 v[88:91], v[148:151], v[216:219], v[88:91]
	v_mfma_f32_16x16x32_bf16 v[80:83], v[164:167], v[216:219], v[80:83]
	s_setprio 0
	s_setprio 1
	v_mfma_f32_16x16x32_bf16 v[108:111], v[168:171], v[188:191], v[108:111]
	v_mfma_f32_16x16x32_bf16 v[100:103], v[180:183], v[188:191], v[100:103]
	v_mfma_f32_16x16x32_bf16 v[92:95], v[168:171], v[196:199], v[92:95]
	v_mfma_f32_16x16x32_bf16 v[84:87], v[180:183], v[196:199], v[84:87]
	v_mfma_f32_16x16x32_bf16 v[76:79], v[168:171], v[204:207], v[76:79]
	v_mfma_f32_16x16x32_bf16 v[72:75], v[180:183], v[204:207], v[72:75]
	v_mfma_f32_16x16x32_bf16 v[68:71], v[168:171], v[212:215], v[68:71]
	v_mfma_f32_16x16x32_bf16 v[64:67], v[180:183], v[212:215], v[64:67]
	v_mfma_f32_16x16x32_bf16 v[108:111], v[172:175], v[192:195], v[108:111]
	v_mfma_f32_16x16x32_bf16 v[100:103], v[184:187], v[192:195], v[100:103]
	v_mfma_f32_16x16x32_bf16 v[92:95], v[172:175], v[200:203], v[92:95]
	v_mfma_f32_16x16x32_bf16 v[84:87], v[184:187], v[200:203], v[84:87]
	v_mfma_f32_16x16x32_bf16 v[76:79], v[172:175], v[208:211], v[76:79]
	v_mfma_f32_16x16x32_bf16 v[72:75], v[184:187], v[208:211], v[72:75]
	v_mfma_f32_16x16x32_bf16 v[68:71], v[172:175], v[216:219], v[68:71]
	v_mfma_f32_16x16x32_bf16 v[64:67], v[184:187], v[216:219], v[64:67]
	s_setprio 0
	s_barrier
; #define PG8_STAGE(bufoff, gbase, voff) do { _Pragma("unroll") for (int _i = 0; _i < 2; ++_i) \
;         __builtin_amdgcn_global_load_lds((const unsigned*)((const char*)(gbase) + (voff)[_i]), (PG8_LAS unsigned*)(lds + (bufoff) + ldsw + _i * 8192), 16, 0, 0); } while (0)
; #define PG8_LDA(dst, b, h) do { _Pragma("unroll") for (int m = 0; m < 4; ++m) _Pragma("unroll") for (int k = 0; k < 2; ++k) dst[m][k] = *(const PG8_LAS bf16x8*)(lds + PG8_SA(b, h) + aoff + m * 2048 + k * 1024); } while (0)
; #define PG8_LDB(dst, b, h) do { _Pragma("unroll") for (int n = 0; n < 2; ++n) _Pragma("unroll") for (int k = 0; k < 2; ++k) dst[n][k] = *(const PG8_LAS bf16x8*)(lds + PG8_SB(b, h) + boff + n * 2048 + k * 1024); } while (0)
; #define PG8_MMA(ai, bj, At, Bt) do { __builtin_amdgcn_s_setprio(1); _Pragma("unroll") for (int m = 0; m < 4; ++m) _Pragma("unroll") for (int n = 0; n < 2; ++n) _Pragma("unroll") for (int k = 0; k < 2; ++k) \
;         acc[ai][bj][m][n] = __builtin_amdgcn_mfma_f32_16x16x32_bf16(Bt[n][k], At[m][k], acc[ai][bj][m][n], 0, 0, 0); __builtin_amdgcn_s_setprio(0); } while (0)
; #define PG8_WAIT_V(n) asm volatile("s_waitcnt vmcnt(" #n ")" ::: "memory")
; #define PG8_WAIT_L(n) asm volatile("s_waitcnt lgkmcnt(" #n ")" ::: "memory")
; #define PG8_BAR __builtin_amdgcn_s_barrier()
; #define PG8_SCHED __builtin_amdgcn_sched_barrier(0)
; template <class Epi, class Sched, bool ALIGN_EPI = false, bool SP2 = false>
; __device__ __forceinline__ void gemm_phase(PG8_LAS unsigned char* lds, const Gemm g, const Sched& S, const Epi& E) {
;     ...
;             PG8_LDB(B0, 0, 0); PG8_LDB(B1, 0, 1); PG8_SCHED; PG8_LDA(At, 0, 0); PG8_STAGE(PG8_SA(1, 1), a1 + hstep, voffA);
;             PG8_WAIT_V(8); PG8_WAIT_L(0); PG8_BAR; PG8_MMA(0, 0, At, B0); PG8_MMA(0, 1, At, B1); PG8_BAR; PG8_SCHED;
;     ...
;             PG8_LDA(At, 1, 1); PG8_STAGE(PG8_SB(1, 0), b3, voffB); PG8_STAGE(PG8_SB(1, 1), b3 + hstep, voffB); PG8_STAGE(PG8_SA(1, 0), a3, voffA);
;             PG8_WAIT_V(8); PG8_WAIT_L(0); PG8_BAR; PG8_MMA(1, 0, At, B0); PG8_MMA(1, 1, At, B1); PG8_BAR; PG8_SCHED;
	s_add_i32 s34, s66, s16
	s_add_i32 m0, s34, 0xffffff80
	ds_read_b128 v[188:191], v161 offset:49152
	ds_read_b128 v[192:195], v161 offset:50176
	ds_read_b128 v[196:199], v161 offset:51200
	ds_read_b128 v[200:203], v161 offset:52224
	ds_read_b128 v[204:207], v161 offset:53248
	ds_read_b128 v[208:211], v161 offset:54272
	ds_read_b128 v[212:215], v161 offset:55296
	ds_read_b128 v[216:219], v161 offset:56320
	global_load_lds_dwordx4 v130, s[98:99] offset:128
	s_add_i32 m0, s34, 0x1f80
	s_add_i32 s34, s67, s16
	global_load_lds_dwordx4 v134, s[98:99] offset:128
	s_add_i32 m0, s34, 0xffffff80
	s_nop 0
	global_load_lds_dwordx4 v130, s[100:101] offset:128
	s_add_i32 m0, s34, 0x1f80
	s_nop 0
	global_load_lds_dwordx4 v134, s[100:101] offset:128
	s_add_i32 m0, s37, 0xffffff80
	s_nop 0
	global_load_lds_dwordx4 v128, s[22:23] offset:128
	s_add_i32 m0, s38, 0xffffff80
	s_nop 0
	global_load_lds_dwordx4 v132, s[22:23] offset:128
	s_waitcnt vmcnt(8)
	s_waitcnt lgkmcnt(0)
	s_barrier
	s_setprio 1
	s_waitcnt lgkmcnt(0)
	v_mfma_f32_16x16x32_bf16 v[60:63], v[144:147], v[188:191], v[60:63]
	v_mfma_f32_16x16x32_bf16 v[56:59], v[152:155], v[188:191], v[56:59]
	v_mfma_f32_16x16x32_bf16 v[52:55], v[144:147], v[196:199], v[52:55]
	v_mfma_f32_16x16x32_bf16 v[48:51], v[152:155], v[196:199], v[48:51]
	v_mfma_f32_16x16x32_bf16 v[40:43], v[144:147], v[204:207], v[40:43]
	v_mfma_f32_16x16x32_bf16 v[32:35], v[152:155], v[204:207], v[32:35]
	v_mfma_f32_16x16x32_bf16 v[24:27], v[144:147], v[212:215], v[24:27]
	v_mfma_f32_16x16x32_bf16 v[16:19], v[152:155], v[212:215], v[16:19]
	v_mfma_f32_16x16x32_bf16 v[60:63], v[148:151], v[192:195], v[60:63]
	v_mfma_f32_16x16x32_bf16 v[56:59], v[164:167], v[192:195], v[56:59]
	v_mfma_f32_16x16x32_bf16 v[52:55], v[148:151], v[200:203], v[52:55]
	v_mfma_f32_16x16x32_bf16 v[48:51], v[164:167], v[200:203], v[48:51]
	v_mfma_f32_16x16x32_bf16 v[40:43], v[148:151], v[208:211], v[40:43]
	v_mfma_f32_16x16x32_bf16 v[32:35], v[164:167], v[208:211], v[32:35]
	v_mfma_f32_16x16x32_bf16 v[24:27], v[148:151], v[216:219], v[24:27]
	v_mfma_f32_16x16x32_bf16 v[16:19], v[164:167], v[216:219], v[16:19]
	s_setprio 0
	s_setprio 1
	v_mfma_f32_16x16x32_bf16 v[44:47], v[168:171], v[188:191], v[44:47]
	v_mfma_f32_16x16x32_bf16 v[36:39], v[180:183], v[188:191], v[36:39]
	v_mfma_f32_16x16x32_bf16 v[28:31], v[168:171], v[196:199], v[28:31]
	v_mfma_f32_16x16x32_bf16 v[20:23], v[180:183], v[196:199], v[20:23]
	v_mfma_f32_16x16x32_bf16 v[12:15], v[168:171], v[204:207], v[12:15]
	v_mfma_f32_16x16x32_bf16 v[8:11], v[180:183], v[204:207], v[8:11]
	v_mfma_f32_16x16x32_bf16 v[4:7], v[168:171], v[212:215], v[4:7]
	v_mfma_f32_16x16x32_bf16 v[0:3], v[180:183], v[212:215], v[0:3]
	v_mfma_f32_16x16x32_bf16 v[44:47], v[172:175], v[192:195], v[44:47]
	v_mfma_f32_16x16x32_bf16 v[36:39], v[184:187], v[192:195], v[36:39]
	v_mfma_f32_16x16x32_bf16 v[28:31], v[172:175], v[200:203], v[28:31]
	v_mfma_f32_16x16x32_bf16 v[20:23], v[184:187], v[200:203], v[20:23]
	v_mfma_f32_16x16x32_bf16 v[12:15], v[172:175], v[208:211], v[12:15]
	v_mfma_f32_16x16x32_bf16 v[8:11], v[184:187], v[208:211], v[8:11]
	v_mfma_f32_16x16x32_bf16 v[4:7], v[172:175], v[216:219], v[4:7]
	v_mfma_f32_16x16x32_bf16 v[0:3], v[184:187], v[216:219], v[0:3]
	s_setprio 0
	s_barrier
	s_add_u32 s30, s30, 0x100
	s_addc_u32 s31, s31, 0
	s_add_u32 s63, s63, 0x100
	s_addc_u32 s64, s64, 0
	s_cmp_ge_i32 s65, s40
	s_mov_b32 s34, s65
	s_cbranch_scc0 .LBB0_1411
	s_branch .Lpeel_x5
.LBB0_1411:
	ds_read_b128 v[144:147], v159
	ds_read_b128 v[148:151], v159 offset:1024
	ds_read_b128 v[152:155], v159 offset:2048
	ds_read_b128 v[164:167], v159 offset:3072
	ds_read_b128 v[168:171], v160
	ds_read_b128 v[172:175], v160 offset:1024
	ds_read_b128 v[180:183], v160 offset:2048
	ds_read_b128 v[184:187], v160 offset:3072
	s_add_i32 s65, s34, 2
	s_add_u32 s66, s30, 0x80
	s_addc_u32 s35, s31, 0
	s_cmp_eq_u32 s41, s34
	s_cselect_b32 s34, s0, s66
	s_cselect_b32 s35, s1, s35
	s_cselect_b32 s67, s29, s64
	s_cselect_b32 s66, s28, s63
	s_add_i32 m0, s17, 0xc000
	ds_read_b128 v[188:191], v161
	ds_read_b128 v[192:195], v161 offset:1024
	ds_read_b128 v[196:199], v161 offset:2048
	ds_read_b128 v[200:203], v161 offset:3072
	ds_read_b128 v[204:207], v161 offset:4096
	ds_read_b128 v[208:211], v161 offset:5120
	ds_read_b128 v[212:215], v161 offset:6144
	ds_read_b128 v[216:219], v161 offset:7168
	global_load_lds_dwordx4 v136, s[30:31]
	s_add_i32 m0, s17, 0xe000
	s_nop 0
	global_load_lds_dwordx4 v138, s[30:31]
	s_waitcnt vmcnt(8)
	s_waitcnt lgkmcnt(0)
	s_barrier
; #define PG8_STAGE(bufoff, gbase, voff) do { _Pragma("unroll") for (int _i = 0; _i < 2; ++_i) \
;         __builtin_amdgcn_global_load_lds((const unsigned*)((const char*)(gbase) + (voff)[_i]), (PG8_LAS unsigned*)(lds + (bufoff) + ldsw + _i * 8192), 16, 0, 0); } while (0)
; #define PG8_LDA(dst, b, h) do { _Pragma("unroll") for (int m = 0; m < 4; ++m) _Pragma("unroll") for (int k = 0; k < 2; ++k) dst[m][k] = *(const PG8_LAS bf16x8*)(lds + PG8_SA(b, h) + aoff + m * 2048 + k * 1024); } while (0)
; #define PG8_MMA(ai, bj, At, Bt) do { __builtin_amdgcn_s_setprio(1); _Pragma("unroll") for (int m = 0; m < 4; ++m) _Pragma("unroll") for (int n = 0; n < 2; ++n) _Pragma("unroll") for (int k = 0; k < 2; ++k) \
;         acc[ai][bj][m][n] = __builtin_amdgcn_mfma_f32_16x16x32_bf16(Bt[n][k], At[m][k], acc[ai][bj][m][n], 0, 0, 0); __builtin_amdgcn_s_setprio(0); } while (0)
; #define PG8_WAIT_V(n) asm volatile("s_waitcnt vmcnt(" #n ")" ::: "memory")
; #define PG8_WAIT_L(n) asm volatile("s_waitcnt lgkmcnt(" #n ")" ::: "memory")
; #define PG8_BAR __builtin_amdgcn_s_barrier()
; #define PG8_SCHED __builtin_amdgcn_sched_barrier(0)
; template <class Epi, class Sched, bool ALIGN_EPI = false, bool SP2 = false>
; __device__ __forceinline__ void gemm_phase(PG8_LAS unsigned char* lds, const Gemm g, const Sched& S, const Epi& E) {
;     ...
;             PG8_WAIT_V(8); PG8_WAIT_L(0); PG8_BAR; PG8_MMA(0, 0, At, B0); PG8_MMA(0, 1, At, B1); PG8_BAR; PG8_SCHED;
;             PG8_LDA(At, 0, 1); PG8_STAGE(PG8_SB(0, 0), b2, voffB); PG8_STAGE(PG8_SB(0, 1), b2 + hstep, voffB); PG8_STAGE(PG8_SA(0, 0), a2, voffA);
;             PG8_WAIT_V(8); PG8_WAIT_L(0); PG8_BAR; PG8_MMA(1, 0, At, B0); PG8_MMA(1, 1, At, B1); PG8_BAR; PG8_SCHED;
	s_setprio 1
	s_waitcnt lgkmcnt(0)
	v_mfma_f32_16x16x32_bf16 v[124:127], v[144:147], v[188:191], v[124:127]
	v_mfma_f32_16x16x32_bf16 v[120:123], v[152:155], v[188:191], v[120:123]
	v_mfma_f32_16x16x32_bf16 v[116:119], v[144:147], v[196:199], v[116:119]
	v_mfma_f32_16x16x32_bf16 v[112:115], v[152:155], v[196:199], v[112:115]
	v_mfma_f32_16x16x32_bf16 v[104:107], v[144:147], v[204:207], v[104:107]
	v_mfma_f32_16x16x32_bf16 v[96:99], v[152:155], v[204:207], v[96:99]
	v_mfma_f32_16x16x32_bf16 v[88:91], v[144:147], v[212:215], v[88:91]
	v_mfma_f32_16x16x32_bf16 v[80:83], v[152:155], v[212:215], v[80:83]
	v_mfma_f32_16x16x32_bf16 v[124:127], v[148:151], v[192:195], v[124:127]
	v_mfma_f32_16x16x32_bf16 v[120:123], v[164:167], v[192:195], v[120:123]
	v_mfma_f32_16x16x32_bf16 v[116:119], v[148:151], v[200:203], v[116:119]
	v_mfma_f32_16x16x32_bf16 v[112:115], v[164:167], v[200:203], v[112:115]
	v_mfma_f32_16x16x32_bf16 v[104:107], v[148:151], v[208:211], v[104:107]
	v_mfma_f32_16x16x32_bf16 v[96:99], v[164:167], v[208:211], v[96:99]
	v_mfma_f32_16x16x32_bf16 v[88:91], v[148:151], v[216:219], v[88:91]
	v_mfma_f32_16x16x32_bf16 v[80:83], v[164:167], v[216:219], v[80:83]
	s_setprio 0
	s_setprio 1
	v_mfma_f32_16x16x32_bf16 v[108:111], v[168:171], v[188:191], v[108:111]
	v_mfma_f32_16x16x32_bf16 v[100:103], v[180:183], v[188:191], v[100:103]
	v_mfma_f32_16x16x32_bf16 v[92:95], v[168:171], v[196:199], v[92:95]
	v_mfma_f32_16x16x32_bf16 v[84:87], v[180:183], v[196:199], v[84:87]
	v_mfma_f32_16x16x32_bf16 v[76:79], v[168:171], v[204:207], v[76:79]
	v_mfma_f32_16x16x32_bf16 v[72:75], v[180:183], v[204:207], v[72:75]
	v_mfma_f32_16x16x32_bf16 v[68:71], v[168:171], v[212:215], v[68:71]
	v_mfma_f32_16x16x32_bf16 v[64:67], v[180:183], v[212:215], v[64:67]
	v_mfma_f32_16x16x32_bf16 v[108:111], v[172:175], v[192:195], v[108:111]
	v_mfma_f32_16x16x32_bf16 v[100:103], v[184:187], v[192:195], v[100:103]
	v_mfma_f32_16x16x32_bf16 v[92:95], v[172:175], v[200:203], v[92:95]
	v_mfma_f32_16x16x32_bf16 v[84:87], v[184:187], v[200:203], v[84:87]
	v_mfma_f32_16x16x32_bf16 v[76:79], v[172:175], v[208:211], v[76:79]
	v_mfma_f32_16x16x32_bf16 v[72:75], v[184:187], v[208:211], v[72:75]
	v_mfma_f32_16x16x32_bf16 v[68:71], v[172:175], v[216:219], v[68:71]
	v_mfma_f32_16x16x32_bf16 v[64:67], v[184:187], v[216:219], v[64:67]
	s_setprio 0
	s_barrier
	s_add_i32 s68, s57, s16
	s_mov_b64 s[98:99], s[66:67]
	s_mov_b32 m0, s68
	ds_read_b128 v[188:191], v161 offset:16384
	ds_read_b128 v[192:195], v161 offset:17408
	ds_read_b128 v[196:199], v161 offset:18432
	ds_read_b128 v[200:203], v161 offset:19456
	ds_read_b128 v[204:207], v161 offset:20480
	ds_read_b128 v[208:211], v161 offset:21504
	ds_read_b128 v[212:215], v161 offset:22528
	ds_read_b128 v[216:219], v161 offset:23552
	global_load_lds_dwordx4 v130, s[66:67]
	s_add_i32 m0, s68, 0x2000
	s_add_u32 s66, s66, s6
	s_addc_u32 s67, s67, s7
	s_add_i32 s68, s58, s16
	global_load_lds_dwordx4 v134, s[98:99]
	s_mov_b64 s[100:101], s[66:67]
	s_mov_b32 m0, s68
	s_nop 0
	global_load_lds_dwordx4 v130, s[66:67]
	s_add_i32 m0, s68, 0x2000
	s_mov_b64 s[22:23], s[34:35]
	global_load_lds_dwordx4 v134, s[66:67]
	s_mov_b32 m0, s17
	s_nop 0
	global_load_lds_dwordx4 v128, s[34:35]
	s_mov_b32 m0, s19
	s_nop 0
	global_load_lds_dwordx4 v132, s[34:35]
	s_waitcnt vmcnt(8)
	s_waitcnt lgkmcnt(0)
	s_barrier
	s_setprio 1
	s_waitcnt lgkmcnt(0)
	v_mfma_f32_16x16x32_bf16 v[60:63], v[144:147], v[188:191], v[60:63]
	v_mfma_f32_16x16x32_bf16 v[56:59], v[152:155], v[188:191], v[56:59]
	v_mfma_f32_16x16x32_bf16 v[52:55], v[144:147], v[196:199], v[52:55]
	v_mfma_f32_16x16x32_bf16 v[48:51], v[152:155], v[196:199], v[48:51]
	v_mfma_f32_16x16x32_bf16 v[40:43], v[144:147], v[204:207], v[40:43]
	v_mfma_f32_16x16x32_bf16 v[32:35], v[152:155], v[204:207], v[32:35]
	v_mfma_f32_16x16x32_bf16 v[24:27], v[144:147], v[212:215], v[24:27]
	v_mfma_f32_16x16x32_bf16 v[16:19], v[152:155], v[212:215], v[16:19]
	v_mfma_f32_16x16x32_bf16 v[60:63], v[148:151], v[192:195], v[60:63]
	v_mfma_f32_16x16x32_bf16 v[56:59], v[164:167], v[192:195], v[56:59]
	v_mfma_f32_16x16x32_bf16 v[52:55], v[148:151], v[200:203], v[52:55]
	v_mfma_f32_16x16x32_bf16 v[48:51], v[164:167], v[200:203], v[48:51]
	v_mfma_f32_16x16x32_bf16 v[40:43], v[148:151], v[208:211], v[40:43]
	v_mfma_f32_16x16x32_bf16 v[32:35], v[164:167], v[208:211], v[32:35]
	v_mfma_f32_16x16x32_bf16 v[24:27], v[148:151], v[216:219], v[24:27]
	v_mfma_f32_16x16x32_bf16 v[16:19], v[164:167], v[216:219], v[16:19]
	s_setprio 0
	s_setprio 1
	v_mfma_f32_16x16x32_bf16 v[44:47], v[168:171], v[188:191], v[44:47]
	v_mfma_f32_16x16x32_bf16 v[36:39], v[180:183], v[188:191], v[36:39]
	v_mfma_f32_16x16x32_bf16 v[28:31], v[168:171], v[196:199], v[28:31]
	v_mfma_f32_16x16x32_bf16 v[20:23], v[180:183], v[196:199], v[20:23]
	v_mfma_f32_16x16x32_bf16 v[12:15], v[168:171], v[204:207], v[12:15]
	v_mfma_f32_16x16x32_bf16 v[8:11], v[180:183], v[204:207], v[8:11]
	v_mfma_f32_16x16x32_bf16 v[4:7], v[168:171], v[212:215], v[4:7]
	v_mfma_f32_16x16x32_bf16 v[0:3], v[180:183], v[212:215], v[0:3]
	v_mfma_f32_16x16x32_bf16 v[44:47], v[172:175], v[192:195], v[44:47]
	v_mfma_f32_16x16x32_bf16 v[36:39], v[184:187], v[192:195], v[36:39]
	v_mfma_f32_16x16x32_bf16 v[28:31], v[172:175], v[200:203], v[28:31]
	v_mfma_f32_16x16x32_bf16 v[20:23], v[184:187], v[200:203], v[20:23]
	v_mfma_f32_16x16x32_bf16 v[12:15], v[172:175], v[208:211], v[12:15]
	v_mfma_f32_16x16x32_bf16 v[8:11], v[184:187], v[208:211], v[8:11]
	v_mfma_f32_16x16x32_bf16 v[4:7], v[172:175], v[216:219], v[4:7]
	v_mfma_f32_16x16x32_bf16 v[0:3], v[184:187], v[216:219], v[0:3]
	s_setprio 0
	s_barrier
; #define PG8_STAGE(bufoff, gbase, voff) do { _Pragma("unroll") for (int _i = 0; _i < 2; ++_i) \
;         __builtin_amdgcn_global_load_lds((const unsigned*)((const char*)(gbase) + (voff)[_i]), (PG8_LAS unsigned*)(lds + (bufoff) + ldsw + _i * 8192), 16, 0, 0); } while (0)
; #define PG8_LDA(dst, b, h) do { _Pragma("unroll") for (int m = 0; m < 4; ++m) _Pragma("unroll") for (int k = 0; k < 2; ++k) dst[m][k] = *(const PG8_LAS bf16x8*)(lds + PG8_SA(b, h) + aoff + m * 2048 + k * 1024); } while (0)
; #define PG8_LDB(dst, b, h) do { _Pragma("unroll") for (int n = 0; n < 2; ++n) _Pragma("unroll") for (int k = 0; k < 2; ++k) dst[n][k] = *(const PG8_LAS bf16x8*)(lds + PG8_SB(b, h) + boff + n * 2048 + k * 1024); } while (0)
; #define PG8_MMA(ai, bj, At, Bt) do { __builtin_amdgcn_s_setprio(1); _Pragma("unroll") for (int m = 0; m < 4; ++m) _Pragma("unroll") for (int n = 0; n < 2; ++n) _Pragma("unroll") for (int k = 0; k < 2; ++k) \
;         acc[ai][bj][m][n] = __builtin_amdgcn_mfma_f32_16x16x32_bf16(Bt[n][k], At[m][k], acc[ai][bj][m][n], 0, 0, 0); __builtin_amdgcn_s_setprio(0); } while (0)
; #define PG8_WAIT_V(n) asm volatile("s_waitcnt vmcnt(" #n ")" ::: "memory")
; #define PG8_WAIT_L(n) asm volatile("s_waitcnt lgkmcnt(" #n ")" ::: "memory")
; #define PG8_BAR __builtin_amdgcn_s_barrier()
; #define PG8_SCHED __builtin_amdgcn_sched_barrier(0)
; template <class Epi, class Sched, bool ALIGN_EPI = false, bool SP2 = false>
; __device__ __forceinline__ void gemm_phase(PG8_LAS unsigned char* lds, const Gemm g, const Sched& S, const Epi& E) {
;     ...
;             PG8_LDB(B0, 1, 0); PG8_LDB(B1, 1, 1); PG8_SCHED; PG8_LDA(At, 1, 0); PG8_STAGE(PG8_SA(0, 1), a2 + hstep, voffA);
;             PG8_WAIT_V(8); PG8_WAIT_L(0); PG8_BAR; PG8_MMA(0, 0, At, B0); PG8_MMA(0, 1, At, B1); PG8_BAR; PG8_SCHED;
;             PG8_LDA(At, 1, 1); PG8_STAGE(PG8_SB(1, 0), b3, voffB); PG8_STAGE(PG8_SB(1, 1), b3 + hstep, voffB); PG8_STAGE(PG8_SA(1, 0), a3, voffA);
;             PG8_WAIT_V(8); PG8_WAIT_L(0); PG8_BAR; PG8_MMA(1, 0, At, B0); PG8_MMA(1, 1, At, B1); PG8_BAR; PG8_SCHED;
	s_add_i32 s66, 0, 0x18000
	v_add_u32_e32 v163, s66, v157
	s_add_i32 s67, 0, 0x1c000
	ds_read_b128 v[144:147], v163
	ds_read_b128 v[148:151], v163 offset:1024
	ds_read_b128 v[152:155], v163 offset:2048
	ds_read_b128 v[164:167], v163 offset:3072
	v_add_u32_e32 v163, s67, v157
	ds_read_b128 v[168:171], v163
	ds_read_b128 v[172:175], v163 offset:1024
	ds_read_b128 v[180:183], v163 offset:2048
	ds_read_b128 v[184:187], v163 offset:3072
	s_add_u32 s34, s34, s6
	s_addc_u32 s35, s35, s7
	s_mov_b32 m0, s33
	ds_read_b128 v[188:191], v161 offset:32768
	ds_read_b128 v[192:195], v161 offset:33792
	ds_read_b128 v[196:199], v161 offset:34816
	ds_read_b128 v[200:203], v161 offset:35840
	ds_read_b128 v[204:207], v161 offset:36864
	ds_read_b128 v[208:211], v161 offset:37888
	ds_read_b128 v[212:215], v161 offset:38912
	ds_read_b128 v[216:219], v161 offset:39936
	global_load_lds_dwordx4 v128, s[34:35]
	s_mov_b32 m0, s36
	s_nop 0
	global_load_lds_dwordx4 v132, s[34:35]
	s_waitcnt vmcnt(8)
	s_waitcnt lgkmcnt(0)
	s_barrier
	s_setprio 1
	s_waitcnt lgkmcnt(0)
	v_mfma_f32_16x16x32_bf16 v[124:127], v[144:147], v[188:191], v[124:127]
	v_mfma_f32_16x16x32_bf16 v[120:123], v[152:155], v[188:191], v[120:123]
	v_mfma_f32_16x16x32_bf16 v[116:119], v[144:147], v[196:199], v[116:119]
	v_mfma_f32_16x16x32_bf16 v[112:115], v[152:155], v[196:199], v[112:115]
	v_mfma_f32_16x16x32_bf16 v[104:107], v[144:147], v[204:207], v[104:107]
	v_mfma_f32_16x16x32_bf16 v[96:99], v[152:155], v[204:207], v[96:99]
	v_mfma_f32_16x16x32_bf16 v[88:91], v[144:147], v[212:215], v[88:91]
	v_mfma_f32_16x16x32_bf16 v[80:83], v[152:155], v[212:215], v[80:83]
	v_mfma_f32_16x16x32_bf16 v[124:127], v[148:151], v[192:195], v[124:127]
	v_mfma_f32_16x16x32_bf16 v[120:123], v[164:167], v[192:195], v[120:123]
	v_mfma_f32_16x16x32_bf16 v[116:119], v[148:151], v[200:203], v[116:119]
	v_mfma_f32_16x16x32_bf16 v[112:115], v[164:167], v[200:203], v[112:115]
	v_mfma_f32_16x16x32_bf16 v[104:107], v[148:151], v[208:211], v[104:107]
	v_mfma_f32_16x16x32_bf16 v[96:99], v[164:167], v[208:211], v[96:99]
	v_mfma_f32_16x16x32_bf16 v[88:91], v[148:151], v[216:219], v[88:91]
	v_mfma_f32_16x16x32_bf16 v[80:83], v[164:167], v[216:219], v[80:83]
	s_setprio 0
	s_setprio 1
	v_mfma_f32_16x16x32_bf16 v[108:111], v[168:171], v[188:191], v[108:111]
	v_mfma_f32_16x16x32_bf16 v[100:103], v[180:183], v[188:191], v[100:103]
	v_mfma_f32_16x16x32_bf16 v[92:95], v[168:171], v[196:199], v[92:95]
	v_mfma_f32_16x16x32_bf16 v[84:87], v[180:183], v[196:199], v[84:87]
	v_mfma_f32_16x16x32_bf16 v[76:79], v[168:171], v[204:207], v[76:79]
	v_mfma_f32_16x16x32_bf16 v[72:75], v[180:183], v[204:207], v[72:75]
	v_mfma_f32_16x16x32_bf16 v[68:71], v[168:171], v[212:215], v[68:71]
	v_mfma_f32_16x16x32_bf16 v[64:67], v[180:183], v[212:215], v[64:67]
	v_mfma_f32_16x16x32_bf16 v[108:111], v[172:175], v[192:195], v[108:111]
	v_mfma_f32_16x16x32_bf16 v[100:103], v[184:187], v[192:195], v[100:103]
	v_mfma_f32_16x16x32_bf16 v[92:95], v[172:175], v[200:203], v[92:95]
	v_mfma_f32_16x16x32_bf16 v[84:87], v[184:187], v[200:203], v[84:87]
	v_mfma_f32_16x16x32_bf16 v[76:79], v[172:175], v[208:211], v[76:79]
	v_mfma_f32_16x16x32_bf16 v[72:75], v[184:187], v[208:211], v[72:75]
	v_mfma_f32_16x16x32_bf16 v[68:71], v[172:175], v[216:219], v[68:71]
	v_mfma_f32_16x16x32_bf16 v[64:67], v[184:187], v[216:219], v[64:67]
	s_setprio 0
	s_barrier
	s_add_i32 s34, s66, s16
	s_add_i32 m0, s34, 0xffffff80
	ds_read_b128 v[188:191], v161 offset:49152
	ds_read_b128 v[192:195], v161 offset:50176
	ds_read_b128 v[196:199], v161 offset:51200
	ds_read_b128 v[200:203], v161 offset:52224
	ds_read_b128 v[204:207], v161 offset:53248
	ds_read_b128 v[208:211], v161 offset:54272
	ds_read_b128 v[212:215], v161 offset:55296
	ds_read_b128 v[216:219], v161 offset:56320
	global_load_lds_dwordx4 v130, s[98:99] offset:128
	s_add_i32 m0, s34, 0x1f80
	s_add_i32 s34, s67, s16
	global_load_lds_dwordx4 v134, s[98:99] offset:128
	s_add_i32 m0, s34, 0xffffff80
	s_nop 0
	global_load_lds_dwordx4 v130, s[100:101] offset:128
	s_add_i32 m0, s34, 0x1f80
	s_nop 0
	global_load_lds_dwordx4 v134, s[100:101] offset:128
	s_add_i32 m0, s37, 0xffffff80
	s_nop 0
	global_load_lds_dwordx4 v128, s[22:23] offset:128
	s_add_i32 m0, s38, 0xffffff80
	s_nop 0
	global_load_lds_dwordx4 v132, s[22:23] offset:128
	s_waitcnt vmcnt(8)
	s_waitcnt lgkmcnt(0)
	s_barrier
	s_setprio 1
	s_waitcnt lgkmcnt(0)
	v_mfma_f32_16x16x32_bf16 v[60:63], v[144:147], v[188:191], v[60:63]
	v_mfma_f32_16x16x32_bf16 v[56:59], v[152:155], v[188:191], v[56:59]
	v_mfma_f32_16x16x32_bf16 v[52:55], v[144:147], v[196:199], v[52:55]
	v_mfma_f32_16x16x32_bf16 v[48:51], v[152:155], v[196:199], v[48:51]
	v_mfma_f32_16x16x32_bf16 v[40:43], v[144:147], v[204:207], v[40:43]
	v_mfma_f32_16x16x32_bf16 v[32:35], v[152:155], v[204:207], v[32:35]
	v_mfma_f32_16x16x32_bf16 v[24:27], v[144:147], v[212:215], v[24:27]
	v_mfma_f32_16x16x32_bf16 v[16:19], v[152:155], v[212:215], v[16:19]
	v_mfma_f32_16x16x32_bf16 v[60:63], v[148:151], v[192:195], v[60:63]
	v_mfma_f32_16x16x32_bf16 v[56:59], v[164:167], v[192:195], v[56:59]
	v_mfma_f32_16x16x32_bf16 v[52:55], v[148:151], v[200:203], v[52:55]
	v_mfma_f32_16x16x32_bf16 v[48:51], v[164:167], v[200:203], v[48:51]
	v_mfma_f32_16x16x32_bf16 v[40:43], v[148:151], v[208:211], v[40:43]
	v_mfma_f32_16x16x32_bf16 v[32:35], v[164:167], v[208:211], v[32:35]
	v_mfma_f32_16x16x32_bf16 v[24:27], v[148:151], v[216:219], v[24:27]
	v_mfma_f32_16x16x32_bf16 v[16:19], v[164:167], v[216:219], v[16:19]
	s_setprio 0
	s_setprio 1
	v_mfma_f32_16x16x32_bf16 v[44:47], v[168:171], v[188:191], v[44:47]
	v_mfma_f32_16x16x32_bf16 v[36:39], v[180:183], v[188:191], v[36:39]
	v_mfma_f32_16x16x32_bf16 v[28:31], v[168:171], v[196:199], v[28:31]
	v_mfma_f32_16x16x32_bf16 v[20:23], v[180:183], v[196:199], v[20:23]
	v_mfma_f32_16x16x32_bf16 v[12:15], v[168:171], v[204:207], v[12:15]
	v_mfma_f32_16x16x32_bf16 v[8:11], v[180:183], v[204:207], v[8:11]
	v_mfma_f32_16x16x32_bf16 v[4:7], v[168:171], v[212:215], v[4:7]
	v_mfma_f32_16x16x32_bf16 v[0:3], v[180:183], v[212:215], v[0:3]
	v_mfma_f32_16x16x32_bf16 v[44:47], v[172:175], v[192:195], v[44:47]
	v_mfma_f32_16x16x32_bf16 v[36:39], v[184:187], v[192:195], v[36:39]
	v_mfma_f32_16x16x32_bf16 v[28:31], v[172:175], v[200:203], v[28:31]
	v_mfma_f32_16x16x32_bf16 v[20:23], v[184:187], v[200:203], v[20:23]
	v_mfma_f32_16x16x32_bf16 v[12:15], v[172:175], v[208:211], v[12:15]
	v_mfma_f32_16x16x32_bf16 v[8:11], v[184:187], v[208:211], v[8:11]
	v_mfma_f32_16x16x32_bf16 v[4:7], v[172:175], v[216:219], v[4:7]
	v_mfma_f32_16x16x32_bf16 v[0:3], v[184:187], v[216:219], v[0:3]
	s_setprio 0
	s_barrier
	s_add_u32 s30, s30, 0x100
	s_addc_u32 s31, s31, 0
	s_add_u32 s63, s63, 0x100
	s_addc_u32 s64, s64, 0
	s_cmp_ge_i32 s65, s40
	s_mov_b32 s34, s65
	s_cbranch_scc0 .LBB0_1411

; #define PG8_STAGE(bufoff, gbase, voff) do { _Pragma("unroll") for (int _i = 0; _i < 2; ++_i) \
;         __builtin_amdgcn_global_load_lds((const unsigned*)((const char*)(gbase) + (voff)[_i]), (PG8_LAS unsigned*)(lds + (bufoff) + ldsw + _i * 8192), 16, 0, 0); } while (0)
; #define PG8_LDA(dst, b, h) do { _Pragma("unroll") for (int m = 0; m < 4; ++m) _Pragma("unroll") for (int k = 0; k < 2; ++k) dst[m][k] = *(const PG8_LAS bf16x8*)(lds + PG8_SA(b, h) + aoff + m * 2048 + k * 1024); } while (0)
; #define PG8_LDB(dst, b, h) do { _Pragma("unroll") for (int n = 0; n < 2; ++n) _Pragma("unroll") for (int k = 0; k < 2; ++k) dst[n][k] = *(const PG8_LAS bf16x8*)(lds + PG8_SB(b, h) + boff + n * 2048 + k * 1024); } while (0)
; #define PG8_MMA(ai, bj, At, Bt) do { __builtin_amdgcn_s_setprio(1); _Pragma("unroll") for (int m = 0; m < 4; ++m) _Pragma("unroll") for (int n = 0; n < 2; ++n) _Pragma("unroll") for (int k = 0; k < 2; ++k) \
;         acc[ai][bj][m][n] = __builtin_amdgcn_mfma_f32_16x16x32_bf16(Bt[n][k], At[m][k], acc[ai][bj][m][n], 0, 0, 0); __builtin_amdgcn_s_setprio(0); } while (0)
; #define PG8_WAIT_V(n) asm volatile("s_waitcnt vmcnt(" #n ")" ::: "memory")
; #define PG8_WAIT_L(n) asm volatile("s_waitcnt lgkmcnt(" #n ")" ::: "memory")
; template <class Epi, class Sched, bool ALIGN_EPI = false, bool SP2 = false>
; __device__ __forceinline__ void gemm_phase(PG8_LAS unsigned char* lds, const Gemm g, const Sched& S, const Epi& E) {
;     ...
;             const bool last = (t == nt - 2);
;             const char* a1 = cA + (size_t)(t + 1) * kstep;
;             const char* a2 = last ? nA : cA + (size_t)(t + 2) * kstep; const char* b2 = last ? nB : cB + (size_t)(t + 2) * kstep;
;             const char* a3 = a2 + kstep; const char* b3 = b2 + kstep;
;             if (last && has_next) S.a_ready(nxt);
;             if constexpr (SP2) {
;             PG8_LDB(B0, 0, 0); PG8_LDB(B1, 0, 1); PG8_SCHED; PG8_LDA(At, 0, 0); PG8_STAGE(PG8_SA(1, 1), a1 + hstep, voffA);
;             PG8_WAIT_V(8); PG8_WAIT_L(0); PG8_BAR; PG8_MMA(0, 0, At, B0); PG8_MMA(0, 1, At, B1); PG8_BAR; PG8_SCHED;
;             PG8_LDA(At, 0, 1); PG8_STAGE(PG8_SB(0, 0), b2, voffB); PG8_STAGE(PG8_SB(0, 1), b2 + hstep, voffB); PG8_STAGE(PG8_SA(0, 0), a2, voffA);
;             PG8_WAIT_V(8); PG8_WAIT_L(0); PG8_BAR; PG8_MMA(1, 0, At, B0); PG8_MMA(1, 1, At, B1); PG8_BAR; PG8_SCHED;
.LBB0_1729:
	s_andn2_b64 vcc, exec, s[36:37]
	s_waitcnt vmcnt(0)
	s_waitcnt lgkmcnt(0)
	s_waitcnt lgkmcnt(0)
	s_cbranch_vccnz .LBB0_1732
	s_add_u32 s0, s8, 0x80
	s_addc_u32 s1, s9, 0
	s_add_u32 s8, s6, 0x100
	s_addc_u32 s9, s7, 0
	s_mov_b32 s6, 0
	ds_read_b128 v[146:149], v167
	ds_read_b128 v[150:153], v167 offset:1024
	ds_read_b128 v[154:157], v167 offset:2048
	ds_read_b128 v[158:161], v167 offset:3072
	ds_read_b128 v[172:175], v168
	ds_read_b128 v[176:179], v168 offset:1024
	ds_read_b128 v[180:183], v168 offset:2048
	ds_read_b128 v[184:187], v168 offset:3072
	s_add_i32 s10, s6, 2
	s_add_u32 s11, s0, 0x80
	s_addc_u32 s7, s1, 0
	s_cmp_eq_u32 s71, s6
	s_cselect_b32 s6, s56, s11
	s_cselect_b32 s7, s57, s7
	s_cselect_b32 s15, s59, s9
	s_cselect_b32 s14, s58, s8
	s_add_i32 m0, s19, 0xc000
	ds_read_b128 v[188:191], v169
	ds_read_b128 v[192:195], v169 offset:1024
	ds_read_b128 v[196:199], v169 offset:2048
	ds_read_b128 v[200:203], v169 offset:3072
	ds_read_b128 v[204:207], v169 offset:4096
	ds_read_b128 v[208:211], v169 offset:5120
	ds_read_b128 v[212:215], v169 offset:6144
	ds_read_b128 v[216:219], v169 offset:7168
	global_load_lds_dwordx4 v138, s[0:1]
	s_add_i32 m0, s19, 0xe000
	s_nop 0
	global_load_lds_dwordx4 v140, s[0:1]
	s_waitcnt vmcnt(8)
	s_waitcnt lgkmcnt(0)
	s_barrier
	s_setprio 1
	s_waitcnt lgkmcnt(0)
	v_mfma_f32_16x16x32_bf16 v[124:127], v[146:149], v[188:191], 0
	v_mfma_f32_16x16x32_bf16 v[120:123], v[154:157], v[188:191], 0
	v_mfma_f32_16x16x32_bf16 v[108:111], v[146:149], v[196:199], 0
	v_mfma_f32_16x16x32_bf16 v[104:107], v[154:157], v[196:199], 0
	v_mfma_f32_16x16x32_bf16 v[92:95], v[146:149], v[204:207], 0
	v_mfma_f32_16x16x32_bf16 v[88:91], v[154:157], v[204:207], 0
	v_mfma_f32_16x16x32_bf16 v[76:79], v[146:149], v[212:215], 0
	v_mfma_f32_16x16x32_bf16 v[72:75], v[154:157], v[212:215], 0
	v_mfma_f32_16x16x32_bf16 v[124:127], v[150:153], v[192:195], v[124:127]
	v_mfma_f32_16x16x32_bf16 v[120:123], v[158:161], v[192:195], v[120:123]
	v_mfma_f32_16x16x32_bf16 v[108:111], v[150:153], v[200:203], v[108:111]
	v_mfma_f32_16x16x32_bf16 v[104:107], v[158:161], v[200:203], v[104:107]
	v_mfma_f32_16x16x32_bf16 v[92:95], v[150:153], v[208:211], v[92:95]
	v_mfma_f32_16x16x32_bf16 v[88:91], v[158:161], v[208:211], v[88:91]
	v_mfma_f32_16x16x32_bf16 v[76:79], v[150:153], v[216:219], v[76:79]
	v_mfma_f32_16x16x32_bf16 v[72:75], v[158:161], v[216:219], v[72:75]
	s_setprio 0
	s_setprio 1
	v_mfma_f32_16x16x32_bf16 v[116:119], v[172:175], v[188:191], 0
	v_mfma_f32_16x16x32_bf16 v[112:115], v[180:183], v[188:191], 0
	v_mfma_f32_16x16x32_bf16 v[100:103], v[172:175], v[196:199], 0
	v_mfma_f32_16x16x32_bf16 v[96:99], v[180:183], v[196:199], 0
	v_mfma_f32_16x16x32_bf16 v[84:87], v[172:175], v[204:207], 0
	v_mfma_f32_16x16x32_bf16 v[80:83], v[180:183], v[204:207], 0
	v_mfma_f32_16x16x32_bf16 v[68:71], v[172:175], v[212:215], 0
	v_mfma_f32_16x16x32_bf16 v[64:67], v[180:183], v[212:215], 0
	v_mfma_f32_16x16x32_bf16 v[116:119], v[176:179], v[192:195], v[116:119]
	v_mfma_f32_16x16x32_bf16 v[112:115], v[184:187], v[192:195], v[112:115]
	v_mfma_f32_16x16x32_bf16 v[100:103], v[176:179], v[200:203], v[100:103]
	v_mfma_f32_16x16x32_bf16 v[96:99], v[184:187], v[200:203], v[96:99]
	v_mfma_f32_16x16x32_bf16 v[84:87], v[176:179], v[208:211], v[84:87]
	v_mfma_f32_16x16x32_bf16 v[80:83], v[184:187], v[208:211], v[80:83]
	v_mfma_f32_16x16x32_bf16 v[68:71], v[176:179], v[216:219], v[68:71]
	v_mfma_f32_16x16x32_bf16 v[64:67], v[184:187], v[216:219], v[64:67]
	s_setprio 0
	s_barrier
	s_add_i32 s11, s75, s17
	s_mov_b64 s[98:99], s[14:15]
	s_mov_b32 m0, s11
	ds_read_b128 v[188:191], v169 offset:16384
	ds_read_b128 v[192:195], v169 offset:17408
	ds_read_b128 v[196:199], v169 offset:18432
	ds_read_b128 v[200:203], v169 offset:19456
	ds_read_b128 v[204:207], v169 offset:20480
	ds_read_b128 v[208:211], v169 offset:21504
	ds_read_b128 v[212:215], v169 offset:22528
	ds_read_b128 v[216:219], v169 offset:23552
	global_load_lds_dwordx4 v130, s[14:15]
	s_add_i32 m0, s11, 0x2000
	s_add_u32 s14, s14, s24
	s_addc_u32 s15, s15, s25
	s_add_i32 s11, s76, s17
	global_load_lds_dwordx4 v134, s[98:99]
	s_mov_b32 m0, s11
	s_nop 0
	global_load_lds_dwordx4 v130, s[14:15]
	s_add_i32 m0, s11, 0x2000
	s_mov_b64 s[100:101], s[6:7]
	global_load_lds_dwordx4 v134, s[14:15]
	s_mov_b32 m0, s19
	s_nop 0
	global_load_lds_dwordx4 v128, s[6:7]
	s_mov_b32 m0, s33
	s_nop 0
	global_load_lds_dwordx4 v132, s[6:7]
	s_waitcnt vmcnt(8)
	s_waitcnt lgkmcnt(0)
	s_barrier
	s_setprio 1
	s_waitcnt lgkmcnt(0)
	v_mfma_f32_16x16x32_bf16 v[60:63], v[146:149], v[188:191], 0
	v_mfma_f32_16x16x32_bf16 v[56:59], v[154:157], v[188:191], 0
	v_mfma_f32_16x16x32_bf16 v[44:47], v[146:149], v[196:199], 0
	v_mfma_f32_16x16x32_bf16 v[40:43], v[154:157], v[196:199], 0
	v_mfma_f32_16x16x32_bf16 v[28:31], v[146:149], v[204:207], 0
	v_mfma_f32_16x16x32_bf16 v[24:27], v[154:157], v[204:207], 0
	v_mfma_f32_16x16x32_bf16 v[12:15], v[146:149], v[212:215], 0
	v_mfma_f32_16x16x32_bf16 v[8:11], v[154:157], v[212:215], 0
	v_mfma_f32_16x16x32_bf16 v[60:63], v[150:153], v[192:195], v[60:63]
	v_mfma_f32_16x16x32_bf16 v[56:59], v[158:161], v[192:195], v[56:59]
	v_mfma_f32_16x16x32_bf16 v[44:47], v[150:153], v[200:203], v[44:47]
	v_mfma_f32_16x16x32_bf16 v[40:43], v[158:161], v[200:203], v[40:43]
	v_mfma_f32_16x16x32_bf16 v[28:31], v[150:153], v[208:211], v[28:31]
	v_mfma_f32_16x16x32_bf16 v[24:27], v[158:161], v[208:211], v[24:27]
	v_mfma_f32_16x16x32_bf16 v[12:15], v[150:153], v[216:219], v[12:15]
	v_mfma_f32_16x16x32_bf16 v[8:11], v[158:161], v[216:219], v[8:11]
	s_setprio 0
	s_setprio 1
	v_mfma_f32_16x16x32_bf16 v[52:55], v[172:175], v[188:191], 0
	v_mfma_f32_16x16x32_bf16 v[48:51], v[180:183], v[188:191], 0
	v_mfma_f32_16x16x32_bf16 v[36:39], v[172:175], v[196:199], 0
	v_mfma_f32_16x16x32_bf16 v[32:35], v[180:183], v[196:199], 0
	v_mfma_f32_16x16x32_bf16 v[20:23], v[172:175], v[204:207], 0
	v_mfma_f32_16x16x32_bf16 v[16:19], v[180:183], v[204:207], 0
	v_mfma_f32_16x16x32_bf16 v[4:7], v[172:175], v[212:215], 0
	v_mfma_f32_16x16x32_bf16 v[0:3], v[180:183], v[212:215], 0
	v_mfma_f32_16x16x32_bf16 v[52:55], v[176:179], v[192:195], v[52:55]
	v_mfma_f32_16x16x32_bf16 v[48:51], v[184:187], v[192:195], v[48:51]
	v_mfma_f32_16x16x32_bf16 v[36:39], v[176:179], v[200:203], v[36:39]
	v_mfma_f32_16x16x32_bf16 v[32:35], v[184:187], v[200:203], v[32:35]
	v_mfma_f32_16x16x32_bf16 v[20:23], v[176:179], v[208:211], v[20:23]
	v_mfma_f32_16x16x32_bf16 v[16:19], v[184:187], v[208:211], v[16:19]
	v_mfma_f32_16x16x32_bf16 v[4:7], v[176:179], v[216:219], v[4:7]
	v_mfma_f32_16x16x32_bf16 v[0:3], v[184:187], v[216:219], v[0:3]
	s_setprio 0
	s_barrier
; #define PG8_STAGE(bufoff, gbase, voff) do { _Pragma("unroll") for (int _i = 0; _i < 2; ++_i) \
;         __builtin_amdgcn_global_load_lds((const unsigned*)((const char*)(gbase) + (voff)[_i]), (PG8_LAS unsigned*)(lds + (bufoff) + ldsw + _i * 8192), 16, 0, 0); } while (0)
; #define PG8_LDA(dst, b, h) do { _Pragma("unroll") for (int m = 0; m < 4; ++m) _Pragma("unroll") for (int k = 0; k < 2; ++k) dst[m][k] = *(const PG8_LAS bf16x8*)(lds + PG8_SA(b, h) + aoff + m * 2048 + k * 1024); } while (0)
; #define PG8_LDB(dst, b, h) do { _Pragma("unroll") for (int n = 0; n < 2; ++n) _Pragma("unroll") for (int k = 0; k < 2; ++k) dst[n][k] = *(const PG8_LAS bf16x8*)(lds + PG8_SB(b, h) + boff + n * 2048 + k * 1024); } while (0)
; #define PG8_MMA(ai, bj, At, Bt) do { __builtin_amdgcn_s_setprio(1); _Pragma("unroll") for (int m = 0; m < 4; ++m) _Pragma("unroll") for (int n = 0; n < 2; ++n) _Pragma("unroll") for (int k = 0; k < 2; ++k) \
;         acc[ai][bj][m][n] = __builtin_amdgcn_mfma_f32_16x16x32_bf16(Bt[n][k], At[m][k], acc[ai][bj][m][n], 0, 0, 0); __builtin_amdgcn_s_setprio(0); } while (0)
; #define PG8_WAIT_V(n) asm volatile("s_waitcnt vmcnt(" #n ")" ::: "memory")
; #define PG8_WAIT_L(n) asm volatile("s_waitcnt lgkmcnt(" #n ")" ::: "memory")
; #define PG8_BAR __builtin_amdgcn_s_barrier()
; #define PG8_SCHED __builtin_amdgcn_sched_barrier(0)
; template <class Epi, class Sched, bool ALIGN_EPI = false, bool SP2 = false>
; __device__ __forceinline__ void gemm_phase(PG8_LAS unsigned char* lds, const Gemm g, const Sched& S, const Epi& E) {
;     ...
;             PG8_LDB(B0, 1, 0); PG8_LDB(B1, 1, 1); PG8_SCHED; PG8_LDA(At, 1, 0); PG8_STAGE(PG8_SA(0, 1), a2 + hstep, voffA);
;             PG8_WAIT_V(8); PG8_WAIT_L(0); PG8_BAR; PG8_MMA(0, 0, At, B0); PG8_MMA(0, 1, At, B1); PG8_BAR; PG8_SCHED;
;             PG8_LDA(At, 1, 1); PG8_STAGE(PG8_SB(1, 0), b3, voffB); PG8_STAGE(PG8_SB(1, 1), b3 + hstep, voffB); PG8_STAGE(PG8_SA(1, 0), a3, voffA);
;             PG8_WAIT_V(8); PG8_WAIT_L(0); PG8_BAR; PG8_MMA(1, 0, At, B0); PG8_MMA(1, 1, At, B1); PG8_BAR; PG8_SCHED;
	s_add_i32 s11, 0, 0x18000
	v_add_u32_e32 v136, s11, v165
	s_add_i32 s13, 0, 0x1c000
	ds_read_b128 v[146:149], v136
	ds_read_b128 v[150:153], v136 offset:1024
	ds_read_b128 v[154:157], v136 offset:2048
	ds_read_b128 v[158:161], v136 offset:3072
	v_add_u32_e32 v136, s13, v165
	ds_read_b128 v[172:175], v136
	ds_read_b128 v[176:179], v136 offset:1024
	ds_read_b128 v[180:183], v136 offset:2048
	ds_read_b128 v[184:187], v136 offset:3072
	s_add_u32 s6, s6, s24
	s_addc_u32 s7, s7, s25
	s_mov_b32 m0, s66
	ds_read_b128 v[188:191], v169 offset:32768
	ds_read_b128 v[192:195], v169 offset:33792
	ds_read_b128 v[196:199], v169 offset:34816
	ds_read_b128 v[200:203], v169 offset:35840
	ds_read_b128 v[204:207], v169 offset:36864
	ds_read_b128 v[208:211], v169 offset:37888
	ds_read_b128 v[212:215], v169 offset:38912
	ds_read_b128 v[216:219], v169 offset:39936
	global_load_lds_dwordx4 v128, s[6:7]
	s_mov_b32 m0, s67
	s_nop 0
	global_load_lds_dwordx4 v132, s[6:7]
	s_waitcnt vmcnt(8)
	s_waitcnt lgkmcnt(0)
	s_barrier
	s_setprio 1
	s_waitcnt lgkmcnt(0)
	v_mfma_f32_16x16x32_bf16 v[124:127], v[146:149], v[188:191], v[124:127]
	v_mfma_f32_16x16x32_bf16 v[120:123], v[154:157], v[188:191], v[120:123]
	v_mfma_f32_16x16x32_bf16 v[108:111], v[146:149], v[196:199], v[108:111]
	v_mfma_f32_16x16x32_bf16 v[104:107], v[154:157], v[196:199], v[104:107]
	v_mfma_f32_16x16x32_bf16 v[92:95], v[146:149], v[204:207], v[92:95]
	v_mfma_f32_16x16x32_bf16 v[88:91], v[154:157], v[204:207], v[88:91]
	v_mfma_f32_16x16x32_bf16 v[76:79], v[146:149], v[212:215], v[76:79]
	v_mfma_f32_16x16x32_bf16 v[72:75], v[154:157], v[212:215], v[72:75]
	v_mfma_f32_16x16x32_bf16 v[124:127], v[150:153], v[192:195], v[124:127]
	v_mfma_f32_16x16x32_bf16 v[120:123], v[158:161], v[192:195], v[120:123]
	v_mfma_f32_16x16x32_bf16 v[108:111], v[150:153], v[200:203], v[108:111]
	v_mfma_f32_16x16x32_bf16 v[104:107], v[158:161], v[200:203], v[104:107]
	v_mfma_f32_16x16x32_bf16 v[92:95], v[150:153], v[208:211], v[92:95]
	v_mfma_f32_16x16x32_bf16 v[88:91], v[158:161], v[208:211], v[88:91]
	v_mfma_f32_16x16x32_bf16 v[76:79], v[150:153], v[216:219], v[76:79]
	v_mfma_f32_16x16x32_bf16 v[72:75], v[158:161], v[216:219], v[72:75]
	s_setprio 0
	s_setprio 1
	v_mfma_f32_16x16x32_bf16 v[116:119], v[172:175], v[188:191], v[116:119]
	v_mfma_f32_16x16x32_bf16 v[112:115], v[180:183], v[188:191], v[112:115]
	v_mfma_f32_16x16x32_bf16 v[100:103], v[172:175], v[196:199], v[100:103]
	v_mfma_f32_16x16x32_bf16 v[96:99], v[180:183], v[196:199], v[96:99]
	v_mfma_f32_16x16x32_bf16 v[84:87], v[172:175], v[204:207], v[84:87]
	v_mfma_f32_16x16x32_bf16 v[80:83], v[180:183], v[204:207], v[80:83]
	v_mfma_f32_16x16x32_bf16 v[68:71], v[172:175], v[212:215], v[68:71]
	v_mfma_f32_16x16x32_bf16 v[64:67], v[180:183], v[212:215], v[64:67]
	v_mfma_f32_16x16x32_bf16 v[116:119], v[176:179], v[192:195], v[116:119]
	v_mfma_f32_16x16x32_bf16 v[112:115], v[184:187], v[192:195], v[112:115]
	v_mfma_f32_16x16x32_bf16 v[100:103], v[176:179], v[200:203], v[100:103]
	v_mfma_f32_16x16x32_bf16 v[96:99], v[184:187], v[200:203], v[96:99]
	v_mfma_f32_16x16x32_bf16 v[84:87], v[176:179], v[208:211], v[84:87]
	v_mfma_f32_16x16x32_bf16 v[80:83], v[184:187], v[208:211], v[80:83]
	v_mfma_f32_16x16x32_bf16 v[68:71], v[176:179], v[216:219], v[68:71]
	v_mfma_f32_16x16x32_bf16 v[64:67], v[184:187], v[216:219], v[64:67]
	s_setprio 0
	s_barrier
	s_add_i32 s6, s11, s17
	s_add_i32 m0, s6, 0xffffff80
	ds_read_b128 v[188:191], v169 offset:49152
	ds_read_b128 v[192:195], v169 offset:50176
	ds_read_b128 v[196:199], v169 offset:51200
	ds_read_b128 v[200:203], v169 offset:52224
	ds_read_b128 v[204:207], v169 offset:53248
	ds_read_b128 v[208:211], v169 offset:54272
	ds_read_b128 v[212:215], v169 offset:55296
	ds_read_b128 v[216:219], v169 offset:56320
	global_load_lds_dwordx4 v130, s[98:99] offset:128
	s_add_i32 m0, s6, 0x1f80
	s_add_i32 s6, s13, s17
	global_load_lds_dwordx4 v134, s[98:99] offset:128
	s_add_i32 m0, s6, 0xffffff80
	s_nop 0
	global_load_lds_dwordx4 v130, s[14:15] offset:128
	s_add_i32 m0, s6, 0x1f80
	s_nop 0
	global_load_lds_dwordx4 v134, s[14:15] offset:128
	s_add_i32 m0, s68, 0xffffff80
	s_nop 0
	global_load_lds_dwordx4 v128, s[100:101] offset:128
	s_add_i32 m0, s69, 0xffffff80
	s_nop 0
	global_load_lds_dwordx4 v132, s[100:101] offset:128
	s_waitcnt vmcnt(8)
	s_waitcnt lgkmcnt(0)
	s_barrier
	s_setprio 1
	s_waitcnt lgkmcnt(0)
	v_mfma_f32_16x16x32_bf16 v[60:63], v[146:149], v[188:191], v[60:63]
	v_mfma_f32_16x16x32_bf16 v[56:59], v[154:157], v[188:191], v[56:59]
	v_mfma_f32_16x16x32_bf16 v[44:47], v[146:149], v[196:199], v[44:47]
	v_mfma_f32_16x16x32_bf16 v[40:43], v[154:157], v[196:199], v[40:43]
	v_mfma_f32_16x16x32_bf16 v[28:31], v[146:149], v[204:207], v[28:31]
	v_mfma_f32_16x16x32_bf16 v[24:27], v[154:157], v[204:207], v[24:27]
	v_mfma_f32_16x16x32_bf16 v[12:15], v[146:149], v[212:215], v[12:15]
	v_mfma_f32_16x16x32_bf16 v[8:11], v[154:157], v[212:215], v[8:11]
	v_mfma_f32_16x16x32_bf16 v[60:63], v[150:153], v[192:195], v[60:63]
	v_mfma_f32_16x16x32_bf16 v[56:59], v[158:161], v[192:195], v[56:59]
	v_mfma_f32_16x16x32_bf16 v[44:47], v[150:153], v[200:203], v[44:47]
	v_mfma_f32_16x16x32_bf16 v[40:43], v[158:161], v[200:203], v[40:43]
	v_mfma_f32_16x16x32_bf16 v[28:31], v[150:153], v[208:211], v[28:31]
	v_mfma_f32_16x16x32_bf16 v[24:27], v[158:161], v[208:211], v[24:27]
	v_mfma_f32_16x16x32_bf16 v[12:15], v[150:153], v[216:219], v[12:15]
	v_mfma_f32_16x16x32_bf16 v[8:11], v[158:161], v[216:219], v[8:11]
	s_setprio 0
	s_setprio 1
	v_mfma_f32_16x16x32_bf16 v[52:55], v[172:175], v[188:191], v[52:55]
	v_mfma_f32_16x16x32_bf16 v[48:51], v[180:183], v[188:191], v[48:51]
	v_mfma_f32_16x16x32_bf16 v[36:39], v[172:175], v[196:199], v[36:39]
	v_mfma_f32_16x16x32_bf16 v[32:35], v[180:183], v[196:199], v[32:35]
	v_mfma_f32_16x16x32_bf16 v[20:23], v[172:175], v[204:207], v[20:23]
	v_mfma_f32_16x16x32_bf16 v[16:19], v[180:183], v[204:207], v[16:19]
	v_mfma_f32_16x16x32_bf16 v[4:7], v[172:175], v[212:215], v[4:7]
	v_mfma_f32_16x16x32_bf16 v[0:3], v[180:183], v[212:215], v[0:3]
	v_mfma_f32_16x16x32_bf16 v[52:55], v[176:179], v[192:195], v[52:55]
	v_mfma_f32_16x16x32_bf16 v[48:51], v[184:187], v[192:195], v[48:51]
	v_mfma_f32_16x16x32_bf16 v[36:39], v[176:179], v[200:203], v[36:39]
	v_mfma_f32_16x16x32_bf16 v[32:35], v[184:187], v[200:203], v[32:35]
	v_mfma_f32_16x16x32_bf16 v[20:23], v[176:179], v[208:211], v[20:23]
	v_mfma_f32_16x16x32_bf16 v[16:19], v[184:187], v[208:211], v[16:19]
	v_mfma_f32_16x16x32_bf16 v[4:7], v[176:179], v[216:219], v[4:7]
	v_mfma_f32_16x16x32_bf16 v[0:3], v[184:187], v[216:219], v[0:3]
	s_setprio 0
	s_barrier
	s_add_u32 s0, s0, 0x100
	s_addc_u32 s1, s1, 0
	s_add_u32 s8, s8, 0x100
	s_addc_u32 s9, s9, 0
	s_cmp_ge_i32 s10, s70
	s_mov_b32 s6, s10
	s_cbranch_scc0 .LBB0_1731
	s_branch .Lpeel_x8
; #define PG8_STAGE(bufoff, gbase, voff) do { _Pragma("unroll") for (int _i = 0; _i < 2; ++_i) \
;         __builtin_amdgcn_global_load_lds((const unsigned*)((const char*)(gbase) + (voff)[_i]), (PG8_LAS unsigned*)(lds + (bufoff) + ldsw + _i * 8192), 16, 0, 0); } while (0)
; #define PG8_LDA(dst, b, h) do { _Pragma("unroll") for (int m = 0; m < 4; ++m) _Pragma("unroll") for (int k = 0; k < 2; ++k) dst[m][k] = *(const PG8_LAS bf16x8*)(lds + PG8_SA(b, h) + aoff + m * 2048 + k * 1024); } while (0)
; #define PG8_LDB(dst, b, h) do { _Pragma("unroll") for (int n = 0; n < 2; ++n) _Pragma("unroll") for (int k = 0; k < 2; ++k) dst[n][k] = *(const PG8_LAS bf16x8*)(lds + PG8_SB(b, h) + boff + n * 2048 + k * 1024); } while (0)
; #define PG8_MMA(ai, bj, At, Bt) do { __builtin_amdgcn_s_setprio(1); _Pragma("unroll") for (int m = 0; m < 4; ++m) _Pragma("unroll") for (int n = 0; n < 2; ++n) _Pragma("unroll") for (int k = 0; k < 2; ++k) \
;         acc[ai][bj][m][n] = __builtin_amdgcn_mfma_f32_16x16x32_bf16(Bt[n][k], At[m][k], acc[ai][bj][m][n], 0, 0, 0); __builtin_amdgcn_s_setprio(0); } while (0)
; #define PG8_WAIT_V(n) asm volatile("s_waitcnt vmcnt(" #n ")" ::: "memory")
; #define PG8_WAIT_L(n) asm volatile("s_waitcnt lgkmcnt(" #n ")" ::: "memory")
; template <class Epi, class Sched, bool ALIGN_EPI = false, bool SP2 = false>
; __device__ __forceinline__ void gemm_phase(PG8_LAS unsigned char* lds, const Gemm g, const Sched& S, const Epi& E) {
;     ...
;             const bool last = (t == nt - 2);
;             const char* a1 = cA + (size_t)(t + 1) * kstep;
;             const char* a2 = last ? nA : cA + (size_t)(t + 2) * kstep; const char* b2 = last ? nB : cB + (size_t)(t + 2) * kstep;
;             const char* a3 = a2 + kstep; const char* b3 = b2 + kstep;
;             if (last && has_next) S.a_ready(nxt);
;             if constexpr (SP2) {
;             PG8_LDB(B0, 0, 0); PG8_LDB(B1, 0, 1); PG8_SCHED; PG8_LDA(At, 0, 0); PG8_STAGE(PG8_SA(1, 1), a1 + hstep, voffA);
;             PG8_WAIT_V(8); PG8_WAIT_L(0); PG8_BAR; PG8_MMA(0, 0, At, B0); PG8_MMA(0, 1, At, B1); PG8_BAR; PG8_SCHED;
;             PG8_LDA(At, 0, 1); PG8_STAGE(PG8_SB(0, 0), b2, voffB); PG8_STAGE(PG8_SB(0, 1), b2 + hstep, voffB); PG8_STAGE(PG8_SA(0, 0), a2, voffA);
;             PG8_WAIT_V(8); PG8_WAIT_L(0); PG8_BAR; PG8_MMA(1, 0, At, B0); PG8_MMA(1, 1, At, B1); PG8_BAR; PG8_SCHED;
.LBB0_1731:
	ds_read_b128 v[146:149], v167
	ds_read_b128 v[150:153], v167 offset:1024
	ds_read_b128 v[154:157], v167 offset:2048
	ds_read_b128 v[158:161], v167 offset:3072
	ds_read_b128 v[172:175], v168
	ds_read_b128 v[176:179], v168 offset:1024
	ds_read_b128 v[180:183], v168 offset:2048
	ds_read_b128 v[184:187], v168 offset:3072
	s_add_i32 s10, s6, 2
	s_add_u32 s11, s0, 0x80
	s_addc_u32 s7, s1, 0
	s_cmp_eq_u32 s71, s6
	s_cselect_b32 s6, s56, s11
	s_cselect_b32 s7, s57, s7
	s_cselect_b32 s15, s59, s9
	s_cselect_b32 s14, s58, s8
	s_add_i32 m0, s19, 0xc000
	ds_read_b128 v[188:191], v169
	ds_read_b128 v[192:195], v169 offset:1024
	ds_read_b128 v[196:199], v169 offset:2048
	ds_read_b128 v[200:203], v169 offset:3072
	ds_read_b128 v[204:207], v169 offset:4096
	ds_read_b128 v[208:211], v169 offset:5120
	ds_read_b128 v[212:215], v169 offset:6144
	ds_read_b128 v[216:219], v169 offset:7168
	global_load_lds_dwordx4 v138, s[0:1]
	s_add_i32 m0, s19, 0xe000
	s_nop 0
	global_load_lds_dwordx4 v140, s[0:1]
	s_waitcnt vmcnt(8)
	s_waitcnt lgkmcnt(0)
	s_barrier
	s_setprio 1
	s_waitcnt lgkmcnt(0)
	v_mfma_f32_16x16x32_bf16 v[124:127], v[146:149], v[188:191], v[124:127]
	v_mfma_f32_16x16x32_bf16 v[120:123], v[154:157], v[188:191], v[120:123]
	v_mfma_f32_16x16x32_bf16 v[108:111], v[146:149], v[196:199], v[108:111]
	v_mfma_f32_16x16x32_bf16 v[104:107], v[154:157], v[196:199], v[104:107]
	v_mfma_f32_16x16x32_bf16 v[92:95], v[146:149], v[204:207], v[92:95]
	v_mfma_f32_16x16x32_bf16 v[88:91], v[154:157], v[204:207], v[88:91]
	v_mfma_f32_16x16x32_bf16 v[76:79], v[146:149], v[212:215], v[76:79]
	v_mfma_f32_16x16x32_bf16 v[72:75], v[154:157], v[212:215], v[72:75]
	v_mfma_f32_16x16x32_bf16 v[124:127], v[150:153], v[192:195], v[124:127]
	v_mfma_f32_16x16x32_bf16 v[120:123], v[158:161], v[192:195], v[120:123]
	v_mfma_f32_16x16x32_bf16 v[108:111], v[150:153], v[200:203], v[108:111]
	v_mfma_f32_16x16x32_bf16 v[104:107], v[158:161], v[200:203], v[104:107]
	v_mfma_f32_16x16x32_bf16 v[92:95], v[150:153], v[208:211], v[92:95]
	v_mfma_f32_16x16x32_bf16 v[88:91], v[158:161], v[208:211], v[88:91]
	v_mfma_f32_16x16x32_bf16 v[76:79], v[150:153], v[216:219], v[76:79]
	v_mfma_f32_16x16x32_bf16 v[72:75], v[158:161], v[216:219], v[72:75]
	s_setprio 0
	s_setprio 1
	v_mfma_f32_16x16x32_bf16 v[116:119], v[172:175], v[188:191], v[116:119]
	v_mfma_f32_16x16x32_bf16 v[112:115], v[180:183], v[188:191], v[112:115]
	v_mfma_f32_16x16x32_bf16 v[100:103], v[172:175], v[196:199], v[100:103]
	v_mfma_f32_16x16x32_bf16 v[96:99], v[180:183], v[196:199], v[96:99]
	v_mfma_f32_16x16x32_bf16 v[84:87], v[172:175], v[204:207], v[84:87]
	v_mfma_f32_16x16x32_bf16 v[80:83], v[180:183], v[204:207], v[80:83]
	v_mfma_f32_16x16x32_bf16 v[68:71], v[172:175], v[212:215], v[68:71]
	v_mfma_f32_16x16x32_bf16 v[64:67], v[180:183], v[212:215], v[64:67]
	v_mfma_f32_16x16x32_bf16 v[116:119], v[176:179], v[192:195], v[116:119]
	v_mfma_f32_16x16x32_bf16 v[112:115], v[184:187], v[192:195], v[112:115]
	v_mfma_f32_16x16x32_bf16 v[100:103], v[176:179], v[200:203], v[100:103]
	v_mfma_f32_16x16x32_bf16 v[96:99], v[184:187], v[200:203], v[96:99]
	v_mfma_f32_16x16x32_bf16 v[84:87], v[176:179], v[208:211], v[84:87]
	v_mfma_f32_16x16x32_bf16 v[80:83], v[184:187], v[208:211], v[80:83]
	v_mfma_f32_16x16x32_bf16 v[68:71], v[176:179], v[216:219], v[68:71]
	v_mfma_f32_16x16x32_bf16 v[64:67], v[184:187], v[216:219], v[64:67]
	s_setprio 0
	s_barrier
	s_add_i32 s11, s75, s17
	s_mov_b64 s[98:99], s[14:15]
	s_mov_b32 m0, s11
	ds_read_b128 v[188:191], v169 offset:16384
	ds_read_b128 v[192:195], v169 offset:17408
	ds_read_b128 v[196:199], v169 offset:18432
	ds_read_b128 v[200:203], v169 offset:19456
	ds_read_b128 v[204:207], v169 offset:20480
	ds_read_b128 v[208:211], v169 offset:21504
	ds_read_b128 v[212:215], v169 offset:22528
	ds_read_b128 v[216:219], v169 offset:23552
	global_load_lds_dwordx4 v130, s[14:15]
	s_add_i32 m0, s11, 0x2000
	s_add_u32 s14, s14, s24
	s_addc_u32 s15, s15, s25
	s_add_i32 s11, s76, s17
	global_load_lds_dwordx4 v134, s[98:99]
	s_mov_b32 m0, s11
	s_nop 0
	global_load_lds_dwordx4 v130, s[14:15]
	s_add_i32 m0, s11, 0x2000
	s_mov_b64 s[100:101], s[6:7]
	global_load_lds_dwordx4 v134, s[14:15]
	s_mov_b32 m0, s19
	s_nop 0
	global_load_lds_dwordx4 v128, s[6:7]
	s_mov_b32 m0, s33
	s_nop 0
	global_load_lds_dwordx4 v132, s[6:7]
	s_waitcnt vmcnt(8)
	s_waitcnt lgkmcnt(0)
	s_barrier
	s_setprio 1
	s_waitcnt lgkmcnt(0)
	v_mfma_f32_16x16x32_bf16 v[60:63], v[146:149], v[188:191], v[60:63]
	v_mfma_f32_16x16x32_bf16 v[56:59], v[154:157], v[188:191], v[56:59]
	v_mfma_f32_16x16x32_bf16 v[44:47], v[146:149], v[196:199], v[44:47]
	v_mfma_f32_16x16x32_bf16 v[40:43], v[154:157], v[196:199], v[40:43]
	v_mfma_f32_16x16x32_bf16 v[28:31], v[146:149], v[204:207], v[28:31]
	v_mfma_f32_16x16x32_bf16 v[24:27], v[154:157], v[204:207], v[24:27]
	v_mfma_f32_16x16x32_bf16 v[12:15], v[146:149], v[212:215], v[12:15]
	v_mfma_f32_16x16x32_bf16 v[8:11], v[154:157], v[212:215], v[8:11]
	v_mfma_f32_16x16x32_bf16 v[60:63], v[150:153], v[192:195], v[60:63]
	v_mfma_f32_16x16x32_bf16 v[56:59], v[158:161], v[192:195], v[56:59]
	v_mfma_f32_16x16x32_bf16 v[44:47], v[150:153], v[200:203], v[44:47]
	v_mfma_f32_16x16x32_bf16 v[40:43], v[158:161], v[200:203], v[40:43]
	v_mfma_f32_16x16x32_bf16 v[28:31], v[150:153], v[208:211], v[28:31]
	v_mfma_f32_16x16x32_bf16 v[24:27], v[158:161], v[208:211], v[24:27]
	v_mfma_f32_16x16x32_bf16 v[12:15], v[150:153], v[216:219], v[12:15]
	v_mfma_f32_16x16x32_bf16 v[8:11], v[158:161], v[216:219], v[8:11]
	s_setprio 0
	s_setprio 1
	v_mfma_f32_16x16x32_bf16 v[52:55], v[172:175], v[188:191], v[52:55]
	v_mfma_f32_16x16x32_bf16 v[48:51], v[180:183], v[188:191], v[48:51]
	v_mfma_f32_16x16x32_bf16 v[36:39], v[172:175], v[196:199], v[36:39]
	v_mfma_f32_16x16x32_bf16 v[32:35], v[180:183], v[196:199], v[32:35]
	v_mfma_f32_16x16x32_bf16 v[20:23], v[172:175], v[204:207], v[20:23]
	v_mfma_f32_16x16x32_bf16 v[16:19], v[180:183], v[204:207], v[16:19]
	v_mfma_f32_16x16x32_bf16 v[4:7], v[172:175], v[212:215], v[4:7]
	v_mfma_f32_16x16x32_bf16 v[0:3], v[180:183], v[212:215], v[0:3]
	v_mfma_f32_16x16x32_bf16 v[52:55], v[176:179], v[192:195], v[52:55]
	v_mfma_f32_16x16x32_bf16 v[48:51], v[184:187], v[192:195], v[48:51]
	v_mfma_f32_16x16x32_bf16 v[36:39], v[176:179], v[200:203], v[36:39]
	v_mfma_f32_16x16x32_bf16 v[32:35], v[184:187], v[200:203], v[32:35]
	v_mfma_f32_16x16x32_bf16 v[20:23], v[176:179], v[208:211], v[20:23]
	v_mfma_f32_16x16x32_bf16 v[16:19], v[184:187], v[208:211], v[16:19]
	v_mfma_f32_16x16x32_bf16 v[4:7], v[176:179], v[216:219], v[4:7]
	v_mfma_f32_16x16x32_bf16 v[0:3], v[184:187], v[216:219], v[0:3]
	s_setprio 0
	s_barrier
; #define PG8_STAGE(bufoff, gbase, voff) do { _Pragma("unroll") for (int _i = 0; _i < 2; ++_i) \
;         __builtin_amdgcn_global_load_lds((const unsigned*)((const char*)(gbase) + (voff)[_i]), (PG8_LAS unsigned*)(lds + (bufoff) + ldsw + _i * 8192), 16, 0, 0); } while (0)
; #define PG8_LDA(dst, b, h) do { _Pragma("unroll") for (int m = 0; m < 4; ++m) _Pragma("unroll") for (int k = 0; k < 2; ++k) dst[m][k] = *(const PG8_LAS bf16x8*)(lds + PG8_SA(b, h) + aoff + m * 2048 + k * 1024); } while (0)
; #define PG8_LDB(dst, b, h) do { _Pragma("unroll") for (int n = 0; n < 2; ++n) _Pragma("unroll") for (int k = 0; k < 2; ++k) dst[n][k] = *(const PG8_LAS bf16x8*)(lds + PG8_SB(b, h) + boff + n * 2048 + k * 1024); } while (0)
; #define PG8_MMA(ai, bj, At, Bt) do { __builtin_amdgcn_s_setprio(1); _Pragma("unroll") for (int m = 0; m < 4; ++m) _Pragma("unroll") for (int n = 0; n < 2; ++n) _Pragma("unroll") for (int k = 0; k < 2; ++k) \
;         acc[ai][bj][m][n] = __builtin_amdgcn_mfma_f32_16x16x32_bf16(Bt[n][k], At[m][k], acc[ai][bj][m][n], 0, 0, 0); __builtin_amdgcn_s_setprio(0); } while (0)
; #define PG8_WAIT_V(n) asm volatile("s_waitcnt vmcnt(" #n ")" ::: "memory")
; #define PG8_WAIT_L(n) asm volatile("s_waitcnt lgkmcnt(" #n ")" ::: "memory")
; #define PG8_BAR __builtin_amdgcn_s_barrier()
; #define PG8_SCHED __builtin_amdgcn_sched_barrier(0)
; template <class Epi, class Sched, bool ALIGN_EPI = false, bool SP2 = false>
; __device__ __forceinline__ void gemm_phase(PG8_LAS unsigned char* lds, const Gemm g, const Sched& S, const Epi& E) {
;     ...
;             PG8_LDB(B0, 1, 0); PG8_LDB(B1, 1, 1); PG8_SCHED; PG8_LDA(At, 1, 0); PG8_STAGE(PG8_SA(0, 1), a2 + hstep, voffA);
;             PG8_WAIT_V(8); PG8_WAIT_L(0); PG8_BAR; PG8_MMA(0, 0, At, B0); PG8_MMA(0, 1, At, B1); PG8_BAR; PG8_SCHED;
;             PG8_LDA(At, 1, 1); PG8_STAGE(PG8_SB(1, 0), b3, voffB); PG8_STAGE(PG8_SB(1, 1), b3 + hstep, voffB); PG8_STAGE(PG8_SA(1, 0), a3, voffA);
;             PG8_WAIT_V(8); PG8_WAIT_L(0); PG8_BAR; PG8_MMA(1, 0, At, B0); PG8_MMA(1, 1, At, B1); PG8_BAR; PG8_SCHED;
	s_add_i32 s11, 0, 0x18000
	v_add_u32_e32 v136, s11, v165
	s_add_i32 s13, 0, 0x1c000
	ds_read_b128 v[146:149], v136
	ds_read_b128 v[150:153], v136 offset:1024
	ds_read_b128 v[154:157], v136 offset:2048
	ds_read_b128 v[158:161], v136 offset:3072
	v_add_u32_e32 v136, s13, v165
	ds_read_b128 v[172:175], v136
	ds_read_b128 v[176:179], v136 offset:1024
	ds_read_b128 v[180:183], v136 offset:2048
	ds_read_b128 v[184:187], v136 offset:3072
	s_add_u32 s6, s6, s24
	s_addc_u32 s7, s7, s25
	s_mov_b32 m0, s66
	ds_read_b128 v[188:191], v169 offset:32768
	ds_read_b128 v[192:195], v169 offset:33792
	ds_read_b128 v[196:199], v169 offset:34816
	ds_read_b128 v[200:203], v169 offset:35840
	ds_read_b128 v[204:207], v169 offset:36864
	ds_read_b128 v[208:211], v169 offset:37888
	ds_read_b128 v[212:215], v169 offset:38912
	ds_read_b128 v[216:219], v169 offset:39936
	global_load_lds_dwordx4 v128, s[6:7]
	s_mov_b32 m0, s67
	s_nop 0
	global_load_lds_dwordx4 v132, s[6:7]
	s_waitcnt vmcnt(8)
	s_waitcnt lgkmcnt(0)
	s_barrier
	s_setprio 1
	s_waitcnt lgkmcnt(0)
	v_mfma_f32_16x16x32_bf16 v[124:127], v[146:149], v[188:191], v[124:127]
	v_mfma_f32_16x16x32_bf16 v[120:123], v[154:157], v[188:191], v[120:123]
	v_mfma_f32_16x16x32_bf16 v[108:111], v[146:149], v[196:199], v[108:111]
	v_mfma_f32_16x16x32_bf16 v[104:107], v[154:157], v[196:199], v[104:107]
	v_mfma_f32_16x16x32_bf16 v[92:95], v[146:149], v[204:207], v[92:95]
	v_mfma_f32_16x16x32_bf16 v[88:91], v[154:157], v[204:207], v[88:91]
	v_mfma_f32_16x16x32_bf16 v[76:79], v[146:149], v[212:215], v[76:79]
	v_mfma_f32_16x16x32_bf16 v[72:75], v[154:157], v[212:215], v[72:75]
	v_mfma_f32_16x16x32_bf16 v[124:127], v[150:153], v[192:195], v[124:127]
	v_mfma_f32_16x16x32_bf16 v[120:123], v[158:161], v[192:195], v[120:123]
	v_mfma_f32_16x16x32_bf16 v[108:111], v[150:153], v[200:203], v[108:111]
	v_mfma_f32_16x16x32_bf16 v[104:107], v[158:161], v[200:203], v[104:107]
	v_mfma_f32_16x16x32_bf16 v[92:95], v[150:153], v[208:211], v[92:95]
	v_mfma_f32_16x16x32_bf16 v[88:91], v[158:161], v[208:211], v[88:91]
	v_mfma_f32_16x16x32_bf16 v[76:79], v[150:153], v[216:219], v[76:79]
	v_mfma_f32_16x16x32_bf16 v[72:75], v[158:161], v[216:219], v[72:75]
	s_setprio 0
	s_setprio 1
	v_mfma_f32_16x16x32_bf16 v[116:119], v[172:175], v[188:191], v[116:119]
	v_mfma_f32_16x16x32_bf16 v[112:115], v[180:183], v[188:191], v[112:115]
	v_mfma_f32_16x16x32_bf16 v[100:103], v[172:175], v[196:199], v[100:103]
	v_mfma_f32_16x16x32_bf16 v[96:99], v[180:183], v[196:199], v[96:99]
	v_mfma_f32_16x16x32_bf16 v[84:87], v[172:175], v[204:207], v[84:87]
	v_mfma_f32_16x16x32_bf16 v[80:83], v[180:183], v[204:207], v[80:83]
	v_mfma_f32_16x16x32_bf16 v[68:71], v[172:175], v[212:215], v[68:71]
	v_mfma_f32_16x16x32_bf16 v[64:67], v[180:183], v[212:215], v[64:67]
	v_mfma_f32_16x16x32_bf16 v[116:119], v[176:179], v[192:195], v[116:119]
	v_mfma_f32_16x16x32_bf16 v[112:115], v[184:187], v[192:195], v[112:115]
	v_mfma_f32_16x16x32_bf16 v[100:103], v[176:179], v[200:203], v[100:103]
	v_mfma_f32_16x16x32_bf16 v[96:99], v[184:187], v[200:203], v[96:99]
	v_mfma_f32_16x16x32_bf16 v[84:87], v[176:179], v[208:211], v[84:87]
	v_mfma_f32_16x16x32_bf16 v[80:83], v[184:187], v[208:211], v[80:83]
	v_mfma_f32_16x16x32_bf16 v[68:71], v[176:179], v[216:219], v[68:71]
	v_mfma_f32_16x16x32_bf16 v[64:67], v[184:187], v[216:219], v[64:67]
	s_setprio 0
	s_barrier
	s_add_i32 s6, s11, s17
	s_add_i32 m0, s6, 0xffffff80
	ds_read_b128 v[188:191], v169 offset:49152
	ds_read_b128 v[192:195], v169 offset:50176
	ds_read_b128 v[196:199], v169 offset:51200
	ds_read_b128 v[200:203], v169 offset:52224
	ds_read_b128 v[204:207], v169 offset:53248
	ds_read_b128 v[208:211], v169 offset:54272
	ds_read_b128 v[212:215], v169 offset:55296
	ds_read_b128 v[216:219], v169 offset:56320
	global_load_lds_dwordx4 v130, s[98:99] offset:128
	s_add_i32 m0, s6, 0x1f80
	s_add_i32 s6, s13, s17
	global_load_lds_dwordx4 v134, s[98:99] offset:128
	s_add_i32 m0, s6, 0xffffff80
	s_nop 0
	global_load_lds_dwordx4 v130, s[14:15] offset:128
	s_add_i32 m0, s6, 0x1f80
	s_nop 0
	global_load_lds_dwordx4 v134, s[14:15] offset:128
	s_add_i32 m0, s68, 0xffffff80
	s_nop 0
	global_load_lds_dwordx4 v128, s[100:101] offset:128
	s_add_i32 m0, s69, 0xffffff80
	s_nop 0
	global_load_lds_dwordx4 v132, s[100:101] offset:128
	s_waitcnt vmcnt(8)
	s_waitcnt lgkmcnt(0)
	s_barrier
	s_setprio 1
	s_waitcnt lgkmcnt(0)
	v_mfma_f32_16x16x32_bf16 v[60:63], v[146:149], v[188:191], v[60:63]
	v_mfma_f32_16x16x32_bf16 v[56:59], v[154:157], v[188:191], v[56:59]
	v_mfma_f32_16x16x32_bf16 v[44:47], v[146:149], v[196:199], v[44:47]
	v_mfma_f32_16x16x32_bf16 v[40:43], v[154:157], v[196:199], v[40:43]
	v_mfma_f32_16x16x32_bf16 v[28:31], v[146:149], v[204:207], v[28:31]
	v_mfma_f32_16x16x32_bf16 v[24:27], v[154:157], v[204:207], v[24:27]
	v_mfma_f32_16x16x32_bf16 v[12:15], v[146:149], v[212:215], v[12:15]
	v_mfma_f32_16x16x32_bf16 v[8:11], v[154:157], v[212:215], v[8:11]
	v_mfma_f32_16x16x32_bf16 v[60:63], v[150:153], v[192:195], v[60:63]
	v_mfma_f32_16x16x32_bf16 v[56:59], v[158:161], v[192:195], v[56:59]
	v_mfma_f32_16x16x32_bf16 v[44:47], v[150:153], v[200:203], v[44:47]
	v_mfma_f32_16x16x32_bf16 v[40:43], v[158:161], v[200:203], v[40:43]
	v_mfma_f32_16x16x32_bf16 v[28:31], v[150:153], v[208:211], v[28:31]
	v_mfma_f32_16x16x32_bf16 v[24:27], v[158:161], v[208:211], v[24:27]
	v_mfma_f32_16x16x32_bf16 v[12:15], v[150:153], v[216:219], v[12:15]
	v_mfma_f32_16x16x32_bf16 v[8:11], v[158:161], v[216:219], v[8:11]
	s_setprio 0
	s_setprio 1
	v_mfma_f32_16x16x32_bf16 v[52:55], v[172:175], v[188:191], v[52:55]
	v_mfma_f32_16x16x32_bf16 v[48:51], v[180:183], v[188:191], v[48:51]
	v_mfma_f32_16x16x32_bf16 v[36:39], v[172:175], v[196:199], v[36:39]
	v_mfma_f32_16x16x32_bf16 v[32:35], v[180:183], v[196:199], v[32:35]
	v_mfma_f32_16x16x32_bf16 v[20:23], v[172:175], v[204:207], v[20:23]
	v_mfma_f32_16x16x32_bf16 v[16:19], v[180:183], v[204:207], v[16:19]
	v_mfma_f32_16x16x32_bf16 v[4:7], v[172:175], v[212:215], v[4:7]
	v_mfma_f32_16x16x32_bf16 v[0:3], v[180:183], v[212:215], v[0:3]
	v_mfma_f32_16x16x32_bf16 v[52:55], v[176:179], v[192:195], v[52:55]
	v_mfma_f32_16x16x32_bf16 v[48:51], v[184:187], v[192:195], v[48:51]
	v_mfma_f32_16x16x32_bf16 v[36:39], v[176:179], v[200:203], v[36:39]
	v_mfma_f32_16x16x32_bf16 v[32:35], v[184:187], v[200:203], v[32:35]
	v_mfma_f32_16x16x32_bf16 v[20:23], v[176:179], v[208:211], v[20:23]
	v_mfma_f32_16x16x32_bf16 v[16:19], v[184:187], v[208:211], v[16:19]
	v_mfma_f32_16x16x32_bf16 v[4:7], v[176:179], v[216:219], v[4:7]
	v_mfma_f32_16x16x32_bf16 v[0:3], v[184:187], v[216:219], v[0:3]
	s_setprio 0
	s_barrier
	s_add_u32 s0, s0, 0x100
	s_addc_u32 s1, s1, 0
	s_add_u32 s8, s8, 0x100
	s_addc_u32 s9, s9, 0
	s_cmp_ge_i32 s10, s70
	s_mov_b32 s6, s10
	s_cbranch_scc0 .LBB0_1731

; #define PG8_STAGE(bufoff, gbase, voff) do { _Pragma("unroll") for (int _i = 0; _i < 2; ++_i) \
;         __builtin_amdgcn_global_load_lds((const unsigned*)((const char*)(gbase) + (voff)[_i]), (PG8_LAS unsigned*)(lds + (bufoff) + ldsw + _i * 8192), 16, 0, 0); } while (0)
; #define PG8_LDA(dst, b, h) do { _Pragma("unroll") for (int m = 0; m < 4; ++m) _Pragma("unroll") for (int k = 0; k < 2; ++k) dst[m][k] = *(const PG8_LAS bf16x8*)(lds + PG8_SA(b, h) + aoff + m * 2048 + k * 1024); } while (0)
; #define PG8_LDB(dst, b, h) do { _Pragma("unroll") for (int n = 0; n < 2; ++n) _Pragma("unroll") for (int k = 0; k < 2; ++k) dst[n][k] = *(const PG8_LAS bf16x8*)(lds + PG8_SB(b, h) + boff + n * 2048 + k * 1024); } while (0)
; #define PG8_MMA(ai, bj, At, Bt) do { __builtin_amdgcn_s_setprio(1); _Pragma("unroll") for (int m = 0; m < 4; ++m) _Pragma("unroll") for (int n = 0; n < 2; ++n) _Pragma("unroll") for (int k = 0; k < 2; ++k) \
;         acc[ai][bj][m][n] = __builtin_amdgcn_mfma_f32_16x16x32_bf16(Bt[n][k], At[m][k], acc[ai][bj][m][n], 0, 0, 0); __builtin_amdgcn_s_setprio(0); } while (0)
; #define PG8_WAIT_V(n) asm volatile("s_waitcnt vmcnt(" #n ")" ::: "memory")
; #define PG8_WAIT_L(n) asm volatile("s_waitcnt lgkmcnt(" #n ")" ::: "memory")
; template <class Epi, class Sched, bool ALIGN_EPI = false, bool SP2 = false>
; __device__ __forceinline__ void gemm_phase(PG8_LAS unsigned char* lds, const Gemm g, const Sched& S, const Epi& E) {
;     ...
;             const bool last = (t == nt - 2);
;             const char* a1 = cA + (size_t)(t + 1) * kstep;
;             const char* a2 = last ? nA : cA + (size_t)(t + 2) * kstep; const char* b2 = last ? nB : cB + (size_t)(t + 2) * kstep;
;             const char* a3 = a2 + kstep; const char* b3 = b2 + kstep;
;             if (last && has_next) S.a_ready(nxt);
;             if constexpr (SP2) {
;             PG8_LDB(B0, 0, 0); PG8_LDB(B1, 0, 1); PG8_SCHED; PG8_LDA(At, 0, 0); PG8_STAGE(PG8_SA(1, 1), a1 + hstep, voffA);
;             PG8_WAIT_V(8); PG8_WAIT_L(0); PG8_BAR; PG8_MMA(0, 0, At, B0); PG8_MMA(0, 1, At, B1); PG8_BAR; PG8_SCHED;
;             PG8_LDA(At, 0, 1); PG8_STAGE(PG8_SB(0, 0), b2, voffB); PG8_STAGE(PG8_SB(0, 1), b2 + hstep, voffB); PG8_STAGE(PG8_SA(0, 0), a2, voffA);
;             PG8_WAIT_V(8); PG8_WAIT_L(0); PG8_BAR; PG8_MMA(1, 0, At, B0); PG8_MMA(1, 1, At, B1); PG8_BAR; PG8_SCHED;
.LBB0_2050:
	s_andn2_b64 vcc, exec, s[24:25]
	s_waitcnt vmcnt(0)
	s_cbranch_vccnz .LBB0_2053
	s_add_u32 s0, s6, 0x80
	s_addc_u32 s1, s7, 0
	s_add_u32 s6, s4, 0x100
	s_addc_u32 s7, s5, 0
	s_mov_b32 s4, 0
	ds_read_b128 v[146:149], v156
	ds_read_b128 v[160:163], v156 offset:1024
	ds_read_b128 v[164:167], v156 offset:2048
	ds_read_b128 v[168:171], v156 offset:3072
	ds_read_b128 v[172:175], v157
	ds_read_b128 v[176:179], v157 offset:1024
	ds_read_b128 v[180:183], v157 offset:2048
	ds_read_b128 v[184:187], v157 offset:3072
	s_add_i32 s78, s4, 2
	s_add_u32 s79, s0, 0x80
	s_addc_u32 s5, s1, 0
	s_cmp_eq_u32 s57, s4
	s_cselect_b32 s4, s36, s79
	s_cselect_b32 s5, s37, s5
	s_cselect_b32 s81, s39, s7
	s_cselect_b32 s80, s38, s6
	s_add_i32 m0, s19, 0xc000
	ds_read_b128 v[188:191], v158
	ds_read_b128 v[192:195], v158 offset:1024
	ds_read_b128 v[196:199], v158 offset:2048
	ds_read_b128 v[200:203], v158 offset:3072
	ds_read_b128 v[204:207], v158 offset:4096
	ds_read_b128 v[208:211], v158 offset:5120
	ds_read_b128 v[212:215], v158 offset:6144
	ds_read_b128 v[216:219], v158 offset:7168
	global_load_lds_dwordx4 v138, s[0:1]
	s_add_i32 m0, s19, 0xe000
	s_nop 0
	global_load_lds_dwordx4 v140, s[0:1]
	s_waitcnt vmcnt(8)
	s_waitcnt lgkmcnt(0)
	s_barrier
	s_setprio 1
	s_waitcnt lgkmcnt(0)
	v_mfma_f32_16x16x32_bf16 v[120:123], v[146:149], v[188:191], 0
	v_mfma_f32_16x16x32_bf16 v[124:127], v[164:167], v[188:191], 0
	v_mfma_f32_16x16x32_bf16 v[108:111], v[146:149], v[196:199], 0
	v_mfma_f32_16x16x32_bf16 v[104:107], v[164:167], v[196:199], 0
	v_mfma_f32_16x16x32_bf16 v[92:95], v[146:149], v[204:207], 0
	v_mfma_f32_16x16x32_bf16 v[88:91], v[164:167], v[204:207], 0
	v_mfma_f32_16x16x32_bf16 v[76:79], v[146:149], v[212:215], 0
	v_mfma_f32_16x16x32_bf16 v[72:75], v[164:167], v[212:215], 0
	v_mfma_f32_16x16x32_bf16 v[120:123], v[160:163], v[192:195], v[120:123]
	v_mfma_f32_16x16x32_bf16 v[124:127], v[168:171], v[192:195], v[124:127]
	v_mfma_f32_16x16x32_bf16 v[108:111], v[160:163], v[200:203], v[108:111]
	v_mfma_f32_16x16x32_bf16 v[104:107], v[168:171], v[200:203], v[104:107]
	v_mfma_f32_16x16x32_bf16 v[92:95], v[160:163], v[208:211], v[92:95]
	v_mfma_f32_16x16x32_bf16 v[88:91], v[168:171], v[208:211], v[88:91]
	v_mfma_f32_16x16x32_bf16 v[76:79], v[160:163], v[216:219], v[76:79]
	v_mfma_f32_16x16x32_bf16 v[72:75], v[168:171], v[216:219], v[72:75]
	s_setprio 0
	s_setprio 1
	v_mfma_f32_16x16x32_bf16 v[116:119], v[172:175], v[188:191], 0
	v_mfma_f32_16x16x32_bf16 v[112:115], v[180:183], v[188:191], 0
	v_mfma_f32_16x16x32_bf16 v[100:103], v[172:175], v[196:199], 0
	v_mfma_f32_16x16x32_bf16 v[96:99], v[180:183], v[196:199], 0
	v_mfma_f32_16x16x32_bf16 v[84:87], v[172:175], v[204:207], 0
	v_mfma_f32_16x16x32_bf16 v[80:83], v[180:183], v[204:207], 0
	v_mfma_f32_16x16x32_bf16 v[68:71], v[172:175], v[212:215], 0
	v_mfma_f32_16x16x32_bf16 v[64:67], v[180:183], v[212:215], 0
	v_mfma_f32_16x16x32_bf16 v[116:119], v[176:179], v[192:195], v[116:119]
	v_mfma_f32_16x16x32_bf16 v[112:115], v[184:187], v[192:195], v[112:115]
	v_mfma_f32_16x16x32_bf16 v[100:103], v[176:179], v[200:203], v[100:103]
	v_mfma_f32_16x16x32_bf16 v[96:99], v[184:187], v[200:203], v[96:99]
	v_mfma_f32_16x16x32_bf16 v[84:87], v[176:179], v[208:211], v[84:87]
	v_mfma_f32_16x16x32_bf16 v[80:83], v[184:187], v[208:211], v[80:83]
	v_mfma_f32_16x16x32_bf16 v[68:71], v[176:179], v[216:219], v[68:71]
	v_mfma_f32_16x16x32_bf16 v[64:67], v[184:187], v[216:219], v[64:67]
	s_setprio 0
	s_barrier
	s_add_i32 s79, s63, s17
	s_mov_b64 s[98:99], s[80:81]
	s_mov_b32 m0, s79
	ds_read_b128 v[188:191], v158 offset:16384
	ds_read_b128 v[192:195], v158 offset:17408
	ds_read_b128 v[196:199], v158 offset:18432
	ds_read_b128 v[200:203], v158 offset:19456
	ds_read_b128 v[204:207], v158 offset:20480
	ds_read_b128 v[208:211], v158 offset:21504
	ds_read_b128 v[212:215], v158 offset:22528
	ds_read_b128 v[216:219], v158 offset:23552
	global_load_lds_dwordx4 v130, s[80:81]
	s_add_i32 m0, s79, 0x2000
	s_add_u32 s80, s80, s12
	s_addc_u32 s81, s81, s13
	s_add_i32 s79, s64, s17
	global_load_lds_dwordx4 v134, s[98:99]
	s_mov_b64 s[100:101], s[80:81]
	s_mov_b32 m0, s79
	s_nop 0
	global_load_lds_dwordx4 v130, s[80:81]
	s_add_i32 m0, s79, 0x2000
	s_mov_b64 s[22:23], s[4:5]
	global_load_lds_dwordx4 v134, s[80:81]
	s_mov_b32 m0, s19
	s_nop 0
	global_load_lds_dwordx4 v128, s[4:5]
	s_mov_b32 m0, s33
	s_nop 0
	global_load_lds_dwordx4 v132, s[4:5]
	s_waitcnt vmcnt(8)
	s_waitcnt lgkmcnt(0)
	s_barrier
	s_setprio 1
	s_waitcnt lgkmcnt(0)
	v_mfma_f32_16x16x32_bf16 v[60:63], v[146:149], v[188:191], 0
	v_mfma_f32_16x16x32_bf16 v[56:59], v[164:167], v[188:191], 0
	v_mfma_f32_16x16x32_bf16 v[44:47], v[146:149], v[196:199], 0
	v_mfma_f32_16x16x32_bf16 v[40:43], v[164:167], v[196:199], 0
	v_mfma_f32_16x16x32_bf16 v[28:31], v[146:149], v[204:207], 0
	v_mfma_f32_16x16x32_bf16 v[24:27], v[164:167], v[204:207], 0
	v_mfma_f32_16x16x32_bf16 v[12:15], v[146:149], v[212:215], 0
	v_mfma_f32_16x16x32_bf16 v[8:11], v[164:167], v[212:215], 0
	v_mfma_f32_16x16x32_bf16 v[60:63], v[160:163], v[192:195], v[60:63]
	v_mfma_f32_16x16x32_bf16 v[56:59], v[168:171], v[192:195], v[56:59]
	v_mfma_f32_16x16x32_bf16 v[44:47], v[160:163], v[200:203], v[44:47]
	v_mfma_f32_16x16x32_bf16 v[40:43], v[168:171], v[200:203], v[40:43]
	v_mfma_f32_16x16x32_bf16 v[28:31], v[160:163], v[208:211], v[28:31]
	v_mfma_f32_16x16x32_bf16 v[24:27], v[168:171], v[208:211], v[24:27]
	v_mfma_f32_16x16x32_bf16 v[12:15], v[160:163], v[216:219], v[12:15]
	v_mfma_f32_16x16x32_bf16 v[8:11], v[168:171], v[216:219], v[8:11]
	s_setprio 0
	s_setprio 1
	v_mfma_f32_16x16x32_bf16 v[52:55], v[172:175], v[188:191], 0
	v_mfma_f32_16x16x32_bf16 v[48:51], v[180:183], v[188:191], 0
	v_mfma_f32_16x16x32_bf16 v[36:39], v[172:175], v[196:199], 0
	v_mfma_f32_16x16x32_bf16 v[32:35], v[180:183], v[196:199], 0
	v_mfma_f32_16x16x32_bf16 v[20:23], v[172:175], v[204:207], 0
	v_mfma_f32_16x16x32_bf16 v[16:19], v[180:183], v[204:207], 0
	v_mfma_f32_16x16x32_bf16 v[4:7], v[172:175], v[212:215], 0
	v_mfma_f32_16x16x32_bf16 v[0:3], v[180:183], v[212:215], 0
	v_mfma_f32_16x16x32_bf16 v[52:55], v[176:179], v[192:195], v[52:55]
	v_mfma_f32_16x16x32_bf16 v[48:51], v[184:187], v[192:195], v[48:51]
	v_mfma_f32_16x16x32_bf16 v[36:39], v[176:179], v[200:203], v[36:39]
	v_mfma_f32_16x16x32_bf16 v[32:35], v[184:187], v[200:203], v[32:35]
	v_mfma_f32_16x16x32_bf16 v[20:23], v[176:179], v[208:211], v[20:23]
	v_mfma_f32_16x16x32_bf16 v[16:19], v[184:187], v[208:211], v[16:19]
	v_mfma_f32_16x16x32_bf16 v[4:7], v[176:179], v[216:219], v[4:7]
	v_mfma_f32_16x16x32_bf16 v[0:3], v[184:187], v[216:219], v[0:3]
	s_setprio 0
	s_barrier
; #define PG8_STAGE(bufoff, gbase, voff) do { _Pragma("unroll") for (int _i = 0; _i < 2; ++_i) \
;         __builtin_amdgcn_global_load_lds((const unsigned*)((const char*)(gbase) + (voff)[_i]), (PG8_LAS unsigned*)(lds + (bufoff) + ldsw + _i * 8192), 16, 0, 0); } while (0)
; #define PG8_LDA(dst, b, h) do { _Pragma("unroll") for (int m = 0; m < 4; ++m) _Pragma("unroll") for (int k = 0; k < 2; ++k) dst[m][k] = *(const PG8_LAS bf16x8*)(lds + PG8_SA(b, h) + aoff + m * 2048 + k * 1024); } while (0)
; #define PG8_LDB(dst, b, h) do { _Pragma("unroll") for (int n = 0; n < 2; ++n) _Pragma("unroll") for (int k = 0; k < 2; ++k) dst[n][k] = *(const PG8_LAS bf16x8*)(lds + PG8_SB(b, h) + boff + n * 2048 + k * 1024); } while (0)
; #define PG8_MMA(ai, bj, At, Bt) do { __builtin_amdgcn_s_setprio(1); _Pragma("unroll") for (int m = 0; m < 4; ++m) _Pragma("unroll") for (int n = 0; n < 2; ++n) _Pragma("unroll") for (int k = 0; k < 2; ++k) \
;         acc[ai][bj][m][n] = __builtin_amdgcn_mfma_f32_16x16x32_bf16(Bt[n][k], At[m][k], acc[ai][bj][m][n], 0, 0, 0); __builtin_amdgcn_s_setprio(0); } while (0)
; #define PG8_WAIT_V(n) asm volatile("s_waitcnt vmcnt(" #n ")" ::: "memory")
; #define PG8_WAIT_L(n) asm volatile("s_waitcnt lgkmcnt(" #n ")" ::: "memory")
; #define PG8_BAR __builtin_amdgcn_s_barrier()
; #define PG8_SCHED __builtin_amdgcn_sched_barrier(0)
; template <class Epi, class Sched, bool ALIGN_EPI = false, bool SP2 = false>
; __device__ __forceinline__ void gemm_phase(PG8_LAS unsigned char* lds, const Gemm g, const Sched& S, const Epi& E) {
;     ...
;             PG8_LDB(B0, 1, 0); PG8_LDB(B1, 1, 1); PG8_SCHED; PG8_LDA(At, 1, 0); PG8_STAGE(PG8_SA(0, 1), a2 + hstep, voffA);
;             PG8_WAIT_V(8); PG8_WAIT_L(0); PG8_BAR; PG8_MMA(0, 0, At, B0); PG8_MMA(0, 1, At, B1); PG8_BAR; PG8_SCHED;
;             PG8_LDA(At, 1, 1); PG8_STAGE(PG8_SB(1, 0), b3, voffB); PG8_STAGE(PG8_SB(1, 1), b3 + hstep, voffB); PG8_STAGE(PG8_SA(1, 0), a3, voffA);
;             PG8_WAIT_V(8); PG8_WAIT_L(0); PG8_BAR; PG8_MMA(1, 0, At, B0); PG8_MMA(1, 1, At, B1); PG8_BAR; PG8_SCHED;
	s_add_i32 s79, 0, 0x18000
	v_add_u32_e32 v137, s79, v153
	s_add_i32 s80, 0, 0x1c000
	ds_read_b128 v[146:149], v137
	ds_read_b128 v[160:163], v137 offset:1024
	ds_read_b128 v[164:167], v137 offset:2048
	ds_read_b128 v[168:171], v137 offset:3072
	v_add_u32_e32 v137, s80, v153
	ds_read_b128 v[172:175], v137
	ds_read_b128 v[176:179], v137 offset:1024
	ds_read_b128 v[180:183], v137 offset:2048
	ds_read_b128 v[184:187], v137 offset:3072
	s_add_u32 s4, s4, s12
	s_addc_u32 s5, s5, s13
	s_mov_b32 m0, s40
	ds_read_b128 v[188:191], v158 offset:32768
	ds_read_b128 v[192:195], v158 offset:33792
	ds_read_b128 v[196:199], v158 offset:34816
	ds_read_b128 v[200:203], v158 offset:35840
	ds_read_b128 v[204:207], v158 offset:36864
	ds_read_b128 v[208:211], v158 offset:37888
	ds_read_b128 v[212:215], v158 offset:38912
	ds_read_b128 v[216:219], v158 offset:39936
	global_load_lds_dwordx4 v128, s[4:5]
	s_mov_b32 m0, s41
	s_nop 0
	global_load_lds_dwordx4 v132, s[4:5]
	s_waitcnt vmcnt(8)
	s_waitcnt lgkmcnt(0)
	s_barrier
	s_setprio 1
	s_waitcnt lgkmcnt(0)
	v_mfma_f32_16x16x32_bf16 v[120:123], v[146:149], v[188:191], v[120:123]
	v_mfma_f32_16x16x32_bf16 v[124:127], v[164:167], v[188:191], v[124:127]
	v_mfma_f32_16x16x32_bf16 v[108:111], v[146:149], v[196:199], v[108:111]
	v_mfma_f32_16x16x32_bf16 v[104:107], v[164:167], v[196:199], v[104:107]
	v_mfma_f32_16x16x32_bf16 v[92:95], v[146:149], v[204:207], v[92:95]
	v_mfma_f32_16x16x32_bf16 v[88:91], v[164:167], v[204:207], v[88:91]
	v_mfma_f32_16x16x32_bf16 v[76:79], v[146:149], v[212:215], v[76:79]
	v_mfma_f32_16x16x32_bf16 v[72:75], v[164:167], v[212:215], v[72:75]
	v_mfma_f32_16x16x32_bf16 v[120:123], v[160:163], v[192:195], v[120:123]
	v_mfma_f32_16x16x32_bf16 v[124:127], v[168:171], v[192:195], v[124:127]
	v_mfma_f32_16x16x32_bf16 v[108:111], v[160:163], v[200:203], v[108:111]
	v_mfma_f32_16x16x32_bf16 v[104:107], v[168:171], v[200:203], v[104:107]
	v_mfma_f32_16x16x32_bf16 v[92:95], v[160:163], v[208:211], v[92:95]
	v_mfma_f32_16x16x32_bf16 v[88:91], v[168:171], v[208:211], v[88:91]
	v_mfma_f32_16x16x32_bf16 v[76:79], v[160:163], v[216:219], v[76:79]
	v_mfma_f32_16x16x32_bf16 v[72:75], v[168:171], v[216:219], v[72:75]
	s_setprio 0
	s_setprio 1
	v_mfma_f32_16x16x32_bf16 v[116:119], v[172:175], v[188:191], v[116:119]
	v_mfma_f32_16x16x32_bf16 v[112:115], v[180:183], v[188:191], v[112:115]
	v_mfma_f32_16x16x32_bf16 v[100:103], v[172:175], v[196:199], v[100:103]
	v_mfma_f32_16x16x32_bf16 v[96:99], v[180:183], v[196:199], v[96:99]
	v_mfma_f32_16x16x32_bf16 v[84:87], v[172:175], v[204:207], v[84:87]
	v_mfma_f32_16x16x32_bf16 v[80:83], v[180:183], v[204:207], v[80:83]
	v_mfma_f32_16x16x32_bf16 v[68:71], v[172:175], v[212:215], v[68:71]
	v_mfma_f32_16x16x32_bf16 v[64:67], v[180:183], v[212:215], v[64:67]
	v_mfma_f32_16x16x32_bf16 v[116:119], v[176:179], v[192:195], v[116:119]
	v_mfma_f32_16x16x32_bf16 v[112:115], v[184:187], v[192:195], v[112:115]
	v_mfma_f32_16x16x32_bf16 v[100:103], v[176:179], v[200:203], v[100:103]
	v_mfma_f32_16x16x32_bf16 v[96:99], v[184:187], v[200:203], v[96:99]
	v_mfma_f32_16x16x32_bf16 v[84:87], v[176:179], v[208:211], v[84:87]
	v_mfma_f32_16x16x32_bf16 v[80:83], v[184:187], v[208:211], v[80:83]
	v_mfma_f32_16x16x32_bf16 v[68:71], v[176:179], v[216:219], v[68:71]
	v_mfma_f32_16x16x32_bf16 v[64:67], v[184:187], v[216:219], v[64:67]
	s_setprio 0
	s_barrier
	s_add_i32 s4, s79, s17
	s_add_i32 m0, s4, 0xffffff80
	ds_read_b128 v[188:191], v158 offset:49152
	ds_read_b128 v[192:195], v158 offset:50176
	ds_read_b128 v[196:199], v158 offset:51200
	ds_read_b128 v[200:203], v158 offset:52224
	ds_read_b128 v[204:207], v158 offset:53248
	ds_read_b128 v[208:211], v158 offset:54272
	ds_read_b128 v[212:215], v158 offset:55296
	ds_read_b128 v[216:219], v158 offset:56320
	global_load_lds_dwordx4 v130, s[98:99] offset:128
	s_add_i32 m0, s4, 0x1f80
	s_add_i32 s4, s80, s17
	global_load_lds_dwordx4 v134, s[98:99] offset:128
	s_add_i32 m0, s4, 0xffffff80
	s_nop 0
	global_load_lds_dwordx4 v130, s[100:101] offset:128
	s_add_i32 m0, s4, 0x1f80
	s_nop 0
	global_load_lds_dwordx4 v134, s[100:101] offset:128
	s_add_i32 m0, s45, 0xffffff80
	s_nop 0
	global_load_lds_dwordx4 v128, s[22:23] offset:128
	s_add_i32 m0, s50, 0xffffff80
	s_nop 0
	global_load_lds_dwordx4 v132, s[22:23] offset:128
	s_waitcnt vmcnt(8)
	s_waitcnt lgkmcnt(0)
	s_barrier
	s_setprio 1
	s_waitcnt lgkmcnt(0)
	v_mfma_f32_16x16x32_bf16 v[60:63], v[146:149], v[188:191], v[60:63]
	v_mfma_f32_16x16x32_bf16 v[56:59], v[164:167], v[188:191], v[56:59]
	v_mfma_f32_16x16x32_bf16 v[44:47], v[146:149], v[196:199], v[44:47]
	v_mfma_f32_16x16x32_bf16 v[40:43], v[164:167], v[196:199], v[40:43]
	v_mfma_f32_16x16x32_bf16 v[28:31], v[146:149], v[204:207], v[28:31]
	v_mfma_f32_16x16x32_bf16 v[24:27], v[164:167], v[204:207], v[24:27]
	v_mfma_f32_16x16x32_bf16 v[12:15], v[146:149], v[212:215], v[12:15]
	v_mfma_f32_16x16x32_bf16 v[8:11], v[164:167], v[212:215], v[8:11]
	v_mfma_f32_16x16x32_bf16 v[60:63], v[160:163], v[192:195], v[60:63]
	v_mfma_f32_16x16x32_bf16 v[56:59], v[168:171], v[192:195], v[56:59]
	v_mfma_f32_16x16x32_bf16 v[44:47], v[160:163], v[200:203], v[44:47]
	v_mfma_f32_16x16x32_bf16 v[40:43], v[168:171], v[200:203], v[40:43]
	v_mfma_f32_16x16x32_bf16 v[28:31], v[160:163], v[208:211], v[28:31]
	v_mfma_f32_16x16x32_bf16 v[24:27], v[168:171], v[208:211], v[24:27]
	v_mfma_f32_16x16x32_bf16 v[12:15], v[160:163], v[216:219], v[12:15]
	v_mfma_f32_16x16x32_bf16 v[8:11], v[168:171], v[216:219], v[8:11]
	s_setprio 0
	s_setprio 1
	v_mfma_f32_16x16x32_bf16 v[52:55], v[172:175], v[188:191], v[52:55]
	v_mfma_f32_16x16x32_bf16 v[48:51], v[180:183], v[188:191], v[48:51]
	v_mfma_f32_16x16x32_bf16 v[36:39], v[172:175], v[196:199], v[36:39]
	v_mfma_f32_16x16x32_bf16 v[32:35], v[180:183], v[196:199], v[32:35]
	v_mfma_f32_16x16x32_bf16 v[20:23], v[172:175], v[204:207], v[20:23]
	v_mfma_f32_16x16x32_bf16 v[16:19], v[180:183], v[204:207], v[16:19]
	v_mfma_f32_16x16x32_bf16 v[4:7], v[172:175], v[212:215], v[4:7]
	v_mfma_f32_16x16x32_bf16 v[0:3], v[180:183], v[212:215], v[0:3]
	v_mfma_f32_16x16x32_bf16 v[52:55], v[176:179], v[192:195], v[52:55]
	v_mfma_f32_16x16x32_bf16 v[48:51], v[184:187], v[192:195], v[48:51]
	v_mfma_f32_16x16x32_bf16 v[36:39], v[176:179], v[200:203], v[36:39]
	v_mfma_f32_16x16x32_bf16 v[32:35], v[184:187], v[200:203], v[32:35]
	v_mfma_f32_16x16x32_bf16 v[20:23], v[176:179], v[208:211], v[20:23]
	v_mfma_f32_16x16x32_bf16 v[16:19], v[184:187], v[208:211], v[16:19]
	v_mfma_f32_16x16x32_bf16 v[4:7], v[176:179], v[216:219], v[4:7]
	v_mfma_f32_16x16x32_bf16 v[0:3], v[184:187], v[216:219], v[0:3]
	s_setprio 0
	s_barrier
	s_add_u32 s0, s0, 0x100
	s_addc_u32 s1, s1, 0
	s_add_u32 s6, s6, 0x100
	s_addc_u32 s7, s7, 0
	s_cmp_ge_i32 s78, s51
	s_mov_b32 s4, s78
	s_cbranch_scc0 .LBB0_2052
	s_branch .Lpeel_x9
; #define PG8_STAGE(bufoff, gbase, voff) do { _Pragma("unroll") for (int _i = 0; _i < 2; ++_i) \
;         __builtin_amdgcn_global_load_lds((const unsigned*)((const char*)(gbase) + (voff)[_i]), (PG8_LAS unsigned*)(lds + (bufoff) + ldsw + _i * 8192), 16, 0, 0); } while (0)
; #define PG8_LDA(dst, b, h) do { _Pragma("unroll") for (int m = 0; m < 4; ++m) _Pragma("unroll") for (int k = 0; k < 2; ++k) dst[m][k] = *(const PG8_LAS bf16x8*)(lds + PG8_SA(b, h) + aoff + m * 2048 + k * 1024); } while (0)
; #define PG8_LDB(dst, b, h) do { _Pragma("unroll") for (int n = 0; n < 2; ++n) _Pragma("unroll") for (int k = 0; k < 2; ++k) dst[n][k] = *(const PG8_LAS bf16x8*)(lds + PG8_SB(b, h) + boff + n * 2048 + k * 1024); } while (0)
; #define PG8_MMA(ai, bj, At, Bt) do { __builtin_amdgcn_s_setprio(1); _Pragma("unroll") for (int m = 0; m < 4; ++m) _Pragma("unroll") for (int n = 0; n < 2; ++n) _Pragma("unroll") for (int k = 0; k < 2; ++k) \
;         acc[ai][bj][m][n] = __builtin_amdgcn_mfma_f32_16x16x32_bf16(Bt[n][k], At[m][k], acc[ai][bj][m][n], 0, 0, 0); __builtin_amdgcn_s_setprio(0); } while (0)
; #define PG8_WAIT_V(n) asm volatile("s_waitcnt vmcnt(" #n ")" ::: "memory")
; #define PG8_WAIT_L(n) asm volatile("s_waitcnt lgkmcnt(" #n ")" ::: "memory")
; template <class Epi, class Sched, bool ALIGN_EPI = false, bool SP2 = false>
; __device__ __forceinline__ void gemm_phase(PG8_LAS unsigned char* lds, const Gemm g, const Sched& S, const Epi& E) {
;     ...
;             const bool last = (t == nt - 2);
;             const char* a1 = cA + (size_t)(t + 1) * kstep;
;             const char* a2 = last ? nA : cA + (size_t)(t + 2) * kstep; const char* b2 = last ? nB : cB + (size_t)(t + 2) * kstep;
;             const char* a3 = a2 + kstep; const char* b3 = b2 + kstep;
;             if (last && has_next) S.a_ready(nxt);
;             if constexpr (SP2) {
;             PG8_LDB(B0, 0, 0); PG8_LDB(B1, 0, 1); PG8_SCHED; PG8_LDA(At, 0, 0); PG8_STAGE(PG8_SA(1, 1), a1 + hstep, voffA);
;             PG8_WAIT_V(8); PG8_WAIT_L(0); PG8_BAR; PG8_MMA(0, 0, At, B0); PG8_MMA(0, 1, At, B1); PG8_BAR; PG8_SCHED;
;             PG8_LDA(At, 0, 1); PG8_STAGE(PG8_SB(0, 0), b2, voffB); PG8_STAGE(PG8_SB(0, 1), b2 + hstep, voffB); PG8_STAGE(PG8_SA(0, 0), a2, voffA);
;             PG8_WAIT_V(8); PG8_WAIT_L(0); PG8_BAR; PG8_MMA(1, 0, At, B0); PG8_MMA(1, 1, At, B1); PG8_BAR; PG8_SCHED;
.LBB0_2052:
	ds_read_b128 v[146:149], v156
	ds_read_b128 v[160:163], v156 offset:1024
	ds_read_b128 v[164:167], v156 offset:2048
	ds_read_b128 v[168:171], v156 offset:3072
	ds_read_b128 v[172:175], v157
	ds_read_b128 v[176:179], v157 offset:1024
	ds_read_b128 v[180:183], v157 offset:2048
	ds_read_b128 v[184:187], v157 offset:3072
	s_add_i32 s78, s4, 2
	s_add_u32 s79, s0, 0x80
	s_addc_u32 s5, s1, 0
	s_cmp_eq_u32 s57, s4
	s_cselect_b32 s4, s36, s79
	s_cselect_b32 s5, s37, s5
	s_cselect_b32 s81, s39, s7
	s_cselect_b32 s80, s38, s6
	s_add_i32 m0, s19, 0xc000
	ds_read_b128 v[188:191], v158
	ds_read_b128 v[192:195], v158 offset:1024
	ds_read_b128 v[196:199], v158 offset:2048
	ds_read_b128 v[200:203], v158 offset:3072
	ds_read_b128 v[204:207], v158 offset:4096
	ds_read_b128 v[208:211], v158 offset:5120
	ds_read_b128 v[212:215], v158 offset:6144
	ds_read_b128 v[216:219], v158 offset:7168
	global_load_lds_dwordx4 v138, s[0:1]
	s_add_i32 m0, s19, 0xe000
	s_nop 0
	global_load_lds_dwordx4 v140, s[0:1]
	s_waitcnt vmcnt(8)
	s_waitcnt lgkmcnt(0)
	s_barrier
	s_setprio 1
	s_waitcnt lgkmcnt(0)
	v_mfma_f32_16x16x32_bf16 v[120:123], v[146:149], v[188:191], v[120:123]
	v_mfma_f32_16x16x32_bf16 v[124:127], v[164:167], v[188:191], v[124:127]
	v_mfma_f32_16x16x32_bf16 v[108:111], v[146:149], v[196:199], v[108:111]
	v_mfma_f32_16x16x32_bf16 v[104:107], v[164:167], v[196:199], v[104:107]
	v_mfma_f32_16x16x32_bf16 v[92:95], v[146:149], v[204:207], v[92:95]
	v_mfma_f32_16x16x32_bf16 v[88:91], v[164:167], v[204:207], v[88:91]
	v_mfma_f32_16x16x32_bf16 v[76:79], v[146:149], v[212:215], v[76:79]
	v_mfma_f32_16x16x32_bf16 v[72:75], v[164:167], v[212:215], v[72:75]
	v_mfma_f32_16x16x32_bf16 v[120:123], v[160:163], v[192:195], v[120:123]
	v_mfma_f32_16x16x32_bf16 v[124:127], v[168:171], v[192:195], v[124:127]
	v_mfma_f32_16x16x32_bf16 v[108:111], v[160:163], v[200:203], v[108:111]
	v_mfma_f32_16x16x32_bf16 v[104:107], v[168:171], v[200:203], v[104:107]
	v_mfma_f32_16x16x32_bf16 v[92:95], v[160:163], v[208:211], v[92:95]
	v_mfma_f32_16x16x32_bf16 v[88:91], v[168:171], v[208:211], v[88:91]
	v_mfma_f32_16x16x32_bf16 v[76:79], v[160:163], v[216:219], v[76:79]
	v_mfma_f32_16x16x32_bf16 v[72:75], v[168:171], v[216:219], v[72:75]
	s_setprio 0
	s_setprio 1
	v_mfma_f32_16x16x32_bf16 v[116:119], v[172:175], v[188:191], v[116:119]
	v_mfma_f32_16x16x32_bf16 v[112:115], v[180:183], v[188:191], v[112:115]
	v_mfma_f32_16x16x32_bf16 v[100:103], v[172:175], v[196:199], v[100:103]
	v_mfma_f32_16x16x32_bf16 v[96:99], v[180:183], v[196:199], v[96:99]
	v_mfma_f32_16x16x32_bf16 v[84:87], v[172:175], v[204:207], v[84:87]
	v_mfma_f32_16x16x32_bf16 v[80:83], v[180:183], v[204:207], v[80:83]
	v_mfma_f32_16x16x32_bf16 v[68:71], v[172:175], v[212:215], v[68:71]
	v_mfma_f32_16x16x32_bf16 v[64:67], v[180:183], v[212:215], v[64:67]
	v_mfma_f32_16x16x32_bf16 v[116:119], v[176:179], v[192:195], v[116:119]
	v_mfma_f32_16x16x32_bf16 v[112:115], v[184:187], v[192:195], v[112:115]
	v_mfma_f32_16x16x32_bf16 v[100:103], v[176:179], v[200:203], v[100:103]
	v_mfma_f32_16x16x32_bf16 v[96:99], v[184:187], v[200:203], v[96:99]
	v_mfma_f32_16x16x32_bf16 v[84:87], v[176:179], v[208:211], v[84:87]
	v_mfma_f32_16x16x32_bf16 v[80:83], v[184:187], v[208:211], v[80:83]
	v_mfma_f32_16x16x32_bf16 v[68:71], v[176:179], v[216:219], v[68:71]
	v_mfma_f32_16x16x32_bf16 v[64:67], v[184:187], v[216:219], v[64:67]
	s_setprio 0
	s_barrier
	s_add_i32 s79, s63, s17
	s_mov_b64 s[98:99], s[80:81]
	s_mov_b32 m0, s79
	ds_read_b128 v[188:191], v158 offset:16384
	ds_read_b128 v[192:195], v158 offset:17408
	ds_read_b128 v[196:199], v158 offset:18432
	ds_read_b128 v[200:203], v158 offset:19456
	ds_read_b128 v[204:207], v158 offset:20480
	ds_read_b128 v[208:211], v158 offset:21504
	ds_read_b128 v[212:215], v158 offset:22528
	ds_read_b128 v[216:219], v158 offset:23552
	global_load_lds_dwordx4 v130, s[80:81]
	s_add_i32 m0, s79, 0x2000
	s_add_u32 s80, s80, s12
	s_addc_u32 s81, s81, s13
	s_add_i32 s79, s64, s17
	global_load_lds_dwordx4 v134, s[98:99]
	s_mov_b64 s[100:101], s[80:81]
	s_mov_b32 m0, s79
	s_nop 0
	global_load_lds_dwordx4 v130, s[80:81]
	s_add_i32 m0, s79, 0x2000
	s_mov_b64 s[22:23], s[4:5]
	global_load_lds_dwordx4 v134, s[80:81]
	s_mov_b32 m0, s19
	s_nop 0
	global_load_lds_dwordx4 v128, s[4:5]
	s_mov_b32 m0, s33
	s_nop 0
	global_load_lds_dwordx4 v132, s[4:5]
	s_waitcnt vmcnt(8)
	s_waitcnt lgkmcnt(0)
	s_barrier
	s_setprio 1
	s_waitcnt lgkmcnt(0)
	v_mfma_f32_16x16x32_bf16 v[60:63], v[146:149], v[188:191], v[60:63]
	v_mfma_f32_16x16x32_bf16 v[56:59], v[164:167], v[188:191], v[56:59]
	v_mfma_f32_16x16x32_bf16 v[44:47], v[146:149], v[196:199], v[44:47]
	v_mfma_f32_16x16x32_bf16 v[40:43], v[164:167], v[196:199], v[40:43]
	v_mfma_f32_16x16x32_bf16 v[28:31], v[146:149], v[204:207], v[28:31]
	v_mfma_f32_16x16x32_bf16 v[24:27], v[164:167], v[204:207], v[24:27]
	v_mfma_f32_16x16x32_bf16 v[12:15], v[146:149], v[212:215], v[12:15]
	v_mfma_f32_16x16x32_bf16 v[8:11], v[164:167], v[212:215], v[8:11]
	v_mfma_f32_16x16x32_bf16 v[60:63], v[160:163], v[192:195], v[60:63]
	v_mfma_f32_16x16x32_bf16 v[56:59], v[168:171], v[192:195], v[56:59]
	v_mfma_f32_16x16x32_bf16 v[44:47], v[160:163], v[200:203], v[44:47]
	v_mfma_f32_16x16x32_bf16 v[40:43], v[168:171], v[200:203], v[40:43]
	v_mfma_f32_16x16x32_bf16 v[28:31], v[160:163], v[208:211], v[28:31]
	v_mfma_f32_16x16x32_bf16 v[24:27], v[168:171], v[208:211], v[24:27]
	v_mfma_f32_16x16x32_bf16 v[12:15], v[160:163], v[216:219], v[12:15]
	v_mfma_f32_16x16x32_bf16 v[8:11], v[168:171], v[216:219], v[8:11]
	s_setprio 0
	s_setprio 1
	v_mfma_f32_16x16x32_bf16 v[52:55], v[172:175], v[188:191], v[52:55]
	v_mfma_f32_16x16x32_bf16 v[48:51], v[180:183], v[188:191], v[48:51]
	v_mfma_f32_16x16x32_bf16 v[36:39], v[172:175], v[196:199], v[36:39]
	v_mfma_f32_16x16x32_bf16 v[32:35], v[180:183], v[196:199], v[32:35]
	v_mfma_f32_16x16x32_bf16 v[20:23], v[172:175], v[204:207], v[20:23]
	v_mfma_f32_16x16x32_bf16 v[16:19], v[180:183], v[204:207], v[16:19]
	v_mfma_f32_16x16x32_bf16 v[4:7], v[172:175], v[212:215], v[4:7]
	v_mfma_f32_16x16x32_bf16 v[0:3], v[180:183], v[212:215], v[0:3]
	v_mfma_f32_16x16x32_bf16 v[52:55], v[176:179], v[192:195], v[52:55]
	v_mfma_f32_16x16x32_bf16 v[48:51], v[184:187], v[192:195], v[48:51]
	v_mfma_f32_16x16x32_bf16 v[36:39], v[176:179], v[200:203], v[36:39]
	v_mfma_f32_16x16x32_bf16 v[32:35], v[184:187], v[200:203], v[32:35]
	v_mfma_f32_16x16x32_bf16 v[20:23], v[176:179], v[208:211], v[20:23]
	v_mfma_f32_16x16x32_bf16 v[16:19], v[184:187], v[208:211], v[16:19]
	v_mfma_f32_16x16x32_bf16 v[4:7], v[176:179], v[216:219], v[4:7]
	v_mfma_f32_16x16x32_bf16 v[0:3], v[184:187], v[216:219], v[0:3]
	s_setprio 0
	s_barrier
; #define PG8_STAGE(bufoff, gbase, voff) do { _Pragma("unroll") for (int _i = 0; _i < 2; ++_i) \
;         __builtin_amdgcn_global_load_lds((const unsigned*)((const char*)(gbase) + (voff)[_i]), (PG8_LAS unsigned*)(lds + (bufoff) + ldsw + _i * 8192), 16, 0, 0); } while (0)
; #define PG8_LDA(dst, b, h) do { _Pragma("unroll") for (int m = 0; m < 4; ++m) _Pragma("unroll") for (int k = 0; k < 2; ++k) dst[m][k] = *(const PG8_LAS bf16x8*)(lds + PG8_SA(b, h) + aoff + m * 2048 + k * 1024); } while (0)
; #define PG8_LDB(dst, b, h) do { _Pragma("unroll") for (int n = 0; n < 2; ++n) _Pragma("unroll") for (int k = 0; k < 2; ++k) dst[n][k] = *(const PG8_LAS bf16x8*)(lds + PG8_SB(b, h) + boff + n * 2048 + k * 1024); } while (0)
; #define PG8_MMA(ai, bj, At, Bt) do { __builtin_amdgcn_s_setprio(1); _Pragma("unroll") for (int m = 0; m < 4; ++m) _Pragma("unroll") for (int n = 0; n < 2; ++n) _Pragma("unroll") for (int k = 0; k < 2; ++k) \
;         acc[ai][bj][m][n] = __builtin_amdgcn_mfma_f32_16x16x32_bf16(Bt[n][k], At[m][k], acc[ai][bj][m][n], 0, 0, 0); __builtin_amdgcn_s_setprio(0); } while (0)
; #define PG8_WAIT_V(n) asm volatile("s_waitcnt vmcnt(" #n ")" ::: "memory")
; #define PG8_WAIT_L(n) asm volatile("s_waitcnt lgkmcnt(" #n ")" ::: "memory")
; #define PG8_BAR __builtin_amdgcn_s_barrier()
; #define PG8_SCHED __builtin_amdgcn_sched_barrier(0)
; template <class Epi, class Sched, bool ALIGN_EPI = false, bool SP2 = false>
; __device__ __forceinline__ void gemm_phase(PG8_LAS unsigned char* lds, const Gemm g, const Sched& S, const Epi& E) {
;     ...
;             PG8_LDB(B0, 1, 0); PG8_LDB(B1, 1, 1); PG8_SCHED; PG8_LDA(At, 1, 0); PG8_STAGE(PG8_SA(0, 1), a2 + hstep, voffA);
;             PG8_WAIT_V(8); PG8_WAIT_L(0); PG8_BAR; PG8_MMA(0, 0, At, B0); PG8_MMA(0, 1, At, B1); PG8_BAR; PG8_SCHED;
;             PG8_LDA(At, 1, 1); PG8_STAGE(PG8_SB(1, 0), b3, voffB); PG8_STAGE(PG8_SB(1, 1), b3 + hstep, voffB); PG8_STAGE(PG8_SA(1, 0), a3, voffA);
;             PG8_WAIT_V(8); PG8_WAIT_L(0); PG8_BAR; PG8_MMA(1, 0, At, B0); PG8_MMA(1, 1, At, B1); PG8_BAR; PG8_SCHED;
	s_add_i32 s79, 0, 0x18000
	v_add_u32_e32 v137, s79, v153
	s_add_i32 s80, 0, 0x1c000
	ds_read_b128 v[146:149], v137
	ds_read_b128 v[160:163], v137 offset:1024
	ds_read_b128 v[164:167], v137 offset:2048
	ds_read_b128 v[168:171], v137 offset:3072
	v_add_u32_e32 v137, s80, v153
	ds_read_b128 v[172:175], v137
	ds_read_b128 v[176:179], v137 offset:1024
	ds_read_b128 v[180:183], v137 offset:2048
	ds_read_b128 v[184:187], v137 offset:3072
	s_add_u32 s4, s4, s12
	s_addc_u32 s5, s5, s13
	s_mov_b32 m0, s40
	ds_read_b128 v[188:191], v158 offset:32768
	ds_read_b128 v[192:195], v158 offset:33792
	ds_read_b128 v[196:199], v158 offset:34816
	ds_read_b128 v[200:203], v158 offset:35840
	ds_read_b128 v[204:207], v158 offset:36864
	ds_read_b128 v[208:211], v158 offset:37888
	ds_read_b128 v[212:215], v158 offset:38912
	ds_read_b128 v[216:219], v158 offset:39936
	global_load_lds_dwordx4 v128, s[4:5]
	s_mov_b32 m0, s41
	s_nop 0
	global_load_lds_dwordx4 v132, s[4:5]
	s_waitcnt vmcnt(8)
	s_waitcnt lgkmcnt(0)
	s_barrier
	s_setprio 1
	s_waitcnt lgkmcnt(0)
	v_mfma_f32_16x16x32_bf16 v[120:123], v[146:149], v[188:191], v[120:123]
	v_mfma_f32_16x16x32_bf16 v[124:127], v[164:167], v[188:191], v[124:127]
	v_mfma_f32_16x16x32_bf16 v[108:111], v[146:149], v[196:199], v[108:111]
	v_mfma_f32_16x16x32_bf16 v[104:107], v[164:167], v[196:199], v[104:107]
	v_mfma_f32_16x16x32_bf16 v[92:95], v[146:149], v[204:207], v[92:95]
	v_mfma_f32_16x16x32_bf16 v[88:91], v[164:167], v[204:207], v[88:91]
	v_mfma_f32_16x16x32_bf16 v[76:79], v[146:149], v[212:215], v[76:79]
	v_mfma_f32_16x16x32_bf16 v[72:75], v[164:167], v[212:215], v[72:75]
	v_mfma_f32_16x16x32_bf16 v[120:123], v[160:163], v[192:195], v[120:123]
	v_mfma_f32_16x16x32_bf16 v[124:127], v[168:171], v[192:195], v[124:127]
	v_mfma_f32_16x16x32_bf16 v[108:111], v[160:163], v[200:203], v[108:111]
	v_mfma_f32_16x16x32_bf16 v[104:107], v[168:171], v[200:203], v[104:107]
	v_mfma_f32_16x16x32_bf16 v[92:95], v[160:163], v[208:211], v[92:95]
	v_mfma_f32_16x16x32_bf16 v[88:91], v[168:171], v[208:211], v[88:91]
	v_mfma_f32_16x16x32_bf16 v[76:79], v[160:163], v[216:219], v[76:79]
	v_mfma_f32_16x16x32_bf16 v[72:75], v[168:171], v[216:219], v[72:75]
	s_setprio 0
	s_setprio 1
	v_mfma_f32_16x16x32_bf16 v[116:119], v[172:175], v[188:191], v[116:119]
	v_mfma_f32_16x16x32_bf16 v[112:115], v[180:183], v[188:191], v[112:115]
	v_mfma_f32_16x16x32_bf16 v[100:103], v[172:175], v[196:199], v[100:103]
	v_mfma_f32_16x16x32_bf16 v[96:99], v[180:183], v[196:199], v[96:99]
	v_mfma_f32_16x16x32_bf16 v[84:87], v[172:175], v[204:207], v[84:87]
	v_mfma_f32_16x16x32_bf16 v[80:83], v[180:183], v[204:207], v[80:83]
	v_mfma_f32_16x16x32_bf16 v[68:71], v[172:175], v[212:215], v[68:71]
	v_mfma_f32_16x16x32_bf16 v[64:67], v[180:183], v[212:215], v[64:67]
	v_mfma_f32_16x16x32_bf16 v[116:119], v[176:179], v[192:195], v[116:119]
	v_mfma_f32_16x16x32_bf16 v[112:115], v[184:187], v[192:195], v[112:115]
	v_mfma_f32_16x16x32_bf16 v[100:103], v[176:179], v[200:203], v[100:103]
	v_mfma_f32_16x16x32_bf16 v[96:99], v[184:187], v[200:203], v[96:99]
	v_mfma_f32_16x16x32_bf16 v[84:87], v[176:179], v[208:211], v[84:87]
	v_mfma_f32_16x16x32_bf16 v[80:83], v[184:187], v[208:211], v[80:83]
	v_mfma_f32_16x16x32_bf16 v[68:71], v[176:179], v[216:219], v[68:71]
	v_mfma_f32_16x16x32_bf16 v[64:67], v[184:187], v[216:219], v[64:67]
	s_setprio 0
	s_barrier
	s_add_i32 s4, s79, s17
	s_add_i32 m0, s4, 0xffffff80
	ds_read_b128 v[188:191], v158 offset:49152
	ds_read_b128 v[192:195], v158 offset:50176
	ds_read_b128 v[196:199], v158 offset:51200
	ds_read_b128 v[200:203], v158 offset:52224
	ds_read_b128 v[204:207], v158 offset:53248
	ds_read_b128 v[208:211], v158 offset:54272
	ds_read_b128 v[212:215], v158 offset:55296
	ds_read_b128 v[216:219], v158 offset:56320
	global_load_lds_dwordx4 v130, s[98:99] offset:128
	s_add_i32 m0, s4, 0x1f80
	s_add_i32 s4, s80, s17
	global_load_lds_dwordx4 v134, s[98:99] offset:128
	s_add_i32 m0, s4, 0xffffff80
	s_nop 0
	global_load_lds_dwordx4 v130, s[100:101] offset:128
	s_add_i32 m0, s4, 0x1f80
	s_nop 0
	global_load_lds_dwordx4 v134, s[100:101] offset:128
	s_add_i32 m0, s45, 0xffffff80
	s_nop 0
	global_load_lds_dwordx4 v128, s[22:23] offset:128
	s_add_i32 m0, s50, 0xffffff80
	s_nop 0
	global_load_lds_dwordx4 v132, s[22:23] offset:128
	s_waitcnt vmcnt(8)
	s_waitcnt lgkmcnt(0)
	s_barrier
	s_setprio 1
	s_waitcnt lgkmcnt(0)
	v_mfma_f32_16x16x32_bf16 v[60:63], v[146:149], v[188:191], v[60:63]
	v_mfma_f32_16x16x32_bf16 v[56:59], v[164:167], v[188:191], v[56:59]
	v_mfma_f32_16x16x32_bf16 v[44:47], v[146:149], v[196:199], v[44:47]
	v_mfma_f32_16x16x32_bf16 v[40:43], v[164:167], v[196:199], v[40:43]
	v_mfma_f32_16x16x32_bf16 v[28:31], v[146:149], v[204:207], v[28:31]
	v_mfma_f32_16x16x32_bf16 v[24:27], v[164:167], v[204:207], v[24:27]
	v_mfma_f32_16x16x32_bf16 v[12:15], v[146:149], v[212:215], v[12:15]
	v_mfma_f32_16x16x32_bf16 v[8:11], v[164:167], v[212:215], v[8:11]
	v_mfma_f32_16x16x32_bf16 v[60:63], v[160:163], v[192:195], v[60:63]
	v_mfma_f32_16x16x32_bf16 v[56:59], v[168:171], v[192:195], v[56:59]
	v_mfma_f32_16x16x32_bf16 v[44:47], v[160:163], v[200:203], v[44:47]
	v_mfma_f32_16x16x32_bf16 v[40:43], v[168:171], v[200:203], v[40:43]
	v_mfma_f32_16x16x32_bf16 v[28:31], v[160:163], v[208:211], v[28:31]
	v_mfma_f32_16x16x32_bf16 v[24:27], v[168:171], v[208:211], v[24:27]
	v_mfma_f32_16x16x32_bf16 v[12:15], v[160:163], v[216:219], v[12:15]
	v_mfma_f32_16x16x32_bf16 v[8:11], v[168:171], v[216:219], v[8:11]
	s_setprio 0
	s_setprio 1
	v_mfma_f32_16x16x32_bf16 v[52:55], v[172:175], v[188:191], v[52:55]
	v_mfma_f32_16x16x32_bf16 v[48:51], v[180:183], v[188:191], v[48:51]
	v_mfma_f32_16x16x32_bf16 v[36:39], v[172:175], v[196:199], v[36:39]
	v_mfma_f32_16x16x32_bf16 v[32:35], v[180:183], v[196:199], v[32:35]
	v_mfma_f32_16x16x32_bf16 v[20:23], v[172:175], v[204:207], v[20:23]
	v_mfma_f32_16x16x32_bf16 v[16:19], v[180:183], v[204:207], v[16:19]
	v_mfma_f32_16x16x32_bf16 v[4:7], v[172:175], v[212:215], v[4:7]
	v_mfma_f32_16x16x32_bf16 v[0:3], v[180:183], v[212:215], v[0:3]
	v_mfma_f32_16x16x32_bf16 v[52:55], v[176:179], v[192:195], v[52:55]
	v_mfma_f32_16x16x32_bf16 v[48:51], v[184:187], v[192:195], v[48:51]
	v_mfma_f32_16x16x32_bf16 v[36:39], v[176:179], v[200:203], v[36:39]
	v_mfma_f32_16x16x32_bf16 v[32:35], v[184:187], v[200:203], v[32:35]
	v_mfma_f32_16x16x32_bf16 v[20:23], v[176:179], v[208:211], v[20:23]
	v_mfma_f32_16x16x32_bf16 v[16:19], v[184:187], v[208:211], v[16:19]
	v_mfma_f32_16x16x32_bf16 v[4:7], v[176:179], v[216:219], v[4:7]
	v_mfma_f32_16x16x32_bf16 v[0:3], v[184:187], v[216:219], v[0:3]
	s_setprio 0
	s_barrier
	s_add_u32 s0, s0, 0x100
	s_addc_u32 s1, s1, 0
	s_add_u32 s6, s6, 0x100
	s_addc_u32 s7, s7, 0
	s_cmp_ge_i32 s78, s51
	s_mov_b32 s4, s78
	s_cbranch_scc0 .LBB0_2052

; #define PG8_STAGE(bufoff, gbase, voff) do { _Pragma("unroll") for (int _i = 0; _i < 2; ++_i) \
;         __builtin_amdgcn_global_load_lds((const unsigned*)((const char*)(gbase) + (voff)[_i]), (PG8_LAS unsigned*)(lds + (bufoff) + ldsw + _i * 8192), 16, 0, 0); } while (0)
; #define PG8_LDA(dst, b, h) do { _Pragma("unroll") for (int m = 0; m < 4; ++m) _Pragma("unroll") for (int k = 0; k < 2; ++k) dst[m][k] = *(const PG8_LAS bf16x8*)(lds + PG8_SA(b, h) + aoff + m * 2048 + k * 1024); } while (0)
; #define PG8_LDB(dst, b, h) do { _Pragma("unroll") for (int n = 0; n < 2; ++n) _Pragma("unroll") for (int k = 0; k < 2; ++k) dst[n][k] = *(const PG8_LAS bf16x8*)(lds + PG8_SB(b, h) + boff + n * 2048 + k * 1024); } while (0)
; #define PG8_MMA(ai, bj, At, Bt) do { __builtin_amdgcn_s_setprio(1); _Pragma("unroll") for (int m = 0; m < 4; ++m) _Pragma("unroll") for (int n = 0; n < 2; ++n) _Pragma("unroll") for (int k = 0; k < 2; ++k) \
;         acc[ai][bj][m][n] = __builtin_amdgcn_mfma_f32_16x16x32_bf16(Bt[n][k], At[m][k], acc[ai][bj][m][n], 0, 0, 0); __builtin_amdgcn_s_setprio(0); } while (0)
; #define PG8_WAIT_V(n) asm volatile("s_waitcnt vmcnt(" #n ")" ::: "memory")
; #define PG8_WAIT_L(n) asm volatile("s_waitcnt lgkmcnt(" #n ")" ::: "memory")
; template <class Epi, class Sched, bool ALIGN_EPI = false, bool SP2 = false>
; __device__ __forceinline__ void gemm_phase(PG8_LAS unsigned char* lds, const Gemm g, const Sched& S, const Epi& E) {
;     ...
;             const bool last = (t == nt - 2);
;             const char* a1 = cA + (size_t)(t + 1) * kstep;
;             const char* a2 = last ? nA : cA + (size_t)(t + 2) * kstep; const char* b2 = last ? nB : cB + (size_t)(t + 2) * kstep;
;             const char* a3 = a2 + kstep; const char* b3 = b2 + kstep;
;             if (last && has_next) S.a_ready(nxt);
;             if constexpr (SP2) {
;             PG8_LDB(B0, 0, 0); PG8_LDB(B1, 0, 1); PG8_SCHED; PG8_LDA(At, 0, 0); PG8_STAGE(PG8_SA(1, 1), a1 + hstep, voffA);
;             PG8_WAIT_V(8); PG8_WAIT_L(0); PG8_BAR; PG8_MMA(0, 0, At, B0); PG8_MMA(0, 1, At, B1); PG8_BAR; PG8_SCHED;
;             PG8_LDA(At, 0, 1); PG8_STAGE(PG8_SB(0, 0), b2, voffB); PG8_STAGE(PG8_SB(0, 1), b2 + hstep, voffB); PG8_STAGE(PG8_SA(0, 0), a2, voffA);
;             PG8_WAIT_V(8); PG8_WAIT_L(0); PG8_BAR; PG8_MMA(1, 0, At, B0); PG8_MMA(1, 1, At, B1); PG8_BAR; PG8_SCHED;
.LBB0_2163:
	s_andn2_b64 vcc, exec, s[22:23]
	s_cbranch_vccnz .LBB0_2166
	s_add_u32 s30, s30, 0x80
	s_addc_u32 s31, s31, 0
	s_add_u32 s77, s34, 0x100
	s_addc_u32 s78, s35, 0
	s_mov_b32 s34, 0
	ds_read_b128 v[146:149], v152
	ds_read_b128 v[158:161], v152 offset:1024
	ds_read_b128 v[162:165], v152 offset:2048
	ds_read_b128 v[166:169], v152 offset:3072
	ds_read_b128 v[170:173], v153
	ds_read_b128 v[174:177], v153 offset:1024
	ds_read_b128 v[178:181], v153 offset:2048
	ds_read_b128 v[182:185], v153 offset:3072
	s_add_i32 s79, s34, 2
	s_add_u32 s80, s30, 0x80
	s_addc_u32 s35, s31, 0
	s_cmp_eq_u32 s50, s34
	s_cselect_b32 s34, s0, s80
	s_cselect_b32 s35, s1, s35
	s_cselect_b32 s81, s29, s78
	s_cselect_b32 s80, s28, s77
	s_add_i32 m0, s33, 0xc000
	ds_read_b128 v[186:189], v154
	ds_read_b128 v[190:193], v154 offset:1024
	ds_read_b128 v[194:197], v154 offset:2048
	ds_read_b128 v[198:201], v154 offset:3072
	ds_read_b128 v[202:205], v154 offset:4096
	ds_read_b128 v[206:209], v154 offset:5120
	ds_read_b128 v[210:213], v154 offset:6144
	ds_read_b128 v[214:217], v154 offset:7168
	global_load_lds_dwordx4 v138, s[30:31]
	s_add_i32 m0, s33, 0xe000
	s_nop 0
	global_load_lds_dwordx4 v140, s[30:31]
	s_waitcnt vmcnt(8)
	s_waitcnt lgkmcnt(0)
	s_barrier
	s_setprio 1
	s_waitcnt lgkmcnt(0)
	v_mfma_f32_16x16x32_bf16 v[120:123], v[146:149], v[186:189], 0
	v_mfma_f32_16x16x32_bf16 v[124:127], v[162:165], v[186:189], 0
	v_mfma_f32_16x16x32_bf16 v[108:111], v[146:149], v[194:197], 0
	v_mfma_f32_16x16x32_bf16 v[104:107], v[162:165], v[194:197], 0
	v_mfma_f32_16x16x32_bf16 v[92:95], v[146:149], v[202:205], 0
	v_mfma_f32_16x16x32_bf16 v[88:91], v[162:165], v[202:205], 0
	v_mfma_f32_16x16x32_bf16 v[76:79], v[146:149], v[210:213], 0
	v_mfma_f32_16x16x32_bf16 v[72:75], v[162:165], v[210:213], 0
	v_mfma_f32_16x16x32_bf16 v[120:123], v[158:161], v[190:193], v[120:123]
	v_mfma_f32_16x16x32_bf16 v[124:127], v[166:169], v[190:193], v[124:127]
	v_mfma_f32_16x16x32_bf16 v[108:111], v[158:161], v[198:201], v[108:111]
	v_mfma_f32_16x16x32_bf16 v[104:107], v[166:169], v[198:201], v[104:107]
	v_mfma_f32_16x16x32_bf16 v[92:95], v[158:161], v[206:209], v[92:95]
	v_mfma_f32_16x16x32_bf16 v[88:91], v[166:169], v[206:209], v[88:91]
	v_mfma_f32_16x16x32_bf16 v[76:79], v[158:161], v[214:217], v[76:79]
	v_mfma_f32_16x16x32_bf16 v[72:75], v[166:169], v[214:217], v[72:75]
	s_setprio 0
	s_setprio 1
	v_mfma_f32_16x16x32_bf16 v[116:119], v[170:173], v[186:189], 0
	v_mfma_f32_16x16x32_bf16 v[112:115], v[178:181], v[186:189], 0
	v_mfma_f32_16x16x32_bf16 v[100:103], v[170:173], v[194:197], 0
	v_mfma_f32_16x16x32_bf16 v[96:99], v[178:181], v[194:197], 0
	v_mfma_f32_16x16x32_bf16 v[84:87], v[170:173], v[202:205], 0
	v_mfma_f32_16x16x32_bf16 v[80:83], v[178:181], v[202:205], 0
	v_mfma_f32_16x16x32_bf16 v[68:71], v[170:173], v[210:213], 0
	v_mfma_f32_16x16x32_bf16 v[64:67], v[178:181], v[210:213], 0
	v_mfma_f32_16x16x32_bf16 v[116:119], v[174:177], v[190:193], v[116:119]
	v_mfma_f32_16x16x32_bf16 v[112:115], v[182:185], v[190:193], v[112:115]
	v_mfma_f32_16x16x32_bf16 v[100:103], v[174:177], v[198:201], v[100:103]
	v_mfma_f32_16x16x32_bf16 v[96:99], v[182:185], v[198:201], v[96:99]
	v_mfma_f32_16x16x32_bf16 v[84:87], v[174:177], v[206:209], v[84:87]
	v_mfma_f32_16x16x32_bf16 v[80:83], v[182:185], v[206:209], v[80:83]
	v_mfma_f32_16x16x32_bf16 v[68:71], v[174:177], v[214:217], v[68:71]
	v_mfma_f32_16x16x32_bf16 v[64:67], v[182:185], v[214:217], v[64:67]
	s_setprio 0
	s_barrier
	s_add_i32 s82, s59, s16
	s_mov_b64 s[98:99], s[80:81]
	s_mov_b32 m0, s82
	ds_read_b128 v[186:189], v154 offset:16384
	ds_read_b128 v[190:193], v154 offset:17408
	ds_read_b128 v[194:197], v154 offset:18432
	ds_read_b128 v[198:201], v154 offset:19456
	ds_read_b128 v[202:205], v154 offset:20480
	ds_read_b128 v[206:209], v154 offset:21504
	ds_read_b128 v[210:213], v154 offset:22528
	ds_read_b128 v[214:217], v154 offset:23552
	global_load_lds_dwordx4 v130, s[80:81]
	s_add_i32 m0, s82, 0x2000
	s_add_u32 s80, s80, s8
	s_addc_u32 s81, s81, s9
	s_add_i32 s82, s60, s16
	global_load_lds_dwordx4 v134, s[98:99]
	s_mov_b64 s[100:101], s[80:81]
	s_mov_b32 m0, s82
	s_nop 0
	global_load_lds_dwordx4 v130, s[80:81]
	s_add_i32 m0, s82, 0x2000
	s_mov_b64 s[20:21], s[34:35]
	global_load_lds_dwordx4 v134, s[80:81]
	s_mov_b32 m0, s33
	s_nop 0
	global_load_lds_dwordx4 v128, s[34:35]
	s_mov_b32 m0, s36
	s_nop 0
	global_load_lds_dwordx4 v132, s[34:35]
	s_waitcnt vmcnt(8)
	s_waitcnt lgkmcnt(0)
	s_barrier
	s_setprio 1
	s_waitcnt lgkmcnt(0)
	v_mfma_f32_16x16x32_bf16 v[60:63], v[146:149], v[186:189], 0
	v_mfma_f32_16x16x32_bf16 v[56:59], v[162:165], v[186:189], 0
	v_mfma_f32_16x16x32_bf16 v[44:47], v[146:149], v[194:197], 0
	v_mfma_f32_16x16x32_bf16 v[40:43], v[162:165], v[194:197], 0
	v_mfma_f32_16x16x32_bf16 v[28:31], v[146:149], v[202:205], 0
	v_mfma_f32_16x16x32_bf16 v[24:27], v[162:165], v[202:205], 0
	v_mfma_f32_16x16x32_bf16 v[12:15], v[146:149], v[210:213], 0
	v_mfma_f32_16x16x32_bf16 v[8:11], v[162:165], v[210:213], 0
	v_mfma_f32_16x16x32_bf16 v[60:63], v[158:161], v[190:193], v[60:63]
	v_mfma_f32_16x16x32_bf16 v[56:59], v[166:169], v[190:193], v[56:59]
	v_mfma_f32_16x16x32_bf16 v[44:47], v[158:161], v[198:201], v[44:47]
	v_mfma_f32_16x16x32_bf16 v[40:43], v[166:169], v[198:201], v[40:43]
	v_mfma_f32_16x16x32_bf16 v[28:31], v[158:161], v[206:209], v[28:31]
	v_mfma_f32_16x16x32_bf16 v[24:27], v[166:169], v[206:209], v[24:27]
	v_mfma_f32_16x16x32_bf16 v[12:15], v[158:161], v[214:217], v[12:15]
	v_mfma_f32_16x16x32_bf16 v[8:11], v[166:169], v[214:217], v[8:11]
	s_setprio 0
	s_setprio 1
	v_mfma_f32_16x16x32_bf16 v[52:55], v[170:173], v[186:189], 0
	v_mfma_f32_16x16x32_bf16 v[48:51], v[178:181], v[186:189], 0
	v_mfma_f32_16x16x32_bf16 v[36:39], v[170:173], v[194:197], 0
	v_mfma_f32_16x16x32_bf16 v[32:35], v[178:181], v[194:197], 0
	v_mfma_f32_16x16x32_bf16 v[20:23], v[170:173], v[202:205], 0
	v_mfma_f32_16x16x32_bf16 v[16:19], v[178:181], v[202:205], 0
	v_mfma_f32_16x16x32_bf16 v[4:7], v[170:173], v[210:213], 0
	v_mfma_f32_16x16x32_bf16 v[0:3], v[178:181], v[210:213], 0
	v_mfma_f32_16x16x32_bf16 v[52:55], v[174:177], v[190:193], v[52:55]
	v_mfma_f32_16x16x32_bf16 v[48:51], v[182:185], v[190:193], v[48:51]
	v_mfma_f32_16x16x32_bf16 v[36:39], v[174:177], v[198:201], v[36:39]
	v_mfma_f32_16x16x32_bf16 v[32:35], v[182:185], v[198:201], v[32:35]
	v_mfma_f32_16x16x32_bf16 v[20:23], v[174:177], v[206:209], v[20:23]
	v_mfma_f32_16x16x32_bf16 v[16:19], v[182:185], v[206:209], v[16:19]
	v_mfma_f32_16x16x32_bf16 v[4:7], v[174:177], v[214:217], v[4:7]
	v_mfma_f32_16x16x32_bf16 v[0:3], v[182:185], v[214:217], v[0:3]
	s_setprio 0
	s_barrier
; #define PG8_STAGE(bufoff, gbase, voff) do { _Pragma("unroll") for (int _i = 0; _i < 2; ++_i) \
;         __builtin_amdgcn_global_load_lds((const unsigned*)((const char*)(gbase) + (voff)[_i]), (PG8_LAS unsigned*)(lds + (bufoff) + ldsw + _i * 8192), 16, 0, 0); } while (0)
; #define PG8_LDA(dst, b, h) do { _Pragma("unroll") for (int m = 0; m < 4; ++m) _Pragma("unroll") for (int k = 0; k < 2; ++k) dst[m][k] = *(const PG8_LAS bf16x8*)(lds + PG8_SA(b, h) + aoff + m * 2048 + k * 1024); } while (0)
; #define PG8_LDB(dst, b, h) do { _Pragma("unroll") for (int n = 0; n < 2; ++n) _Pragma("unroll") for (int k = 0; k < 2; ++k) dst[n][k] = *(const PG8_LAS bf16x8*)(lds + PG8_SB(b, h) + boff + n * 2048 + k * 1024); } while (0)
; #define PG8_MMA(ai, bj, At, Bt) do { __builtin_amdgcn_s_setprio(1); _Pragma("unroll") for (int m = 0; m < 4; ++m) _Pragma("unroll") for (int n = 0; n < 2; ++n) _Pragma("unroll") for (int k = 0; k < 2; ++k) \
;         acc[ai][bj][m][n] = __builtin_amdgcn_mfma_f32_16x16x32_bf16(Bt[n][k], At[m][k], acc[ai][bj][m][n], 0, 0, 0); __builtin_amdgcn_s_setprio(0); } while (0)
; #define PG8_WAIT_V(n) asm volatile("s_waitcnt vmcnt(" #n ")" ::: "memory")
; #define PG8_WAIT_L(n) asm volatile("s_waitcnt lgkmcnt(" #n ")" ::: "memory")
; #define PG8_BAR __builtin_amdgcn_s_barrier()
; #define PG8_SCHED __builtin_amdgcn_sched_barrier(0)
; template <class Epi, class Sched, bool ALIGN_EPI = false, bool SP2 = false>
; __device__ __forceinline__ void gemm_phase(PG8_LAS unsigned char* lds, const Gemm g, const Sched& S, const Epi& E) {
;     ...
;             PG8_LDB(B0, 1, 0); PG8_LDB(B1, 1, 1); PG8_SCHED; PG8_LDA(At, 1, 0); PG8_STAGE(PG8_SA(0, 1), a2 + hstep, voffA);
;             PG8_WAIT_V(8); PG8_WAIT_L(0); PG8_BAR; PG8_MMA(0, 0, At, B0); PG8_MMA(0, 1, At, B1); PG8_BAR; PG8_SCHED;
;             PG8_LDA(At, 1, 1); PG8_STAGE(PG8_SB(1, 0), b3, voffB); PG8_STAGE(PG8_SB(1, 1), b3 + hstep, voffB); PG8_STAGE(PG8_SA(1, 0), a3, voffA);
;             PG8_WAIT_V(8); PG8_WAIT_L(0); PG8_BAR; PG8_MMA(1, 0, At, B0); PG8_MMA(1, 1, At, B1); PG8_BAR; PG8_SCHED;
	s_add_i32 s80, 0, 0x18000
	s_add_i32 s81, 0, 0x1c000
	v_add_u32_e32 v166, s80, v151
	v_add_u32_e32 v182, s81, v151
	ds_read_b128 v[146:149], v166
	ds_read_b128 v[158:161], v166 offset:1024
	ds_read_b128 v[162:165], v166 offset:2048
	ds_read_b128 v[166:169], v166 offset:3072
	ds_read_b128 v[170:173], v182
	ds_read_b128 v[174:177], v182 offset:1024
	ds_read_b128 v[178:181], v182 offset:2048
	ds_read_b128 v[182:185], v182 offset:3072
	s_add_u32 s34, s34, s8
	s_addc_u32 s35, s35, s9
	s_mov_b32 m0, s37
	ds_read_b128 v[186:189], v154 offset:32768
	ds_read_b128 v[190:193], v154 offset:33792
	ds_read_b128 v[194:197], v154 offset:34816
	ds_read_b128 v[198:201], v154 offset:35840
	ds_read_b128 v[202:205], v154 offset:36864
	ds_read_b128 v[206:209], v154 offset:37888
	ds_read_b128 v[210:213], v154 offset:38912
	ds_read_b128 v[214:217], v154 offset:39936
	global_load_lds_dwordx4 v128, s[34:35]
	s_mov_b32 m0, s38
	s_nop 0
	global_load_lds_dwordx4 v132, s[34:35]
	s_waitcnt vmcnt(8)
	s_waitcnt lgkmcnt(0)
	s_barrier
	s_setprio 1
	s_waitcnt lgkmcnt(0)
	v_mfma_f32_16x16x32_bf16 v[120:123], v[146:149], v[186:189], v[120:123]
	v_mfma_f32_16x16x32_bf16 v[124:127], v[162:165], v[186:189], v[124:127]
	v_mfma_f32_16x16x32_bf16 v[108:111], v[146:149], v[194:197], v[108:111]
	v_mfma_f32_16x16x32_bf16 v[104:107], v[162:165], v[194:197], v[104:107]
	v_mfma_f32_16x16x32_bf16 v[92:95], v[146:149], v[202:205], v[92:95]
	v_mfma_f32_16x16x32_bf16 v[88:91], v[162:165], v[202:205], v[88:91]
	v_mfma_f32_16x16x32_bf16 v[76:79], v[146:149], v[210:213], v[76:79]
	v_mfma_f32_16x16x32_bf16 v[72:75], v[162:165], v[210:213], v[72:75]
	v_mfma_f32_16x16x32_bf16 v[120:123], v[158:161], v[190:193], v[120:123]
	v_mfma_f32_16x16x32_bf16 v[124:127], v[166:169], v[190:193], v[124:127]
	v_mfma_f32_16x16x32_bf16 v[108:111], v[158:161], v[198:201], v[108:111]
	v_mfma_f32_16x16x32_bf16 v[104:107], v[166:169], v[198:201], v[104:107]
	v_mfma_f32_16x16x32_bf16 v[92:95], v[158:161], v[206:209], v[92:95]
	v_mfma_f32_16x16x32_bf16 v[88:91], v[166:169], v[206:209], v[88:91]
	v_mfma_f32_16x16x32_bf16 v[76:79], v[158:161], v[214:217], v[76:79]
	v_mfma_f32_16x16x32_bf16 v[72:75], v[166:169], v[214:217], v[72:75]
	s_setprio 0
	s_setprio 1
	v_mfma_f32_16x16x32_bf16 v[116:119], v[170:173], v[186:189], v[116:119]
	v_mfma_f32_16x16x32_bf16 v[112:115], v[178:181], v[186:189], v[112:115]
	v_mfma_f32_16x16x32_bf16 v[100:103], v[170:173], v[194:197], v[100:103]
	v_mfma_f32_16x16x32_bf16 v[96:99], v[178:181], v[194:197], v[96:99]
	v_mfma_f32_16x16x32_bf16 v[84:87], v[170:173], v[202:205], v[84:87]
	v_mfma_f32_16x16x32_bf16 v[80:83], v[178:181], v[202:205], v[80:83]
	v_mfma_f32_16x16x32_bf16 v[68:71], v[170:173], v[210:213], v[68:71]
	v_mfma_f32_16x16x32_bf16 v[64:67], v[178:181], v[210:213], v[64:67]
	v_mfma_f32_16x16x32_bf16 v[116:119], v[174:177], v[190:193], v[116:119]
	v_mfma_f32_16x16x32_bf16 v[112:115], v[182:185], v[190:193], v[112:115]
	v_mfma_f32_16x16x32_bf16 v[100:103], v[174:177], v[198:201], v[100:103]
	v_mfma_f32_16x16x32_bf16 v[96:99], v[182:185], v[198:201], v[96:99]
	v_mfma_f32_16x16x32_bf16 v[84:87], v[174:177], v[206:209], v[84:87]
	v_mfma_f32_16x16x32_bf16 v[80:83], v[182:185], v[206:209], v[80:83]
	v_mfma_f32_16x16x32_bf16 v[68:71], v[174:177], v[214:217], v[68:71]
	v_mfma_f32_16x16x32_bf16 v[64:67], v[182:185], v[214:217], v[64:67]
	s_setprio 0
	s_barrier
	s_add_i32 s34, s80, s16
	s_add_i32 m0, s34, 0xffffff80
	ds_read_b128 v[186:189], v154 offset:49152
	ds_read_b128 v[190:193], v154 offset:50176
	ds_read_b128 v[194:197], v154 offset:51200
	ds_read_b128 v[198:201], v154 offset:52224
	ds_read_b128 v[202:205], v154 offset:53248
	ds_read_b128 v[206:209], v154 offset:54272
	ds_read_b128 v[210:213], v154 offset:55296
	ds_read_b128 v[214:217], v154 offset:56320
	global_load_lds_dwordx4 v130, s[98:99] offset:128
	s_add_i32 m0, s34, 0x1f80
	s_add_i32 s34, s81, s16
	global_load_lds_dwordx4 v134, s[98:99] offset:128
	s_add_i32 m0, s34, 0xffffff80
	s_nop 0
	global_load_lds_dwordx4 v130, s[100:101] offset:128
	s_add_i32 m0, s34, 0x1f80
	s_nop 0
	global_load_lds_dwordx4 v134, s[100:101] offset:128
	s_add_i32 m0, s44, 0xffffff80
	s_nop 0
	global_load_lds_dwordx4 v128, s[20:21] offset:128
	s_add_i32 m0, s45, 0xffffff80
	s_nop 0
	global_load_lds_dwordx4 v132, s[20:21] offset:128
	s_waitcnt vmcnt(8)
	s_waitcnt lgkmcnt(0)
	s_barrier
	s_setprio 1
	s_waitcnt lgkmcnt(0)
	v_mfma_f32_16x16x32_bf16 v[60:63], v[146:149], v[186:189], v[60:63]
	v_mfma_f32_16x16x32_bf16 v[56:59], v[162:165], v[186:189], v[56:59]
	v_mfma_f32_16x16x32_bf16 v[44:47], v[146:149], v[194:197], v[44:47]
	v_mfma_f32_16x16x32_bf16 v[40:43], v[162:165], v[194:197], v[40:43]
	v_mfma_f32_16x16x32_bf16 v[28:31], v[146:149], v[202:205], v[28:31]
	v_mfma_f32_16x16x32_bf16 v[24:27], v[162:165], v[202:205], v[24:27]
	v_mfma_f32_16x16x32_bf16 v[12:15], v[146:149], v[210:213], v[12:15]
	v_mfma_f32_16x16x32_bf16 v[8:11], v[162:165], v[210:213], v[8:11]
	v_mfma_f32_16x16x32_bf16 v[60:63], v[158:161], v[190:193], v[60:63]
	v_mfma_f32_16x16x32_bf16 v[56:59], v[166:169], v[190:193], v[56:59]
	v_mfma_f32_16x16x32_bf16 v[44:47], v[158:161], v[198:201], v[44:47]
	v_mfma_f32_16x16x32_bf16 v[40:43], v[166:169], v[198:201], v[40:43]
	v_mfma_f32_16x16x32_bf16 v[28:31], v[158:161], v[206:209], v[28:31]
	v_mfma_f32_16x16x32_bf16 v[24:27], v[166:169], v[206:209], v[24:27]
	v_mfma_f32_16x16x32_bf16 v[12:15], v[158:161], v[214:217], v[12:15]
	v_mfma_f32_16x16x32_bf16 v[8:11], v[166:169], v[214:217], v[8:11]
	s_setprio 0
	s_setprio 1
	v_mfma_f32_16x16x32_bf16 v[52:55], v[170:173], v[186:189], v[52:55]
	v_mfma_f32_16x16x32_bf16 v[48:51], v[178:181], v[186:189], v[48:51]
	v_mfma_f32_16x16x32_bf16 v[36:39], v[170:173], v[194:197], v[36:39]
	v_mfma_f32_16x16x32_bf16 v[32:35], v[178:181], v[194:197], v[32:35]
	v_mfma_f32_16x16x32_bf16 v[20:23], v[170:173], v[202:205], v[20:23]
	v_mfma_f32_16x16x32_bf16 v[16:19], v[178:181], v[202:205], v[16:19]
	v_mfma_f32_16x16x32_bf16 v[4:7], v[170:173], v[210:213], v[4:7]
	v_mfma_f32_16x16x32_bf16 v[0:3], v[178:181], v[210:213], v[0:3]
	v_mfma_f32_16x16x32_bf16 v[52:55], v[174:177], v[190:193], v[52:55]
	v_mfma_f32_16x16x32_bf16 v[48:51], v[182:185], v[190:193], v[48:51]
	v_mfma_f32_16x16x32_bf16 v[36:39], v[174:177], v[198:201], v[36:39]
	v_mfma_f32_16x16x32_bf16 v[32:35], v[182:185], v[198:201], v[32:35]
	v_mfma_f32_16x16x32_bf16 v[20:23], v[174:177], v[206:209], v[20:23]
	v_mfma_f32_16x16x32_bf16 v[16:19], v[182:185], v[206:209], v[16:19]
	v_mfma_f32_16x16x32_bf16 v[4:7], v[174:177], v[214:217], v[4:7]
	v_mfma_f32_16x16x32_bf16 v[0:3], v[182:185], v[214:217], v[0:3]
	s_setprio 0
	s_barrier
	s_add_u32 s30, s30, 0x100
	s_addc_u32 s31, s31, 0
	s_add_u32 s77, s77, 0x100
	s_addc_u32 s78, s78, 0
	s_cmp_ge_i32 s79, s40
	s_mov_b32 s34, s79
	s_cbranch_scc0 .LBB0_2165
	s_branch .Lpeel_x10
; #define PG8_STAGE(bufoff, gbase, voff) do { _Pragma("unroll") for (int _i = 0; _i < 2; ++_i) \
;         __builtin_amdgcn_global_load_lds((const unsigned*)((const char*)(gbase) + (voff)[_i]), (PG8_LAS unsigned*)(lds + (bufoff) + ldsw + _i * 8192), 16, 0, 0); } while (0)
; #define PG8_LDA(dst, b, h) do { _Pragma("unroll") for (int m = 0; m < 4; ++m) _Pragma("unroll") for (int k = 0; k < 2; ++k) dst[m][k] = *(const PG8_LAS bf16x8*)(lds + PG8_SA(b, h) + aoff + m * 2048 + k * 1024); } while (0)
; #define PG8_LDB(dst, b, h) do { _Pragma("unroll") for (int n = 0; n < 2; ++n) _Pragma("unroll") for (int k = 0; k < 2; ++k) dst[n][k] = *(const PG8_LAS bf16x8*)(lds + PG8_SB(b, h) + boff + n * 2048 + k * 1024); } while (0)
; #define PG8_MMA(ai, bj, At, Bt) do { __builtin_amdgcn_s_setprio(1); _Pragma("unroll") for (int m = 0; m < 4; ++m) _Pragma("unroll") for (int n = 0; n < 2; ++n) _Pragma("unroll") for (int k = 0; k < 2; ++k) \
;         acc[ai][bj][m][n] = __builtin_amdgcn_mfma_f32_16x16x32_bf16(Bt[n][k], At[m][k], acc[ai][bj][m][n], 0, 0, 0); __builtin_amdgcn_s_setprio(0); } while (0)
; #define PG8_WAIT_V(n) asm volatile("s_waitcnt vmcnt(" #n ")" ::: "memory")
; #define PG8_WAIT_L(n) asm volatile("s_waitcnt lgkmcnt(" #n ")" ::: "memory")
; template <class Epi, class Sched, bool ALIGN_EPI = false, bool SP2 = false>
; __device__ __forceinline__ void gemm_phase(PG8_LAS unsigned char* lds, const Gemm g, const Sched& S, const Epi& E) {
;     ...
;             const bool last = (t == nt - 2);
;             const char* a1 = cA + (size_t)(t + 1) * kstep;
;             const char* a2 = last ? nA : cA + (size_t)(t + 2) * kstep; const char* b2 = last ? nB : cB + (size_t)(t + 2) * kstep;
;             const char* a3 = a2 + kstep; const char* b3 = b2 + kstep;
;             if (last && has_next) S.a_ready(nxt);
;             if constexpr (SP2) {
;             PG8_LDB(B0, 0, 0); PG8_LDB(B1, 0, 1); PG8_SCHED; PG8_LDA(At, 0, 0); PG8_STAGE(PG8_SA(1, 1), a1 + hstep, voffA);
;             PG8_WAIT_V(8); PG8_WAIT_L(0); PG8_BAR; PG8_MMA(0, 0, At, B0); PG8_MMA(0, 1, At, B1); PG8_BAR; PG8_SCHED;
;             PG8_LDA(At, 0, 1); PG8_STAGE(PG8_SB(0, 0), b2, voffB); PG8_STAGE(PG8_SB(0, 1), b2 + hstep, voffB); PG8_STAGE(PG8_SA(0, 0), a2, voffA);
;             PG8_WAIT_V(8); PG8_WAIT_L(0); PG8_BAR; PG8_MMA(1, 0, At, B0); PG8_MMA(1, 1, At, B1); PG8_BAR; PG8_SCHED;
.LBB0_2165:
	ds_read_b128 v[146:149], v152
	ds_read_b128 v[158:161], v152 offset:1024
	ds_read_b128 v[162:165], v152 offset:2048
	ds_read_b128 v[166:169], v152 offset:3072
	ds_read_b128 v[170:173], v153
	ds_read_b128 v[174:177], v153 offset:1024
	ds_read_b128 v[178:181], v153 offset:2048
	ds_read_b128 v[182:185], v153 offset:3072
	s_add_i32 s79, s34, 2
	s_add_u32 s80, s30, 0x80
	s_addc_u32 s35, s31, 0
	s_cmp_eq_u32 s50, s34
	s_cselect_b32 s34, s0, s80
	s_cselect_b32 s35, s1, s35
	s_cselect_b32 s81, s29, s78
	s_cselect_b32 s80, s28, s77
	s_add_i32 m0, s33, 0xc000
	ds_read_b128 v[186:189], v154
	ds_read_b128 v[190:193], v154 offset:1024
	ds_read_b128 v[194:197], v154 offset:2048
	ds_read_b128 v[198:201], v154 offset:3072
	ds_read_b128 v[202:205], v154 offset:4096
	ds_read_b128 v[206:209], v154 offset:5120
	ds_read_b128 v[210:213], v154 offset:6144
	ds_read_b128 v[214:217], v154 offset:7168
	global_load_lds_dwordx4 v138, s[30:31]
	s_add_i32 m0, s33, 0xe000
	s_nop 0
	global_load_lds_dwordx4 v140, s[30:31]
	s_waitcnt vmcnt(8)
	s_waitcnt lgkmcnt(0)
	s_barrier
	s_setprio 1
	s_waitcnt lgkmcnt(0)
	v_mfma_f32_16x16x32_bf16 v[120:123], v[146:149], v[186:189], v[120:123]
	v_mfma_f32_16x16x32_bf16 v[124:127], v[162:165], v[186:189], v[124:127]
	v_mfma_f32_16x16x32_bf16 v[108:111], v[146:149], v[194:197], v[108:111]
	v_mfma_f32_16x16x32_bf16 v[104:107], v[162:165], v[194:197], v[104:107]
	v_mfma_f32_16x16x32_bf16 v[92:95], v[146:149], v[202:205], v[92:95]
	v_mfma_f32_16x16x32_bf16 v[88:91], v[162:165], v[202:205], v[88:91]
	v_mfma_f32_16x16x32_bf16 v[76:79], v[146:149], v[210:213], v[76:79]
	v_mfma_f32_16x16x32_bf16 v[72:75], v[162:165], v[210:213], v[72:75]
	v_mfma_f32_16x16x32_bf16 v[120:123], v[158:161], v[190:193], v[120:123]
	v_mfma_f32_16x16x32_bf16 v[124:127], v[166:169], v[190:193], v[124:127]
	v_mfma_f32_16x16x32_bf16 v[108:111], v[158:161], v[198:201], v[108:111]
	v_mfma_f32_16x16x32_bf16 v[104:107], v[166:169], v[198:201], v[104:107]
	v_mfma_f32_16x16x32_bf16 v[92:95], v[158:161], v[206:209], v[92:95]
	v_mfma_f32_16x16x32_bf16 v[88:91], v[166:169], v[206:209], v[88:91]
	v_mfma_f32_16x16x32_bf16 v[76:79], v[158:161], v[214:217], v[76:79]
	v_mfma_f32_16x16x32_bf16 v[72:75], v[166:169], v[214:217], v[72:75]
	s_setprio 0
	s_setprio 1
	v_mfma_f32_16x16x32_bf16 v[116:119], v[170:173], v[186:189], v[116:119]
	v_mfma_f32_16x16x32_bf16 v[112:115], v[178:181], v[186:189], v[112:115]
	v_mfma_f32_16x16x32_bf16 v[100:103], v[170:173], v[194:197], v[100:103]
	v_mfma_f32_16x16x32_bf16 v[96:99], v[178:181], v[194:197], v[96:99]
	v_mfma_f32_16x16x32_bf16 v[84:87], v[170:173], v[202:205], v[84:87]
	v_mfma_f32_16x16x32_bf16 v[80:83], v[178:181], v[202:205], v[80:83]
	v_mfma_f32_16x16x32_bf16 v[68:71], v[170:173], v[210:213], v[68:71]
	v_mfma_f32_16x16x32_bf16 v[64:67], v[178:181], v[210:213], v[64:67]
	v_mfma_f32_16x16x32_bf16 v[116:119], v[174:177], v[190:193], v[116:119]
	v_mfma_f32_16x16x32_bf16 v[112:115], v[182:185], v[190:193], v[112:115]
	v_mfma_f32_16x16x32_bf16 v[100:103], v[174:177], v[198:201], v[100:103]
	v_mfma_f32_16x16x32_bf16 v[96:99], v[182:185], v[198:201], v[96:99]
	v_mfma_f32_16x16x32_bf16 v[84:87], v[174:177], v[206:209], v[84:87]
	v_mfma_f32_16x16x32_bf16 v[80:83], v[182:185], v[206:209], v[80:83]
	v_mfma_f32_16x16x32_bf16 v[68:71], v[174:177], v[214:217], v[68:71]
	v_mfma_f32_16x16x32_bf16 v[64:67], v[182:185], v[214:217], v[64:67]
	s_setprio 0
	s_barrier
	s_add_i32 s82, s59, s16
	s_mov_b64 s[98:99], s[80:81]
	s_mov_b32 m0, s82
	ds_read_b128 v[186:189], v154 offset:16384
	ds_read_b128 v[190:193], v154 offset:17408
	ds_read_b128 v[194:197], v154 offset:18432
	ds_read_b128 v[198:201], v154 offset:19456
	ds_read_b128 v[202:205], v154 offset:20480
	ds_read_b128 v[206:209], v154 offset:21504
	ds_read_b128 v[210:213], v154 offset:22528
	ds_read_b128 v[214:217], v154 offset:23552
	global_load_lds_dwordx4 v130, s[80:81]
	s_add_i32 m0, s82, 0x2000
	s_add_u32 s80, s80, s8
	s_addc_u32 s81, s81, s9
	s_add_i32 s82, s60, s16
	global_load_lds_dwordx4 v134, s[98:99]
	s_mov_b64 s[100:101], s[80:81]
	s_mov_b32 m0, s82
	s_nop 0
	global_load_lds_dwordx4 v130, s[80:81]
	s_add_i32 m0, s82, 0x2000
	s_mov_b64 s[20:21], s[34:35]
	global_load_lds_dwordx4 v134, s[80:81]
	s_mov_b32 m0, s33
	s_nop 0
	global_load_lds_dwordx4 v128, s[34:35]
	s_mov_b32 m0, s36
	s_nop 0
	global_load_lds_dwordx4 v132, s[34:35]
	s_waitcnt vmcnt(8)
	s_waitcnt lgkmcnt(0)
	s_barrier
	s_setprio 1
	s_waitcnt lgkmcnt(0)
	v_mfma_f32_16x16x32_bf16 v[60:63], v[146:149], v[186:189], v[60:63]
	v_mfma_f32_16x16x32_bf16 v[56:59], v[162:165], v[186:189], v[56:59]
	v_mfma_f32_16x16x32_bf16 v[44:47], v[146:149], v[194:197], v[44:47]
	v_mfma_f32_16x16x32_bf16 v[40:43], v[162:165], v[194:197], v[40:43]
	v_mfma_f32_16x16x32_bf16 v[28:31], v[146:149], v[202:205], v[28:31]
	v_mfma_f32_16x16x32_bf16 v[24:27], v[162:165], v[202:205], v[24:27]
	v_mfma_f32_16x16x32_bf16 v[12:15], v[146:149], v[210:213], v[12:15]
	v_mfma_f32_16x16x32_bf16 v[8:11], v[162:165], v[210:213], v[8:11]
	v_mfma_f32_16x16x32_bf16 v[60:63], v[158:161], v[190:193], v[60:63]
	v_mfma_f32_16x16x32_bf16 v[56:59], v[166:169], v[190:193], v[56:59]
	v_mfma_f32_16x16x32_bf16 v[44:47], v[158:161], v[198:201], v[44:47]
	v_mfma_f32_16x16x32_bf16 v[40:43], v[166:169], v[198:201], v[40:43]
	v_mfma_f32_16x16x32_bf16 v[28:31], v[158:161], v[206:209], v[28:31]
	v_mfma_f32_16x16x32_bf16 v[24:27], v[166:169], v[206:209], v[24:27]
	v_mfma_f32_16x16x32_bf16 v[12:15], v[158:161], v[214:217], v[12:15]
	v_mfma_f32_16x16x32_bf16 v[8:11], v[166:169], v[214:217], v[8:11]
	s_setprio 0
	s_setprio 1
	v_mfma_f32_16x16x32_bf16 v[52:55], v[170:173], v[186:189], v[52:55]
	v_mfma_f32_16x16x32_bf16 v[48:51], v[178:181], v[186:189], v[48:51]
	v_mfma_f32_16x16x32_bf16 v[36:39], v[170:173], v[194:197], v[36:39]
	v_mfma_f32_16x16x32_bf16 v[32:35], v[178:181], v[194:197], v[32:35]
	v_mfma_f32_16x16x32_bf16 v[20:23], v[170:173], v[202:205], v[20:23]
	v_mfma_f32_16x16x32_bf16 v[16:19], v[178:181], v[202:205], v[16:19]
	v_mfma_f32_16x16x32_bf16 v[4:7], v[170:173], v[210:213], v[4:7]
	v_mfma_f32_16x16x32_bf16 v[0:3], v[178:181], v[210:213], v[0:3]
	v_mfma_f32_16x16x32_bf16 v[52:55], v[174:177], v[190:193], v[52:55]
	v_mfma_f32_16x16x32_bf16 v[48:51], v[182:185], v[190:193], v[48:51]
	v_mfma_f32_16x16x32_bf16 v[36:39], v[174:177], v[198:201], v[36:39]
	v_mfma_f32_16x16x32_bf16 v[32:35], v[182:185], v[198:201], v[32:35]
	v_mfma_f32_16x16x32_bf16 v[20:23], v[174:177], v[206:209], v[20:23]
	v_mfma_f32_16x16x32_bf16 v[16:19], v[182:185], v[206:209], v[16:19]
	v_mfma_f32_16x16x32_bf16 v[4:7], v[174:177], v[214:217], v[4:7]
	v_mfma_f32_16x16x32_bf16 v[0:3], v[182:185], v[214:217], v[0:3]
	s_setprio 0
	s_barrier
; #define PG8_STAGE(bufoff, gbase, voff) do { _Pragma("unroll") for (int _i = 0; _i < 2; ++_i) \
;         __builtin_amdgcn_global_load_lds((const unsigned*)((const char*)(gbase) + (voff)[_i]), (PG8_LAS unsigned*)(lds + (bufoff) + ldsw + _i * 8192), 16, 0, 0); } while (0)
; #define PG8_LDA(dst, b, h) do { _Pragma("unroll") for (int m = 0; m < 4; ++m) _Pragma("unroll") for (int k = 0; k < 2; ++k) dst[m][k] = *(const PG8_LAS bf16x8*)(lds + PG8_SA(b, h) + aoff + m * 2048 + k * 1024); } while (0)
; #define PG8_LDB(dst, b, h) do { _Pragma("unroll") for (int n = 0; n < 2; ++n) _Pragma("unroll") for (int k = 0; k < 2; ++k) dst[n][k] = *(const PG8_LAS bf16x8*)(lds + PG8_SB(b, h) + boff + n * 2048 + k * 1024); } while (0)
; #define PG8_MMA(ai, bj, At, Bt) do { __builtin_amdgcn_s_setprio(1); _Pragma("unroll") for (int m = 0; m < 4; ++m) _Pragma("unroll") for (int n = 0; n < 2; ++n) _Pragma("unroll") for (int k = 0; k < 2; ++k) \
;         acc[ai][bj][m][n] = __builtin_amdgcn_mfma_f32_16x16x32_bf16(Bt[n][k], At[m][k], acc[ai][bj][m][n], 0, 0, 0); __builtin_amdgcn_s_setprio(0); } while (0)
; #define PG8_WAIT_V(n) asm volatile("s_waitcnt vmcnt(" #n ")" ::: "memory")
; #define PG8_WAIT_L(n) asm volatile("s_waitcnt lgkmcnt(" #n ")" ::: "memory")
; #define PG8_BAR __builtin_amdgcn_s_barrier()
; #define PG8_SCHED __builtin_amdgcn_sched_barrier(0)
; template <class Epi, class Sched, bool ALIGN_EPI = false, bool SP2 = false>
; __device__ __forceinline__ void gemm_phase(PG8_LAS unsigned char* lds, const Gemm g, const Sched& S, const Epi& E) {
;     ...
;             PG8_LDB(B0, 1, 0); PG8_LDB(B1, 1, 1); PG8_SCHED; PG8_LDA(At, 1, 0); PG8_STAGE(PG8_SA(0, 1), a2 + hstep, voffA);
;             PG8_WAIT_V(8); PG8_WAIT_L(0); PG8_BAR; PG8_MMA(0, 0, At, B0); PG8_MMA(0, 1, At, B1); PG8_BAR; PG8_SCHED;
;             PG8_LDA(At, 1, 1); PG8_STAGE(PG8_SB(1, 0), b3, voffB); PG8_STAGE(PG8_SB(1, 1), b3 + hstep, voffB); PG8_STAGE(PG8_SA(1, 0), a3, voffA);
;             PG8_WAIT_V(8); PG8_WAIT_L(0); PG8_BAR; PG8_MMA(1, 0, At, B0); PG8_MMA(1, 1, At, B1); PG8_BAR; PG8_SCHED;
	s_add_i32 s80, 0, 0x18000
	s_add_i32 s81, 0, 0x1c000
	v_add_u32_e32 v166, s80, v151
	v_add_u32_e32 v182, s81, v151
	ds_read_b128 v[146:149], v166
	ds_read_b128 v[158:161], v166 offset:1024
	ds_read_b128 v[162:165], v166 offset:2048
	ds_read_b128 v[166:169], v166 offset:3072
	ds_read_b128 v[170:173], v182
	ds_read_b128 v[174:177], v182 offset:1024
	ds_read_b128 v[178:181], v182 offset:2048
	ds_read_b128 v[182:185], v182 offset:3072
	s_add_u32 s34, s34, s8
	s_addc_u32 s35, s35, s9
	s_mov_b32 m0, s37
	ds_read_b128 v[186:189], v154 offset:32768
	ds_read_b128 v[190:193], v154 offset:33792
	ds_read_b128 v[194:197], v154 offset:34816
	ds_read_b128 v[198:201], v154 offset:35840
	ds_read_b128 v[202:205], v154 offset:36864
	ds_read_b128 v[206:209], v154 offset:37888
	ds_read_b128 v[210:213], v154 offset:38912
	ds_read_b128 v[214:217], v154 offset:39936
	global_load_lds_dwordx4 v128, s[34:35]
	s_mov_b32 m0, s38
	s_nop 0
	global_load_lds_dwordx4 v132, s[34:35]
	s_waitcnt vmcnt(8)
	s_waitcnt lgkmcnt(0)
	s_barrier
	s_setprio 1
	s_waitcnt lgkmcnt(0)
	v_mfma_f32_16x16x32_bf16 v[120:123], v[146:149], v[186:189], v[120:123]
	v_mfma_f32_16x16x32_bf16 v[124:127], v[162:165], v[186:189], v[124:127]
	v_mfma_f32_16x16x32_bf16 v[108:111], v[146:149], v[194:197], v[108:111]
	v_mfma_f32_16x16x32_bf16 v[104:107], v[162:165], v[194:197], v[104:107]
	v_mfma_f32_16x16x32_bf16 v[92:95], v[146:149], v[202:205], v[92:95]
	v_mfma_f32_16x16x32_bf16 v[88:91], v[162:165], v[202:205], v[88:91]
	v_mfma_f32_16x16x32_bf16 v[76:79], v[146:149], v[210:213], v[76:79]
	v_mfma_f32_16x16x32_bf16 v[72:75], v[162:165], v[210:213], v[72:75]
	v_mfma_f32_16x16x32_bf16 v[120:123], v[158:161], v[190:193], v[120:123]
	v_mfma_f32_16x16x32_bf16 v[124:127], v[166:169], v[190:193], v[124:127]
	v_mfma_f32_16x16x32_bf16 v[108:111], v[158:161], v[198:201], v[108:111]
	v_mfma_f32_16x16x32_bf16 v[104:107], v[166:169], v[198:201], v[104:107]
	v_mfma_f32_16x16x32_bf16 v[92:95], v[158:161], v[206:209], v[92:95]
	v_mfma_f32_16x16x32_bf16 v[88:91], v[166:169], v[206:209], v[88:91]
	v_mfma_f32_16x16x32_bf16 v[76:79], v[158:161], v[214:217], v[76:79]
	v_mfma_f32_16x16x32_bf16 v[72:75], v[166:169], v[214:217], v[72:75]
	s_setprio 0
	s_setprio 1
	v_mfma_f32_16x16x32_bf16 v[116:119], v[170:173], v[186:189], v[116:119]
	v_mfma_f32_16x16x32_bf16 v[112:115], v[178:181], v[186:189], v[112:115]
	v_mfma_f32_16x16x32_bf16 v[100:103], v[170:173], v[194:197], v[100:103]
	v_mfma_f32_16x16x32_bf16 v[96:99], v[178:181], v[194:197], v[96:99]
	v_mfma_f32_16x16x32_bf16 v[84:87], v[170:173], v[202:205], v[84:87]
	v_mfma_f32_16x16x32_bf16 v[80:83], v[178:181], v[202:205], v[80:83]
	v_mfma_f32_16x16x32_bf16 v[68:71], v[170:173], v[210:213], v[68:71]
	v_mfma_f32_16x16x32_bf16 v[64:67], v[178:181], v[210:213], v[64:67]
	v_mfma_f32_16x16x32_bf16 v[116:119], v[174:177], v[190:193], v[116:119]
	v_mfma_f32_16x16x32_bf16 v[112:115], v[182:185], v[190:193], v[112:115]
	v_mfma_f32_16x16x32_bf16 v[100:103], v[174:177], v[198:201], v[100:103]
	v_mfma_f32_16x16x32_bf16 v[96:99], v[182:185], v[198:201], v[96:99]
	v_mfma_f32_16x16x32_bf16 v[84:87], v[174:177], v[206:209], v[84:87]
	v_mfma_f32_16x16x32_bf16 v[80:83], v[182:185], v[206:209], v[80:83]
	v_mfma_f32_16x16x32_bf16 v[68:71], v[174:177], v[214:217], v[68:71]
	v_mfma_f32_16x16x32_bf16 v[64:67], v[182:185], v[214:217], v[64:67]
	s_setprio 0
	s_barrier
	s_add_i32 s34, s80, s16
	s_add_i32 m0, s34, 0xffffff80
	ds_read_b128 v[186:189], v154 offset:49152
	ds_read_b128 v[190:193], v154 offset:50176
	ds_read_b128 v[194:197], v154 offset:51200
	ds_read_b128 v[198:201], v154 offset:52224
	ds_read_b128 v[202:205], v154 offset:53248
	ds_read_b128 v[206:209], v154 offset:54272
	ds_read_b128 v[210:213], v154 offset:55296
	ds_read_b128 v[214:217], v154 offset:56320
	global_load_lds_dwordx4 v130, s[98:99] offset:128
	s_add_i32 m0, s34, 0x1f80
	s_add_i32 s34, s81, s16
	global_load_lds_dwordx4 v134, s[98:99] offset:128
	s_add_i32 m0, s34, 0xffffff80
	s_nop 0
	global_load_lds_dwordx4 v130, s[100:101] offset:128
	s_add_i32 m0, s34, 0x1f80
	s_nop 0
	global_load_lds_dwordx4 v134, s[100:101] offset:128
	s_add_i32 m0, s44, 0xffffff80
	s_nop 0
	global_load_lds_dwordx4 v128, s[20:21] offset:128
	s_add_i32 m0, s45, 0xffffff80
	s_nop 0
	global_load_lds_dwordx4 v132, s[20:21] offset:128
	s_waitcnt vmcnt(8)
	s_waitcnt lgkmcnt(0)
	s_barrier
	s_setprio 1
	s_waitcnt lgkmcnt(0)
	v_mfma_f32_16x16x32_bf16 v[60:63], v[146:149], v[186:189], v[60:63]
	v_mfma_f32_16x16x32_bf16 v[56:59], v[162:165], v[186:189], v[56:59]
	v_mfma_f32_16x16x32_bf16 v[44:47], v[146:149], v[194:197], v[44:47]
	v_mfma_f32_16x16x32_bf16 v[40:43], v[162:165], v[194:197], v[40:43]
	v_mfma_f32_16x16x32_bf16 v[28:31], v[146:149], v[202:205], v[28:31]
	v_mfma_f32_16x16x32_bf16 v[24:27], v[162:165], v[202:205], v[24:27]
	v_mfma_f32_16x16x32_bf16 v[12:15], v[146:149], v[210:213], v[12:15]
	v_mfma_f32_16x16x32_bf16 v[8:11], v[162:165], v[210:213], v[8:11]
	v_mfma_f32_16x16x32_bf16 v[60:63], v[158:161], v[190:193], v[60:63]
	v_mfma_f32_16x16x32_bf16 v[56:59], v[166:169], v[190:193], v[56:59]
	v_mfma_f32_16x16x32_bf16 v[44:47], v[158:161], v[198:201], v[44:47]
	v_mfma_f32_16x16x32_bf16 v[40:43], v[166:169], v[198:201], v[40:43]
	v_mfma_f32_16x16x32_bf16 v[28:31], v[158:161], v[206:209], v[28:31]
	v_mfma_f32_16x16x32_bf16 v[24:27], v[166:169], v[206:209], v[24:27]
	v_mfma_f32_16x16x32_bf16 v[12:15], v[158:161], v[214:217], v[12:15]
	v_mfma_f32_16x16x32_bf16 v[8:11], v[166:169], v[214:217], v[8:11]
	s_setprio 0
	s_setprio 1
	v_mfma_f32_16x16x32_bf16 v[52:55], v[170:173], v[186:189], v[52:55]
	v_mfma_f32_16x16x32_bf16 v[48:51], v[178:181], v[186:189], v[48:51]
	v_mfma_f32_16x16x32_bf16 v[36:39], v[170:173], v[194:197], v[36:39]
	v_mfma_f32_16x16x32_bf16 v[32:35], v[178:181], v[194:197], v[32:35]
	v_mfma_f32_16x16x32_bf16 v[20:23], v[170:173], v[202:205], v[20:23]
	v_mfma_f32_16x16x32_bf16 v[16:19], v[178:181], v[202:205], v[16:19]
	v_mfma_f32_16x16x32_bf16 v[4:7], v[170:173], v[210:213], v[4:7]
	v_mfma_f32_16x16x32_bf16 v[0:3], v[178:181], v[210:213], v[0:3]
	v_mfma_f32_16x16x32_bf16 v[52:55], v[174:177], v[190:193], v[52:55]
	v_mfma_f32_16x16x32_bf16 v[48:51], v[182:185], v[190:193], v[48:51]
	v_mfma_f32_16x16x32_bf16 v[36:39], v[174:177], v[198:201], v[36:39]
	v_mfma_f32_16x16x32_bf16 v[32:35], v[182:185], v[198:201], v[32:35]
	v_mfma_f32_16x16x32_bf16 v[20:23], v[174:177], v[206:209], v[20:23]
	v_mfma_f32_16x16x32_bf16 v[16:19], v[182:185], v[206:209], v[16:19]
	v_mfma_f32_16x16x32_bf16 v[4:7], v[174:177], v[214:217], v[4:7]
	v_mfma_f32_16x16x32_bf16 v[0:3], v[182:185], v[214:217], v[0:3]
	s_setprio 0
	s_barrier
	s_add_u32 s30, s30, 0x100
	s_addc_u32 s31, s31, 0
	s_add_u32 s77, s77, 0x100
	s_addc_u32 s78, s78, 0
	s_cmp_ge_i32 s79, s40
	s_mov_b32 s34, s79
	s_cbranch_scc0 .LBB0_2165

; #define PG8_STAGE(bufoff, gbase, voff) do { _Pragma("unroll") for (int _i = 0; _i < 2; ++_i) \
;         __builtin_amdgcn_global_load_lds((const unsigned*)((const char*)(gbase) + (voff)[_i]), (PG8_LAS unsigned*)(lds + (bufoff) + ldsw + _i * 8192), 16, 0, 0); } while (0)
; #define PG8_LDA(dst, b, h) do { _Pragma("unroll") for (int m = 0; m < 4; ++m) _Pragma("unroll") for (int k = 0; k < 2; ++k) dst[m][k] = *(const PG8_LAS bf16x8*)(lds + PG8_SA(b, h) + aoff + m * 2048 + k * 1024); } while (0)
; #define PG8_LDB(dst, b, h) do { _Pragma("unroll") for (int n = 0; n < 2; ++n) _Pragma("unroll") for (int k = 0; k < 2; ++k) dst[n][k] = *(const PG8_LAS bf16x8*)(lds + PG8_SB(b, h) + boff + n * 2048 + k * 1024); } while (0)
; #define PG8_MMA(ai, bj, At, Bt) do { __builtin_amdgcn_s_setprio(1); _Pragma("unroll") for (int m = 0; m < 4; ++m) _Pragma("unroll") for (int n = 0; n < 2; ++n) _Pragma("unroll") for (int k = 0; k < 2; ++k) \
;         acc[ai][bj][m][n] = __builtin_amdgcn_mfma_f32_16x16x32_bf16(Bt[n][k], At[m][k], acc[ai][bj][m][n], 0, 0, 0); __builtin_amdgcn_s_setprio(0); } while (0)
; #define PG8_WAIT_V(n) asm volatile("s_waitcnt vmcnt(" #n ")" ::: "memory")
; #define PG8_WAIT_L(n) asm volatile("s_waitcnt lgkmcnt(" #n ")" ::: "memory")
; template <class Epi, class Sched, bool ALIGN_EPI = false, bool SP2 = false>
; __device__ __forceinline__ void gemm_phase(PG8_LAS unsigned char* lds, const Gemm g, const Sched& S, const Epi& E) {
;     ...
;             const bool last = (t == nt - 2);
;             const char* a1 = cA + (size_t)(t + 1) * kstep;
;             const char* a2 = last ? nA : cA + (size_t)(t + 2) * kstep; const char* b2 = last ? nB : cB + (size_t)(t + 2) * kstep;
;             const char* a3 = a2 + kstep; const char* b3 = b2 + kstep;
;             if (last && has_next) S.a_ready(nxt);
;             if constexpr (SP2) {
;             PG8_LDB(B0, 0, 0); PG8_LDB(B1, 0, 1); PG8_SCHED; PG8_LDA(At, 0, 0); PG8_STAGE(PG8_SA(1, 1), a1 + hstep, voffA);
;             PG8_WAIT_V(8); PG8_WAIT_L(0); PG8_BAR; PG8_MMA(0, 0, At, B0); PG8_MMA(0, 1, At, B1); PG8_BAR; PG8_SCHED;
;             PG8_LDA(At, 0, 1); PG8_STAGE(PG8_SB(0, 0), b2, voffB); PG8_STAGE(PG8_SB(0, 1), b2 + hstep, voffB); PG8_STAGE(PG8_SA(0, 0), a2, voffA);
;             PG8_WAIT_V(8); PG8_WAIT_L(0); PG8_BAR; PG8_MMA(1, 0, At, B0); PG8_MMA(1, 1, At, B1); PG8_BAR; PG8_SCHED;
.LBB0_2384:
	s_andn2_b64 vcc, exec, s[24:25]
	s_waitcnt vmcnt(0)
	s_waitcnt lgkmcnt(0)
	s_cbranch_vccnz .LBB0_2387
	s_add_u32 s30, s30, 0x80
	s_addc_u32 s31, s31, 0
	s_add_u32 s61, s34, 0x100
	s_addc_u32 s62, s35, 0
	s_mov_b32 s34, 0
	ds_read_b128 v[144:147], v151
	ds_read_b128 v[156:159], v151 offset:1024
	ds_read_b128 v[160:163], v151 offset:2048
	ds_read_b128 v[164:167], v151 offset:3072
	ds_read_b128 v[168:171], v152
	ds_read_b128 v[172:175], v152 offset:1024
	ds_read_b128 v[176:179], v152 offset:2048
	ds_read_b128 v[180:183], v152 offset:3072
	s_add_i32 s63, s34, 2
	s_add_u32 s64, s30, 0x80
	s_addc_u32 s35, s31, 0
	s_cmp_eq_u32 s41, s34
	s_cselect_b32 s34, s0, s64
	s_cselect_b32 s35, s1, s35
	s_cselect_b32 s65, s29, s62
	s_cselect_b32 s64, s28, s61
	s_add_i32 m0, s17, 0xc000
	ds_read_b128 v[184:187], v153
	ds_read_b128 v[188:191], v153 offset:1024
	ds_read_b128 v[192:195], v153 offset:2048
	ds_read_b128 v[196:199], v153 offset:3072
	ds_read_b128 v[200:203], v153 offset:4096
	ds_read_b128 v[204:207], v153 offset:5120
	ds_read_b128 v[208:211], v153 offset:6144
	ds_read_b128 v[212:215], v153 offset:7168
	global_load_lds_dwordx4 v136, s[30:31]
	s_add_i32 m0, s17, 0xe000
	s_nop 0
	global_load_lds_dwordx4 v138, s[30:31]
	s_waitcnt vmcnt(8)
	s_waitcnt lgkmcnt(0)
	s_barrier
	s_setprio 1
	s_waitcnt lgkmcnt(0)
	v_mfma_f32_16x16x32_bf16 v[124:127], v[144:147], v[184:187], 0
	v_mfma_f32_16x16x32_bf16 v[120:123], v[160:163], v[184:187], 0
	v_mfma_f32_16x16x32_bf16 v[108:111], v[144:147], v[192:195], 0
	v_mfma_f32_16x16x32_bf16 v[104:107], v[160:163], v[192:195], 0
	v_mfma_f32_16x16x32_bf16 v[92:95], v[144:147], v[200:203], 0
	v_mfma_f32_16x16x32_bf16 v[88:91], v[160:163], v[200:203], 0
	v_mfma_f32_16x16x32_bf16 v[76:79], v[144:147], v[208:211], 0
	v_mfma_f32_16x16x32_bf16 v[72:75], v[160:163], v[208:211], 0
	v_mfma_f32_16x16x32_bf16 v[124:127], v[156:159], v[188:191], v[124:127]
	v_mfma_f32_16x16x32_bf16 v[120:123], v[164:167], v[188:191], v[120:123]
	v_mfma_f32_16x16x32_bf16 v[108:111], v[156:159], v[196:199], v[108:111]
	v_mfma_f32_16x16x32_bf16 v[104:107], v[164:167], v[196:199], v[104:107]
	v_mfma_f32_16x16x32_bf16 v[92:95], v[156:159], v[204:207], v[92:95]
	v_mfma_f32_16x16x32_bf16 v[88:91], v[164:167], v[204:207], v[88:91]
	v_mfma_f32_16x16x32_bf16 v[76:79], v[156:159], v[212:215], v[76:79]
	v_mfma_f32_16x16x32_bf16 v[72:75], v[164:167], v[212:215], v[72:75]
	s_setprio 0
	s_setprio 1
	v_mfma_f32_16x16x32_bf16 v[116:119], v[168:171], v[184:187], 0
	v_mfma_f32_16x16x32_bf16 v[112:115], v[176:179], v[184:187], 0
	v_mfma_f32_16x16x32_bf16 v[100:103], v[168:171], v[192:195], 0
	v_mfma_f32_16x16x32_bf16 v[96:99], v[176:179], v[192:195], 0
	v_mfma_f32_16x16x32_bf16 v[84:87], v[168:171], v[200:203], 0
	v_mfma_f32_16x16x32_bf16 v[80:83], v[176:179], v[200:203], 0
	v_mfma_f32_16x16x32_bf16 v[68:71], v[168:171], v[208:211], 0
	v_mfma_f32_16x16x32_bf16 v[64:67], v[176:179], v[208:211], 0
	v_mfma_f32_16x16x32_bf16 v[116:119], v[172:175], v[188:191], v[116:119]
	v_mfma_f32_16x16x32_bf16 v[112:115], v[180:183], v[188:191], v[112:115]
	v_mfma_f32_16x16x32_bf16 v[100:103], v[172:175], v[196:199], v[100:103]
	v_mfma_f32_16x16x32_bf16 v[96:99], v[180:183], v[196:199], v[96:99]
	v_mfma_f32_16x16x32_bf16 v[84:87], v[172:175], v[204:207], v[84:87]
	v_mfma_f32_16x16x32_bf16 v[80:83], v[180:183], v[204:207], v[80:83]
	v_mfma_f32_16x16x32_bf16 v[68:71], v[172:175], v[212:215], v[68:71]
	v_mfma_f32_16x16x32_bf16 v[64:67], v[180:183], v[212:215], v[64:67]
	s_setprio 0
	s_barrier
	s_add_i32 s66, s51, s16
	s_mov_b64 s[98:99], s[64:65]
	s_mov_b32 m0, s66
	ds_read_b128 v[184:187], v153 offset:16384
	ds_read_b128 v[188:191], v153 offset:17408
	ds_read_b128 v[192:195], v153 offset:18432
	ds_read_b128 v[196:199], v153 offset:19456
	ds_read_b128 v[200:203], v153 offset:20480
	ds_read_b128 v[204:207], v153 offset:21504
	ds_read_b128 v[208:211], v153 offset:22528
	ds_read_b128 v[212:215], v153 offset:23552
	global_load_lds_dwordx4 v130, s[64:65]
	s_add_i32 m0, s66, 0x2000
	s_add_u32 s64, s64, s6
	s_addc_u32 s65, s65, s7
	s_add_i32 s66, s56, s16
	global_load_lds_dwordx4 v134, s[98:99]
	s_mov_b64 s[100:101], s[64:65]
	s_mov_b32 m0, s66
	s_nop 0
	global_load_lds_dwordx4 v130, s[64:65]
	s_add_i32 m0, s66, 0x2000
	s_mov_b64 s[22:23], s[34:35]
	global_load_lds_dwordx4 v134, s[64:65]
	s_mov_b32 m0, s17
	s_nop 0
	global_load_lds_dwordx4 v128, s[34:35]
	s_mov_b32 m0, s19
	s_nop 0
	global_load_lds_dwordx4 v132, s[34:35]
	s_waitcnt vmcnt(8)
	s_waitcnt lgkmcnt(0)
	s_barrier
	s_setprio 1
	s_waitcnt lgkmcnt(0)
	v_mfma_f32_16x16x32_bf16 v[60:63], v[144:147], v[184:187], 0
	v_mfma_f32_16x16x32_bf16 v[56:59], v[160:163], v[184:187], 0
	v_mfma_f32_16x16x32_bf16 v[44:47], v[144:147], v[192:195], 0
	v_mfma_f32_16x16x32_bf16 v[40:43], v[160:163], v[192:195], 0
	v_mfma_f32_16x16x32_bf16 v[28:31], v[144:147], v[200:203], 0
	v_mfma_f32_16x16x32_bf16 v[24:27], v[160:163], v[200:203], 0
	v_mfma_f32_16x16x32_bf16 v[12:15], v[144:147], v[208:211], 0
	v_mfma_f32_16x16x32_bf16 v[8:11], v[160:163], v[208:211], 0
	v_mfma_f32_16x16x32_bf16 v[60:63], v[156:159], v[188:191], v[60:63]
	v_mfma_f32_16x16x32_bf16 v[56:59], v[164:167], v[188:191], v[56:59]
	v_mfma_f32_16x16x32_bf16 v[44:47], v[156:159], v[196:199], v[44:47]
	v_mfma_f32_16x16x32_bf16 v[40:43], v[164:167], v[196:199], v[40:43]
	v_mfma_f32_16x16x32_bf16 v[28:31], v[156:159], v[204:207], v[28:31]
	v_mfma_f32_16x16x32_bf16 v[24:27], v[164:167], v[204:207], v[24:27]
	v_mfma_f32_16x16x32_bf16 v[12:15], v[156:159], v[212:215], v[12:15]
	v_mfma_f32_16x16x32_bf16 v[8:11], v[164:167], v[212:215], v[8:11]
	s_setprio 0
	s_setprio 1
	v_mfma_f32_16x16x32_bf16 v[52:55], v[168:171], v[184:187], 0
	v_mfma_f32_16x16x32_bf16 v[48:51], v[176:179], v[184:187], 0
	v_mfma_f32_16x16x32_bf16 v[36:39], v[168:171], v[192:195], 0
	v_mfma_f32_16x16x32_bf16 v[32:35], v[176:179], v[192:195], 0
	v_mfma_f32_16x16x32_bf16 v[20:23], v[168:171], v[200:203], 0
	v_mfma_f32_16x16x32_bf16 v[16:19], v[176:179], v[200:203], 0
	v_mfma_f32_16x16x32_bf16 v[4:7], v[168:171], v[208:211], 0
	v_mfma_f32_16x16x32_bf16 v[0:3], v[176:179], v[208:211], 0
	v_mfma_f32_16x16x32_bf16 v[52:55], v[172:175], v[188:191], v[52:55]
	v_mfma_f32_16x16x32_bf16 v[48:51], v[180:183], v[188:191], v[48:51]
	v_mfma_f32_16x16x32_bf16 v[36:39], v[172:175], v[196:199], v[36:39]
	v_mfma_f32_16x16x32_bf16 v[32:35], v[180:183], v[196:199], v[32:35]
	v_mfma_f32_16x16x32_bf16 v[20:23], v[172:175], v[204:207], v[20:23]
	v_mfma_f32_16x16x32_bf16 v[16:19], v[180:183], v[204:207], v[16:19]
	v_mfma_f32_16x16x32_bf16 v[4:7], v[172:175], v[212:215], v[4:7]
	v_mfma_f32_16x16x32_bf16 v[0:3], v[180:183], v[212:215], v[0:3]
	s_setprio 0
	s_barrier
; #define PG8_STAGE(bufoff, gbase, voff) do { _Pragma("unroll") for (int _i = 0; _i < 2; ++_i) \
;         __builtin_amdgcn_global_load_lds((const unsigned*)((const char*)(gbase) + (voff)[_i]), (PG8_LAS unsigned*)(lds + (bufoff) + ldsw + _i * 8192), 16, 0, 0); } while (0)
; #define PG8_LDA(dst, b, h) do { _Pragma("unroll") for (int m = 0; m < 4; ++m) _Pragma("unroll") for (int k = 0; k < 2; ++k) dst[m][k] = *(const PG8_LAS bf16x8*)(lds + PG8_SA(b, h) + aoff + m * 2048 + k * 1024); } while (0)
; #define PG8_LDB(dst, b, h) do { _Pragma("unroll") for (int n = 0; n < 2; ++n) _Pragma("unroll") for (int k = 0; k < 2; ++k) dst[n][k] = *(const PG8_LAS bf16x8*)(lds + PG8_SB(b, h) + boff + n * 2048 + k * 1024); } while (0)
; #define PG8_MMA(ai, bj, At, Bt) do { __builtin_amdgcn_s_setprio(1); _Pragma("unroll") for (int m = 0; m < 4; ++m) _Pragma("unroll") for (int n = 0; n < 2; ++n) _Pragma("unroll") for (int k = 0; k < 2; ++k) \
;         acc[ai][bj][m][n] = __builtin_amdgcn_mfma_f32_16x16x32_bf16(Bt[n][k], At[m][k], acc[ai][bj][m][n], 0, 0, 0); __builtin_amdgcn_s_setprio(0); } while (0)
; #define PG8_WAIT_V(n) asm volatile("s_waitcnt vmcnt(" #n ")" ::: "memory")
; #define PG8_WAIT_L(n) asm volatile("s_waitcnt lgkmcnt(" #n ")" ::: "memory")
; #define PG8_BAR __builtin_amdgcn_s_barrier()
; #define PG8_SCHED __builtin_amdgcn_sched_barrier(0)
; template <class Epi, class Sched, bool ALIGN_EPI = false, bool SP2 = false>
; __device__ __forceinline__ void gemm_phase(PG8_LAS unsigned char* lds, const Gemm g, const Sched& S, const Epi& E) {
;     ...
;             PG8_LDB(B0, 1, 0); PG8_LDB(B1, 1, 1); PG8_SCHED; PG8_LDA(At, 1, 0); PG8_STAGE(PG8_SA(0, 1), a2 + hstep, voffA);
;             PG8_WAIT_V(8); PG8_WAIT_L(0); PG8_BAR; PG8_MMA(0, 0, At, B0); PG8_MMA(0, 1, At, B1); PG8_BAR; PG8_SCHED;
;             PG8_LDA(At, 1, 1); PG8_STAGE(PG8_SB(1, 0), b3, voffB); PG8_STAGE(PG8_SB(1, 1), b3 + hstep, voffB); PG8_STAGE(PG8_SA(1, 0), a3, voffA);
;             PG8_WAIT_V(8); PG8_WAIT_L(0); PG8_BAR; PG8_MMA(1, 0, At, B0); PG8_MMA(1, 1, At, B1); PG8_BAR; PG8_SCHED;
	s_add_i32 s64, 0, 0x18000
	v_add_u32_e32 v155, s64, v149
	s_add_i32 s65, 0, 0x1c000
	ds_read_b128 v[144:147], v155
	ds_read_b128 v[156:159], v155 offset:1024
	ds_read_b128 v[160:163], v155 offset:2048
	ds_read_b128 v[164:167], v155 offset:3072
	v_add_u32_e32 v155, s65, v149
	ds_read_b128 v[168:171], v155
	ds_read_b128 v[172:175], v155 offset:1024
	ds_read_b128 v[176:179], v155 offset:2048
	ds_read_b128 v[180:183], v155 offset:3072
	s_add_u32 s34, s34, s6
	s_addc_u32 s35, s35, s7
	s_mov_b32 m0, s33
	ds_read_b128 v[184:187], v153 offset:32768
	ds_read_b128 v[188:191], v153 offset:33792
	ds_read_b128 v[192:195], v153 offset:34816
	ds_read_b128 v[196:199], v153 offset:35840
	ds_read_b128 v[200:203], v153 offset:36864
	ds_read_b128 v[204:207], v153 offset:37888
	ds_read_b128 v[208:211], v153 offset:38912
	ds_read_b128 v[212:215], v153 offset:39936
	global_load_lds_dwordx4 v128, s[34:35]
	s_mov_b32 m0, s36
	s_nop 0
	global_load_lds_dwordx4 v132, s[34:35]
	s_waitcnt vmcnt(8)
	s_waitcnt lgkmcnt(0)
	s_barrier
	s_setprio 1
	s_waitcnt lgkmcnt(0)
	v_mfma_f32_16x16x32_bf16 v[124:127], v[144:147], v[184:187], v[124:127]
	v_mfma_f32_16x16x32_bf16 v[120:123], v[160:163], v[184:187], v[120:123]
	v_mfma_f32_16x16x32_bf16 v[108:111], v[144:147], v[192:195], v[108:111]
	v_mfma_f32_16x16x32_bf16 v[104:107], v[160:163], v[192:195], v[104:107]
	v_mfma_f32_16x16x32_bf16 v[92:95], v[144:147], v[200:203], v[92:95]
	v_mfma_f32_16x16x32_bf16 v[88:91], v[160:163], v[200:203], v[88:91]
	v_mfma_f32_16x16x32_bf16 v[76:79], v[144:147], v[208:211], v[76:79]
	v_mfma_f32_16x16x32_bf16 v[72:75], v[160:163], v[208:211], v[72:75]
	v_mfma_f32_16x16x32_bf16 v[124:127], v[156:159], v[188:191], v[124:127]
	v_mfma_f32_16x16x32_bf16 v[120:123], v[164:167], v[188:191], v[120:123]
	v_mfma_f32_16x16x32_bf16 v[108:111], v[156:159], v[196:199], v[108:111]
	v_mfma_f32_16x16x32_bf16 v[104:107], v[164:167], v[196:199], v[104:107]
	v_mfma_f32_16x16x32_bf16 v[92:95], v[156:159], v[204:207], v[92:95]
	v_mfma_f32_16x16x32_bf16 v[88:91], v[164:167], v[204:207], v[88:91]
	v_mfma_f32_16x16x32_bf16 v[76:79], v[156:159], v[212:215], v[76:79]
	v_mfma_f32_16x16x32_bf16 v[72:75], v[164:167], v[212:215], v[72:75]
	s_setprio 0
	s_setprio 1
	v_mfma_f32_16x16x32_bf16 v[116:119], v[168:171], v[184:187], v[116:119]
	v_mfma_f32_16x16x32_bf16 v[112:115], v[176:179], v[184:187], v[112:115]
	v_mfma_f32_16x16x32_bf16 v[100:103], v[168:171], v[192:195], v[100:103]
	v_mfma_f32_16x16x32_bf16 v[96:99], v[176:179], v[192:195], v[96:99]
	v_mfma_f32_16x16x32_bf16 v[84:87], v[168:171], v[200:203], v[84:87]
	v_mfma_f32_16x16x32_bf16 v[80:83], v[176:179], v[200:203], v[80:83]
	v_mfma_f32_16x16x32_bf16 v[68:71], v[168:171], v[208:211], v[68:71]
	v_mfma_f32_16x16x32_bf16 v[64:67], v[176:179], v[208:211], v[64:67]
	v_mfma_f32_16x16x32_bf16 v[116:119], v[172:175], v[188:191], v[116:119]
	v_mfma_f32_16x16x32_bf16 v[112:115], v[180:183], v[188:191], v[112:115]
	v_mfma_f32_16x16x32_bf16 v[100:103], v[172:175], v[196:199], v[100:103]
	v_mfma_f32_16x16x32_bf16 v[96:99], v[180:183], v[196:199], v[96:99]
	v_mfma_f32_16x16x32_bf16 v[84:87], v[172:175], v[204:207], v[84:87]
	v_mfma_f32_16x16x32_bf16 v[80:83], v[180:183], v[204:207], v[80:83]
	v_mfma_f32_16x16x32_bf16 v[68:71], v[172:175], v[212:215], v[68:71]
	v_mfma_f32_16x16x32_bf16 v[64:67], v[180:183], v[212:215], v[64:67]
	s_setprio 0
	s_barrier
	s_add_i32 s34, s64, s16
	s_add_i32 m0, s34, 0xffffff80
	ds_read_b128 v[184:187], v153 offset:49152
	ds_read_b128 v[188:191], v153 offset:50176
	ds_read_b128 v[192:195], v153 offset:51200
	ds_read_b128 v[196:199], v153 offset:52224
	ds_read_b128 v[200:203], v153 offset:53248
	ds_read_b128 v[204:207], v153 offset:54272
	ds_read_b128 v[208:211], v153 offset:55296
	ds_read_b128 v[212:215], v153 offset:56320
	global_load_lds_dwordx4 v130, s[98:99] offset:128
	s_add_i32 m0, s34, 0x1f80
	s_add_i32 s34, s65, s16
	global_load_lds_dwordx4 v134, s[98:99] offset:128
	s_add_i32 m0, s34, 0xffffff80
	s_nop 0
	global_load_lds_dwordx4 v130, s[100:101] offset:128
	s_add_i32 m0, s34, 0x1f80
	s_nop 0
	global_load_lds_dwordx4 v134, s[100:101] offset:128
	s_add_i32 m0, s37, 0xffffff80
	s_nop 0
	global_load_lds_dwordx4 v128, s[22:23] offset:128
	s_add_i32 m0, s38, 0xffffff80
	s_nop 0
	global_load_lds_dwordx4 v132, s[22:23] offset:128
	s_waitcnt vmcnt(8)
	s_waitcnt lgkmcnt(0)
	s_barrier
	s_setprio 1
	s_waitcnt lgkmcnt(0)
	v_mfma_f32_16x16x32_bf16 v[60:63], v[144:147], v[184:187], v[60:63]
	v_mfma_f32_16x16x32_bf16 v[56:59], v[160:163], v[184:187], v[56:59]
	v_mfma_f32_16x16x32_bf16 v[44:47], v[144:147], v[192:195], v[44:47]
	v_mfma_f32_16x16x32_bf16 v[40:43], v[160:163], v[192:195], v[40:43]
	v_mfma_f32_16x16x32_bf16 v[28:31], v[144:147], v[200:203], v[28:31]
	v_mfma_f32_16x16x32_bf16 v[24:27], v[160:163], v[200:203], v[24:27]
	v_mfma_f32_16x16x32_bf16 v[12:15], v[144:147], v[208:211], v[12:15]
	v_mfma_f32_16x16x32_bf16 v[8:11], v[160:163], v[208:211], v[8:11]
	v_mfma_f32_16x16x32_bf16 v[60:63], v[156:159], v[188:191], v[60:63]
	v_mfma_f32_16x16x32_bf16 v[56:59], v[164:167], v[188:191], v[56:59]
	v_mfma_f32_16x16x32_bf16 v[44:47], v[156:159], v[196:199], v[44:47]
	v_mfma_f32_16x16x32_bf16 v[40:43], v[164:167], v[196:199], v[40:43]
	v_mfma_f32_16x16x32_bf16 v[28:31], v[156:159], v[204:207], v[28:31]
	v_mfma_f32_16x16x32_bf16 v[24:27], v[164:167], v[204:207], v[24:27]
	v_mfma_f32_16x16x32_bf16 v[12:15], v[156:159], v[212:215], v[12:15]
	v_mfma_f32_16x16x32_bf16 v[8:11], v[164:167], v[212:215], v[8:11]
	s_setprio 0
	s_setprio 1
	v_mfma_f32_16x16x32_bf16 v[52:55], v[168:171], v[184:187], v[52:55]
	v_mfma_f32_16x16x32_bf16 v[48:51], v[176:179], v[184:187], v[48:51]
	v_mfma_f32_16x16x32_bf16 v[36:39], v[168:171], v[192:195], v[36:39]
	v_mfma_f32_16x16x32_bf16 v[32:35], v[176:179], v[192:195], v[32:35]
	v_mfma_f32_16x16x32_bf16 v[20:23], v[168:171], v[200:203], v[20:23]
	v_mfma_f32_16x16x32_bf16 v[16:19], v[176:179], v[200:203], v[16:19]
	v_mfma_f32_16x16x32_bf16 v[4:7], v[168:171], v[208:211], v[4:7]
	v_mfma_f32_16x16x32_bf16 v[0:3], v[176:179], v[208:211], v[0:3]
	v_mfma_f32_16x16x32_bf16 v[52:55], v[172:175], v[188:191], v[52:55]
	v_mfma_f32_16x16x32_bf16 v[48:51], v[180:183], v[188:191], v[48:51]
	v_mfma_f32_16x16x32_bf16 v[36:39], v[172:175], v[196:199], v[36:39]
	v_mfma_f32_16x16x32_bf16 v[32:35], v[180:183], v[196:199], v[32:35]
	v_mfma_f32_16x16x32_bf16 v[20:23], v[172:175], v[204:207], v[20:23]
	v_mfma_f32_16x16x32_bf16 v[16:19], v[180:183], v[204:207], v[16:19]
	v_mfma_f32_16x16x32_bf16 v[4:7], v[172:175], v[212:215], v[4:7]
	v_mfma_f32_16x16x32_bf16 v[0:3], v[180:183], v[212:215], v[0:3]
	s_setprio 0
	s_barrier
	s_add_u32 s30, s30, 0x100
	s_addc_u32 s31, s31, 0
	s_add_u32 s61, s61, 0x100
	s_addc_u32 s62, s62, 0
	s_cmp_ge_i32 s63, s40
	s_mov_b32 s34, s63
	s_cbranch_scc0 .LBB0_2386
	s_branch .Lpeel_x11
; #define PG8_STAGE(bufoff, gbase, voff) do { _Pragma("unroll") for (int _i = 0; _i < 2; ++_i) \
;         __builtin_amdgcn_global_load_lds((const unsigned*)((const char*)(gbase) + (voff)[_i]), (PG8_LAS unsigned*)(lds + (bufoff) + ldsw + _i * 8192), 16, 0, 0); } while (0)
; #define PG8_LDA(dst, b, h) do { _Pragma("unroll") for (int m = 0; m < 4; ++m) _Pragma("unroll") for (int k = 0; k < 2; ++k) dst[m][k] = *(const PG8_LAS bf16x8*)(lds + PG8_SA(b, h) + aoff + m * 2048 + k * 1024); } while (0)
; #define PG8_LDB(dst, b, h) do { _Pragma("unroll") for (int n = 0; n < 2; ++n) _Pragma("unroll") for (int k = 0; k < 2; ++k) dst[n][k] = *(const PG8_LAS bf16x8*)(lds + PG8_SB(b, h) + boff + n * 2048 + k * 1024); } while (0)
; #define PG8_MMA(ai, bj, At, Bt) do { __builtin_amdgcn_s_setprio(1); _Pragma("unroll") for (int m = 0; m < 4; ++m) _Pragma("unroll") for (int n = 0; n < 2; ++n) _Pragma("unroll") for (int k = 0; k < 2; ++k) \
;         acc[ai][bj][m][n] = __builtin_amdgcn_mfma_f32_16x16x32_bf16(Bt[n][k], At[m][k], acc[ai][bj][m][n], 0, 0, 0); __builtin_amdgcn_s_setprio(0); } while (0)
; #define PG8_WAIT_V(n) asm volatile("s_waitcnt vmcnt(" #n ")" ::: "memory")
; #define PG8_WAIT_L(n) asm volatile("s_waitcnt lgkmcnt(" #n ")" ::: "memory")
; template <class Epi, class Sched, bool ALIGN_EPI = false, bool SP2 = false>
; __device__ __forceinline__ void gemm_phase(PG8_LAS unsigned char* lds, const Gemm g, const Sched& S, const Epi& E) {
;     ...
;             const bool last = (t == nt - 2);
;             const char* a1 = cA + (size_t)(t + 1) * kstep;
;             const char* a2 = last ? nA : cA + (size_t)(t + 2) * kstep; const char* b2 = last ? nB : cB + (size_t)(t + 2) * kstep;
;             const char* a3 = a2 + kstep; const char* b3 = b2 + kstep;
;             if (last && has_next) S.a_ready(nxt);
;             if constexpr (SP2) {
;             PG8_LDB(B0, 0, 0); PG8_LDB(B1, 0, 1); PG8_SCHED; PG8_LDA(At, 0, 0); PG8_STAGE(PG8_SA(1, 1), a1 + hstep, voffA);
;             PG8_WAIT_V(8); PG8_WAIT_L(0); PG8_BAR; PG8_MMA(0, 0, At, B0); PG8_MMA(0, 1, At, B1); PG8_BAR; PG8_SCHED;
;             PG8_LDA(At, 0, 1); PG8_STAGE(PG8_SB(0, 0), b2, voffB); PG8_STAGE(PG8_SB(0, 1), b2 + hstep, voffB); PG8_STAGE(PG8_SA(0, 0), a2, voffA);
;             PG8_WAIT_V(8); PG8_WAIT_L(0); PG8_BAR; PG8_MMA(1, 0, At, B0); PG8_MMA(1, 1, At, B1); PG8_BAR; PG8_SCHED;
.LBB0_2386:
	ds_read_b128 v[144:147], v151
	ds_read_b128 v[156:159], v151 offset:1024
	ds_read_b128 v[160:163], v151 offset:2048
	ds_read_b128 v[164:167], v151 offset:3072
	ds_read_b128 v[168:171], v152
	ds_read_b128 v[172:175], v152 offset:1024
	ds_read_b128 v[176:179], v152 offset:2048
	ds_read_b128 v[180:183], v152 offset:3072
	s_add_i32 s63, s34, 2
	s_add_u32 s64, s30, 0x80
	s_addc_u32 s35, s31, 0
	s_cmp_eq_u32 s41, s34
	s_cselect_b32 s34, s0, s64
	s_cselect_b32 s35, s1, s35
	s_cselect_b32 s65, s29, s62
	s_cselect_b32 s64, s28, s61
	s_add_i32 m0, s17, 0xc000
	ds_read_b128 v[184:187], v153
	ds_read_b128 v[188:191], v153 offset:1024
	ds_read_b128 v[192:195], v153 offset:2048
	ds_read_b128 v[196:199], v153 offset:3072
	ds_read_b128 v[200:203], v153 offset:4096
	ds_read_b128 v[204:207], v153 offset:5120
	ds_read_b128 v[208:211], v153 offset:6144
	ds_read_b128 v[212:215], v153 offset:7168
	global_load_lds_dwordx4 v136, s[30:31]
	s_add_i32 m0, s17, 0xe000
	s_nop 0
	global_load_lds_dwordx4 v138, s[30:31]
	s_waitcnt vmcnt(8)
	s_waitcnt lgkmcnt(0)
	s_barrier
	s_setprio 1
	s_waitcnt lgkmcnt(0)
	v_mfma_f32_16x16x32_bf16 v[124:127], v[144:147], v[184:187], v[124:127]
	v_mfma_f32_16x16x32_bf16 v[120:123], v[160:163], v[184:187], v[120:123]
	v_mfma_f32_16x16x32_bf16 v[108:111], v[144:147], v[192:195], v[108:111]
	v_mfma_f32_16x16x32_bf16 v[104:107], v[160:163], v[192:195], v[104:107]
	v_mfma_f32_16x16x32_bf16 v[92:95], v[144:147], v[200:203], v[92:95]
	v_mfma_f32_16x16x32_bf16 v[88:91], v[160:163], v[200:203], v[88:91]
	v_mfma_f32_16x16x32_bf16 v[76:79], v[144:147], v[208:211], v[76:79]
	v_mfma_f32_16x16x32_bf16 v[72:75], v[160:163], v[208:211], v[72:75]
	v_mfma_f32_16x16x32_bf16 v[124:127], v[156:159], v[188:191], v[124:127]
	v_mfma_f32_16x16x32_bf16 v[120:123], v[164:167], v[188:191], v[120:123]
	v_mfma_f32_16x16x32_bf16 v[108:111], v[156:159], v[196:199], v[108:111]
	v_mfma_f32_16x16x32_bf16 v[104:107], v[164:167], v[196:199], v[104:107]
	v_mfma_f32_16x16x32_bf16 v[92:95], v[156:159], v[204:207], v[92:95]
	v_mfma_f32_16x16x32_bf16 v[88:91], v[164:167], v[204:207], v[88:91]
	v_mfma_f32_16x16x32_bf16 v[76:79], v[156:159], v[212:215], v[76:79]
	v_mfma_f32_16x16x32_bf16 v[72:75], v[164:167], v[212:215], v[72:75]
	s_setprio 0
	s_setprio 1
	v_mfma_f32_16x16x32_bf16 v[116:119], v[168:171], v[184:187], v[116:119]
	v_mfma_f32_16x16x32_bf16 v[112:115], v[176:179], v[184:187], v[112:115]
	v_mfma_f32_16x16x32_bf16 v[100:103], v[168:171], v[192:195], v[100:103]
	v_mfma_f32_16x16x32_bf16 v[96:99], v[176:179], v[192:195], v[96:99]
	v_mfma_f32_16x16x32_bf16 v[84:87], v[168:171], v[200:203], v[84:87]
	v_mfma_f32_16x16x32_bf16 v[80:83], v[176:179], v[200:203], v[80:83]
	v_mfma_f32_16x16x32_bf16 v[68:71], v[168:171], v[208:211], v[68:71]
	v_mfma_f32_16x16x32_bf16 v[64:67], v[176:179], v[208:211], v[64:67]
	v_mfma_f32_16x16x32_bf16 v[116:119], v[172:175], v[188:191], v[116:119]
	v_mfma_f32_16x16x32_bf16 v[112:115], v[180:183], v[188:191], v[112:115]
	v_mfma_f32_16x16x32_bf16 v[100:103], v[172:175], v[196:199], v[100:103]
	v_mfma_f32_16x16x32_bf16 v[96:99], v[180:183], v[196:199], v[96:99]
	v_mfma_f32_16x16x32_bf16 v[84:87], v[172:175], v[204:207], v[84:87]
	v_mfma_f32_16x16x32_bf16 v[80:83], v[180:183], v[204:207], v[80:83]
	v_mfma_f32_16x16x32_bf16 v[68:71], v[172:175], v[212:215], v[68:71]
	v_mfma_f32_16x16x32_bf16 v[64:67], v[180:183], v[212:215], v[64:67]
	s_setprio 0
	s_barrier
	s_add_i32 s66, s51, s16
	s_mov_b64 s[98:99], s[64:65]
	s_mov_b32 m0, s66
	ds_read_b128 v[184:187], v153 offset:16384
	ds_read_b128 v[188:191], v153 offset:17408
	ds_read_b128 v[192:195], v153 offset:18432
	ds_read_b128 v[196:199], v153 offset:19456
	ds_read_b128 v[200:203], v153 offset:20480
	ds_read_b128 v[204:207], v153 offset:21504
	ds_read_b128 v[208:211], v153 offset:22528
	ds_read_b128 v[212:215], v153 offset:23552
	global_load_lds_dwordx4 v130, s[64:65]
	s_add_i32 m0, s66, 0x2000
	s_add_u32 s64, s64, s6
	s_addc_u32 s65, s65, s7
	s_add_i32 s66, s56, s16
	global_load_lds_dwordx4 v134, s[98:99]
	s_mov_b64 s[100:101], s[64:65]
	s_mov_b32 m0, s66
	s_nop 0
	global_load_lds_dwordx4 v130, s[64:65]
	s_add_i32 m0, s66, 0x2000
	s_mov_b64 s[22:23], s[34:35]
	global_load_lds_dwordx4 v134, s[64:65]
	s_mov_b32 m0, s17
	s_nop 0
	global_load_lds_dwordx4 v128, s[34:35]
	s_mov_b32 m0, s19
	s_nop 0
	global_load_lds_dwordx4 v132, s[34:35]
	s_waitcnt vmcnt(8)
	s_waitcnt lgkmcnt(0)
	s_barrier
	s_setprio 1
	s_waitcnt lgkmcnt(0)
	v_mfma_f32_16x16x32_bf16 v[60:63], v[144:147], v[184:187], v[60:63]
	v_mfma_f32_16x16x32_bf16 v[56:59], v[160:163], v[184:187], v[56:59]
	v_mfma_f32_16x16x32_bf16 v[44:47], v[144:147], v[192:195], v[44:47]
	v_mfma_f32_16x16x32_bf16 v[40:43], v[160:163], v[192:195], v[40:43]
	v_mfma_f32_16x16x32_bf16 v[28:31], v[144:147], v[200:203], v[28:31]
	v_mfma_f32_16x16x32_bf16 v[24:27], v[160:163], v[200:203], v[24:27]
	v_mfma_f32_16x16x32_bf16 v[12:15], v[144:147], v[208:211], v[12:15]
	v_mfma_f32_16x16x32_bf16 v[8:11], v[160:163], v[208:211], v[8:11]
	v_mfma_f32_16x16x32_bf16 v[60:63], v[156:159], v[188:191], v[60:63]
	v_mfma_f32_16x16x32_bf16 v[56:59], v[164:167], v[188:191], v[56:59]
	v_mfma_f32_16x16x32_bf16 v[44:47], v[156:159], v[196:199], v[44:47]
	v_mfma_f32_16x16x32_bf16 v[40:43], v[164:167], v[196:199], v[40:43]
	v_mfma_f32_16x16x32_bf16 v[28:31], v[156:159], v[204:207], v[28:31]
	v_mfma_f32_16x16x32_bf16 v[24:27], v[164:167], v[204:207], v[24:27]
	v_mfma_f32_16x16x32_bf16 v[12:15], v[156:159], v[212:215], v[12:15]
	v_mfma_f32_16x16x32_bf16 v[8:11], v[164:167], v[212:215], v[8:11]
	s_setprio 0
	s_setprio 1
	v_mfma_f32_16x16x32_bf16 v[52:55], v[168:171], v[184:187], v[52:55]
	v_mfma_f32_16x16x32_bf16 v[48:51], v[176:179], v[184:187], v[48:51]
	v_mfma_f32_16x16x32_bf16 v[36:39], v[168:171], v[192:195], v[36:39]
	v_mfma_f32_16x16x32_bf16 v[32:35], v[176:179], v[192:195], v[32:35]
	v_mfma_f32_16x16x32_bf16 v[20:23], v[168:171], v[200:203], v[20:23]
	v_mfma_f32_16x16x32_bf16 v[16:19], v[176:179], v[200:203], v[16:19]
	v_mfma_f32_16x16x32_bf16 v[4:7], v[168:171], v[208:211], v[4:7]
	v_mfma_f32_16x16x32_bf16 v[0:3], v[176:179], v[208:211], v[0:3]
	v_mfma_f32_16x16x32_bf16 v[52:55], v[172:175], v[188:191], v[52:55]
	v_mfma_f32_16x16x32_bf16 v[48:51], v[180:183], v[188:191], v[48:51]
	v_mfma_f32_16x16x32_bf16 v[36:39], v[172:175], v[196:199], v[36:39]
	v_mfma_f32_16x16x32_bf16 v[32:35], v[180:183], v[196:199], v[32:35]
	v_mfma_f32_16x16x32_bf16 v[20:23], v[172:175], v[204:207], v[20:23]
	v_mfma_f32_16x16x32_bf16 v[16:19], v[180:183], v[204:207], v[16:19]
	v_mfma_f32_16x16x32_bf16 v[4:7], v[172:175], v[212:215], v[4:7]
	v_mfma_f32_16x16x32_bf16 v[0:3], v[180:183], v[212:215], v[0:3]
	s_setprio 0
	s_barrier
; #define PG8_STAGE(bufoff, gbase, voff) do { _Pragma("unroll") for (int _i = 0; _i < 2; ++_i) \
;         __builtin_amdgcn_global_load_lds((const unsigned*)((const char*)(gbase) + (voff)[_i]), (PG8_LAS unsigned*)(lds + (bufoff) + ldsw + _i * 8192), 16, 0, 0); } while (0)
; #define PG8_LDA(dst, b, h) do { _Pragma("unroll") for (int m = 0; m < 4; ++m) _Pragma("unroll") for (int k = 0; k < 2; ++k) dst[m][k] = *(const PG8_LAS bf16x8*)(lds + PG8_SA(b, h) + aoff + m * 2048 + k * 1024); } while (0)
; #define PG8_LDB(dst, b, h) do { _Pragma("unroll") for (int n = 0; n < 2; ++n) _Pragma("unroll") for (int k = 0; k < 2; ++k) dst[n][k] = *(const PG8_LAS bf16x8*)(lds + PG8_SB(b, h) + boff + n * 2048 + k * 1024); } while (0)
; #define PG8_MMA(ai, bj, At, Bt) do { __builtin_amdgcn_s_setprio(1); _Pragma("unroll") for (int m = 0; m < 4; ++m) _Pragma("unroll") for (int n = 0; n < 2; ++n) _Pragma("unroll") for (int k = 0; k < 2; ++k) \
;         acc[ai][bj][m][n] = __builtin_amdgcn_mfma_f32_16x16x32_bf16(Bt[n][k], At[m][k], acc[ai][bj][m][n], 0, 0, 0); __builtin_amdgcn_s_setprio(0); } while (0)
; #define PG8_WAIT_V(n) asm volatile("s_waitcnt vmcnt(" #n ")" ::: "memory")
; #define PG8_WAIT_L(n) asm volatile("s_waitcnt lgkmcnt(" #n ")" ::: "memory")
; #define PG8_BAR __builtin_amdgcn_s_barrier()
; #define PG8_SCHED __builtin_amdgcn_sched_barrier(0)
; template <class Epi, class Sched, bool ALIGN_EPI = false, bool SP2 = false>
; __device__ __forceinline__ void gemm_phase(PG8_LAS unsigned char* lds, const Gemm g, const Sched& S, const Epi& E) {
;     ...
;             PG8_LDB(B0, 1, 0); PG8_LDB(B1, 1, 1); PG8_SCHED; PG8_LDA(At, 1, 0); PG8_STAGE(PG8_SA(0, 1), a2 + hstep, voffA);
;             PG8_WAIT_V(8); PG8_WAIT_L(0); PG8_BAR; PG8_MMA(0, 0, At, B0); PG8_MMA(0, 1, At, B1); PG8_BAR; PG8_SCHED;
;             PG8_LDA(At, 1, 1); PG8_STAGE(PG8_SB(1, 0), b3, voffB); PG8_STAGE(PG8_SB(1, 1), b3 + hstep, voffB); PG8_STAGE(PG8_SA(1, 0), a3, voffA);
;             PG8_WAIT_V(8); PG8_WAIT_L(0); PG8_BAR; PG8_MMA(1, 0, At, B0); PG8_MMA(1, 1, At, B1); PG8_BAR; PG8_SCHED;
	s_add_i32 s64, 0, 0x18000
	v_add_u32_e32 v155, s64, v149
	s_add_i32 s65, 0, 0x1c000
	ds_read_b128 v[144:147], v155
	ds_read_b128 v[156:159], v155 offset:1024
	ds_read_b128 v[160:163], v155 offset:2048
	ds_read_b128 v[164:167], v155 offset:3072
	v_add_u32_e32 v155, s65, v149
	ds_read_b128 v[168:171], v155
	ds_read_b128 v[172:175], v155 offset:1024
	ds_read_b128 v[176:179], v155 offset:2048
	ds_read_b128 v[180:183], v155 offset:3072
	s_add_u32 s34, s34, s6
	s_addc_u32 s35, s35, s7
	s_mov_b32 m0, s33
	ds_read_b128 v[184:187], v153 offset:32768
	ds_read_b128 v[188:191], v153 offset:33792
	ds_read_b128 v[192:195], v153 offset:34816
	ds_read_b128 v[196:199], v153 offset:35840
	ds_read_b128 v[200:203], v153 offset:36864
	ds_read_b128 v[204:207], v153 offset:37888
	ds_read_b128 v[208:211], v153 offset:38912
	ds_read_b128 v[212:215], v153 offset:39936
	global_load_lds_dwordx4 v128, s[34:35]
	s_mov_b32 m0, s36
	s_nop 0
	global_load_lds_dwordx4 v132, s[34:35]
	s_waitcnt vmcnt(8)
	s_waitcnt lgkmcnt(0)
	s_barrier
	s_setprio 1
	s_waitcnt lgkmcnt(0)
	v_mfma_f32_16x16x32_bf16 v[124:127], v[144:147], v[184:187], v[124:127]
	v_mfma_f32_16x16x32_bf16 v[120:123], v[160:163], v[184:187], v[120:123]
	v_mfma_f32_16x16x32_bf16 v[108:111], v[144:147], v[192:195], v[108:111]
	v_mfma_f32_16x16x32_bf16 v[104:107], v[160:163], v[192:195], v[104:107]
	v_mfma_f32_16x16x32_bf16 v[92:95], v[144:147], v[200:203], v[92:95]
	v_mfma_f32_16x16x32_bf16 v[88:91], v[160:163], v[200:203], v[88:91]
	v_mfma_f32_16x16x32_bf16 v[76:79], v[144:147], v[208:211], v[76:79]
	v_mfma_f32_16x16x32_bf16 v[72:75], v[160:163], v[208:211], v[72:75]
	v_mfma_f32_16x16x32_bf16 v[124:127], v[156:159], v[188:191], v[124:127]
	v_mfma_f32_16x16x32_bf16 v[120:123], v[164:167], v[188:191], v[120:123]
	v_mfma_f32_16x16x32_bf16 v[108:111], v[156:159], v[196:199], v[108:111]
	v_mfma_f32_16x16x32_bf16 v[104:107], v[164:167], v[196:199], v[104:107]
	v_mfma_f32_16x16x32_bf16 v[92:95], v[156:159], v[204:207], v[92:95]
	v_mfma_f32_16x16x32_bf16 v[88:91], v[164:167], v[204:207], v[88:91]
	v_mfma_f32_16x16x32_bf16 v[76:79], v[156:159], v[212:215], v[76:79]
	v_mfma_f32_16x16x32_bf16 v[72:75], v[164:167], v[212:215], v[72:75]
	s_setprio 0
	s_setprio 1
	v_mfma_f32_16x16x32_bf16 v[116:119], v[168:171], v[184:187], v[116:119]
	v_mfma_f32_16x16x32_bf16 v[112:115], v[176:179], v[184:187], v[112:115]
	v_mfma_f32_16x16x32_bf16 v[100:103], v[168:171], v[192:195], v[100:103]
	v_mfma_f32_16x16x32_bf16 v[96:99], v[176:179], v[192:195], v[96:99]
	v_mfma_f32_16x16x32_bf16 v[84:87], v[168:171], v[200:203], v[84:87]
	v_mfma_f32_16x16x32_bf16 v[80:83], v[176:179], v[200:203], v[80:83]
	v_mfma_f32_16x16x32_bf16 v[68:71], v[168:171], v[208:211], v[68:71]
	v_mfma_f32_16x16x32_bf16 v[64:67], v[176:179], v[208:211], v[64:67]
	v_mfma_f32_16x16x32_bf16 v[116:119], v[172:175], v[188:191], v[116:119]
	v_mfma_f32_16x16x32_bf16 v[112:115], v[180:183], v[188:191], v[112:115]
	v_mfma_f32_16x16x32_bf16 v[100:103], v[172:175], v[196:199], v[100:103]
	v_mfma_f32_16x16x32_bf16 v[96:99], v[180:183], v[196:199], v[96:99]
	v_mfma_f32_16x16x32_bf16 v[84:87], v[172:175], v[204:207], v[84:87]
	v_mfma_f32_16x16x32_bf16 v[80:83], v[180:183], v[204:207], v[80:83]
	v_mfma_f32_16x16x32_bf16 v[68:71], v[172:175], v[212:215], v[68:71]
	v_mfma_f32_16x16x32_bf16 v[64:67], v[180:183], v[212:215], v[64:67]
	s_setprio 0
	s_barrier
	s_add_i32 s34, s64, s16
	s_add_i32 m0, s34, 0xffffff80
	ds_read_b128 v[184:187], v153 offset:49152
	ds_read_b128 v[188:191], v153 offset:50176
	ds_read_b128 v[192:195], v153 offset:51200
	ds_read_b128 v[196:199], v153 offset:52224
	ds_read_b128 v[200:203], v153 offset:53248
	ds_read_b128 v[204:207], v153 offset:54272
	ds_read_b128 v[208:211], v153 offset:55296
	ds_read_b128 v[212:215], v153 offset:56320
	global_load_lds_dwordx4 v130, s[98:99] offset:128
	s_add_i32 m0, s34, 0x1f80
	s_add_i32 s34, s65, s16
	global_load_lds_dwordx4 v134, s[98:99] offset:128
	s_add_i32 m0, s34, 0xffffff80
	s_nop 0
	global_load_lds_dwordx4 v130, s[100:101] offset:128
	s_add_i32 m0, s34, 0x1f80
	s_nop 0
	global_load_lds_dwordx4 v134, s[100:101] offset:128
	s_add_i32 m0, s37, 0xffffff80
	s_nop 0
	global_load_lds_dwordx4 v128, s[22:23] offset:128
	s_add_i32 m0, s38, 0xffffff80
	s_nop 0
	global_load_lds_dwordx4 v132, s[22:23] offset:128
	s_waitcnt vmcnt(8)
	s_waitcnt lgkmcnt(0)
	s_barrier
	s_setprio 1
	s_waitcnt lgkmcnt(0)
	v_mfma_f32_16x16x32_bf16 v[60:63], v[144:147], v[184:187], v[60:63]
	v_mfma_f32_16x16x32_bf16 v[56:59], v[160:163], v[184:187], v[56:59]
	v_mfma_f32_16x16x32_bf16 v[44:47], v[144:147], v[192:195], v[44:47]
	v_mfma_f32_16x16x32_bf16 v[40:43], v[160:163], v[192:195], v[40:43]
	v_mfma_f32_16x16x32_bf16 v[28:31], v[144:147], v[200:203], v[28:31]
	v_mfma_f32_16x16x32_bf16 v[24:27], v[160:163], v[200:203], v[24:27]
	v_mfma_f32_16x16x32_bf16 v[12:15], v[144:147], v[208:211], v[12:15]
	v_mfma_f32_16x16x32_bf16 v[8:11], v[160:163], v[208:211], v[8:11]
	v_mfma_f32_16x16x32_bf16 v[60:63], v[156:159], v[188:191], v[60:63]
	v_mfma_f32_16x16x32_bf16 v[56:59], v[164:167], v[188:191], v[56:59]
	v_mfma_f32_16x16x32_bf16 v[44:47], v[156:159], v[196:199], v[44:47]
	v_mfma_f32_16x16x32_bf16 v[40:43], v[164:167], v[196:199], v[40:43]
	v_mfma_f32_16x16x32_bf16 v[28:31], v[156:159], v[204:207], v[28:31]
	v_mfma_f32_16x16x32_bf16 v[24:27], v[164:167], v[204:207], v[24:27]
	v_mfma_f32_16x16x32_bf16 v[12:15], v[156:159], v[212:215], v[12:15]
	v_mfma_f32_16x16x32_bf16 v[8:11], v[164:167], v[212:215], v[8:11]
	s_setprio 0
	s_setprio 1
	v_mfma_f32_16x16x32_bf16 v[52:55], v[168:171], v[184:187], v[52:55]
	v_mfma_f32_16x16x32_bf16 v[48:51], v[176:179], v[184:187], v[48:51]
	v_mfma_f32_16x16x32_bf16 v[36:39], v[168:171], v[192:195], v[36:39]
	v_mfma_f32_16x16x32_bf16 v[32:35], v[176:179], v[192:195], v[32:35]
	v_mfma_f32_16x16x32_bf16 v[20:23], v[168:171], v[200:203], v[20:23]
	v_mfma_f32_16x16x32_bf16 v[16:19], v[176:179], v[200:203], v[16:19]
	v_mfma_f32_16x16x32_bf16 v[4:7], v[168:171], v[208:211], v[4:7]
	v_mfma_f32_16x16x32_bf16 v[0:3], v[176:179], v[208:211], v[0:3]
	v_mfma_f32_16x16x32_bf16 v[52:55], v[172:175], v[188:191], v[52:55]
	v_mfma_f32_16x16x32_bf16 v[48:51], v[180:183], v[188:191], v[48:51]
	v_mfma_f32_16x16x32_bf16 v[36:39], v[172:175], v[196:199], v[36:39]
	v_mfma_f32_16x16x32_bf16 v[32:35], v[180:183], v[196:199], v[32:35]
	v_mfma_f32_16x16x32_bf16 v[20:23], v[172:175], v[204:207], v[20:23]
	v_mfma_f32_16x16x32_bf16 v[16:19], v[180:183], v[204:207], v[16:19]
	v_mfma_f32_16x16x32_bf16 v[4:7], v[172:175], v[212:215], v[4:7]
	v_mfma_f32_16x16x32_bf16 v[0:3], v[180:183], v[212:215], v[0:3]
	s_setprio 0
	s_barrier
	s_add_u32 s30, s30, 0x100
	s_addc_u32 s31, s31, 0
	s_add_u32 s61, s61, 0x100
	s_addc_u32 s62, s62, 0
	s_cmp_ge_i32 s63, s40
	s_mov_b32 s34, s63
	s_cbranch_scc0 .LBB0_2386

; #define PG8_STAGE(bufoff, gbase, voff) do { _Pragma("unroll") for (int _i = 0; _i < 2; ++_i) \
;         __builtin_amdgcn_global_load_lds((const unsigned*)((const char*)(gbase) + (voff)[_i]), (PG8_LAS unsigned*)(lds + (bufoff) + ldsw + _i * 8192), 16, 0, 0); } while (0)
; #define PG8_LDA(dst, b, h) do { _Pragma("unroll") for (int m = 0; m < 4; ++m) _Pragma("unroll") for (int k = 0; k < 2; ++k) dst[m][k] = *(const PG8_LAS bf16x8*)(lds + PG8_SA(b, h) + aoff + m * 2048 + k * 1024); } while (0)
; #define PG8_LDB(dst, b, h) do { _Pragma("unroll") for (int n = 0; n < 2; ++n) _Pragma("unroll") for (int k = 0; k < 2; ++k) dst[n][k] = *(const PG8_LAS bf16x8*)(lds + PG8_SB(b, h) + boff + n * 2048 + k * 1024); } while (0)
; #define PG8_MMA(ai, bj, At, Bt) do { __builtin_amdgcn_s_setprio(1); _Pragma("unroll") for (int m = 0; m < 4; ++m) _Pragma("unroll") for (int n = 0; n < 2; ++n) _Pragma("unroll") for (int k = 0; k < 2; ++k) \
;         acc[ai][bj][m][n] = __builtin_amdgcn_mfma_f32_16x16x32_bf16(Bt[n][k], At[m][k], acc[ai][bj][m][n], 0, 0, 0); __builtin_amdgcn_s_setprio(0); } while (0)
; #define PG8_WAIT_V(n) asm volatile("s_waitcnt vmcnt(" #n ")" ::: "memory")
; #define PG8_BAR __builtin_amdgcn_s_barrier()
; template <class Epi, class Sched, bool ALIGN_EPI = false, bool SP2 = false>
; __device__ __forceinline__ void gemm_phase(PG8_LAS unsigned char* lds, const Gemm g, const Sched& S, const Epi& E) {
;     ...
;         for (int t = 0; t < nt; t += 2) {
;             const bool last = (t == nt - 2);
;             const char* a1 = cA + (size_t)(t + 1) * kstep;
;             const char* a2 = last ? nA : cA + (size_t)(t + 2) * kstep; const char* b2 = last ? nB : cB + (size_t)(t + 2) * kstep;
;             const char* a3 = a2 + kstep; const char* b3 = b2 + kstep;
;             if (last && has_next) S.a_ready(nxt);
;             if constexpr (SP2) {
;             PG8_LDB(B0, 0, 0); PG8_LDB(B1, 0, 1); PG8_SCHED; PG8_LDA(At, 0, 0); PG8_STAGE(PG8_SA(1, 1), a1 + hstep, voffA);
;             PG8_WAIT_V(8); PG8_WAIT_L(0); PG8_BAR; PG8_MMA(0, 0, At, B0); PG8_MMA(0, 1, At, B1); PG8_BAR; PG8_SCHED;
;             PG8_LDA(At, 0, 1); PG8_STAGE(PG8_SB(0, 0), b2, voffB); PG8_STAGE(PG8_SB(0, 1), b2 + hstep, voffB); PG8_STAGE(PG8_SA(0, 0), a2, voffA);
;             PG8_WAIT_V(8); PG8_WAIT_L(0); PG8_BAR; PG8_MMA(1, 0, At, B0); PG8_MMA(1, 1, At, B1); PG8_BAR; PG8_SCHED;
.LBB0_2479:
	s_andn2_b64 vcc, exec, s[20:21]
	s_waitcnt vmcnt(0)
	s_cbranch_vccnz .LBB0_2482
	s_add_u32 s26, s26, 0x80
	s_addc_u32 s27, s27, 0
	s_add_u32 s60, s28, 0x100
	s_addc_u32 s61, s29, 0
	s_mov_b32 s28, 0
	ds_read_b128 v[154:157], v149
	ds_read_b128 v[158:161], v149 offset:1024
	ds_read_b128 v[162:165], v149 offset:2048
	ds_read_b128 v[166:169], v149 offset:3072
	ds_read_b128 v[170:173], v150
	ds_read_b128 v[174:177], v150 offset:1024
	ds_read_b128 v[178:181], v150 offset:2048
	ds_read_b128 v[182:185], v150 offset:3072
	s_add_i32 s62, s28, 2
	s_add_u32 s63, s26, 0x80
	s_addc_u32 s29, s27, 0
	s_cmp_eq_u32 s39, s28
	s_cselect_b32 s28, s0, s63
	s_cselect_b32 s29, s1, s29
	s_cselect_b32 s65, s25, s61
	s_cselect_b32 s64, s24, s60
	s_add_i32 m0, s30, 0xc000
	ds_read_b128 v[186:189], v151
	ds_read_b128 v[190:193], v151 offset:1024
	ds_read_b128 v[194:197], v151 offset:2048
	ds_read_b128 v[198:201], v151 offset:3072
	ds_read_b128 v[202:205], v151 offset:4096
	ds_read_b128 v[206:209], v151 offset:5120
	ds_read_b128 v[210:213], v151 offset:6144
	ds_read_b128 v[214:217], v151 offset:7168
	global_load_lds_dwordx4 v136, s[26:27]
	s_add_i32 m0, s30, 0xe000
	s_nop 0
	global_load_lds_dwordx4 v138, s[26:27]
	s_waitcnt vmcnt(8)
	s_waitcnt lgkmcnt(0)
	s_barrier
	s_setprio 1
	s_waitcnt lgkmcnt(0)
	v_mfma_f32_16x16x32_bf16 v[116:119], v[154:157], v[186:189], 0
	v_mfma_f32_16x16x32_bf16 v[112:115], v[162:165], v[186:189], 0
	v_mfma_f32_16x16x32_bf16 v[100:103], v[154:157], v[194:197], 0
	v_mfma_f32_16x16x32_bf16 v[96:99], v[162:165], v[194:197], 0
	v_mfma_f32_16x16x32_bf16 v[84:87], v[154:157], v[202:205], 0
	v_mfma_f32_16x16x32_bf16 v[80:83], v[162:165], v[202:205], 0
	v_mfma_f32_16x16x32_bf16 v[68:71], v[154:157], v[210:213], 0
	v_mfma_f32_16x16x32_bf16 v[64:67], v[162:165], v[210:213], 0
	v_mfma_f32_16x16x32_bf16 v[116:119], v[158:161], v[190:193], v[116:119]
	v_mfma_f32_16x16x32_bf16 v[112:115], v[166:169], v[190:193], v[112:115]
	v_mfma_f32_16x16x32_bf16 v[100:103], v[158:161], v[198:201], v[100:103]
	v_mfma_f32_16x16x32_bf16 v[96:99], v[166:169], v[198:201], v[96:99]
	v_mfma_f32_16x16x32_bf16 v[84:87], v[158:161], v[206:209], v[84:87]
	v_mfma_f32_16x16x32_bf16 v[80:83], v[166:169], v[206:209], v[80:83]
	v_mfma_f32_16x16x32_bf16 v[68:71], v[158:161], v[214:217], v[68:71]
	v_mfma_f32_16x16x32_bf16 v[64:67], v[166:169], v[214:217], v[64:67]
	s_setprio 0
	s_setprio 1
	v_mfma_f32_16x16x32_bf16 v[124:127], v[170:173], v[186:189], 0
	v_mfma_f32_16x16x32_bf16 v[120:123], v[178:181], v[186:189], 0
	v_mfma_f32_16x16x32_bf16 v[108:111], v[170:173], v[194:197], 0
	v_mfma_f32_16x16x32_bf16 v[104:107], v[178:181], v[194:197], 0
	v_mfma_f32_16x16x32_bf16 v[92:95], v[170:173], v[202:205], 0
	v_mfma_f32_16x16x32_bf16 v[88:91], v[178:181], v[202:205], 0
	v_mfma_f32_16x16x32_bf16 v[76:79], v[170:173], v[210:213], 0
	v_mfma_f32_16x16x32_bf16 v[72:75], v[178:181], v[210:213], 0
	v_mfma_f32_16x16x32_bf16 v[124:127], v[174:177], v[190:193], v[124:127]
	v_mfma_f32_16x16x32_bf16 v[120:123], v[182:185], v[190:193], v[120:123]
	v_mfma_f32_16x16x32_bf16 v[108:111], v[174:177], v[198:201], v[108:111]
	v_mfma_f32_16x16x32_bf16 v[104:107], v[182:185], v[198:201], v[104:107]
	v_mfma_f32_16x16x32_bf16 v[92:95], v[174:177], v[206:209], v[92:95]
	v_mfma_f32_16x16x32_bf16 v[88:91], v[182:185], v[206:209], v[88:91]
	v_mfma_f32_16x16x32_bf16 v[76:79], v[174:177], v[214:217], v[76:79]
	v_mfma_f32_16x16x32_bf16 v[72:75], v[182:185], v[214:217], v[72:75]
	s_setprio 0
	s_barrier
	s_add_i32 s63, s44, s16
	s_mov_b64 s[98:99], s[64:65]
	s_mov_b32 m0, s63
	ds_read_b128 v[186:189], v151 offset:16384
	ds_read_b128 v[190:193], v151 offset:17408
	ds_read_b128 v[194:197], v151 offset:18432
	ds_read_b128 v[198:201], v151 offset:19456
	ds_read_b128 v[202:205], v151 offset:20480
	ds_read_b128 v[206:209], v151 offset:21504
	ds_read_b128 v[210:213], v151 offset:22528
	ds_read_b128 v[214:217], v151 offset:23552
	global_load_lds_dwordx4 v132, s[64:65]
	s_add_i32 m0, s63, 0x2000
	s_add_u32 s64, s64, s8
	s_addc_u32 s65, s65, s9
	s_add_i32 s63, s45, s16
	global_load_lds_dwordx4 v128, s[98:99]
	s_mov_b64 s[100:101], s[64:65]
	s_mov_b32 m0, s63
	s_nop 0
	global_load_lds_dwordx4 v132, s[64:65]
	s_add_i32 m0, s63, 0x2000
	s_mov_b64 s[14:15], s[28:29]
	global_load_lds_dwordx4 v128, s[64:65]
	s_mov_b32 m0, s30
	s_nop 0
	global_load_lds_dwordx4 v134, s[28:29]
	s_mov_b32 m0, s31
	s_nop 0
	global_load_lds_dwordx4 v130, s[28:29]
	s_waitcnt vmcnt(8)
	s_waitcnt lgkmcnt(0)
	s_barrier
	s_setprio 1
	s_waitcnt lgkmcnt(0)
	v_mfma_f32_16x16x32_bf16 v[52:55], v[154:157], v[186:189], 0
	v_mfma_f32_16x16x32_bf16 v[48:51], v[162:165], v[186:189], 0
	v_mfma_f32_16x16x32_bf16 v[36:39], v[154:157], v[194:197], 0
	v_mfma_f32_16x16x32_bf16 v[32:35], v[162:165], v[194:197], 0
	v_mfma_f32_16x16x32_bf16 v[20:23], v[154:157], v[202:205], 0
	v_mfma_f32_16x16x32_bf16 v[16:19], v[162:165], v[202:205], 0
	v_mfma_f32_16x16x32_bf16 v[4:7], v[154:157], v[210:213], 0
	v_mfma_f32_16x16x32_bf16 v[0:3], v[162:165], v[210:213], 0
	v_mfma_f32_16x16x32_bf16 v[52:55], v[158:161], v[190:193], v[52:55]
	v_mfma_f32_16x16x32_bf16 v[48:51], v[166:169], v[190:193], v[48:51]
	v_mfma_f32_16x16x32_bf16 v[36:39], v[158:161], v[198:201], v[36:39]
	v_mfma_f32_16x16x32_bf16 v[32:35], v[166:169], v[198:201], v[32:35]
	v_mfma_f32_16x16x32_bf16 v[20:23], v[158:161], v[206:209], v[20:23]
	v_mfma_f32_16x16x32_bf16 v[16:19], v[166:169], v[206:209], v[16:19]
	v_mfma_f32_16x16x32_bf16 v[4:7], v[158:161], v[214:217], v[4:7]
	v_mfma_f32_16x16x32_bf16 v[0:3], v[166:169], v[214:217], v[0:3]
	s_setprio 0
	s_setprio 1
	v_mfma_f32_16x16x32_bf16 v[60:63], v[170:173], v[186:189], 0
	v_mfma_f32_16x16x32_bf16 v[56:59], v[178:181], v[186:189], 0
	v_mfma_f32_16x16x32_bf16 v[44:47], v[170:173], v[194:197], 0
	v_mfma_f32_16x16x32_bf16 v[40:43], v[178:181], v[194:197], 0
	v_mfma_f32_16x16x32_bf16 v[28:31], v[170:173], v[202:205], 0
	v_mfma_f32_16x16x32_bf16 v[24:27], v[178:181], v[202:205], 0
	v_mfma_f32_16x16x32_bf16 v[12:15], v[170:173], v[210:213], 0
	v_mfma_f32_16x16x32_bf16 v[8:11], v[178:181], v[210:213], 0
	v_mfma_f32_16x16x32_bf16 v[60:63], v[174:177], v[190:193], v[60:63]
	v_mfma_f32_16x16x32_bf16 v[56:59], v[182:185], v[190:193], v[56:59]
	v_mfma_f32_16x16x32_bf16 v[44:47], v[174:177], v[198:201], v[44:47]
	v_mfma_f32_16x16x32_bf16 v[40:43], v[182:185], v[198:201], v[40:43]
	v_mfma_f32_16x16x32_bf16 v[28:31], v[174:177], v[206:209], v[28:31]
	v_mfma_f32_16x16x32_bf16 v[24:27], v[182:185], v[206:209], v[24:27]
	v_mfma_f32_16x16x32_bf16 v[12:15], v[174:177], v[214:217], v[12:15]
	v_mfma_f32_16x16x32_bf16 v[8:11], v[182:185], v[214:217], v[8:11]
	s_setprio 0
	s_barrier
; #define PG8_STAGE(bufoff, gbase, voff) do { _Pragma("unroll") for (int _i = 0; _i < 2; ++_i) \
;         __builtin_amdgcn_global_load_lds((const unsigned*)((const char*)(gbase) + (voff)[_i]), (PG8_LAS unsigned*)(lds + (bufoff) + ldsw + _i * 8192), 16, 0, 0); } while (0)
; #define PG8_LDA(dst, b, h) do { _Pragma("unroll") for (int m = 0; m < 4; ++m) _Pragma("unroll") for (int k = 0; k < 2; ++k) dst[m][k] = *(const PG8_LAS bf16x8*)(lds + PG8_SA(b, h) + aoff + m * 2048 + k * 1024); } while (0)
; #define PG8_LDB(dst, b, h) do { _Pragma("unroll") for (int n = 0; n < 2; ++n) _Pragma("unroll") for (int k = 0; k < 2; ++k) dst[n][k] = *(const PG8_LAS bf16x8*)(lds + PG8_SB(b, h) + boff + n * 2048 + k * 1024); } while (0)
; #define PG8_MMA(ai, bj, At, Bt) do { __builtin_amdgcn_s_setprio(1); _Pragma("unroll") for (int m = 0; m < 4; ++m) _Pragma("unroll") for (int n = 0; n < 2; ++n) _Pragma("unroll") for (int k = 0; k < 2; ++k) \
;         acc[ai][bj][m][n] = __builtin_amdgcn_mfma_f32_16x16x32_bf16(Bt[n][k], At[m][k], acc[ai][bj][m][n], 0, 0, 0); __builtin_amdgcn_s_setprio(0); } while (0)
; #define PG8_WAIT_V(n) asm volatile("s_waitcnt vmcnt(" #n ")" ::: "memory")
; #define PG8_WAIT_L(n) asm volatile("s_waitcnt lgkmcnt(" #n ")" ::: "memory")
; #define PG8_BAR __builtin_amdgcn_s_barrier()
; template <class Epi, class Sched, bool ALIGN_EPI = false, bool SP2 = false>
; __device__ __forceinline__ void gemm_phase(PG8_LAS unsigned char* lds, const Gemm g, const Sched& S, const Epi& E) {
;     ...
;         for (int t = 0; t < nt; t += 2) {
;             const bool last = (t == nt - 2);
;             const char* a1 = cA + (size_t)(t + 1) * kstep;
;             const char* a2 = last ? nA : cA + (size_t)(t + 2) * kstep; const char* b2 = last ? nB : cB + (size_t)(t + 2) * kstep;
;             const char* a3 = a2 + kstep; const char* b3 = b2 + kstep;
;     ...
;             PG8_LDB(B0, 1, 0); PG8_LDB(B1, 1, 1); PG8_SCHED; PG8_LDA(At, 1, 0); PG8_STAGE(PG8_SA(0, 1), a2 + hstep, voffA);
;             PG8_WAIT_V(8); PG8_WAIT_L(0); PG8_BAR; PG8_MMA(0, 0, At, B0); PG8_MMA(0, 1, At, B1); PG8_BAR; PG8_SCHED;
;             PG8_LDA(At, 1, 1); PG8_STAGE(PG8_SB(1, 0), b3, voffB); PG8_STAGE(PG8_SB(1, 1), b3 + hstep, voffB); PG8_STAGE(PG8_SA(1, 0), a3, voffA);
;             PG8_WAIT_V(8); PG8_WAIT_L(0); PG8_BAR; PG8_MMA(1, 0, At, B0); PG8_MMA(1, 1, At, B1); PG8_BAR; PG8_SCHED;
	s_add_i32 s63, 0, 0x18000
	v_add_u32_e32 v153, s63, v147
	s_add_i32 s64, 0, 0x1c000
	ds_read_b128 v[154:157], v153
	ds_read_b128 v[158:161], v153 offset:1024
	ds_read_b128 v[162:165], v153 offset:2048
	ds_read_b128 v[166:169], v153 offset:3072
	v_add_u32_e32 v153, s64, v147
	ds_read_b128 v[170:173], v153
	ds_read_b128 v[174:177], v153 offset:1024
	ds_read_b128 v[178:181], v153 offset:2048
	ds_read_b128 v[182:185], v153 offset:3072
	s_add_u32 s28, s28, s8
	s_addc_u32 s29, s29, s9
	s_mov_b32 m0, s33
	ds_read_b128 v[186:189], v151 offset:32768
	ds_read_b128 v[190:193], v151 offset:33792
	ds_read_b128 v[194:197], v151 offset:34816
	ds_read_b128 v[198:201], v151 offset:35840
	ds_read_b128 v[202:205], v151 offset:36864
	ds_read_b128 v[206:209], v151 offset:37888
	ds_read_b128 v[210:213], v151 offset:38912
	ds_read_b128 v[214:217], v151 offset:39936
	global_load_lds_dwordx4 v134, s[28:29]
	s_mov_b32 m0, s34
	s_nop 0
	global_load_lds_dwordx4 v130, s[28:29]
	s_waitcnt vmcnt(8)
	s_waitcnt lgkmcnt(0)
	s_barrier
	s_setprio 1
	s_waitcnt lgkmcnt(0)
	v_mfma_f32_16x16x32_bf16 v[116:119], v[154:157], v[186:189], v[116:119]
	v_mfma_f32_16x16x32_bf16 v[112:115], v[162:165], v[186:189], v[112:115]
	v_mfma_f32_16x16x32_bf16 v[100:103], v[154:157], v[194:197], v[100:103]
	v_mfma_f32_16x16x32_bf16 v[96:99], v[162:165], v[194:197], v[96:99]
	v_mfma_f32_16x16x32_bf16 v[84:87], v[154:157], v[202:205], v[84:87]
	v_mfma_f32_16x16x32_bf16 v[80:83], v[162:165], v[202:205], v[80:83]
	v_mfma_f32_16x16x32_bf16 v[68:71], v[154:157], v[210:213], v[68:71]
	v_mfma_f32_16x16x32_bf16 v[64:67], v[162:165], v[210:213], v[64:67]
	v_mfma_f32_16x16x32_bf16 v[116:119], v[158:161], v[190:193], v[116:119]
	v_mfma_f32_16x16x32_bf16 v[112:115], v[166:169], v[190:193], v[112:115]
	v_mfma_f32_16x16x32_bf16 v[100:103], v[158:161], v[198:201], v[100:103]
	v_mfma_f32_16x16x32_bf16 v[96:99], v[166:169], v[198:201], v[96:99]
	v_mfma_f32_16x16x32_bf16 v[84:87], v[158:161], v[206:209], v[84:87]
	v_mfma_f32_16x16x32_bf16 v[80:83], v[166:169], v[206:209], v[80:83]
	v_mfma_f32_16x16x32_bf16 v[68:71], v[158:161], v[214:217], v[68:71]
	v_mfma_f32_16x16x32_bf16 v[64:67], v[166:169], v[214:217], v[64:67]
	s_setprio 0
	s_setprio 1
	v_mfma_f32_16x16x32_bf16 v[124:127], v[170:173], v[186:189], v[124:127]
	v_mfma_f32_16x16x32_bf16 v[120:123], v[178:181], v[186:189], v[120:123]
	v_mfma_f32_16x16x32_bf16 v[108:111], v[170:173], v[194:197], v[108:111]
	v_mfma_f32_16x16x32_bf16 v[104:107], v[178:181], v[194:197], v[104:107]
	v_mfma_f32_16x16x32_bf16 v[92:95], v[170:173], v[202:205], v[92:95]
	v_mfma_f32_16x16x32_bf16 v[88:91], v[178:181], v[202:205], v[88:91]
	v_mfma_f32_16x16x32_bf16 v[76:79], v[170:173], v[210:213], v[76:79]
	v_mfma_f32_16x16x32_bf16 v[72:75], v[178:181], v[210:213], v[72:75]
	v_mfma_f32_16x16x32_bf16 v[124:127], v[174:177], v[190:193], v[124:127]
	v_mfma_f32_16x16x32_bf16 v[120:123], v[182:185], v[190:193], v[120:123]
	v_mfma_f32_16x16x32_bf16 v[108:111], v[174:177], v[198:201], v[108:111]
	v_mfma_f32_16x16x32_bf16 v[104:107], v[182:185], v[198:201], v[104:107]
	v_mfma_f32_16x16x32_bf16 v[92:95], v[174:177], v[206:209], v[92:95]
	v_mfma_f32_16x16x32_bf16 v[88:91], v[182:185], v[206:209], v[88:91]
	v_mfma_f32_16x16x32_bf16 v[76:79], v[174:177], v[214:217], v[76:79]
	v_mfma_f32_16x16x32_bf16 v[72:75], v[182:185], v[214:217], v[72:75]
	s_setprio 0
	s_barrier
	s_add_i32 s28, s63, s16
	s_add_i32 m0, s28, 0xffffff80
	ds_read_b128 v[186:189], v151 offset:49152
	ds_read_b128 v[190:193], v151 offset:50176
	ds_read_b128 v[194:197], v151 offset:51200
	ds_read_b128 v[198:201], v151 offset:52224
	ds_read_b128 v[202:205], v151 offset:53248
	ds_read_b128 v[206:209], v151 offset:54272
	ds_read_b128 v[210:213], v151 offset:55296
	ds_read_b128 v[214:217], v151 offset:56320
	global_load_lds_dwordx4 v132, s[98:99] offset:128
	s_add_i32 m0, s28, 0x1f80
	s_add_i32 s28, s64, s16
	global_load_lds_dwordx4 v128, s[98:99] offset:128
	s_add_i32 m0, s28, 0xffffff80
	s_nop 0
	global_load_lds_dwordx4 v132, s[100:101] offset:128
	s_add_i32 m0, s28, 0x1f80
	s_nop 0
	global_load_lds_dwordx4 v128, s[100:101] offset:128
	s_add_i32 m0, s36, 0xffffff80
	s_nop 0
	global_load_lds_dwordx4 v134, s[14:15] offset:128
	s_add_i32 m0, s37, 0xffffff80
	s_nop 0
	global_load_lds_dwordx4 v130, s[14:15] offset:128
	s_waitcnt vmcnt(8)
	s_waitcnt lgkmcnt(0)
	s_barrier
	s_setprio 1
	s_waitcnt lgkmcnt(0)
	v_mfma_f32_16x16x32_bf16 v[52:55], v[154:157], v[186:189], v[52:55]
	v_mfma_f32_16x16x32_bf16 v[48:51], v[162:165], v[186:189], v[48:51]
	v_mfma_f32_16x16x32_bf16 v[36:39], v[154:157], v[194:197], v[36:39]
	v_mfma_f32_16x16x32_bf16 v[32:35], v[162:165], v[194:197], v[32:35]
	v_mfma_f32_16x16x32_bf16 v[20:23], v[154:157], v[202:205], v[20:23]
	v_mfma_f32_16x16x32_bf16 v[16:19], v[162:165], v[202:205], v[16:19]
	v_mfma_f32_16x16x32_bf16 v[4:7], v[154:157], v[210:213], v[4:7]
	v_mfma_f32_16x16x32_bf16 v[0:3], v[162:165], v[210:213], v[0:3]
	v_mfma_f32_16x16x32_bf16 v[52:55], v[158:161], v[190:193], v[52:55]
	v_mfma_f32_16x16x32_bf16 v[48:51], v[166:169], v[190:193], v[48:51]
	v_mfma_f32_16x16x32_bf16 v[36:39], v[158:161], v[198:201], v[36:39]
	v_mfma_f32_16x16x32_bf16 v[32:35], v[166:169], v[198:201], v[32:35]
	v_mfma_f32_16x16x32_bf16 v[20:23], v[158:161], v[206:209], v[20:23]
	v_mfma_f32_16x16x32_bf16 v[16:19], v[166:169], v[206:209], v[16:19]
	v_mfma_f32_16x16x32_bf16 v[4:7], v[158:161], v[214:217], v[4:7]
	v_mfma_f32_16x16x32_bf16 v[0:3], v[166:169], v[214:217], v[0:3]
	s_setprio 0
	s_setprio 1
	v_mfma_f32_16x16x32_bf16 v[60:63], v[170:173], v[186:189], v[60:63]
	v_mfma_f32_16x16x32_bf16 v[56:59], v[178:181], v[186:189], v[56:59]
	v_mfma_f32_16x16x32_bf16 v[44:47], v[170:173], v[194:197], v[44:47]
	v_mfma_f32_16x16x32_bf16 v[40:43], v[178:181], v[194:197], v[40:43]
	v_mfma_f32_16x16x32_bf16 v[28:31], v[170:173], v[202:205], v[28:31]
	v_mfma_f32_16x16x32_bf16 v[24:27], v[178:181], v[202:205], v[24:27]
	v_mfma_f32_16x16x32_bf16 v[12:15], v[170:173], v[210:213], v[12:15]
	v_mfma_f32_16x16x32_bf16 v[8:11], v[178:181], v[210:213], v[8:11]
	v_mfma_f32_16x16x32_bf16 v[60:63], v[174:177], v[190:193], v[60:63]
	v_mfma_f32_16x16x32_bf16 v[56:59], v[182:185], v[190:193], v[56:59]
	v_mfma_f32_16x16x32_bf16 v[44:47], v[174:177], v[198:201], v[44:47]
	v_mfma_f32_16x16x32_bf16 v[40:43], v[182:185], v[198:201], v[40:43]
	v_mfma_f32_16x16x32_bf16 v[28:31], v[174:177], v[206:209], v[28:31]
	v_mfma_f32_16x16x32_bf16 v[24:27], v[182:185], v[206:209], v[24:27]
	v_mfma_f32_16x16x32_bf16 v[12:15], v[174:177], v[214:217], v[12:15]
	v_mfma_f32_16x16x32_bf16 v[8:11], v[182:185], v[214:217], v[8:11]
	s_setprio 0
	s_barrier
	s_add_u32 s26, s26, 0x100
	s_addc_u32 s27, s27, 0
	s_add_u32 s60, s60, 0x100
	s_addc_u32 s61, s61, 0
	s_cmp_ge_i32 s62, s38
	s_mov_b32 s28, s62
	s_cbranch_scc0 .LBB0_2481
	s_branch .Lpeel_x12
; #define PG8_STAGE(bufoff, gbase, voff) do { _Pragma("unroll") for (int _i = 0; _i < 2; ++_i) \
;         __builtin_amdgcn_global_load_lds((const unsigned*)((const char*)(gbase) + (voff)[_i]), (PG8_LAS unsigned*)(lds + (bufoff) + ldsw + _i * 8192), 16, 0, 0); } while (0)
; #define PG8_LDA(dst, b, h) do { _Pragma("unroll") for (int m = 0; m < 4; ++m) _Pragma("unroll") for (int k = 0; k < 2; ++k) dst[m][k] = *(const PG8_LAS bf16x8*)(lds + PG8_SA(b, h) + aoff + m * 2048 + k * 1024); } while (0)
; #define PG8_LDB(dst, b, h) do { _Pragma("unroll") for (int n = 0; n < 2; ++n) _Pragma("unroll") for (int k = 0; k < 2; ++k) dst[n][k] = *(const PG8_LAS bf16x8*)(lds + PG8_SB(b, h) + boff + n * 2048 + k * 1024); } while (0)
; #define PG8_MMA(ai, bj, At, Bt) do { __builtin_amdgcn_s_setprio(1); _Pragma("unroll") for (int m = 0; m < 4; ++m) _Pragma("unroll") for (int n = 0; n < 2; ++n) _Pragma("unroll") for (int k = 0; k < 2; ++k) \
;         acc[ai][bj][m][n] = __builtin_amdgcn_mfma_f32_16x16x32_bf16(Bt[n][k], At[m][k], acc[ai][bj][m][n], 0, 0, 0); __builtin_amdgcn_s_setprio(0); } while (0)
; #define PG8_WAIT_V(n) asm volatile("s_waitcnt vmcnt(" #n ")" ::: "memory")
; #define PG8_BAR __builtin_amdgcn_s_barrier()
; template <class Epi, class Sched, bool ALIGN_EPI = false, bool SP2 = false>
; __device__ __forceinline__ void gemm_phase(PG8_LAS unsigned char* lds, const Gemm g, const Sched& S, const Epi& E) {
;     ...
;         for (int t = 0; t < nt; t += 2) {
;             const bool last = (t == nt - 2);
;             const char* a1 = cA + (size_t)(t + 1) * kstep;
;             const char* a2 = last ? nA : cA + (size_t)(t + 2) * kstep; const char* b2 = last ? nB : cB + (size_t)(t + 2) * kstep;
;             const char* a3 = a2 + kstep; const char* b3 = b2 + kstep;
;             if (last && has_next) S.a_ready(nxt);
;             if constexpr (SP2) {
;             PG8_LDB(B0, 0, 0); PG8_LDB(B1, 0, 1); PG8_SCHED; PG8_LDA(At, 0, 0); PG8_STAGE(PG8_SA(1, 1), a1 + hstep, voffA);
;             PG8_WAIT_V(8); PG8_WAIT_L(0); PG8_BAR; PG8_MMA(0, 0, At, B0); PG8_MMA(0, 1, At, B1); PG8_BAR; PG8_SCHED;
;             PG8_LDA(At, 0, 1); PG8_STAGE(PG8_SB(0, 0), b2, voffB); PG8_STAGE(PG8_SB(0, 1), b2 + hstep, voffB); PG8_STAGE(PG8_SA(0, 0), a2, voffA);
;             PG8_WAIT_V(8); PG8_WAIT_L(0); PG8_BAR; PG8_MMA(1, 0, At, B0); PG8_MMA(1, 1, At, B1); PG8_BAR; PG8_SCHED;
.LBB0_2481:
	ds_read_b128 v[154:157], v149
	ds_read_b128 v[158:161], v149 offset:1024
	ds_read_b128 v[162:165], v149 offset:2048
	ds_read_b128 v[166:169], v149 offset:3072
	ds_read_b128 v[170:173], v150
	ds_read_b128 v[174:177], v150 offset:1024
	ds_read_b128 v[178:181], v150 offset:2048
	ds_read_b128 v[182:185], v150 offset:3072
	s_add_i32 s62, s28, 2
	s_add_u32 s63, s26, 0x80
	s_addc_u32 s29, s27, 0
	s_cmp_eq_u32 s39, s28
	s_cselect_b32 s28, s0, s63
	s_cselect_b32 s29, s1, s29
	s_cselect_b32 s65, s25, s61
	s_cselect_b32 s64, s24, s60
	s_add_i32 m0, s30, 0xc000
	ds_read_b128 v[186:189], v151
	ds_read_b128 v[190:193], v151 offset:1024
	ds_read_b128 v[194:197], v151 offset:2048
	ds_read_b128 v[198:201], v151 offset:3072
	ds_read_b128 v[202:205], v151 offset:4096
	ds_read_b128 v[206:209], v151 offset:5120
	ds_read_b128 v[210:213], v151 offset:6144
	ds_read_b128 v[214:217], v151 offset:7168
	global_load_lds_dwordx4 v136, s[26:27]
	s_add_i32 m0, s30, 0xe000
	s_nop 0
	global_load_lds_dwordx4 v138, s[26:27]
	s_waitcnt vmcnt(8)
	s_waitcnt lgkmcnt(0)
	s_barrier
	s_setprio 1
	s_waitcnt lgkmcnt(0)
	v_mfma_f32_16x16x32_bf16 v[116:119], v[154:157], v[186:189], v[116:119]
	v_mfma_f32_16x16x32_bf16 v[112:115], v[162:165], v[186:189], v[112:115]
	v_mfma_f32_16x16x32_bf16 v[100:103], v[154:157], v[194:197], v[100:103]
	v_mfma_f32_16x16x32_bf16 v[96:99], v[162:165], v[194:197], v[96:99]
	v_mfma_f32_16x16x32_bf16 v[84:87], v[154:157], v[202:205], v[84:87]
	v_mfma_f32_16x16x32_bf16 v[80:83], v[162:165], v[202:205], v[80:83]
	v_mfma_f32_16x16x32_bf16 v[68:71], v[154:157], v[210:213], v[68:71]
	v_mfma_f32_16x16x32_bf16 v[64:67], v[162:165], v[210:213], v[64:67]
	v_mfma_f32_16x16x32_bf16 v[116:119], v[158:161], v[190:193], v[116:119]
	v_mfma_f32_16x16x32_bf16 v[112:115], v[166:169], v[190:193], v[112:115]
	v_mfma_f32_16x16x32_bf16 v[100:103], v[158:161], v[198:201], v[100:103]
	v_mfma_f32_16x16x32_bf16 v[96:99], v[166:169], v[198:201], v[96:99]
	v_mfma_f32_16x16x32_bf16 v[84:87], v[158:161], v[206:209], v[84:87]
	v_mfma_f32_16x16x32_bf16 v[80:83], v[166:169], v[206:209], v[80:83]
	v_mfma_f32_16x16x32_bf16 v[68:71], v[158:161], v[214:217], v[68:71]
	v_mfma_f32_16x16x32_bf16 v[64:67], v[166:169], v[214:217], v[64:67]
	s_setprio 0
	s_setprio 1
	v_mfma_f32_16x16x32_bf16 v[124:127], v[170:173], v[186:189], v[124:127]
	v_mfma_f32_16x16x32_bf16 v[120:123], v[178:181], v[186:189], v[120:123]
	v_mfma_f32_16x16x32_bf16 v[108:111], v[170:173], v[194:197], v[108:111]
	v_mfma_f32_16x16x32_bf16 v[104:107], v[178:181], v[194:197], v[104:107]
	v_mfma_f32_16x16x32_bf16 v[92:95], v[170:173], v[202:205], v[92:95]
	v_mfma_f32_16x16x32_bf16 v[88:91], v[178:181], v[202:205], v[88:91]
	v_mfma_f32_16x16x32_bf16 v[76:79], v[170:173], v[210:213], v[76:79]
	v_mfma_f32_16x16x32_bf16 v[72:75], v[178:181], v[210:213], v[72:75]
	v_mfma_f32_16x16x32_bf16 v[124:127], v[174:177], v[190:193], v[124:127]
	v_mfma_f32_16x16x32_bf16 v[120:123], v[182:185], v[190:193], v[120:123]
	v_mfma_f32_16x16x32_bf16 v[108:111], v[174:177], v[198:201], v[108:111]
	v_mfma_f32_16x16x32_bf16 v[104:107], v[182:185], v[198:201], v[104:107]
	v_mfma_f32_16x16x32_bf16 v[92:95], v[174:177], v[206:209], v[92:95]
	v_mfma_f32_16x16x32_bf16 v[88:91], v[182:185], v[206:209], v[88:91]
	v_mfma_f32_16x16x32_bf16 v[76:79], v[174:177], v[214:217], v[76:79]
	v_mfma_f32_16x16x32_bf16 v[72:75], v[182:185], v[214:217], v[72:75]
	s_setprio 0
	s_barrier
	s_add_i32 s63, s44, s16
	s_mov_b64 s[98:99], s[64:65]
	s_mov_b32 m0, s63
	ds_read_b128 v[186:189], v151 offset:16384
	ds_read_b128 v[190:193], v151 offset:17408
	ds_read_b128 v[194:197], v151 offset:18432
	ds_read_b128 v[198:201], v151 offset:19456
	ds_read_b128 v[202:205], v151 offset:20480
	ds_read_b128 v[206:209], v151 offset:21504
	ds_read_b128 v[210:213], v151 offset:22528
	ds_read_b128 v[214:217], v151 offset:23552
	global_load_lds_dwordx4 v132, s[64:65]
	s_add_i32 m0, s63, 0x2000
	s_add_u32 s64, s64, s8
	s_addc_u32 s65, s65, s9
	s_add_i32 s63, s45, s16
	global_load_lds_dwordx4 v128, s[98:99]
	s_mov_b64 s[100:101], s[64:65]
	s_mov_b32 m0, s63
	s_nop 0
	global_load_lds_dwordx4 v132, s[64:65]
	s_add_i32 m0, s63, 0x2000
	s_mov_b64 s[14:15], s[28:29]
	global_load_lds_dwordx4 v128, s[64:65]
	s_mov_b32 m0, s30
	s_nop 0
	global_load_lds_dwordx4 v134, s[28:29]
	s_mov_b32 m0, s31
	s_nop 0
	global_load_lds_dwordx4 v130, s[28:29]
	s_waitcnt vmcnt(8)
	s_waitcnt lgkmcnt(0)
	s_barrier
	s_setprio 1
	s_waitcnt lgkmcnt(0)
	v_mfma_f32_16x16x32_bf16 v[52:55], v[154:157], v[186:189], v[52:55]
	v_mfma_f32_16x16x32_bf16 v[48:51], v[162:165], v[186:189], v[48:51]
	v_mfma_f32_16x16x32_bf16 v[36:39], v[154:157], v[194:197], v[36:39]
	v_mfma_f32_16x16x32_bf16 v[32:35], v[162:165], v[194:197], v[32:35]
	v_mfma_f32_16x16x32_bf16 v[20:23], v[154:157], v[202:205], v[20:23]
	v_mfma_f32_16x16x32_bf16 v[16:19], v[162:165], v[202:205], v[16:19]
	v_mfma_f32_16x16x32_bf16 v[4:7], v[154:157], v[210:213], v[4:7]
	v_mfma_f32_16x16x32_bf16 v[0:3], v[162:165], v[210:213], v[0:3]
	v_mfma_f32_16x16x32_bf16 v[52:55], v[158:161], v[190:193], v[52:55]
	v_mfma_f32_16x16x32_bf16 v[48:51], v[166:169], v[190:193], v[48:51]
	v_mfma_f32_16x16x32_bf16 v[36:39], v[158:161], v[198:201], v[36:39]
	v_mfma_f32_16x16x32_bf16 v[32:35], v[166:169], v[198:201], v[32:35]
	v_mfma_f32_16x16x32_bf16 v[20:23], v[158:161], v[206:209], v[20:23]
	v_mfma_f32_16x16x32_bf16 v[16:19], v[166:169], v[206:209], v[16:19]
	v_mfma_f32_16x16x32_bf16 v[4:7], v[158:161], v[214:217], v[4:7]
	v_mfma_f32_16x16x32_bf16 v[0:3], v[166:169], v[214:217], v[0:3]
	s_setprio 0
	s_setprio 1
	v_mfma_f32_16x16x32_bf16 v[60:63], v[170:173], v[186:189], v[60:63]
	v_mfma_f32_16x16x32_bf16 v[56:59], v[178:181], v[186:189], v[56:59]
	v_mfma_f32_16x16x32_bf16 v[44:47], v[170:173], v[194:197], v[44:47]
	v_mfma_f32_16x16x32_bf16 v[40:43], v[178:181], v[194:197], v[40:43]
	v_mfma_f32_16x16x32_bf16 v[28:31], v[170:173], v[202:205], v[28:31]
	v_mfma_f32_16x16x32_bf16 v[24:27], v[178:181], v[202:205], v[24:27]
	v_mfma_f32_16x16x32_bf16 v[12:15], v[170:173], v[210:213], v[12:15]
	v_mfma_f32_16x16x32_bf16 v[8:11], v[178:181], v[210:213], v[8:11]
	v_mfma_f32_16x16x32_bf16 v[60:63], v[174:177], v[190:193], v[60:63]
	v_mfma_f32_16x16x32_bf16 v[56:59], v[182:185], v[190:193], v[56:59]
	v_mfma_f32_16x16x32_bf16 v[44:47], v[174:177], v[198:201], v[44:47]
	v_mfma_f32_16x16x32_bf16 v[40:43], v[182:185], v[198:201], v[40:43]
	v_mfma_f32_16x16x32_bf16 v[28:31], v[174:177], v[206:209], v[28:31]
	v_mfma_f32_16x16x32_bf16 v[24:27], v[182:185], v[206:209], v[24:27]
	v_mfma_f32_16x16x32_bf16 v[12:15], v[174:177], v[214:217], v[12:15]
	v_mfma_f32_16x16x32_bf16 v[8:11], v[182:185], v[214:217], v[8:11]
	s_setprio 0
	s_barrier
; #define PG8_STAGE(bufoff, gbase, voff) do { _Pragma("unroll") for (int _i = 0; _i < 2; ++_i) \
;         __builtin_amdgcn_global_load_lds((const unsigned*)((const char*)(gbase) + (voff)[_i]), (PG8_LAS unsigned*)(lds + (bufoff) + ldsw + _i * 8192), 16, 0, 0); } while (0)
; #define PG8_LDA(dst, b, h) do { _Pragma("unroll") for (int m = 0; m < 4; ++m) _Pragma("unroll") for (int k = 0; k < 2; ++k) dst[m][k] = *(const PG8_LAS bf16x8*)(lds + PG8_SA(b, h) + aoff + m * 2048 + k * 1024); } while (0)
; #define PG8_LDB(dst, b, h) do { _Pragma("unroll") for (int n = 0; n < 2; ++n) _Pragma("unroll") for (int k = 0; k < 2; ++k) dst[n][k] = *(const PG8_LAS bf16x8*)(lds + PG8_SB(b, h) + boff + n * 2048 + k * 1024); } while (0)
; #define PG8_MMA(ai, bj, At, Bt) do { __builtin_amdgcn_s_setprio(1); _Pragma("unroll") for (int m = 0; m < 4; ++m) _Pragma("unroll") for (int n = 0; n < 2; ++n) _Pragma("unroll") for (int k = 0; k < 2; ++k) \
;         acc[ai][bj][m][n] = __builtin_amdgcn_mfma_f32_16x16x32_bf16(Bt[n][k], At[m][k], acc[ai][bj][m][n], 0, 0, 0); __builtin_amdgcn_s_setprio(0); } while (0)
; #define PG8_WAIT_V(n) asm volatile("s_waitcnt vmcnt(" #n ")" ::: "memory")
; #define PG8_WAIT_L(n) asm volatile("s_waitcnt lgkmcnt(" #n ")" ::: "memory")
; #define PG8_BAR __builtin_amdgcn_s_barrier()
; template <class Epi, class Sched, bool ALIGN_EPI = false, bool SP2 = false>
; __device__ __forceinline__ void gemm_phase(PG8_LAS unsigned char* lds, const Gemm g, const Sched& S, const Epi& E) {
;     ...
;         for (int t = 0; t < nt; t += 2) {
;             const bool last = (t == nt - 2);
;             const char* a1 = cA + (size_t)(t + 1) * kstep;
;             const char* a2 = last ? nA : cA + (size_t)(t + 2) * kstep; const char* b2 = last ? nB : cB + (size_t)(t + 2) * kstep;
;             const char* a3 = a2 + kstep; const char* b3 = b2 + kstep;
;     ...
;             PG8_LDB(B0, 1, 0); PG8_LDB(B1, 1, 1); PG8_SCHED; PG8_LDA(At, 1, 0); PG8_STAGE(PG8_SA(0, 1), a2 + hstep, voffA);
;             PG8_WAIT_V(8); PG8_WAIT_L(0); PG8_BAR; PG8_MMA(0, 0, At, B0); PG8_MMA(0, 1, At, B1); PG8_BAR; PG8_SCHED;
;             PG8_LDA(At, 1, 1); PG8_STAGE(PG8_SB(1, 0), b3, voffB); PG8_STAGE(PG8_SB(1, 1), b3 + hstep, voffB); PG8_STAGE(PG8_SA(1, 0), a3, voffA);
;             PG8_WAIT_V(8); PG8_WAIT_L(0); PG8_BAR; PG8_MMA(1, 0, At, B0); PG8_MMA(1, 1, At, B1); PG8_BAR; PG8_SCHED;
	s_add_i32 s63, 0, 0x18000
	v_add_u32_e32 v153, s63, v147
	s_add_i32 s64, 0, 0x1c000
	ds_read_b128 v[154:157], v153
	ds_read_b128 v[158:161], v153 offset:1024
	ds_read_b128 v[162:165], v153 offset:2048
	ds_read_b128 v[166:169], v153 offset:3072
	v_add_u32_e32 v153, s64, v147
	ds_read_b128 v[170:173], v153
	ds_read_b128 v[174:177], v153 offset:1024
	ds_read_b128 v[178:181], v153 offset:2048
	ds_read_b128 v[182:185], v153 offset:3072
	s_add_u32 s28, s28, s8
	s_addc_u32 s29, s29, s9
	s_mov_b32 m0, s33
	ds_read_b128 v[186:189], v151 offset:32768
	ds_read_b128 v[190:193], v151 offset:33792
	ds_read_b128 v[194:197], v151 offset:34816
	ds_read_b128 v[198:201], v151 offset:35840
	ds_read_b128 v[202:205], v151 offset:36864
	ds_read_b128 v[206:209], v151 offset:37888
	ds_read_b128 v[210:213], v151 offset:38912
	ds_read_b128 v[214:217], v151 offset:39936
	global_load_lds_dwordx4 v134, s[28:29]
	s_mov_b32 m0, s34
	s_nop 0
	global_load_lds_dwordx4 v130, s[28:29]
	s_waitcnt vmcnt(8)
	s_waitcnt lgkmcnt(0)
	s_barrier
	s_setprio 1
	s_waitcnt lgkmcnt(0)
	v_mfma_f32_16x16x32_bf16 v[116:119], v[154:157], v[186:189], v[116:119]
	v_mfma_f32_16x16x32_bf16 v[112:115], v[162:165], v[186:189], v[112:115]
	v_mfma_f32_16x16x32_bf16 v[100:103], v[154:157], v[194:197], v[100:103]
	v_mfma_f32_16x16x32_bf16 v[96:99], v[162:165], v[194:197], v[96:99]
	v_mfma_f32_16x16x32_bf16 v[84:87], v[154:157], v[202:205], v[84:87]
	v_mfma_f32_16x16x32_bf16 v[80:83], v[162:165], v[202:205], v[80:83]
	v_mfma_f32_16x16x32_bf16 v[68:71], v[154:157], v[210:213], v[68:71]
	v_mfma_f32_16x16x32_bf16 v[64:67], v[162:165], v[210:213], v[64:67]
	v_mfma_f32_16x16x32_bf16 v[116:119], v[158:161], v[190:193], v[116:119]
	v_mfma_f32_16x16x32_bf16 v[112:115], v[166:169], v[190:193], v[112:115]
	v_mfma_f32_16x16x32_bf16 v[100:103], v[158:161], v[198:201], v[100:103]
	v_mfma_f32_16x16x32_bf16 v[96:99], v[166:169], v[198:201], v[96:99]
	v_mfma_f32_16x16x32_bf16 v[84:87], v[158:161], v[206:209], v[84:87]
	v_mfma_f32_16x16x32_bf16 v[80:83], v[166:169], v[206:209], v[80:83]
	v_mfma_f32_16x16x32_bf16 v[68:71], v[158:161], v[214:217], v[68:71]
	v_mfma_f32_16x16x32_bf16 v[64:67], v[166:169], v[214:217], v[64:67]
	s_setprio 0
	s_setprio 1
	v_mfma_f32_16x16x32_bf16 v[124:127], v[170:173], v[186:189], v[124:127]
	v_mfma_f32_16x16x32_bf16 v[120:123], v[178:181], v[186:189], v[120:123]
	v_mfma_f32_16x16x32_bf16 v[108:111], v[170:173], v[194:197], v[108:111]
	v_mfma_f32_16x16x32_bf16 v[104:107], v[178:181], v[194:197], v[104:107]
	v_mfma_f32_16x16x32_bf16 v[92:95], v[170:173], v[202:205], v[92:95]
	v_mfma_f32_16x16x32_bf16 v[88:91], v[178:181], v[202:205], v[88:91]
	v_mfma_f32_16x16x32_bf16 v[76:79], v[170:173], v[210:213], v[76:79]
	v_mfma_f32_16x16x32_bf16 v[72:75], v[178:181], v[210:213], v[72:75]
	v_mfma_f32_16x16x32_bf16 v[124:127], v[174:177], v[190:193], v[124:127]
	v_mfma_f32_16x16x32_bf16 v[120:123], v[182:185], v[190:193], v[120:123]
	v_mfma_f32_16x16x32_bf16 v[108:111], v[174:177], v[198:201], v[108:111]
	v_mfma_f32_16x16x32_bf16 v[104:107], v[182:185], v[198:201], v[104:107]
	v_mfma_f32_16x16x32_bf16 v[92:95], v[174:177], v[206:209], v[92:95]
	v_mfma_f32_16x16x32_bf16 v[88:91], v[182:185], v[206:209], v[88:91]
	v_mfma_f32_16x16x32_bf16 v[76:79], v[174:177], v[214:217], v[76:79]
	v_mfma_f32_16x16x32_bf16 v[72:75], v[182:185], v[214:217], v[72:75]
	s_setprio 0
	s_barrier
	s_add_i32 s28, s63, s16
	s_add_i32 m0, s28, 0xffffff80
	ds_read_b128 v[186:189], v151 offset:49152
	ds_read_b128 v[190:193], v151 offset:50176
	ds_read_b128 v[194:197], v151 offset:51200
	ds_read_b128 v[198:201], v151 offset:52224
	ds_read_b128 v[202:205], v151 offset:53248
	ds_read_b128 v[206:209], v151 offset:54272
	ds_read_b128 v[210:213], v151 offset:55296
	ds_read_b128 v[214:217], v151 offset:56320
	global_load_lds_dwordx4 v132, s[98:99] offset:128
	s_add_i32 m0, s28, 0x1f80
	s_add_i32 s28, s64, s16
	global_load_lds_dwordx4 v128, s[98:99] offset:128
	s_add_i32 m0, s28, 0xffffff80
	s_nop 0
	global_load_lds_dwordx4 v132, s[100:101] offset:128
	s_add_i32 m0, s28, 0x1f80
	s_nop 0
	global_load_lds_dwordx4 v128, s[100:101] offset:128
	s_add_i32 m0, s36, 0xffffff80
	s_nop 0
	global_load_lds_dwordx4 v134, s[14:15] offset:128
	s_add_i32 m0, s37, 0xffffff80
	s_nop 0
	global_load_lds_dwordx4 v130, s[14:15] offset:128
	s_waitcnt vmcnt(8)
	s_waitcnt lgkmcnt(0)
	s_barrier
	s_setprio 1
	s_waitcnt lgkmcnt(0)
	v_mfma_f32_16x16x32_bf16 v[52:55], v[154:157], v[186:189], v[52:55]
	v_mfma_f32_16x16x32_bf16 v[48:51], v[162:165], v[186:189], v[48:51]
	v_mfma_f32_16x16x32_bf16 v[36:39], v[154:157], v[194:197], v[36:39]
	v_mfma_f32_16x16x32_bf16 v[32:35], v[162:165], v[194:197], v[32:35]
	v_mfma_f32_16x16x32_bf16 v[20:23], v[154:157], v[202:205], v[20:23]
	v_mfma_f32_16x16x32_bf16 v[16:19], v[162:165], v[202:205], v[16:19]
	v_mfma_f32_16x16x32_bf16 v[4:7], v[154:157], v[210:213], v[4:7]
	v_mfma_f32_16x16x32_bf16 v[0:3], v[162:165], v[210:213], v[0:3]
	v_mfma_f32_16x16x32_bf16 v[52:55], v[158:161], v[190:193], v[52:55]
	v_mfma_f32_16x16x32_bf16 v[48:51], v[166:169], v[190:193], v[48:51]
	v_mfma_f32_16x16x32_bf16 v[36:39], v[158:161], v[198:201], v[36:39]
	v_mfma_f32_16x16x32_bf16 v[32:35], v[166:169], v[198:201], v[32:35]
	v_mfma_f32_16x16x32_bf16 v[20:23], v[158:161], v[206:209], v[20:23]
	v_mfma_f32_16x16x32_bf16 v[16:19], v[166:169], v[206:209], v[16:19]
	v_mfma_f32_16x16x32_bf16 v[4:7], v[158:161], v[214:217], v[4:7]
	v_mfma_f32_16x16x32_bf16 v[0:3], v[166:169], v[214:217], v[0:3]
	s_setprio 0
	s_setprio 1
	v_mfma_f32_16x16x32_bf16 v[60:63], v[170:173], v[186:189], v[60:63]
	v_mfma_f32_16x16x32_bf16 v[56:59], v[178:181], v[186:189], v[56:59]
	v_mfma_f32_16x16x32_bf16 v[44:47], v[170:173], v[194:197], v[44:47]
	v_mfma_f32_16x16x32_bf16 v[40:43], v[178:181], v[194:197], v[40:43]
	v_mfma_f32_16x16x32_bf16 v[28:31], v[170:173], v[202:205], v[28:31]
	v_mfma_f32_16x16x32_bf16 v[24:27], v[178:181], v[202:205], v[24:27]
	v_mfma_f32_16x16x32_bf16 v[12:15], v[170:173], v[210:213], v[12:15]
	v_mfma_f32_16x16x32_bf16 v[8:11], v[178:181], v[210:213], v[8:11]
	v_mfma_f32_16x16x32_bf16 v[60:63], v[174:177], v[190:193], v[60:63]
	v_mfma_f32_16x16x32_bf16 v[56:59], v[182:185], v[190:193], v[56:59]
	v_mfma_f32_16x16x32_bf16 v[44:47], v[174:177], v[198:201], v[44:47]
	v_mfma_f32_16x16x32_bf16 v[40:43], v[182:185], v[198:201], v[40:43]
	v_mfma_f32_16x16x32_bf16 v[28:31], v[174:177], v[206:209], v[28:31]
	v_mfma_f32_16x16x32_bf16 v[24:27], v[182:185], v[206:209], v[24:27]
	v_mfma_f32_16x16x32_bf16 v[12:15], v[174:177], v[214:217], v[12:15]
	v_mfma_f32_16x16x32_bf16 v[8:11], v[182:185], v[214:217], v[8:11]
	s_setprio 0
	s_barrier
	s_add_u32 s26, s26, 0x100
	s_addc_u32 s27, s27, 0
	s_add_u32 s60, s60, 0x100
	s_addc_u32 s61, s61, 0
	s_cmp_ge_i32 s62, s38
	s_mov_b32 s28, s62
	s_cbranch_scc0 .LBB0_2481

; #define PG8_STAGE(bufoff, gbase, voff) do { _Pragma("unroll") for (int _i = 0; _i < 2; ++_i) \
;         __builtin_amdgcn_global_load_lds((const unsigned*)((const char*)(gbase) + (voff)[_i]), (PG8_LAS unsigned*)(lds + (bufoff) + ldsw + _i * 8192), 16, 0, 0); } while (0)
; #define PG8_LDA(dst, b, h) do { _Pragma("unroll") for (int m = 0; m < 4; ++m) _Pragma("unroll") for (int k = 0; k < 2; ++k) dst[m][k] = *(const PG8_LAS bf16x8*)(lds + PG8_SA(b, h) + aoff + m * 2048 + k * 1024); } while (0)
; #define PG8_LDB(dst, b, h) do { _Pragma("unroll") for (int n = 0; n < 2; ++n) _Pragma("unroll") for (int k = 0; k < 2; ++k) dst[n][k] = *(const PG8_LAS bf16x8*)(lds + PG8_SB(b, h) + boff + n * 2048 + k * 1024); } while (0)
; #define PG8_MMA(ai, bj, At, Bt) do { __builtin_amdgcn_s_setprio(1); _Pragma("unroll") for (int m = 0; m < 4; ++m) _Pragma("unroll") for (int n = 0; n < 2; ++n) _Pragma("unroll") for (int k = 0; k < 2; ++k) \
;         acc[ai][bj][m][n] = __builtin_amdgcn_mfma_f32_16x16x32_bf16(Bt[n][k], At[m][k], acc[ai][bj][m][n], 0, 0, 0); __builtin_amdgcn_s_setprio(0); } while (0)
; #define PG8_WAIT_V(n) asm volatile("s_waitcnt vmcnt(" #n ")" ::: "memory")
; #define PG8_WAIT_L(n) asm volatile("s_waitcnt lgkmcnt(" #n ")" ::: "memory")
; #define PG8_BAR __builtin_amdgcn_s_barrier()
; #define PG8_SCHED __builtin_amdgcn_sched_barrier(0)
; template <class Epi, class Sched, bool ALIGN_EPI = false, bool SP2 = false>
; __device__ __forceinline__ void gemm_phase(PG8_LAS unsigned char* lds, const Gemm g, const Sched& S, const Epi& E) {
;     ...
;             PG8_LDB(B0, 0, 0); PG8_LDB(B1, 0, 1); PG8_SCHED; PG8_LDA(At, 0, 0); PG8_STAGE(PG8_SA(1, 1), a1 + hstep, voffA);
;             PG8_WAIT_V(8); PG8_WAIT_L(0); PG8_BAR; PG8_MMA(0, 0, At, B0); PG8_MMA(0, 1, At, B1); PG8_BAR; PG8_SCHED;
;             PG8_LDA(At, 0, 1); PG8_STAGE(PG8_SB(0, 0), b2, voffB); PG8_STAGE(PG8_SB(0, 1), b2 + hstep, voffB); PG8_STAGE(PG8_SA(0, 0), a2, voffA);
.LBB0_2573:
	v_mov_b32_e32 v151, 0
	s_andn2_b64 vcc, exec, s[24:25]
	v_mov_b32_e32 v150, 0
	v_mov_b32_e32 v155, 0
	v_mov_b32_e32 v154, 0
	v_mov_b32_e32 v153, 0
	v_mov_b32_e32 v152, 0
	v_mov_b32_e32 v149, 0
	v_mov_b32_e32 v148, 0
	s_waitcnt vmcnt(0)
	v_mov_b32_e32 v145, 0
	v_mov_b32_e32 v144, 0
	v_mov_b32_e32 v147, 0
	v_mov_b32_e32 v146, 0
	s_waitcnt lgkmcnt(0)
	s_cbranch_vccnz .LBB0_2577
	s_add_u32 s30, s30, 0x80
	s_addc_u32 s31, s31, 0
	s_add_u32 s61, s34, 0x100
	s_addc_u32 s62, s35, 0
	s_mov_b32 s34, 0
	ds_read_b128 v[144:147], v159
	ds_read_b128 v[148:151], v159 offset:1024
	ds_read_b128 v[152:155], v159 offset:2048
	ds_read_b128 v[164:167], v159 offset:3072
	ds_read_b128 v[168:171], v160
	ds_read_b128 v[172:175], v160 offset:1024
	ds_read_b128 v[176:179], v160 offset:2048
	ds_read_b128 v[180:183], v160 offset:3072
	s_add_i32 s63, s34, 2
	s_add_u32 s64, s30, 0x80
	s_addc_u32 s35, s31, 0
	s_cmp_eq_u32 s41, s34
	s_cselect_b32 s34, s0, s64
	s_cselect_b32 s35, s1, s35
	s_cselect_b32 s65, s29, s62
	s_cselect_b32 s64, s28, s61
	s_add_i32 m0, s17, 0xc000
	ds_read_b128 v[184:187], v161
	ds_read_b128 v[188:191], v161 offset:1024
	ds_read_b128 v[192:195], v161 offset:2048
	ds_read_b128 v[196:199], v161 offset:3072
	ds_read_b128 v[200:203], v161 offset:4096
	ds_read_b128 v[204:207], v161 offset:5120
	ds_read_b128 v[208:211], v161 offset:6144
	ds_read_b128 v[212:215], v161 offset:7168
	global_load_lds_dwordx4 v136, s[30:31]
	s_add_i32 m0, s17, 0xe000
	s_nop 0
	global_load_lds_dwordx4 v138, s[30:31]
	s_waitcnt vmcnt(8)
	s_waitcnt lgkmcnt(0)
	s_barrier
	s_setprio 1
	s_waitcnt lgkmcnt(0)
	v_mfma_f32_16x16x32_bf16 v[124:127], v[144:147], v[184:187], 0
	v_mfma_f32_16x16x32_bf16 v[120:123], v[152:155], v[184:187], 0
	v_mfma_f32_16x16x32_bf16 v[116:119], v[144:147], v[192:195], 0
	v_mfma_f32_16x16x32_bf16 v[112:115], v[152:155], v[192:195], 0
	v_mfma_f32_16x16x32_bf16 v[104:107], v[144:147], v[200:203], 0
	v_mfma_f32_16x16x32_bf16 v[96:99], v[152:155], v[200:203], 0
	v_mfma_f32_16x16x32_bf16 v[88:91], v[144:147], v[208:211], 0
	v_mfma_f32_16x16x32_bf16 v[80:83], v[152:155], v[208:211], 0
	v_mfma_f32_16x16x32_bf16 v[124:127], v[148:151], v[188:191], v[124:127]
	v_mfma_f32_16x16x32_bf16 v[120:123], v[164:167], v[188:191], v[120:123]
	v_mfma_f32_16x16x32_bf16 v[116:119], v[148:151], v[196:199], v[116:119]
	v_mfma_f32_16x16x32_bf16 v[112:115], v[164:167], v[196:199], v[112:115]
	v_mfma_f32_16x16x32_bf16 v[104:107], v[148:151], v[204:207], v[104:107]
	v_mfma_f32_16x16x32_bf16 v[96:99], v[164:167], v[204:207], v[96:99]
	v_mfma_f32_16x16x32_bf16 v[88:91], v[148:151], v[212:215], v[88:91]
	v_mfma_f32_16x16x32_bf16 v[80:83], v[164:167], v[212:215], v[80:83]
	s_setprio 0
	s_setprio 1
	v_mfma_f32_16x16x32_bf16 v[108:111], v[168:171], v[184:187], 0
	v_mfma_f32_16x16x32_bf16 v[100:103], v[176:179], v[184:187], 0
	v_mfma_f32_16x16x32_bf16 v[92:95], v[168:171], v[192:195], 0
	v_mfma_f32_16x16x32_bf16 v[84:87], v[176:179], v[192:195], 0
	v_mfma_f32_16x16x32_bf16 v[76:79], v[168:171], v[200:203], 0
	v_mfma_f32_16x16x32_bf16 v[72:75], v[176:179], v[200:203], 0
	v_mfma_f32_16x16x32_bf16 v[68:71], v[168:171], v[208:211], 0
	v_mfma_f32_16x16x32_bf16 v[64:67], v[176:179], v[208:211], 0
	v_mfma_f32_16x16x32_bf16 v[108:111], v[172:175], v[188:191], v[108:111]
	v_mfma_f32_16x16x32_bf16 v[100:103], v[180:183], v[188:191], v[100:103]
	v_mfma_f32_16x16x32_bf16 v[92:95], v[172:175], v[196:199], v[92:95]
	v_mfma_f32_16x16x32_bf16 v[84:87], v[180:183], v[196:199], v[84:87]
	v_mfma_f32_16x16x32_bf16 v[76:79], v[172:175], v[204:207], v[76:79]
	v_mfma_f32_16x16x32_bf16 v[72:75], v[180:183], v[204:207], v[72:75]
	v_mfma_f32_16x16x32_bf16 v[68:71], v[172:175], v[212:215], v[68:71]
	v_mfma_f32_16x16x32_bf16 v[64:67], v[180:183], v[212:215], v[64:67]
	s_setprio 0
	s_barrier
	s_add_i32 s66, s51, s16
	s_mov_b64 s[98:99], s[64:65]
	s_mov_b32 m0, s66
	ds_read_b128 v[184:187], v161 offset:16384
	ds_read_b128 v[188:191], v161 offset:17408
	ds_read_b128 v[192:195], v161 offset:18432
	ds_read_b128 v[196:199], v161 offset:19456
	ds_read_b128 v[200:203], v161 offset:20480
	ds_read_b128 v[204:207], v161 offset:21504
	ds_read_b128 v[208:211], v161 offset:22528
	ds_read_b128 v[212:215], v161 offset:23552
	global_load_lds_dwordx4 v130, s[64:65]
	s_add_i32 m0, s66, 0x2000
	s_add_u32 s64, s64, s6
	s_addc_u32 s65, s65, s7
	s_add_i32 s66, s56, s16
	global_load_lds_dwordx4 v134, s[98:99]
	s_mov_b64 s[100:101], s[64:65]
	s_mov_b32 m0, s66
	s_nop 0
	global_load_lds_dwordx4 v130, s[64:65]
	s_add_i32 m0, s66, 0x2000
	s_mov_b64 s[22:23], s[34:35]
	global_load_lds_dwordx4 v134, s[64:65]
	s_mov_b32 m0, s17
	s_nop 0
	global_load_lds_dwordx4 v128, s[34:35]
	s_mov_b32 m0, s19
	s_nop 0
	global_load_lds_dwordx4 v132, s[34:35]
	s_waitcnt vmcnt(8)
	s_waitcnt lgkmcnt(0)
	s_barrier
; #define PG8_STAGE(bufoff, gbase, voff) do { _Pragma("unroll") for (int _i = 0; _i < 2; ++_i) \
;         __builtin_amdgcn_global_load_lds((const unsigned*)((const char*)(gbase) + (voff)[_i]), (PG8_LAS unsigned*)(lds + (bufoff) + ldsw + _i * 8192), 16, 0, 0); } while (0)
; #define PG8_LDA(dst, b, h) do { _Pragma("unroll") for (int m = 0; m < 4; ++m) _Pragma("unroll") for (int k = 0; k < 2; ++k) dst[m][k] = *(const PG8_LAS bf16x8*)(lds + PG8_SA(b, h) + aoff + m * 2048 + k * 1024); } while (0)
; #define PG8_LDB(dst, b, h) do { _Pragma("unroll") for (int n = 0; n < 2; ++n) _Pragma("unroll") for (int k = 0; k < 2; ++k) dst[n][k] = *(const PG8_LAS bf16x8*)(lds + PG8_SB(b, h) + boff + n * 2048 + k * 1024); } while (0)
; #define PG8_MMA(ai, bj, At, Bt) do { __builtin_amdgcn_s_setprio(1); _Pragma("unroll") for (int m = 0; m < 4; ++m) _Pragma("unroll") for (int n = 0; n < 2; ++n) _Pragma("unroll") for (int k = 0; k < 2; ++k) \
;         acc[ai][bj][m][n] = __builtin_amdgcn_mfma_f32_16x16x32_bf16(Bt[n][k], At[m][k], acc[ai][bj][m][n], 0, 0, 0); __builtin_amdgcn_s_setprio(0); } while (0)
; #define PG8_WAIT_V(n) asm volatile("s_waitcnt vmcnt(" #n ")" ::: "memory")
; #define PG8_WAIT_L(n) asm volatile("s_waitcnt lgkmcnt(" #n ")" ::: "memory")
; #define PG8_BAR __builtin_amdgcn_s_barrier()
; #define PG8_SCHED __builtin_amdgcn_sched_barrier(0)
; template <class Epi, class Sched, bool ALIGN_EPI = false, bool SP2 = false>
; __device__ __forceinline__ void gemm_phase(PG8_LAS unsigned char* lds, const Gemm g, const Sched& S, const Epi& E) {
;     ...
;             PG8_WAIT_V(8); PG8_WAIT_L(0); PG8_BAR; PG8_MMA(1, 0, At, B0); PG8_MMA(1, 1, At, B1); PG8_BAR; PG8_SCHED;
;             PG8_LDB(B0, 1, 0); PG8_LDB(B1, 1, 1); PG8_SCHED; PG8_LDA(At, 1, 0); PG8_STAGE(PG8_SA(0, 1), a2 + hstep, voffA);
;             PG8_WAIT_V(8); PG8_WAIT_L(0); PG8_BAR; PG8_MMA(0, 0, At, B0); PG8_MMA(0, 1, At, B1); PG8_BAR; PG8_SCHED;
	s_setprio 1
	s_waitcnt lgkmcnt(0)
	v_mfma_f32_16x16x32_bf16 v[60:63], v[144:147], v[184:187], 0
	v_mfma_f32_16x16x32_bf16 v[56:59], v[152:155], v[184:187], 0
	v_mfma_f32_16x16x32_bf16 v[52:55], v[144:147], v[192:195], 0
	v_mfma_f32_16x16x32_bf16 v[48:51], v[152:155], v[192:195], 0
	v_mfma_f32_16x16x32_bf16 v[40:43], v[144:147], v[200:203], 0
	v_mfma_f32_16x16x32_bf16 v[32:35], v[152:155], v[200:203], 0
	v_mfma_f32_16x16x32_bf16 v[24:27], v[144:147], v[208:211], 0
	v_mfma_f32_16x16x32_bf16 v[16:19], v[152:155], v[208:211], 0
	v_mfma_f32_16x16x32_bf16 v[60:63], v[148:151], v[188:191], v[60:63]
	v_mfma_f32_16x16x32_bf16 v[56:59], v[164:167], v[188:191], v[56:59]
	v_mfma_f32_16x16x32_bf16 v[52:55], v[148:151], v[196:199], v[52:55]
	v_mfma_f32_16x16x32_bf16 v[48:51], v[164:167], v[196:199], v[48:51]
	v_mfma_f32_16x16x32_bf16 v[40:43], v[148:151], v[204:207], v[40:43]
	v_mfma_f32_16x16x32_bf16 v[32:35], v[164:167], v[204:207], v[32:35]
	v_mfma_f32_16x16x32_bf16 v[24:27], v[148:151], v[212:215], v[24:27]
	v_mfma_f32_16x16x32_bf16 v[16:19], v[164:167], v[212:215], v[16:19]
	s_setprio 0
	s_setprio 1
	v_mfma_f32_16x16x32_bf16 v[44:47], v[168:171], v[184:187], 0
	v_mfma_f32_16x16x32_bf16 v[36:39], v[176:179], v[184:187], 0
	v_mfma_f32_16x16x32_bf16 v[28:31], v[168:171], v[192:195], 0
	v_mfma_f32_16x16x32_bf16 v[20:23], v[176:179], v[192:195], 0
	v_mfma_f32_16x16x32_bf16 v[12:15], v[168:171], v[200:203], 0
	v_mfma_f32_16x16x32_bf16 v[8:11], v[176:179], v[200:203], 0
	v_mfma_f32_16x16x32_bf16 v[4:7], v[168:171], v[208:211], 0
	v_mfma_f32_16x16x32_bf16 v[0:3], v[176:179], v[208:211], 0
	v_mfma_f32_16x16x32_bf16 v[44:47], v[172:175], v[188:191], v[44:47]
	v_mfma_f32_16x16x32_bf16 v[36:39], v[180:183], v[188:191], v[36:39]
	v_mfma_f32_16x16x32_bf16 v[28:31], v[172:175], v[196:199], v[28:31]
	v_mfma_f32_16x16x32_bf16 v[20:23], v[180:183], v[196:199], v[20:23]
	v_mfma_f32_16x16x32_bf16 v[12:15], v[172:175], v[204:207], v[12:15]
	v_mfma_f32_16x16x32_bf16 v[8:11], v[180:183], v[204:207], v[8:11]
	v_mfma_f32_16x16x32_bf16 v[4:7], v[172:175], v[212:215], v[4:7]
	v_mfma_f32_16x16x32_bf16 v[0:3], v[180:183], v[212:215], v[0:3]
	s_setprio 0
	s_barrier
	s_add_i32 s64, 0, 0x18000
	v_add_u32_e32 v163, s64, v157
	s_add_i32 s65, 0, 0x1c000
	ds_read_b128 v[144:147], v163
	ds_read_b128 v[148:151], v163 offset:1024
	ds_read_b128 v[152:155], v163 offset:2048
	ds_read_b128 v[164:167], v163 offset:3072
	v_add_u32_e32 v163, s65, v157
	ds_read_b128 v[168:171], v163
	ds_read_b128 v[172:175], v163 offset:1024
	ds_read_b128 v[176:179], v163 offset:2048
	ds_read_b128 v[180:183], v163 offset:3072
	s_add_u32 s34, s34, s6
	s_addc_u32 s35, s35, s7
	s_mov_b32 m0, s33
	ds_read_b128 v[184:187], v161 offset:32768
	ds_read_b128 v[188:191], v161 offset:33792
	ds_read_b128 v[192:195], v161 offset:34816
	ds_read_b128 v[196:199], v161 offset:35840
	ds_read_b128 v[200:203], v161 offset:36864
	ds_read_b128 v[204:207], v161 offset:37888
	ds_read_b128 v[208:211], v161 offset:38912
	ds_read_b128 v[212:215], v161 offset:39936
	global_load_lds_dwordx4 v128, s[34:35]
	s_mov_b32 m0, s36
	s_nop 0
	global_load_lds_dwordx4 v132, s[34:35]
	s_waitcnt vmcnt(8)
	s_waitcnt lgkmcnt(0)
	s_barrier
	s_setprio 1
	s_waitcnt lgkmcnt(0)
	v_mfma_f32_16x16x32_bf16 v[124:127], v[144:147], v[184:187], v[124:127]
	v_mfma_f32_16x16x32_bf16 v[120:123], v[152:155], v[184:187], v[120:123]
	v_mfma_f32_16x16x32_bf16 v[116:119], v[144:147], v[192:195], v[116:119]
	v_mfma_f32_16x16x32_bf16 v[112:115], v[152:155], v[192:195], v[112:115]
	v_mfma_f32_16x16x32_bf16 v[104:107], v[144:147], v[200:203], v[104:107]
	v_mfma_f32_16x16x32_bf16 v[96:99], v[152:155], v[200:203], v[96:99]
	v_mfma_f32_16x16x32_bf16 v[88:91], v[144:147], v[208:211], v[88:91]
	v_mfma_f32_16x16x32_bf16 v[80:83], v[152:155], v[208:211], v[80:83]
	v_mfma_f32_16x16x32_bf16 v[124:127], v[148:151], v[188:191], v[124:127]
	v_mfma_f32_16x16x32_bf16 v[120:123], v[164:167], v[188:191], v[120:123]
	v_mfma_f32_16x16x32_bf16 v[116:119], v[148:151], v[196:199], v[116:119]
	v_mfma_f32_16x16x32_bf16 v[112:115], v[164:167], v[196:199], v[112:115]
	v_mfma_f32_16x16x32_bf16 v[104:107], v[148:151], v[204:207], v[104:107]
	v_mfma_f32_16x16x32_bf16 v[96:99], v[164:167], v[204:207], v[96:99]
	v_mfma_f32_16x16x32_bf16 v[88:91], v[148:151], v[212:215], v[88:91]
	v_mfma_f32_16x16x32_bf16 v[80:83], v[164:167], v[212:215], v[80:83]
	s_setprio 0
	s_setprio 1
	v_mfma_f32_16x16x32_bf16 v[108:111], v[168:171], v[184:187], v[108:111]
	v_mfma_f32_16x16x32_bf16 v[100:103], v[176:179], v[184:187], v[100:103]
	v_mfma_f32_16x16x32_bf16 v[92:95], v[168:171], v[192:195], v[92:95]
	v_mfma_f32_16x16x32_bf16 v[84:87], v[176:179], v[192:195], v[84:87]
	v_mfma_f32_16x16x32_bf16 v[76:79], v[168:171], v[200:203], v[76:79]
	v_mfma_f32_16x16x32_bf16 v[72:75], v[176:179], v[200:203], v[72:75]
	v_mfma_f32_16x16x32_bf16 v[68:71], v[168:171], v[208:211], v[68:71]
	v_mfma_f32_16x16x32_bf16 v[64:67], v[176:179], v[208:211], v[64:67]
	v_mfma_f32_16x16x32_bf16 v[108:111], v[172:175], v[188:191], v[108:111]
	v_mfma_f32_16x16x32_bf16 v[100:103], v[180:183], v[188:191], v[100:103]
	v_mfma_f32_16x16x32_bf16 v[92:95], v[172:175], v[196:199], v[92:95]
	v_mfma_f32_16x16x32_bf16 v[84:87], v[180:183], v[196:199], v[84:87]
	v_mfma_f32_16x16x32_bf16 v[76:79], v[172:175], v[204:207], v[76:79]
	v_mfma_f32_16x16x32_bf16 v[72:75], v[180:183], v[204:207], v[72:75]
	v_mfma_f32_16x16x32_bf16 v[68:71], v[172:175], v[212:215], v[68:71]
	v_mfma_f32_16x16x32_bf16 v[64:67], v[180:183], v[212:215], v[64:67]
	s_setprio 0
	s_barrier
; #define PG8_STAGE(bufoff, gbase, voff) do { _Pragma("unroll") for (int _i = 0; _i < 2; ++_i) \
;         __builtin_amdgcn_global_load_lds((const unsigned*)((const char*)(gbase) + (voff)[_i]), (PG8_LAS unsigned*)(lds + (bufoff) + ldsw + _i * 8192), 16, 0, 0); } while (0)
; #define PG8_LDA(dst, b, h) do { _Pragma("unroll") for (int m = 0; m < 4; ++m) _Pragma("unroll") for (int k = 0; k < 2; ++k) dst[m][k] = *(const PG8_LAS bf16x8*)(lds + PG8_SA(b, h) + aoff + m * 2048 + k * 1024); } while (0)
; #define PG8_LDB(dst, b, h) do { _Pragma("unroll") for (int n = 0; n < 2; ++n) _Pragma("unroll") for (int k = 0; k < 2; ++k) dst[n][k] = *(const PG8_LAS bf16x8*)(lds + PG8_SB(b, h) + boff + n * 2048 + k * 1024); } while (0)
; #define PG8_MMA(ai, bj, At, Bt) do { __builtin_amdgcn_s_setprio(1); _Pragma("unroll") for (int m = 0; m < 4; ++m) _Pragma("unroll") for (int n = 0; n < 2; ++n) _Pragma("unroll") for (int k = 0; k < 2; ++k) \
;         acc[ai][bj][m][n] = __builtin_amdgcn_mfma_f32_16x16x32_bf16(Bt[n][k], At[m][k], acc[ai][bj][m][n], 0, 0, 0); __builtin_amdgcn_s_setprio(0); } while (0)
; #define PG8_WAIT_V(n) asm volatile("s_waitcnt vmcnt(" #n ")" ::: "memory")
; #define PG8_WAIT_L(n) asm volatile("s_waitcnt lgkmcnt(" #n ")" ::: "memory")
; #define PG8_BAR __builtin_amdgcn_s_barrier()
; #define PG8_SCHED __builtin_amdgcn_sched_barrier(0)
; template <class Epi, class Sched, bool ALIGN_EPI = false, bool SP2 = false>
; __device__ __forceinline__ void gemm_phase(PG8_LAS unsigned char* lds, const Gemm g, const Sched& S, const Epi& E) {
;     ...
;             PG8_LDB(B0, 0, 0); PG8_LDB(B1, 0, 1); PG8_SCHED; PG8_LDA(At, 0, 0); PG8_STAGE(PG8_SA(1, 1), a1 + hstep, voffA);
;             PG8_WAIT_V(8); PG8_WAIT_L(0); PG8_BAR; PG8_MMA(0, 0, At, B0); PG8_MMA(0, 1, At, B1); PG8_BAR; PG8_SCHED;
;     ...
;             PG8_LDA(At, 1, 1); PG8_STAGE(PG8_SB(1, 0), b3, voffB); PG8_STAGE(PG8_SB(1, 1), b3 + hstep, voffB); PG8_STAGE(PG8_SA(1, 0), a3, voffA);
;             PG8_WAIT_V(8); PG8_WAIT_L(0); PG8_BAR; PG8_MMA(1, 0, At, B0); PG8_MMA(1, 1, At, B1); PG8_BAR; PG8_SCHED;
	s_add_i32 s34, s64, s16
	s_add_i32 m0, s34, 0xffffff80
	ds_read_b128 v[184:187], v161 offset:49152
	ds_read_b128 v[188:191], v161 offset:50176
	ds_read_b128 v[192:195], v161 offset:51200
	ds_read_b128 v[196:199], v161 offset:52224
	ds_read_b128 v[200:203], v161 offset:53248
	ds_read_b128 v[204:207], v161 offset:54272
	ds_read_b128 v[208:211], v161 offset:55296
	ds_read_b128 v[212:215], v161 offset:56320
	global_load_lds_dwordx4 v130, s[98:99] offset:128
	s_add_i32 m0, s34, 0x1f80
	s_add_i32 s34, s65, s16
	global_load_lds_dwordx4 v134, s[98:99] offset:128
	s_add_i32 m0, s34, 0xffffff80
	s_nop 0
	global_load_lds_dwordx4 v130, s[100:101] offset:128
	s_add_i32 m0, s34, 0x1f80
	s_nop 0
	global_load_lds_dwordx4 v134, s[100:101] offset:128
	s_add_i32 m0, s37, 0xffffff80
	s_nop 0
	global_load_lds_dwordx4 v128, s[22:23] offset:128
	s_add_i32 m0, s38, 0xffffff80
	s_nop 0
	global_load_lds_dwordx4 v132, s[22:23] offset:128
	s_waitcnt vmcnt(8)
	s_waitcnt lgkmcnt(0)
	s_barrier
	s_setprio 1
	s_waitcnt lgkmcnt(0)
	v_mfma_f32_16x16x32_bf16 v[60:63], v[144:147], v[184:187], v[60:63]
	v_mfma_f32_16x16x32_bf16 v[56:59], v[152:155], v[184:187], v[56:59]
	v_mfma_f32_16x16x32_bf16 v[52:55], v[144:147], v[192:195], v[52:55]
	v_mfma_f32_16x16x32_bf16 v[48:51], v[152:155], v[192:195], v[48:51]
	v_mfma_f32_16x16x32_bf16 v[40:43], v[144:147], v[200:203], v[40:43]
	v_mfma_f32_16x16x32_bf16 v[32:35], v[152:155], v[200:203], v[32:35]
	v_mfma_f32_16x16x32_bf16 v[24:27], v[144:147], v[208:211], v[24:27]
	v_mfma_f32_16x16x32_bf16 v[16:19], v[152:155], v[208:211], v[16:19]
	v_mfma_f32_16x16x32_bf16 v[60:63], v[148:151], v[188:191], v[60:63]
	v_mfma_f32_16x16x32_bf16 v[56:59], v[164:167], v[188:191], v[56:59]
	v_mfma_f32_16x16x32_bf16 v[52:55], v[148:151], v[196:199], v[52:55]
	v_mfma_f32_16x16x32_bf16 v[48:51], v[164:167], v[196:199], v[48:51]
	v_mfma_f32_16x16x32_bf16 v[40:43], v[148:151], v[204:207], v[40:43]
	v_mfma_f32_16x16x32_bf16 v[32:35], v[164:167], v[204:207], v[32:35]
	v_mfma_f32_16x16x32_bf16 v[24:27], v[148:151], v[212:215], v[24:27]
	v_mfma_f32_16x16x32_bf16 v[16:19], v[164:167], v[212:215], v[16:19]
	s_setprio 0
	s_setprio 1
	v_mfma_f32_16x16x32_bf16 v[44:47], v[168:171], v[184:187], v[44:47]
	v_mfma_f32_16x16x32_bf16 v[36:39], v[176:179], v[184:187], v[36:39]
	v_mfma_f32_16x16x32_bf16 v[28:31], v[168:171], v[192:195], v[28:31]
	v_mfma_f32_16x16x32_bf16 v[20:23], v[176:179], v[192:195], v[20:23]
	v_mfma_f32_16x16x32_bf16 v[12:15], v[168:171], v[200:203], v[12:15]
	v_mfma_f32_16x16x32_bf16 v[8:11], v[176:179], v[200:203], v[8:11]
	v_mfma_f32_16x16x32_bf16 v[4:7], v[168:171], v[208:211], v[4:7]
	v_mfma_f32_16x16x32_bf16 v[0:3], v[176:179], v[208:211], v[0:3]
	v_mfma_f32_16x16x32_bf16 v[44:47], v[172:175], v[188:191], v[44:47]
	v_mfma_f32_16x16x32_bf16 v[36:39], v[180:183], v[188:191], v[36:39]
	v_mfma_f32_16x16x32_bf16 v[28:31], v[172:175], v[196:199], v[28:31]
	v_mfma_f32_16x16x32_bf16 v[20:23], v[180:183], v[196:199], v[20:23]
	v_mfma_f32_16x16x32_bf16 v[12:15], v[172:175], v[204:207], v[12:15]
	v_mfma_f32_16x16x32_bf16 v[8:11], v[180:183], v[204:207], v[8:11]
	v_mfma_f32_16x16x32_bf16 v[4:7], v[172:175], v[212:215], v[4:7]
	v_mfma_f32_16x16x32_bf16 v[0:3], v[180:183], v[212:215], v[0:3]
	s_setprio 0
	s_barrier
	s_add_u32 s30, s30, 0x100
	s_addc_u32 s31, s31, 0
	s_add_u32 s61, s61, 0x100
	s_addc_u32 s62, s62, 0
	s_cmp_ge_i32 s63, s40
	s_mov_b32 s34, s63
	s_cbranch_scc0 .LBB0_2575
	s_branch .Lpeel_x13
.LBB0_2575:
	ds_read_b128 v[144:147], v159
	ds_read_b128 v[148:151], v159 offset:1024
	ds_read_b128 v[152:155], v159 offset:2048
	ds_read_b128 v[164:167], v159 offset:3072
	ds_read_b128 v[168:171], v160
	ds_read_b128 v[172:175], v160 offset:1024
	ds_read_b128 v[176:179], v160 offset:2048
	ds_read_b128 v[180:183], v160 offset:3072
	s_add_i32 s63, s34, 2
	s_add_u32 s64, s30, 0x80
	s_addc_u32 s35, s31, 0
	s_cmp_eq_u32 s41, s34
	s_cselect_b32 s34, s0, s64
	s_cselect_b32 s35, s1, s35
	s_cselect_b32 s65, s29, s62
	s_cselect_b32 s64, s28, s61
	s_add_i32 m0, s17, 0xc000
	ds_read_b128 v[184:187], v161
	ds_read_b128 v[188:191], v161 offset:1024
	ds_read_b128 v[192:195], v161 offset:2048
	ds_read_b128 v[196:199], v161 offset:3072
	ds_read_b128 v[200:203], v161 offset:4096
	ds_read_b128 v[204:207], v161 offset:5120
	ds_read_b128 v[208:211], v161 offset:6144
	ds_read_b128 v[212:215], v161 offset:7168
	global_load_lds_dwordx4 v136, s[30:31]
	s_add_i32 m0, s17, 0xe000
	s_nop 0
	global_load_lds_dwordx4 v138, s[30:31]
	s_waitcnt vmcnt(8)
	s_waitcnt lgkmcnt(0)
	s_barrier
; #define PG8_STAGE(bufoff, gbase, voff) do { _Pragma("unroll") for (int _i = 0; _i < 2; ++_i) \
;         __builtin_amdgcn_global_load_lds((const unsigned*)((const char*)(gbase) + (voff)[_i]), (PG8_LAS unsigned*)(lds + (bufoff) + ldsw + _i * 8192), 16, 0, 0); } while (0)
; #define PG8_LDA(dst, b, h) do { _Pragma("unroll") for (int m = 0; m < 4; ++m) _Pragma("unroll") for (int k = 0; k < 2; ++k) dst[m][k] = *(const PG8_LAS bf16x8*)(lds + PG8_SA(b, h) + aoff + m * 2048 + k * 1024); } while (0)
; #define PG8_MMA(ai, bj, At, Bt) do { __builtin_amdgcn_s_setprio(1); _Pragma("unroll") for (int m = 0; m < 4; ++m) _Pragma("unroll") for (int n = 0; n < 2; ++n) _Pragma("unroll") for (int k = 0; k < 2; ++k) \
;         acc[ai][bj][m][n] = __builtin_amdgcn_mfma_f32_16x16x32_bf16(Bt[n][k], At[m][k], acc[ai][bj][m][n], 0, 0, 0); __builtin_amdgcn_s_setprio(0); } while (0)
; #define PG8_WAIT_V(n) asm volatile("s_waitcnt vmcnt(" #n ")" ::: "memory")
; #define PG8_WAIT_L(n) asm volatile("s_waitcnt lgkmcnt(" #n ")" ::: "memory")
; #define PG8_BAR __builtin_amdgcn_s_barrier()
; #define PG8_SCHED __builtin_amdgcn_sched_barrier(0)
; template <class Epi, class Sched, bool ALIGN_EPI = false, bool SP2 = false>
; __device__ __forceinline__ void gemm_phase(PG8_LAS unsigned char* lds, const Gemm g, const Sched& S, const Epi& E) {
;     ...
;             PG8_WAIT_V(8); PG8_WAIT_L(0); PG8_BAR; PG8_MMA(0, 0, At, B0); PG8_MMA(0, 1, At, B1); PG8_BAR; PG8_SCHED;
;             PG8_LDA(At, 0, 1); PG8_STAGE(PG8_SB(0, 0), b2, voffB); PG8_STAGE(PG8_SB(0, 1), b2 + hstep, voffB); PG8_STAGE(PG8_SA(0, 0), a2, voffA);
;             PG8_WAIT_V(8); PG8_WAIT_L(0); PG8_BAR; PG8_MMA(1, 0, At, B0); PG8_MMA(1, 1, At, B1); PG8_BAR; PG8_SCHED;
	s_setprio 1
	s_waitcnt lgkmcnt(0)
	v_mfma_f32_16x16x32_bf16 v[124:127], v[144:147], v[184:187], v[124:127]
	v_mfma_f32_16x16x32_bf16 v[120:123], v[152:155], v[184:187], v[120:123]
	v_mfma_f32_16x16x32_bf16 v[116:119], v[144:147], v[192:195], v[116:119]
	v_mfma_f32_16x16x32_bf16 v[112:115], v[152:155], v[192:195], v[112:115]
	v_mfma_f32_16x16x32_bf16 v[104:107], v[144:147], v[200:203], v[104:107]
	v_mfma_f32_16x16x32_bf16 v[96:99], v[152:155], v[200:203], v[96:99]
	v_mfma_f32_16x16x32_bf16 v[88:91], v[144:147], v[208:211], v[88:91]
	v_mfma_f32_16x16x32_bf16 v[80:83], v[152:155], v[208:211], v[80:83]
	v_mfma_f32_16x16x32_bf16 v[124:127], v[148:151], v[188:191], v[124:127]
	v_mfma_f32_16x16x32_bf16 v[120:123], v[164:167], v[188:191], v[120:123]
	v_mfma_f32_16x16x32_bf16 v[116:119], v[148:151], v[196:199], v[116:119]
	v_mfma_f32_16x16x32_bf16 v[112:115], v[164:167], v[196:199], v[112:115]
	v_mfma_f32_16x16x32_bf16 v[104:107], v[148:151], v[204:207], v[104:107]
	v_mfma_f32_16x16x32_bf16 v[96:99], v[164:167], v[204:207], v[96:99]
	v_mfma_f32_16x16x32_bf16 v[88:91], v[148:151], v[212:215], v[88:91]
	v_mfma_f32_16x16x32_bf16 v[80:83], v[164:167], v[212:215], v[80:83]
	s_setprio 0
	s_setprio 1
	v_mfma_f32_16x16x32_bf16 v[108:111], v[168:171], v[184:187], v[108:111]
	v_mfma_f32_16x16x32_bf16 v[100:103], v[176:179], v[184:187], v[100:103]
	v_mfma_f32_16x16x32_bf16 v[92:95], v[168:171], v[192:195], v[92:95]
	v_mfma_f32_16x16x32_bf16 v[84:87], v[176:179], v[192:195], v[84:87]
	v_mfma_f32_16x16x32_bf16 v[76:79], v[168:171], v[200:203], v[76:79]
	v_mfma_f32_16x16x32_bf16 v[72:75], v[176:179], v[200:203], v[72:75]
	v_mfma_f32_16x16x32_bf16 v[68:71], v[168:171], v[208:211], v[68:71]
	v_mfma_f32_16x16x32_bf16 v[64:67], v[176:179], v[208:211], v[64:67]
	v_mfma_f32_16x16x32_bf16 v[108:111], v[172:175], v[188:191], v[108:111]
	v_mfma_f32_16x16x32_bf16 v[100:103], v[180:183], v[188:191], v[100:103]
	v_mfma_f32_16x16x32_bf16 v[92:95], v[172:175], v[196:199], v[92:95]
	v_mfma_f32_16x16x32_bf16 v[84:87], v[180:183], v[196:199], v[84:87]
	v_mfma_f32_16x16x32_bf16 v[76:79], v[172:175], v[204:207], v[76:79]
	v_mfma_f32_16x16x32_bf16 v[72:75], v[180:183], v[204:207], v[72:75]
	v_mfma_f32_16x16x32_bf16 v[68:71], v[172:175], v[212:215], v[68:71]
	v_mfma_f32_16x16x32_bf16 v[64:67], v[180:183], v[212:215], v[64:67]
	s_setprio 0
	s_barrier
	s_add_i32 s66, s51, s16
	s_mov_b64 s[98:99], s[64:65]
	s_mov_b32 m0, s66
	ds_read_b128 v[184:187], v161 offset:16384
	ds_read_b128 v[188:191], v161 offset:17408
	ds_read_b128 v[192:195], v161 offset:18432
	ds_read_b128 v[196:199], v161 offset:19456
	ds_read_b128 v[200:203], v161 offset:20480
	ds_read_b128 v[204:207], v161 offset:21504
	ds_read_b128 v[208:211], v161 offset:22528
	ds_read_b128 v[212:215], v161 offset:23552
	global_load_lds_dwordx4 v130, s[64:65]
	s_add_i32 m0, s66, 0x2000
	s_add_u32 s64, s64, s6
	s_addc_u32 s65, s65, s7
	s_add_i32 s66, s56, s16
	global_load_lds_dwordx4 v134, s[98:99]
	s_mov_b64 s[100:101], s[64:65]
	s_mov_b32 m0, s66
	s_nop 0
	global_load_lds_dwordx4 v130, s[64:65]
	s_add_i32 m0, s66, 0x2000
	s_mov_b64 s[22:23], s[34:35]
	global_load_lds_dwordx4 v134, s[64:65]
	s_mov_b32 m0, s17
	s_nop 0
	global_load_lds_dwordx4 v128, s[34:35]
	s_mov_b32 m0, s19
	s_nop 0
	global_load_lds_dwordx4 v132, s[34:35]
	s_waitcnt vmcnt(8)
	s_waitcnt lgkmcnt(0)
	s_barrier
	s_setprio 1
	s_waitcnt lgkmcnt(0)
	v_mfma_f32_16x16x32_bf16 v[60:63], v[144:147], v[184:187], v[60:63]
	v_mfma_f32_16x16x32_bf16 v[56:59], v[152:155], v[184:187], v[56:59]
	v_mfma_f32_16x16x32_bf16 v[52:55], v[144:147], v[192:195], v[52:55]
	v_mfma_f32_16x16x32_bf16 v[48:51], v[152:155], v[192:195], v[48:51]
	v_mfma_f32_16x16x32_bf16 v[40:43], v[144:147], v[200:203], v[40:43]
	v_mfma_f32_16x16x32_bf16 v[32:35], v[152:155], v[200:203], v[32:35]
	v_mfma_f32_16x16x32_bf16 v[24:27], v[144:147], v[208:211], v[24:27]
	v_mfma_f32_16x16x32_bf16 v[16:19], v[152:155], v[208:211], v[16:19]
	v_mfma_f32_16x16x32_bf16 v[60:63], v[148:151], v[188:191], v[60:63]
	v_mfma_f32_16x16x32_bf16 v[56:59], v[164:167], v[188:191], v[56:59]
	v_mfma_f32_16x16x32_bf16 v[52:55], v[148:151], v[196:199], v[52:55]
	v_mfma_f32_16x16x32_bf16 v[48:51], v[164:167], v[196:199], v[48:51]
	v_mfma_f32_16x16x32_bf16 v[40:43], v[148:151], v[204:207], v[40:43]
	v_mfma_f32_16x16x32_bf16 v[32:35], v[164:167], v[204:207], v[32:35]
	v_mfma_f32_16x16x32_bf16 v[24:27], v[148:151], v[212:215], v[24:27]
	v_mfma_f32_16x16x32_bf16 v[16:19], v[164:167], v[212:215], v[16:19]
	s_setprio 0
	s_setprio 1
	v_mfma_f32_16x16x32_bf16 v[44:47], v[168:171], v[184:187], v[44:47]
	v_mfma_f32_16x16x32_bf16 v[36:39], v[176:179], v[184:187], v[36:39]
	v_mfma_f32_16x16x32_bf16 v[28:31], v[168:171], v[192:195], v[28:31]
	v_mfma_f32_16x16x32_bf16 v[20:23], v[176:179], v[192:195], v[20:23]
	v_mfma_f32_16x16x32_bf16 v[12:15], v[168:171], v[200:203], v[12:15]
	v_mfma_f32_16x16x32_bf16 v[8:11], v[176:179], v[200:203], v[8:11]
	v_mfma_f32_16x16x32_bf16 v[4:7], v[168:171], v[208:211], v[4:7]
	v_mfma_f32_16x16x32_bf16 v[0:3], v[176:179], v[208:211], v[0:3]
	v_mfma_f32_16x16x32_bf16 v[44:47], v[172:175], v[188:191], v[44:47]
	v_mfma_f32_16x16x32_bf16 v[36:39], v[180:183], v[188:191], v[36:39]
	v_mfma_f32_16x16x32_bf16 v[28:31], v[172:175], v[196:199], v[28:31]
	v_mfma_f32_16x16x32_bf16 v[20:23], v[180:183], v[196:199], v[20:23]
	v_mfma_f32_16x16x32_bf16 v[12:15], v[172:175], v[204:207], v[12:15]
	v_mfma_f32_16x16x32_bf16 v[8:11], v[180:183], v[204:207], v[8:11]
	v_mfma_f32_16x16x32_bf16 v[4:7], v[172:175], v[212:215], v[4:7]
	v_mfma_f32_16x16x32_bf16 v[0:3], v[180:183], v[212:215], v[0:3]
	s_setprio 0
	s_barrier
; #define PG8_STAGE(bufoff, gbase, voff) do { _Pragma("unroll") for (int _i = 0; _i < 2; ++_i) \
;         __builtin_amdgcn_global_load_lds((const unsigned*)((const char*)(gbase) + (voff)[_i]), (PG8_LAS unsigned*)(lds + (bufoff) + ldsw + _i * 8192), 16, 0, 0); } while (0)
; #define PG8_LDA(dst, b, h) do { _Pragma("unroll") for (int m = 0; m < 4; ++m) _Pragma("unroll") for (int k = 0; k < 2; ++k) dst[m][k] = *(const PG8_LAS bf16x8*)(lds + PG8_SA(b, h) + aoff + m * 2048 + k * 1024); } while (0)
; #define PG8_LDB(dst, b, h) do { _Pragma("unroll") for (int n = 0; n < 2; ++n) _Pragma("unroll") for (int k = 0; k < 2; ++k) dst[n][k] = *(const PG8_LAS bf16x8*)(lds + PG8_SB(b, h) + boff + n * 2048 + k * 1024); } while (0)
; #define PG8_MMA(ai, bj, At, Bt) do { __builtin_amdgcn_s_setprio(1); _Pragma("unroll") for (int m = 0; m < 4; ++m) _Pragma("unroll") for (int n = 0; n < 2; ++n) _Pragma("unroll") for (int k = 0; k < 2; ++k) \
;         acc[ai][bj][m][n] = __builtin_amdgcn_mfma_f32_16x16x32_bf16(Bt[n][k], At[m][k], acc[ai][bj][m][n], 0, 0, 0); __builtin_amdgcn_s_setprio(0); } while (0)
; #define PG8_WAIT_V(n) asm volatile("s_waitcnt vmcnt(" #n ")" ::: "memory")
; #define PG8_WAIT_L(n) asm volatile("s_waitcnt lgkmcnt(" #n ")" ::: "memory")
; #define PG8_BAR __builtin_amdgcn_s_barrier()
; template <class Epi, class Sched, bool ALIGN_EPI = false, bool SP2 = false>
; __device__ __forceinline__ void gemm_phase(PG8_LAS unsigned char* lds, const Gemm g, const Sched& S, const Epi& E) {
;     ...
;         for (int t = 0; t < nt; t += 2) {
;             const bool last = (t == nt - 2);
;             const char* a1 = cA + (size_t)(t + 1) * kstep;
;             const char* a2 = last ? nA : cA + (size_t)(t + 2) * kstep; const char* b2 = last ? nB : cB + (size_t)(t + 2) * kstep;
;             const char* a3 = a2 + kstep; const char* b3 = b2 + kstep;
;     ...
;             PG8_LDB(B0, 1, 0); PG8_LDB(B1, 1, 1); PG8_SCHED; PG8_LDA(At, 1, 0); PG8_STAGE(PG8_SA(0, 1), a2 + hstep, voffA);
;             PG8_WAIT_V(8); PG8_WAIT_L(0); PG8_BAR; PG8_MMA(0, 0, At, B0); PG8_MMA(0, 1, At, B1); PG8_BAR; PG8_SCHED;
;             PG8_LDA(At, 1, 1); PG8_STAGE(PG8_SB(1, 0), b3, voffB); PG8_STAGE(PG8_SB(1, 1), b3 + hstep, voffB); PG8_STAGE(PG8_SA(1, 0), a3, voffA);
;             PG8_WAIT_V(8); PG8_WAIT_L(0); PG8_BAR; PG8_MMA(1, 0, At, B0); PG8_MMA(1, 1, At, B1); PG8_BAR; PG8_SCHED;
	s_add_i32 s64, 0, 0x18000
	v_add_u32_e32 v163, s64, v157
	s_add_i32 s65, 0, 0x1c000
	ds_read_b128 v[144:147], v163
	ds_read_b128 v[148:151], v163 offset:1024
	ds_read_b128 v[152:155], v163 offset:2048
	ds_read_b128 v[164:167], v163 offset:3072
	v_add_u32_e32 v163, s65, v157
	ds_read_b128 v[168:171], v163
	ds_read_b128 v[172:175], v163 offset:1024
	ds_read_b128 v[176:179], v163 offset:2048
	ds_read_b128 v[180:183], v163 offset:3072
	s_add_u32 s34, s34, s6
	s_addc_u32 s35, s35, s7
	s_mov_b32 m0, s33
	ds_read_b128 v[184:187], v161 offset:32768
	ds_read_b128 v[188:191], v161 offset:33792
	ds_read_b128 v[192:195], v161 offset:34816
	ds_read_b128 v[196:199], v161 offset:35840
	ds_read_b128 v[200:203], v161 offset:36864
	ds_read_b128 v[204:207], v161 offset:37888
	ds_read_b128 v[208:211], v161 offset:38912
	ds_read_b128 v[212:215], v161 offset:39936
	global_load_lds_dwordx4 v128, s[34:35]
	s_mov_b32 m0, s36
	s_nop 0
	global_load_lds_dwordx4 v132, s[34:35]
	s_waitcnt vmcnt(8)
	s_waitcnt lgkmcnt(0)
	s_barrier
	s_setprio 1
	s_waitcnt lgkmcnt(0)
	v_mfma_f32_16x16x32_bf16 v[124:127], v[144:147], v[184:187], v[124:127]
	v_mfma_f32_16x16x32_bf16 v[120:123], v[152:155], v[184:187], v[120:123]
	v_mfma_f32_16x16x32_bf16 v[116:119], v[144:147], v[192:195], v[116:119]
	v_mfma_f32_16x16x32_bf16 v[112:115], v[152:155], v[192:195], v[112:115]
	v_mfma_f32_16x16x32_bf16 v[104:107], v[144:147], v[200:203], v[104:107]
	v_mfma_f32_16x16x32_bf16 v[96:99], v[152:155], v[200:203], v[96:99]
	v_mfma_f32_16x16x32_bf16 v[88:91], v[144:147], v[208:211], v[88:91]
	v_mfma_f32_16x16x32_bf16 v[80:83], v[152:155], v[208:211], v[80:83]
	v_mfma_f32_16x16x32_bf16 v[124:127], v[148:151], v[188:191], v[124:127]
	v_mfma_f32_16x16x32_bf16 v[120:123], v[164:167], v[188:191], v[120:123]
	v_mfma_f32_16x16x32_bf16 v[116:119], v[148:151], v[196:199], v[116:119]
	v_mfma_f32_16x16x32_bf16 v[112:115], v[164:167], v[196:199], v[112:115]
	v_mfma_f32_16x16x32_bf16 v[104:107], v[148:151], v[204:207], v[104:107]
	v_mfma_f32_16x16x32_bf16 v[96:99], v[164:167], v[204:207], v[96:99]
	v_mfma_f32_16x16x32_bf16 v[88:91], v[148:151], v[212:215], v[88:91]
	v_mfma_f32_16x16x32_bf16 v[80:83], v[164:167], v[212:215], v[80:83]
	s_setprio 0
	s_setprio 1
	v_mfma_f32_16x16x32_bf16 v[108:111], v[168:171], v[184:187], v[108:111]
	v_mfma_f32_16x16x32_bf16 v[100:103], v[176:179], v[184:187], v[100:103]
	v_mfma_f32_16x16x32_bf16 v[92:95], v[168:171], v[192:195], v[92:95]
	v_mfma_f32_16x16x32_bf16 v[84:87], v[176:179], v[192:195], v[84:87]
	v_mfma_f32_16x16x32_bf16 v[76:79], v[168:171], v[200:203], v[76:79]
	v_mfma_f32_16x16x32_bf16 v[72:75], v[176:179], v[200:203], v[72:75]
	v_mfma_f32_16x16x32_bf16 v[68:71], v[168:171], v[208:211], v[68:71]
	v_mfma_f32_16x16x32_bf16 v[64:67], v[176:179], v[208:211], v[64:67]
	v_mfma_f32_16x16x32_bf16 v[108:111], v[172:175], v[188:191], v[108:111]
	v_mfma_f32_16x16x32_bf16 v[100:103], v[180:183], v[188:191], v[100:103]
	v_mfma_f32_16x16x32_bf16 v[92:95], v[172:175], v[196:199], v[92:95]
	v_mfma_f32_16x16x32_bf16 v[84:87], v[180:183], v[196:199], v[84:87]
	v_mfma_f32_16x16x32_bf16 v[76:79], v[172:175], v[204:207], v[76:79]
	v_mfma_f32_16x16x32_bf16 v[72:75], v[180:183], v[204:207], v[72:75]
	v_mfma_f32_16x16x32_bf16 v[68:71], v[172:175], v[212:215], v[68:71]
	v_mfma_f32_16x16x32_bf16 v[64:67], v[180:183], v[212:215], v[64:67]
	s_setprio 0
	s_barrier
	s_add_i32 s34, s64, s16
	s_add_i32 m0, s34, 0xffffff80
	ds_read_b128 v[184:187], v161 offset:49152
	ds_read_b128 v[188:191], v161 offset:50176
	ds_read_b128 v[192:195], v161 offset:51200
	ds_read_b128 v[196:199], v161 offset:52224
	ds_read_b128 v[200:203], v161 offset:53248
	ds_read_b128 v[204:207], v161 offset:54272
	ds_read_b128 v[208:211], v161 offset:55296
	ds_read_b128 v[212:215], v161 offset:56320
	global_load_lds_dwordx4 v130, s[98:99] offset:128
	s_add_i32 m0, s34, 0x1f80
	s_add_i32 s34, s65, s16
	global_load_lds_dwordx4 v134, s[98:99] offset:128
	s_add_i32 m0, s34, 0xffffff80
	s_nop 0
	global_load_lds_dwordx4 v130, s[100:101] offset:128
	s_add_i32 m0, s34, 0x1f80
	s_nop 0
	global_load_lds_dwordx4 v134, s[100:101] offset:128
	s_add_i32 m0, s37, 0xffffff80
	s_nop 0
	global_load_lds_dwordx4 v128, s[22:23] offset:128
	s_add_i32 m0, s38, 0xffffff80
	s_nop 0
	global_load_lds_dwordx4 v132, s[22:23] offset:128
	s_waitcnt vmcnt(8)
	s_waitcnt lgkmcnt(0)
	s_barrier
	s_setprio 1
	s_waitcnt lgkmcnt(0)
	v_mfma_f32_16x16x32_bf16 v[60:63], v[144:147], v[184:187], v[60:63]
	v_mfma_f32_16x16x32_bf16 v[56:59], v[152:155], v[184:187], v[56:59]
	v_mfma_f32_16x16x32_bf16 v[52:55], v[144:147], v[192:195], v[52:55]
	v_mfma_f32_16x16x32_bf16 v[48:51], v[152:155], v[192:195], v[48:51]
	v_mfma_f32_16x16x32_bf16 v[40:43], v[144:147], v[200:203], v[40:43]
	v_mfma_f32_16x16x32_bf16 v[32:35], v[152:155], v[200:203], v[32:35]
	v_mfma_f32_16x16x32_bf16 v[24:27], v[144:147], v[208:211], v[24:27]
	v_mfma_f32_16x16x32_bf16 v[16:19], v[152:155], v[208:211], v[16:19]
	v_mfma_f32_16x16x32_bf16 v[60:63], v[148:151], v[188:191], v[60:63]
	v_mfma_f32_16x16x32_bf16 v[56:59], v[164:167], v[188:191], v[56:59]
	v_mfma_f32_16x16x32_bf16 v[52:55], v[148:151], v[196:199], v[52:55]
	v_mfma_f32_16x16x32_bf16 v[48:51], v[164:167], v[196:199], v[48:51]
	v_mfma_f32_16x16x32_bf16 v[40:43], v[148:151], v[204:207], v[40:43]
	v_mfma_f32_16x16x32_bf16 v[32:35], v[164:167], v[204:207], v[32:35]
	v_mfma_f32_16x16x32_bf16 v[24:27], v[148:151], v[212:215], v[24:27]
	v_mfma_f32_16x16x32_bf16 v[16:19], v[164:167], v[212:215], v[16:19]
	s_setprio 0
	s_setprio 1
	v_mfma_f32_16x16x32_bf16 v[44:47], v[168:171], v[184:187], v[44:47]
	v_mfma_f32_16x16x32_bf16 v[36:39], v[176:179], v[184:187], v[36:39]
	v_mfma_f32_16x16x32_bf16 v[28:31], v[168:171], v[192:195], v[28:31]
	v_mfma_f32_16x16x32_bf16 v[20:23], v[176:179], v[192:195], v[20:23]
	v_mfma_f32_16x16x32_bf16 v[12:15], v[168:171], v[200:203], v[12:15]
	v_mfma_f32_16x16x32_bf16 v[8:11], v[176:179], v[200:203], v[8:11]
	v_mfma_f32_16x16x32_bf16 v[4:7], v[168:171], v[208:211], v[4:7]
	v_mfma_f32_16x16x32_bf16 v[0:3], v[176:179], v[208:211], v[0:3]
	v_mfma_f32_16x16x32_bf16 v[44:47], v[172:175], v[188:191], v[44:47]
	v_mfma_f32_16x16x32_bf16 v[36:39], v[180:183], v[188:191], v[36:39]
	v_mfma_f32_16x16x32_bf16 v[28:31], v[172:175], v[196:199], v[28:31]
	v_mfma_f32_16x16x32_bf16 v[20:23], v[180:183], v[196:199], v[20:23]
	v_mfma_f32_16x16x32_bf16 v[12:15], v[172:175], v[204:207], v[12:15]
	v_mfma_f32_16x16x32_bf16 v[8:11], v[180:183], v[204:207], v[8:11]
	v_mfma_f32_16x16x32_bf16 v[4:7], v[172:175], v[212:215], v[4:7]
	v_mfma_f32_16x16x32_bf16 v[0:3], v[180:183], v[212:215], v[0:3]
	s_setprio 0
	s_barrier
	s_add_u32 s30, s30, 0x100
	s_addc_u32 s31, s31, 0
	s_add_u32 s61, s61, 0x100
	s_addc_u32 s62, s62, 0
	s_cmp_ge_i32 s63, s40
	s_mov_b32 s34, s63
	s_cbranch_scc0 .LBB0_2575
